# SSM-GLU projection fused into the group RMSNorm phase (64-row blocks per workgroup, operands staged through LDS with full-line DMA), GGLU phase skipped; S5 B/C bf16 fragment tables; lane-major power t
# speedup vs baseline: 1.4275x; 1.0157x over previous
.LBB0_126:
	s_add_i32 s28, s28, 1
	s_cmp_eq_u32 s28, 6
	s_cbranch_scc1 .Lskip_gglu
	s_cmp_eq_u32 s28, 17
	s_cbranch_scc0 .Lkeep_ph

.Lkeep_ph:
	s_cmp_ge_i32 s28, s79
	s_cbranch_scc0 .LBB0_127
	s_getpc_b64 s[98:99]

.Lss3_body:
	s_mul_i32 s10, s36, 0xf0f1
	s_lshr_b32 s10, s10, 22
	s_mul_i32 s11, s10, 68
	s_sub_i32 s8, s36, s11
	s_and_b32 s7, s10, 15
	s_lshr_b32 s6, s10, 4
	s_lshl_b32 s10, s8, 6
	s_lshl_b32 s11, s6, 8
	s_add_i32 s9, s10, s11
	s_lshl_b32 s11, s6, 12
	s_add_i32 s11, s11, s10
	s_add_i32 s11, s11, 0x300
	s_cmp_lt_u32 s8, 4
	s_cselect_b32 s9, s9, s11
	v_mov_b32_e32 v0, 0
	v_mov_b32_e32 v1, 0
	v_mov_b32_e32 v2, 0
	v_mov_b32_e32 v3, 0
	v_mov_b32_e32 v4, 0
	v_mov_b32_e32 v5, 0
	v_mov_b32_e32 v6, 0
	v_mov_b32_e32 v7, 0
	v_mov_b32_e32 v8, 0
	v_mov_b32_e32 v9, 0
	v_mov_b32_e32 v10, 0
	v_mov_b32_e32 v11, 0
	v_mov_b32_e32 v12, 0
	v_mov_b32_e32 v13, 0
	v_mov_b32_e32 v14, 0
	v_mov_b32_e32 v15, 0
	v_and_b32_e32 v207, 15, v205
	v_mul_u32_u24_e32 v207, 0xe00, v207
	v_and_b32_e32 v208, 16, v205
	v_add_u32_e32 v207, v207, v208
	s_mul_i32 s18, s9, 0xe00
	s_lshl_b32 s19, s7, 5
	s_add_i32 s18, s18, s19
	s_add_u32 s18, s18, 0x5e00c00
	s_add_u32 s18, s4, s18
	s_addc_u32 s19, s5, 0
	s_mov_b32 exec_hi, 0
	global_load_dwordx4 v[0:3], v207, s[18:19]
	s_add_u32 s18, s18, 0xe000
	s_addc_u32 s19, s19, 0
	global_load_dwordx4 v[4:7], v207, s[18:19]
	s_add_u32 s18, s18, 0xe000
	s_addc_u32 s19, s19, 0
	global_load_dwordx4 v[8:11], v207, s[18:19]
	s_add_u32 s18, s18, 0xe000
	s_addc_u32 s19, s19, 0
	global_load_dwordx4 v[12:15], v207, s[18:19]
	s_mov_b64 exec, -1
	v_lshlrev_b32_e32 v134, 4, v205
	v_add_u32_e32 v208, 0x1000, v134
	v_and_b32_e32 v135, 15, v205
	v_lshlrev_b32_e32 v136, 8, v135
	v_lshlrev_b32_e32 v135, 6, v135
	v_and_b32_e32 v207, 16, v205
	v_lshl_add_u32 v135, v207, 1, v135
	v_lshrrev_b32_e32 v207, 4, v205
	v_lshl_add_u32 v136, v207, 4, v136
	v_lshlrev_b32_e32 v206, 5, v207
	v_readlane_b32 s10, v247, 28
	s_mov_b32 s11, s8
	s_lshl_b32 s16, s10, 1
	s_add_i32 s16, s16, 0
	s_lshl_b32 s16, s16, 4
	s_add_i32 s16, s16, s7
	s_lshl_b32 s17, s6, 1
	s_add_i32 s17, s17, 0
	s_lshl_b32 s17, s17, 4
	s_add_i32 s17, s17, s7
	s_mul_i32 s17, s17, 68
	s_add_i32 s17, s17, s11
	s_lshl_b32 s17, s17, 6
	s_lshl_b32 s20, s16, 13
	s_add_u32 s20, s20, 0xfd00000
	s_add_u32 s20, s4, s20
	s_addc_u32 s21, s5, 0
	s_lshl_b32 s38, s16, 12
	s_add_u32 s38, s38, 0xfd80000
	s_add_u32 s38, s4, s38
	s_addc_u32 s39, s5, 0
	s_lshl_b32 s42, s16, 15
	s_add_u32 s42, s42, 0xf900000
	s_add_u32 s42, s4, s42
	s_addc_u32 s43, s5, 0
	s_lshl_b32 s44, s17, 3
	s_add_u32 s44, s44, 0x740000
	s_add_u32 s44, s4, s44
	s_addc_u32 s45, s5, 0
	global_load_dwordx4 v[64:67], v134, s[20:21]
	global_load_dwordx4 v[72:75], v134, s[20:21] offset:1024
	s_add_u32 s20, s20, 0x800
	s_addc_u32 s21, s21, 0
	global_load_dwordx4 v[138:141], v134, s[42:43] offset:0
	global_load_dwordx4 v[142:145], v134, s[42:43] offset:1024
	global_load_dwordx4 v[146:149], v134, s[42:43] offset:2048
	global_load_dwordx4 v[150:153], v134, s[42:43] offset:3072
	global_load_dwordx4 v[154:157], v208, s[42:43] offset:0
	global_load_dwordx4 v[158:161], v208, s[42:43] offset:1024
	global_load_dwordx4 v[162:165], v208, s[42:43] offset:2048
	global_load_dwordx4 v[166:169], v208, s[42:43] offset:3072
	global_load_dwordx4 v[170:173], v206, s[44:45]
	global_load_dwordx4 v[174:177], v206, s[44:45] offset:16
	s_add_u32 s42, s42, 0x2000
	s_addc_u32 s43, s43, 0
	s_add_u32 s44, s44, 0x80
	s_addc_u32 s45, s45, 0
	s_waitcnt vmcnt(12)
	s_waitcnt vmcnt(10)
	global_load_dwordx4 v[80:83], v134, s[38:39]
	s_add_u32 s38, s38, 0x400
	s_addc_u32 s39, s39, 0
	v_mfma_f32_16x16x32_bf16 v[32:35], v[64:67], v[0:3], 0
	v_mfma_f32_16x16x32_bf16 v[36:39], v[72:75], v[0:3], 0
	v_mfma_f32_16x16x32_bf16 v[40:43], v[64:67], v[4:7], 0
	v_mfma_f32_16x16x32_bf16 v[44:47], v[72:75], v[4:7], 0
	v_mfma_f32_16x16x32_bf16 v[48:51], v[64:67], v[8:11], 0
	v_mfma_f32_16x16x32_bf16 v[52:55], v[72:75], v[8:11], 0
	v_mfma_f32_16x16x32_bf16 v[56:59], v[64:67], v[12:15], 0
	v_mfma_f32_16x16x32_bf16 v[60:63], v[72:75], v[12:15], 0
	global_load_dwordx4 v[64:67], v134, s[20:21]
	global_load_dwordx4 v[72:75], v134, s[20:21] offset:1024
	s_add_u32 s20, s20, 0x800
	s_addc_u32 s21, s21, 0
	global_load_dwordx4 v[100:103], v134, s[42:43] offset:0
	global_load_dwordx4 v[104:107], v134, s[42:43] offset:1024
	global_load_dwordx4 v[108:111], v134, s[42:43] offset:2048
	global_load_dwordx4 v[112:115], v134, s[42:43] offset:3072
	global_load_dwordx4 v[116:119], v208, s[42:43] offset:0
	global_load_dwordx4 v[120:123], v208, s[42:43] offset:1024
	global_load_dwordx4 v[124:127], v208, s[42:43] offset:2048
	global_load_dwordx4 v[128:131], v208, s[42:43] offset:3072
	global_load_dwordx4 v[178:181], v206, s[44:45]
	global_load_dwordx4 v[182:185], v206, s[44:45] offset:16
	s_add_u32 s42, s42, 0x2000
	s_addc_u32 s43, s43, 0
	s_add_u32 s44, s44, 0x80
	s_addc_u32 s45, s45, 0
	s_waitcnt vmcnt(13)
	v_mul_f32_e32 v132, v171, v157
	v_mul_f32_e32 v133, v170, v157
	v_fma_f32 v170, v170, v156, -v132
	v_fma_f32 v171, v171, v156, v133
	v_mul_f32_e32 v132, v173, v161
	v_mul_f32_e32 v133, v172, v161
	v_fma_f32 v172, v172, v160, -v132
	v_fma_f32 v173, v173, v160, v133
	v_mul_f32_e32 v132, v175, v165
	v_mul_f32_e32 v133, v174, v165
	v_fma_f32 v174, v174, v164, -v132
	v_fma_f32 v175, v175, v164, v133
	v_mul_f32_e32 v132, v177, v169
	v_mul_f32_e32 v133, v176, v169
	v_fma_f32 v176, v176, v168, -v132
	v_fma_f32 v177, v177, v168, v133
	v_mul_f32_e32 v132, v32, v139
	v_mul_f32_e32 v32, v32, v138
	v_fma_f32 v32, -v36, v139, v32
	v_fma_f32 v36, v36, v138, v132
	v_mul_f32_e32 v133, v33, v143
	v_mul_f32_e32 v33, v33, v142
	v_fma_f32 v33, -v37, v143, v33
	v_fma_f32 v37, v37, v142, v133
	v_mul_f32_e32 v132, v34, v147
	v_mul_f32_e32 v34, v34, v146
	v_fma_f32 v34, -v38, v147, v34
	v_fma_f32 v38, v38, v146, v132
	v_mul_f32_e32 v133, v35, v151
	v_mul_f32_e32 v35, v35, v150
	v_fma_f32 v35, -v39, v151, v35
	v_fma_f32 v39, v39, v150, v133
	v_add_f32_dpp v32, v32, v32 row_shr:1 row_mask:0xf bank_mask:0xf bound_ctrl:1
	v_add_f32_dpp v33, v33, v33 row_shr:1 row_mask:0xf bank_mask:0xf bound_ctrl:1
	v_add_f32_dpp v34, v34, v34 row_shr:1 row_mask:0xf bank_mask:0xf bound_ctrl:1
	v_add_f32_dpp v35, v35, v35 row_shr:1 row_mask:0xf bank_mask:0xf bound_ctrl:1
	v_add_f32_dpp v36, v36, v36 row_shr:1 row_mask:0xf bank_mask:0xf bound_ctrl:1
	v_add_f32_dpp v37, v37, v37 row_shr:1 row_mask:0xf bank_mask:0xf bound_ctrl:1
	v_add_f32_dpp v38, v38, v38 row_shr:1 row_mask:0xf bank_mask:0xf bound_ctrl:1
	v_add_f32_dpp v39, v39, v39 row_shr:1 row_mask:0xf bank_mask:0xf bound_ctrl:1
	v_add_f32_dpp v32, v32, v32 row_shr:2 row_mask:0xf bank_mask:0xf bound_ctrl:1
	v_add_f32_dpp v33, v33, v33 row_shr:2 row_mask:0xf bank_mask:0xf bound_ctrl:1
	v_add_f32_dpp v34, v34, v34 row_shr:2 row_mask:0xf bank_mask:0xf bound_ctrl:1
	v_add_f32_dpp v35, v35, v35 row_shr:2 row_mask:0xf bank_mask:0xf bound_ctrl:1
	v_add_f32_dpp v36, v36, v36 row_shr:2 row_mask:0xf bank_mask:0xf bound_ctrl:1
	v_add_f32_dpp v37, v37, v37 row_shr:2 row_mask:0xf bank_mask:0xf bound_ctrl:1
	v_add_f32_dpp v38, v38, v38 row_shr:2 row_mask:0xf bank_mask:0xf bound_ctrl:1
	v_add_f32_dpp v39, v39, v39 row_shr:2 row_mask:0xf bank_mask:0xf bound_ctrl:1
	v_add_f32_dpp v32, v32, v32 row_shr:4 row_mask:0xf bank_mask:0xf bound_ctrl:1
	v_add_f32_dpp v33, v33, v33 row_shr:4 row_mask:0xf bank_mask:0xf bound_ctrl:1
	v_add_f32_dpp v34, v34, v34 row_shr:4 row_mask:0xf bank_mask:0xf bound_ctrl:1
	v_add_f32_dpp v35, v35, v35 row_shr:4 row_mask:0xf bank_mask:0xf bound_ctrl:1
	v_add_f32_dpp v36, v36, v36 row_shr:4 row_mask:0xf bank_mask:0xf bound_ctrl:1
	v_add_f32_dpp v37, v37, v37 row_shr:4 row_mask:0xf bank_mask:0xf bound_ctrl:1
	v_add_f32_dpp v38, v38, v38 row_shr:4 row_mask:0xf bank_mask:0xf bound_ctrl:1
	v_add_f32_dpp v39, v39, v39 row_shr:4 row_mask:0xf bank_mask:0xf bound_ctrl:1
	v_add_f32_dpp v32, v32, v32 row_shr:8 row_mask:0xf bank_mask:0xf bound_ctrl:1
	v_add_f32_dpp v33, v33, v33 row_shr:8 row_mask:0xf bank_mask:0xf bound_ctrl:1
	v_add_f32_dpp v34, v34, v34 row_shr:8 row_mask:0xf bank_mask:0xf bound_ctrl:1
	v_add_f32_dpp v35, v35, v35 row_shr:8 row_mask:0xf bank_mask:0xf bound_ctrl:1
	v_add_f32_dpp v36, v36, v36 row_shr:8 row_mask:0xf bank_mask:0xf bound_ctrl:1
	v_add_f32_dpp v37, v37, v37 row_shr:8 row_mask:0xf bank_mask:0xf bound_ctrl:1
	v_add_f32_dpp v38, v38, v38 row_shr:8 row_mask:0xf bank_mask:0xf bound_ctrl:1
	v_add_f32_dpp v39, v39, v39 row_shr:8 row_mask:0xf bank_mask:0xf bound_ctrl:1
	v_mov_b32_dpp v88, v32 row_newbcast:15 row_mask:0xf bank_mask:0xf
	v_mov_b32_dpp v89, v33 row_newbcast:15 row_mask:0xf bank_mask:0xf
	v_mov_b32_dpp v90, v34 row_newbcast:15 row_mask:0xf bank_mask:0xf
	v_mov_b32_dpp v91, v35 row_newbcast:15 row_mask:0xf bank_mask:0xf
	v_mov_b32_dpp v92, v36 row_newbcast:15 row_mask:0xf bank_mask:0xf
	v_mov_b32_dpp v93, v37 row_newbcast:15 row_mask:0xf bank_mask:0xf
	v_mov_b32_dpp v94, v38 row_newbcast:15 row_mask:0xf bank_mask:0xf
	v_mov_b32_dpp v95, v39 row_newbcast:15 row_mask:0xf bank_mask:0xf
	v_add_f32_e32 v32, v32, v170
	v_add_f32_e32 v36, v36, v171
	v_add_f32_e32 v33, v33, v172
	v_add_f32_e32 v37, v37, v173
	v_add_f32_e32 v34, v34, v174
	v_add_f32_e32 v38, v38, v175
	v_add_f32_e32 v35, v35, v176
	v_add_f32_e32 v39, v39, v177
	v_mul_f32_e32 v132, v32, v141
	v_mul_f32_e32 v32, v32, v140
	v_fma_f32 v32, -v36, v141, v32
	v_fma_f32 v36, v36, v140, v132
	v_mul_f32_e32 v133, v33, v145
	v_mul_f32_e32 v33, v33, v144
	v_fma_f32 v33, -v37, v145, v33
	v_fma_f32 v37, v37, v144, v133
	v_mul_f32_e32 v132, v34, v149
	v_mul_f32_e32 v34, v34, v148
	v_fma_f32 v34, -v38, v149, v34
	v_fma_f32 v38, v38, v148, v132
	v_mul_f32_e32 v133, v35, v153
	v_mul_f32_e32 v35, v35, v152
	v_fma_f32 v35, -v39, v153, v35
	v_fma_f32 v39, v39, v152, v133
	v_add_f32_e32 v88, v88, v170
	v_add_f32_e32 v92, v92, v171
	v_mul_f32_e32 v132, v92, v155
	v_mul_f32_e32 v171, v88, v155
	v_fma_f32 v170, v88, v154, -v132
	v_fma_f32 v171, v92, v154, v171
	v_add_f32_e32 v89, v89, v172
	v_add_f32_e32 v93, v93, v173
	v_mul_f32_e32 v133, v93, v159
	v_mul_f32_e32 v173, v89, v159
	v_fma_f32 v172, v89, v158, -v133
	v_fma_f32 v173, v93, v158, v173
	v_add_f32_e32 v90, v90, v174
	v_add_f32_e32 v94, v94, v175
	v_mul_f32_e32 v132, v94, v163
	v_mul_f32_e32 v175, v90, v163
	v_fma_f32 v174, v90, v162, -v132
	v_fma_f32 v175, v94, v162, v175
	v_add_f32_e32 v91, v91, v176
	v_add_f32_e32 v95, v95, v177
	v_mul_f32_e32 v133, v95, v167
	v_mul_f32_e32 v177, v91, v167
	v_fma_f32 v176, v91, v166, -v133
	v_fma_f32 v177, v95, v166, v177
	v_mul_f32_e32 v132, v40, v139
	v_mul_f32_e32 v40, v40, v138
	v_fma_f32 v40, -v44, v139, v40
	v_fma_f32 v44, v44, v138, v132
	v_mul_f32_e32 v133, v41, v143
	v_mul_f32_e32 v41, v41, v142
	v_fma_f32 v41, -v45, v143, v41
	v_fma_f32 v45, v45, v142, v133
	v_mul_f32_e32 v132, v42, v147
	v_mul_f32_e32 v42, v42, v146
	v_fma_f32 v42, -v46, v147, v42
	v_fma_f32 v46, v46, v146, v132
	v_mul_f32_e32 v133, v43, v151
	v_mul_f32_e32 v43, v43, v150
	v_fma_f32 v43, -v47, v151, v43
	v_fma_f32 v47, v47, v150, v133
	v_add_f32_dpp v40, v40, v40 row_shr:1 row_mask:0xf bank_mask:0xf bound_ctrl:1
	v_add_f32_dpp v41, v41, v41 row_shr:1 row_mask:0xf bank_mask:0xf bound_ctrl:1
	v_add_f32_dpp v42, v42, v42 row_shr:1 row_mask:0xf bank_mask:0xf bound_ctrl:1
	v_add_f32_dpp v43, v43, v43 row_shr:1 row_mask:0xf bank_mask:0xf bound_ctrl:1
	v_add_f32_dpp v44, v44, v44 row_shr:1 row_mask:0xf bank_mask:0xf bound_ctrl:1
	v_add_f32_dpp v45, v45, v45 row_shr:1 row_mask:0xf bank_mask:0xf bound_ctrl:1
	v_add_f32_dpp v46, v46, v46 row_shr:1 row_mask:0xf bank_mask:0xf bound_ctrl:1
	v_add_f32_dpp v47, v47, v47 row_shr:1 row_mask:0xf bank_mask:0xf bound_ctrl:1
	v_add_f32_dpp v40, v40, v40 row_shr:2 row_mask:0xf bank_mask:0xf bound_ctrl:1
	v_add_f32_dpp v41, v41, v41 row_shr:2 row_mask:0xf bank_mask:0xf bound_ctrl:1
	v_add_f32_dpp v42, v42, v42 row_shr:2 row_mask:0xf bank_mask:0xf bound_ctrl:1
	v_add_f32_dpp v43, v43, v43 row_shr:2 row_mask:0xf bank_mask:0xf bound_ctrl:1
	v_add_f32_dpp v44, v44, v44 row_shr:2 row_mask:0xf bank_mask:0xf bound_ctrl:1
	v_add_f32_dpp v45, v45, v45 row_shr:2 row_mask:0xf bank_mask:0xf bound_ctrl:1
	v_add_f32_dpp v46, v46, v46 row_shr:2 row_mask:0xf bank_mask:0xf bound_ctrl:1
	v_add_f32_dpp v47, v47, v47 row_shr:2 row_mask:0xf bank_mask:0xf bound_ctrl:1
	v_add_f32_dpp v40, v40, v40 row_shr:4 row_mask:0xf bank_mask:0xf bound_ctrl:1
	v_add_f32_dpp v41, v41, v41 row_shr:4 row_mask:0xf bank_mask:0xf bound_ctrl:1
	v_add_f32_dpp v42, v42, v42 row_shr:4 row_mask:0xf bank_mask:0xf bound_ctrl:1
	v_add_f32_dpp v43, v43, v43 row_shr:4 row_mask:0xf bank_mask:0xf bound_ctrl:1
	v_add_f32_dpp v44, v44, v44 row_shr:4 row_mask:0xf bank_mask:0xf bound_ctrl:1
	v_add_f32_dpp v45, v45, v45 row_shr:4 row_mask:0xf bank_mask:0xf bound_ctrl:1
	v_add_f32_dpp v46, v46, v46 row_shr:4 row_mask:0xf bank_mask:0xf bound_ctrl:1
	v_add_f32_dpp v47, v47, v47 row_shr:4 row_mask:0xf bank_mask:0xf bound_ctrl:1
	v_add_f32_dpp v40, v40, v40 row_shr:8 row_mask:0xf bank_mask:0xf bound_ctrl:1
	v_add_f32_dpp v41, v41, v41 row_shr:8 row_mask:0xf bank_mask:0xf bound_ctrl:1
	v_add_f32_dpp v42, v42, v42 row_shr:8 row_mask:0xf bank_mask:0xf bound_ctrl:1
	v_add_f32_dpp v43, v43, v43 row_shr:8 row_mask:0xf bank_mask:0xf bound_ctrl:1
	v_add_f32_dpp v44, v44, v44 row_shr:8 row_mask:0xf bank_mask:0xf bound_ctrl:1
	v_add_f32_dpp v45, v45, v45 row_shr:8 row_mask:0xf bank_mask:0xf bound_ctrl:1
	v_add_f32_dpp v46, v46, v46 row_shr:8 row_mask:0xf bank_mask:0xf bound_ctrl:1
	v_add_f32_dpp v47, v47, v47 row_shr:8 row_mask:0xf bank_mask:0xf bound_ctrl:1
	v_mov_b32_dpp v88, v40 row_newbcast:15 row_mask:0xf bank_mask:0xf
	v_mov_b32_dpp v89, v41 row_newbcast:15 row_mask:0xf bank_mask:0xf
	v_mov_b32_dpp v90, v42 row_newbcast:15 row_mask:0xf bank_mask:0xf
	v_mov_b32_dpp v91, v43 row_newbcast:15 row_mask:0xf bank_mask:0xf
	v_mov_b32_dpp v92, v44 row_newbcast:15 row_mask:0xf bank_mask:0xf
	v_mov_b32_dpp v93, v45 row_newbcast:15 row_mask:0xf bank_mask:0xf
	v_mov_b32_dpp v94, v46 row_newbcast:15 row_mask:0xf bank_mask:0xf
	v_mov_b32_dpp v95, v47 row_newbcast:15 row_mask:0xf bank_mask:0xf
	v_add_f32_e32 v40, v40, v170
	v_add_f32_e32 v44, v44, v171
	v_add_f32_e32 v41, v41, v172
	v_add_f32_e32 v45, v45, v173
	v_add_f32_e32 v42, v42, v174
	v_add_f32_e32 v46, v46, v175
	v_add_f32_e32 v43, v43, v176
	v_add_f32_e32 v47, v47, v177
	v_mul_f32_e32 v132, v40, v141
	v_mul_f32_e32 v40, v40, v140
	v_fma_f32 v40, -v44, v141, v40
	v_fma_f32 v44, v44, v140, v132
	v_mul_f32_e32 v133, v41, v145
	v_mul_f32_e32 v41, v41, v144
	v_fma_f32 v41, -v45, v145, v41
	v_fma_f32 v45, v45, v144, v133
	v_mul_f32_e32 v132, v42, v149
	v_mul_f32_e32 v42, v42, v148
	v_fma_f32 v42, -v46, v149, v42
	v_fma_f32 v46, v46, v148, v132
	v_mul_f32_e32 v133, v43, v153
	v_mul_f32_e32 v43, v43, v152
	v_fma_f32 v43, -v47, v153, v43
	v_fma_f32 v47, v47, v152, v133
	v_add_f32_e32 v88, v88, v170
	v_add_f32_e32 v92, v92, v171
	v_mul_f32_e32 v132, v92, v155
	v_mul_f32_e32 v171, v88, v155
	v_fma_f32 v170, v88, v154, -v132
	v_fma_f32 v171, v92, v154, v171
	v_add_f32_e32 v89, v89, v172
	v_add_f32_e32 v93, v93, v173
	v_mul_f32_e32 v133, v93, v159
	v_mul_f32_e32 v173, v89, v159
	v_fma_f32 v172, v89, v158, -v133
	v_fma_f32 v173, v93, v158, v173
	v_add_f32_e32 v90, v90, v174
	v_add_f32_e32 v94, v94, v175
	v_mul_f32_e32 v132, v94, v163
	v_mul_f32_e32 v175, v90, v163
	v_fma_f32 v174, v90, v162, -v132
	v_fma_f32 v175, v94, v162, v175
	v_add_f32_e32 v91, v91, v176
	v_add_f32_e32 v95, v95, v177
	v_mul_f32_e32 v133, v95, v167
	v_mul_f32_e32 v177, v91, v167
	v_fma_f32 v176, v91, v166, -v133
	v_fma_f32 v177, v95, v166, v177
	v_mul_f32_e32 v132, v48, v139
	v_mul_f32_e32 v48, v48, v138
	v_fma_f32 v48, -v52, v139, v48
	v_fma_f32 v52, v52, v138, v132
	v_mul_f32_e32 v133, v49, v143
	v_mul_f32_e32 v49, v49, v142
	v_fma_f32 v49, -v53, v143, v49
	v_fma_f32 v53, v53, v142, v133
	v_mul_f32_e32 v132, v50, v147
	v_mul_f32_e32 v50, v50, v146
	v_fma_f32 v50, -v54, v147, v50
	v_fma_f32 v54, v54, v146, v132
	v_mul_f32_e32 v133, v51, v151
	v_mul_f32_e32 v51, v51, v150
	v_fma_f32 v51, -v55, v151, v51
	v_fma_f32 v55, v55, v150, v133
	v_add_f32_dpp v48, v48, v48 row_shr:1 row_mask:0xf bank_mask:0xf bound_ctrl:1
	v_add_f32_dpp v49, v49, v49 row_shr:1 row_mask:0xf bank_mask:0xf bound_ctrl:1
	v_add_f32_dpp v50, v50, v50 row_shr:1 row_mask:0xf bank_mask:0xf bound_ctrl:1
	v_add_f32_dpp v51, v51, v51 row_shr:1 row_mask:0xf bank_mask:0xf bound_ctrl:1
	v_add_f32_dpp v52, v52, v52 row_shr:1 row_mask:0xf bank_mask:0xf bound_ctrl:1
	v_add_f32_dpp v53, v53, v53 row_shr:1 row_mask:0xf bank_mask:0xf bound_ctrl:1
	v_add_f32_dpp v54, v54, v54 row_shr:1 row_mask:0xf bank_mask:0xf bound_ctrl:1
	v_add_f32_dpp v55, v55, v55 row_shr:1 row_mask:0xf bank_mask:0xf bound_ctrl:1
	v_add_f32_dpp v48, v48, v48 row_shr:2 row_mask:0xf bank_mask:0xf bound_ctrl:1
	v_add_f32_dpp v49, v49, v49 row_shr:2 row_mask:0xf bank_mask:0xf bound_ctrl:1
	v_add_f32_dpp v50, v50, v50 row_shr:2 row_mask:0xf bank_mask:0xf bound_ctrl:1
	v_add_f32_dpp v51, v51, v51 row_shr:2 row_mask:0xf bank_mask:0xf bound_ctrl:1
	v_add_f32_dpp v52, v52, v52 row_shr:2 row_mask:0xf bank_mask:0xf bound_ctrl:1
	v_add_f32_dpp v53, v53, v53 row_shr:2 row_mask:0xf bank_mask:0xf bound_ctrl:1
	v_add_f32_dpp v54, v54, v54 row_shr:2 row_mask:0xf bank_mask:0xf bound_ctrl:1
	v_add_f32_dpp v55, v55, v55 row_shr:2 row_mask:0xf bank_mask:0xf bound_ctrl:1
	v_add_f32_dpp v48, v48, v48 row_shr:4 row_mask:0xf bank_mask:0xf bound_ctrl:1
	v_add_f32_dpp v49, v49, v49 row_shr:4 row_mask:0xf bank_mask:0xf bound_ctrl:1
	v_add_f32_dpp v50, v50, v50 row_shr:4 row_mask:0xf bank_mask:0xf bound_ctrl:1
	v_add_f32_dpp v51, v51, v51 row_shr:4 row_mask:0xf bank_mask:0xf bound_ctrl:1
	v_add_f32_dpp v52, v52, v52 row_shr:4 row_mask:0xf bank_mask:0xf bound_ctrl:1
	v_add_f32_dpp v53, v53, v53 row_shr:4 row_mask:0xf bank_mask:0xf bound_ctrl:1
	v_add_f32_dpp v54, v54, v54 row_shr:4 row_mask:0xf bank_mask:0xf bound_ctrl:1
	v_add_f32_dpp v55, v55, v55 row_shr:4 row_mask:0xf bank_mask:0xf bound_ctrl:1
	v_add_f32_dpp v48, v48, v48 row_shr:8 row_mask:0xf bank_mask:0xf bound_ctrl:1
	v_add_f32_dpp v49, v49, v49 row_shr:8 row_mask:0xf bank_mask:0xf bound_ctrl:1
	v_add_f32_dpp v50, v50, v50 row_shr:8 row_mask:0xf bank_mask:0xf bound_ctrl:1
	v_add_f32_dpp v51, v51, v51 row_shr:8 row_mask:0xf bank_mask:0xf bound_ctrl:1
	v_add_f32_dpp v52, v52, v52 row_shr:8 row_mask:0xf bank_mask:0xf bound_ctrl:1
	v_add_f32_dpp v53, v53, v53 row_shr:8 row_mask:0xf bank_mask:0xf bound_ctrl:1
	v_add_f32_dpp v54, v54, v54 row_shr:8 row_mask:0xf bank_mask:0xf bound_ctrl:1
	v_add_f32_dpp v55, v55, v55 row_shr:8 row_mask:0xf bank_mask:0xf bound_ctrl:1
	v_mov_b32_dpp v88, v48 row_newbcast:15 row_mask:0xf bank_mask:0xf
	v_mov_b32_dpp v89, v49 row_newbcast:15 row_mask:0xf bank_mask:0xf
	v_mov_b32_dpp v90, v50 row_newbcast:15 row_mask:0xf bank_mask:0xf
	v_mov_b32_dpp v91, v51 row_newbcast:15 row_mask:0xf bank_mask:0xf
	v_mov_b32_dpp v92, v52 row_newbcast:15 row_mask:0xf bank_mask:0xf
	v_mov_b32_dpp v93, v53 row_newbcast:15 row_mask:0xf bank_mask:0xf
	v_mov_b32_dpp v94, v54 row_newbcast:15 row_mask:0xf bank_mask:0xf
	v_mov_b32_dpp v95, v55 row_newbcast:15 row_mask:0xf bank_mask:0xf
	v_add_f32_e32 v48, v48, v170
	v_add_f32_e32 v52, v52, v171
	v_add_f32_e32 v49, v49, v172
	v_add_f32_e32 v53, v53, v173
	v_add_f32_e32 v50, v50, v174
	v_add_f32_e32 v54, v54, v175
	v_add_f32_e32 v51, v51, v176
	v_add_f32_e32 v55, v55, v177
	v_mul_f32_e32 v132, v48, v141
	v_mul_f32_e32 v48, v48, v140
	v_fma_f32 v48, -v52, v141, v48
	v_fma_f32 v52, v52, v140, v132
	v_mul_f32_e32 v133, v49, v145
	v_mul_f32_e32 v49, v49, v144
	v_fma_f32 v49, -v53, v145, v49
	v_fma_f32 v53, v53, v144, v133
	v_mul_f32_e32 v132, v50, v149
	v_mul_f32_e32 v50, v50, v148
	v_fma_f32 v50, -v54, v149, v50
	v_fma_f32 v54, v54, v148, v132
	v_mul_f32_e32 v133, v51, v153
	v_mul_f32_e32 v51, v51, v152
	v_fma_f32 v51, -v55, v153, v51
	v_fma_f32 v55, v55, v152, v133
	v_add_f32_e32 v88, v88, v170
	v_add_f32_e32 v92, v92, v171
	v_mul_f32_e32 v132, v92, v155
	v_mul_f32_e32 v171, v88, v155
	v_fma_f32 v170, v88, v154, -v132
	v_fma_f32 v171, v92, v154, v171
	v_add_f32_e32 v89, v89, v172
	v_add_f32_e32 v93, v93, v173
	v_mul_f32_e32 v133, v93, v159
	v_mul_f32_e32 v173, v89, v159
	v_fma_f32 v172, v89, v158, -v133
	v_fma_f32 v173, v93, v158, v173
	v_add_f32_e32 v90, v90, v174
	v_add_f32_e32 v94, v94, v175
	v_mul_f32_e32 v132, v94, v163
	v_mul_f32_e32 v175, v90, v163
	v_fma_f32 v174, v90, v162, -v132
	v_fma_f32 v175, v94, v162, v175
	v_add_f32_e32 v91, v91, v176
	v_add_f32_e32 v95, v95, v177
	v_mul_f32_e32 v133, v95, v167
	v_mul_f32_e32 v177, v91, v167
	v_fma_f32 v176, v91, v166, -v133
	v_fma_f32 v177, v95, v166, v177
	v_mul_f32_e32 v132, v56, v139
	v_mul_f32_e32 v56, v56, v138
	v_fma_f32 v56, -v60, v139, v56
	v_fma_f32 v60, v60, v138, v132
	v_mul_f32_e32 v133, v57, v143
	v_mul_f32_e32 v57, v57, v142
	v_fma_f32 v57, -v61, v143, v57
	v_fma_f32 v61, v61, v142, v133
	v_mul_f32_e32 v132, v58, v147
	v_mul_f32_e32 v58, v58, v146
	v_fma_f32 v58, -v62, v147, v58
	v_fma_f32 v62, v62, v146, v132
	v_mul_f32_e32 v133, v59, v151
	v_mul_f32_e32 v59, v59, v150
	v_fma_f32 v59, -v63, v151, v59
	v_fma_f32 v63, v63, v150, v133
	v_add_f32_dpp v56, v56, v56 row_shr:1 row_mask:0xf bank_mask:0xf bound_ctrl:1
	v_add_f32_dpp v57, v57, v57 row_shr:1 row_mask:0xf bank_mask:0xf bound_ctrl:1
	v_add_f32_dpp v58, v58, v58 row_shr:1 row_mask:0xf bank_mask:0xf bound_ctrl:1
	v_add_f32_dpp v59, v59, v59 row_shr:1 row_mask:0xf bank_mask:0xf bound_ctrl:1
	v_add_f32_dpp v60, v60, v60 row_shr:1 row_mask:0xf bank_mask:0xf bound_ctrl:1
	v_add_f32_dpp v61, v61, v61 row_shr:1 row_mask:0xf bank_mask:0xf bound_ctrl:1
	v_add_f32_dpp v62, v62, v62 row_shr:1 row_mask:0xf bank_mask:0xf bound_ctrl:1
	v_add_f32_dpp v63, v63, v63 row_shr:1 row_mask:0xf bank_mask:0xf bound_ctrl:1
	v_add_f32_dpp v56, v56, v56 row_shr:2 row_mask:0xf bank_mask:0xf bound_ctrl:1
	v_add_f32_dpp v57, v57, v57 row_shr:2 row_mask:0xf bank_mask:0xf bound_ctrl:1
	v_add_f32_dpp v58, v58, v58 row_shr:2 row_mask:0xf bank_mask:0xf bound_ctrl:1
	v_add_f32_dpp v59, v59, v59 row_shr:2 row_mask:0xf bank_mask:0xf bound_ctrl:1
	v_add_f32_dpp v60, v60, v60 row_shr:2 row_mask:0xf bank_mask:0xf bound_ctrl:1
	v_add_f32_dpp v61, v61, v61 row_shr:2 row_mask:0xf bank_mask:0xf bound_ctrl:1
	v_add_f32_dpp v62, v62, v62 row_shr:2 row_mask:0xf bank_mask:0xf bound_ctrl:1
	v_add_f32_dpp v63, v63, v63 row_shr:2 row_mask:0xf bank_mask:0xf bound_ctrl:1
	v_add_f32_dpp v56, v56, v56 row_shr:4 row_mask:0xf bank_mask:0xf bound_ctrl:1
	v_add_f32_dpp v57, v57, v57 row_shr:4 row_mask:0xf bank_mask:0xf bound_ctrl:1
	v_add_f32_dpp v58, v58, v58 row_shr:4 row_mask:0xf bank_mask:0xf bound_ctrl:1
	v_add_f32_dpp v59, v59, v59 row_shr:4 row_mask:0xf bank_mask:0xf bound_ctrl:1
	v_add_f32_dpp v60, v60, v60 row_shr:4 row_mask:0xf bank_mask:0xf bound_ctrl:1
	v_add_f32_dpp v61, v61, v61 row_shr:4 row_mask:0xf bank_mask:0xf bound_ctrl:1
	v_add_f32_dpp v62, v62, v62 row_shr:4 row_mask:0xf bank_mask:0xf bound_ctrl:1
	v_add_f32_dpp v63, v63, v63 row_shr:4 row_mask:0xf bank_mask:0xf bound_ctrl:1
	v_add_f32_dpp v56, v56, v56 row_shr:8 row_mask:0xf bank_mask:0xf bound_ctrl:1
	v_add_f32_dpp v57, v57, v57 row_shr:8 row_mask:0xf bank_mask:0xf bound_ctrl:1
	v_add_f32_dpp v58, v58, v58 row_shr:8 row_mask:0xf bank_mask:0xf bound_ctrl:1
	v_add_f32_dpp v59, v59, v59 row_shr:8 row_mask:0xf bank_mask:0xf bound_ctrl:1
	v_add_f32_dpp v60, v60, v60 row_shr:8 row_mask:0xf bank_mask:0xf bound_ctrl:1
	v_add_f32_dpp v61, v61, v61 row_shr:8 row_mask:0xf bank_mask:0xf bound_ctrl:1
	v_add_f32_dpp v62, v62, v62 row_shr:8 row_mask:0xf bank_mask:0xf bound_ctrl:1
	v_add_f32_dpp v63, v63, v63 row_shr:8 row_mask:0xf bank_mask:0xf bound_ctrl:1
	v_mov_b32_dpp v88, v56 row_newbcast:15 row_mask:0xf bank_mask:0xf
	v_mov_b32_dpp v89, v57 row_newbcast:15 row_mask:0xf bank_mask:0xf
	v_mov_b32_dpp v90, v58 row_newbcast:15 row_mask:0xf bank_mask:0xf
	v_mov_b32_dpp v91, v59 row_newbcast:15 row_mask:0xf bank_mask:0xf
	v_mov_b32_dpp v92, v60 row_newbcast:15 row_mask:0xf bank_mask:0xf
	v_mov_b32_dpp v93, v61 row_newbcast:15 row_mask:0xf bank_mask:0xf
	v_mov_b32_dpp v94, v62 row_newbcast:15 row_mask:0xf bank_mask:0xf
	v_mov_b32_dpp v95, v63 row_newbcast:15 row_mask:0xf bank_mask:0xf
	v_add_f32_e32 v56, v56, v170
	v_add_f32_e32 v60, v60, v171
	v_add_f32_e32 v57, v57, v172
	v_add_f32_e32 v61, v61, v173
	v_add_f32_e32 v58, v58, v174
	v_add_f32_e32 v62, v62, v175
	v_add_f32_e32 v59, v59, v176
	v_add_f32_e32 v63, v63, v177
	v_mul_f32_e32 v132, v56, v141
	v_mul_f32_e32 v56, v56, v140
	v_fma_f32 v56, -v60, v141, v56
	v_fma_f32 v60, v60, v140, v132
	v_mul_f32_e32 v133, v57, v145
	v_mul_f32_e32 v57, v57, v144
	v_fma_f32 v57, -v61, v145, v57
	v_fma_f32 v61, v61, v144, v133
	v_mul_f32_e32 v132, v58, v149
	v_mul_f32_e32 v58, v58, v148
	v_fma_f32 v58, -v62, v149, v58
	v_fma_f32 v62, v62, v148, v132
	v_mul_f32_e32 v133, v59, v153
	v_mul_f32_e32 v59, v59, v152
	v_fma_f32 v59, -v63, v153, v59
	v_fma_f32 v63, v63, v152, v133
	v_add_f32_e32 v88, v88, v170
	v_add_f32_e32 v92, v92, v171
	v_mul_f32_e32 v132, v92, v155
	v_mul_f32_e32 v171, v88, v155
	v_fma_f32 v170, v88, v154, -v132
	v_fma_f32 v171, v92, v154, v171
	v_add_f32_e32 v89, v89, v172
	v_add_f32_e32 v93, v93, v173
	v_mul_f32_e32 v133, v93, v159
	v_mul_f32_e32 v173, v89, v159
	v_fma_f32 v172, v89, v158, -v133
	v_fma_f32 v173, v93, v158, v173
	v_add_f32_e32 v90, v90, v174
	v_add_f32_e32 v94, v94, v175
	v_mul_f32_e32 v132, v94, v163
	v_mul_f32_e32 v175, v90, v163
	v_fma_f32 v174, v90, v162, -v132
	v_fma_f32 v175, v94, v162, v175
	v_add_f32_e32 v91, v91, v176
	v_add_f32_e32 v95, v95, v177
	v_mul_f32_e32 v133, v95, v167
	v_mul_f32_e32 v177, v91, v167
	v_fma_f32 v176, v91, v166, -v133
	v_fma_f32 v177, v95, v166, v177
	s_waitcnt vmcnt(12)
	v_cvt_pk_bf16_f32 v96, v32, v33
	v_cvt_pk_bf16_f32 v97, v34, v35
	v_cvt_pk_bf16_f32 v98, v36, v37
	v_cvt_pk_bf16_f32 v99, v38, v39
	s_nop 1
	v_mfma_f32_16x16x32_bf16 v[16:19], v[80:83], v[96:99], 0
	v_cvt_pk_bf16_f32 v96, v40, v41
	v_cvt_pk_bf16_f32 v97, v42, v43
	v_cvt_pk_bf16_f32 v98, v44, v45
	v_cvt_pk_bf16_f32 v99, v46, v47
	s_nop 1
	v_mfma_f32_16x16x32_bf16 v[20:23], v[80:83], v[96:99], 0
	v_cvt_pk_bf16_f32 v96, v48, v49
	v_cvt_pk_bf16_f32 v97, v50, v51
	v_cvt_pk_bf16_f32 v98, v52, v53
	v_cvt_pk_bf16_f32 v99, v54, v55
	s_nop 1
	v_mfma_f32_16x16x32_bf16 v[24:27], v[80:83], v[96:99], 0
	v_cvt_pk_bf16_f32 v96, v56, v57
	v_cvt_pk_bf16_f32 v97, v58, v59
	v_cvt_pk_bf16_f32 v98, v60, v61
	v_cvt_pk_bf16_f32 v99, v62, v63
	s_nop 1
	v_mfma_f32_16x16x32_bf16 v[28:31], v[80:83], v[96:99], 0
	s_waitcnt vmcnt(10)
	global_load_dwordx4 v[80:83], v134, s[38:39]
	s_add_u32 s38, s38, 0x400
	s_addc_u32 s39, s39, 0
	v_mfma_f32_16x16x32_bf16 v[32:35], v[64:67], v[0:3], 0
	v_mfma_f32_16x16x32_bf16 v[36:39], v[72:75], v[0:3], 0
	v_mfma_f32_16x16x32_bf16 v[40:43], v[64:67], v[4:7], 0
	v_mfma_f32_16x16x32_bf16 v[44:47], v[72:75], v[4:7], 0
	v_mfma_f32_16x16x32_bf16 v[48:51], v[64:67], v[8:11], 0
	v_mfma_f32_16x16x32_bf16 v[52:55], v[72:75], v[8:11], 0
	v_mfma_f32_16x16x32_bf16 v[56:59], v[64:67], v[12:15], 0
	v_mfma_f32_16x16x32_bf16 v[60:63], v[72:75], v[12:15], 0
	global_load_dwordx4 v[64:67], v134, s[20:21]
	global_load_dwordx4 v[72:75], v134, s[20:21] offset:1024
	s_add_u32 s20, s20, 0x800
	s_addc_u32 s21, s21, 0
	global_load_dwordx4 v[138:141], v134, s[42:43] offset:0
	global_load_dwordx4 v[142:145], v134, s[42:43] offset:1024
	global_load_dwordx4 v[146:149], v134, s[42:43] offset:2048
	global_load_dwordx4 v[150:153], v134, s[42:43] offset:3072
	global_load_dwordx4 v[154:157], v208, s[42:43] offset:0
	global_load_dwordx4 v[158:161], v208, s[42:43] offset:1024
	global_load_dwordx4 v[162:165], v208, s[42:43] offset:2048
	global_load_dwordx4 v[166:169], v208, s[42:43] offset:3072
	global_load_dwordx4 v[170:173], v206, s[44:45]
	global_load_dwordx4 v[174:177], v206, s[44:45] offset:16
	s_add_u32 s42, s42, 0x2000
	s_addc_u32 s43, s43, 0
	s_add_u32 s44, s44, 0x80
	s_addc_u32 s45, s45, 0
	s_waitcnt vmcnt(13)
	v_mul_f32_e32 v132, v179, v119
	v_mul_f32_e32 v133, v178, v119
	v_fma_f32 v178, v178, v118, -v132
	v_fma_f32 v179, v179, v118, v133
	v_mul_f32_e32 v132, v181, v123
	v_mul_f32_e32 v133, v180, v123
	v_fma_f32 v180, v180, v122, -v132
	v_fma_f32 v181, v181, v122, v133
	v_mul_f32_e32 v132, v183, v127
	v_mul_f32_e32 v133, v182, v127
	v_fma_f32 v182, v182, v126, -v132
	v_fma_f32 v183, v183, v126, v133
	v_mul_f32_e32 v132, v185, v131
	v_mul_f32_e32 v133, v184, v131
	v_fma_f32 v184, v184, v130, -v132
	v_fma_f32 v185, v185, v130, v133
	v_mul_f32_e32 v132, v32, v101
	v_mul_f32_e32 v32, v32, v100
	v_fma_f32 v32, -v36, v101, v32
	v_fma_f32 v36, v36, v100, v132
	v_mul_f32_e32 v133, v33, v105
	v_mul_f32_e32 v33, v33, v104
	v_fma_f32 v33, -v37, v105, v33
	v_fma_f32 v37, v37, v104, v133
	v_mul_f32_e32 v132, v34, v109
	v_mul_f32_e32 v34, v34, v108
	v_fma_f32 v34, -v38, v109, v34
	v_fma_f32 v38, v38, v108, v132
	v_mul_f32_e32 v133, v35, v113
	v_mul_f32_e32 v35, v35, v112
	v_fma_f32 v35, -v39, v113, v35
	v_fma_f32 v39, v39, v112, v133
	v_add_f32_dpp v32, v32, v32 row_shr:1 row_mask:0xf bank_mask:0xf bound_ctrl:1
	v_add_f32_dpp v33, v33, v33 row_shr:1 row_mask:0xf bank_mask:0xf bound_ctrl:1
	v_add_f32_dpp v34, v34, v34 row_shr:1 row_mask:0xf bank_mask:0xf bound_ctrl:1
	v_add_f32_dpp v35, v35, v35 row_shr:1 row_mask:0xf bank_mask:0xf bound_ctrl:1
	v_add_f32_dpp v36, v36, v36 row_shr:1 row_mask:0xf bank_mask:0xf bound_ctrl:1
	v_add_f32_dpp v37, v37, v37 row_shr:1 row_mask:0xf bank_mask:0xf bound_ctrl:1
	v_add_f32_dpp v38, v38, v38 row_shr:1 row_mask:0xf bank_mask:0xf bound_ctrl:1
	v_add_f32_dpp v39, v39, v39 row_shr:1 row_mask:0xf bank_mask:0xf bound_ctrl:1
	v_add_f32_dpp v32, v32, v32 row_shr:2 row_mask:0xf bank_mask:0xf bound_ctrl:1
	v_add_f32_dpp v33, v33, v33 row_shr:2 row_mask:0xf bank_mask:0xf bound_ctrl:1
	v_add_f32_dpp v34, v34, v34 row_shr:2 row_mask:0xf bank_mask:0xf bound_ctrl:1
	v_add_f32_dpp v35, v35, v35 row_shr:2 row_mask:0xf bank_mask:0xf bound_ctrl:1
	v_add_f32_dpp v36, v36, v36 row_shr:2 row_mask:0xf bank_mask:0xf bound_ctrl:1
	v_add_f32_dpp v37, v37, v37 row_shr:2 row_mask:0xf bank_mask:0xf bound_ctrl:1
	v_add_f32_dpp v38, v38, v38 row_shr:2 row_mask:0xf bank_mask:0xf bound_ctrl:1
	v_add_f32_dpp v39, v39, v39 row_shr:2 row_mask:0xf bank_mask:0xf bound_ctrl:1
	v_add_f32_dpp v32, v32, v32 row_shr:4 row_mask:0xf bank_mask:0xf bound_ctrl:1
	v_add_f32_dpp v33, v33, v33 row_shr:4 row_mask:0xf bank_mask:0xf bound_ctrl:1
	v_add_f32_dpp v34, v34, v34 row_shr:4 row_mask:0xf bank_mask:0xf bound_ctrl:1
	v_add_f32_dpp v35, v35, v35 row_shr:4 row_mask:0xf bank_mask:0xf bound_ctrl:1
	v_add_f32_dpp v36, v36, v36 row_shr:4 row_mask:0xf bank_mask:0xf bound_ctrl:1
	v_add_f32_dpp v37, v37, v37 row_shr:4 row_mask:0xf bank_mask:0xf bound_ctrl:1
	v_add_f32_dpp v38, v38, v38 row_shr:4 row_mask:0xf bank_mask:0xf bound_ctrl:1
	v_add_f32_dpp v39, v39, v39 row_shr:4 row_mask:0xf bank_mask:0xf bound_ctrl:1
	v_add_f32_dpp v32, v32, v32 row_shr:8 row_mask:0xf bank_mask:0xf bound_ctrl:1
	v_add_f32_dpp v33, v33, v33 row_shr:8 row_mask:0xf bank_mask:0xf bound_ctrl:1
	v_add_f32_dpp v34, v34, v34 row_shr:8 row_mask:0xf bank_mask:0xf bound_ctrl:1
	v_add_f32_dpp v35, v35, v35 row_shr:8 row_mask:0xf bank_mask:0xf bound_ctrl:1
	v_add_f32_dpp v36, v36, v36 row_shr:8 row_mask:0xf bank_mask:0xf bound_ctrl:1
	v_add_f32_dpp v37, v37, v37 row_shr:8 row_mask:0xf bank_mask:0xf bound_ctrl:1
	v_add_f32_dpp v38, v38, v38 row_shr:8 row_mask:0xf bank_mask:0xf bound_ctrl:1
	v_add_f32_dpp v39, v39, v39 row_shr:8 row_mask:0xf bank_mask:0xf bound_ctrl:1
	v_mov_b32_dpp v88, v32 row_newbcast:15 row_mask:0xf bank_mask:0xf
	v_mov_b32_dpp v89, v33 row_newbcast:15 row_mask:0xf bank_mask:0xf
	v_mov_b32_dpp v90, v34 row_newbcast:15 row_mask:0xf bank_mask:0xf
	v_mov_b32_dpp v91, v35 row_newbcast:15 row_mask:0xf bank_mask:0xf
	v_mov_b32_dpp v92, v36 row_newbcast:15 row_mask:0xf bank_mask:0xf
	v_mov_b32_dpp v93, v37 row_newbcast:15 row_mask:0xf bank_mask:0xf
	v_mov_b32_dpp v94, v38 row_newbcast:15 row_mask:0xf bank_mask:0xf
	v_mov_b32_dpp v95, v39 row_newbcast:15 row_mask:0xf bank_mask:0xf
	v_add_f32_e32 v32, v32, v178
	v_add_f32_e32 v36, v36, v179
	v_add_f32_e32 v33, v33, v180
	v_add_f32_e32 v37, v37, v181
	v_add_f32_e32 v34, v34, v182
	v_add_f32_e32 v38, v38, v183
	v_add_f32_e32 v35, v35, v184
	v_add_f32_e32 v39, v39, v185
	v_mul_f32_e32 v132, v32, v103
	v_mul_f32_e32 v32, v32, v102
	v_fma_f32 v32, -v36, v103, v32
	v_fma_f32 v36, v36, v102, v132
	v_mul_f32_e32 v133, v33, v107
	v_mul_f32_e32 v33, v33, v106
	v_fma_f32 v33, -v37, v107, v33
	v_fma_f32 v37, v37, v106, v133
	v_mul_f32_e32 v132, v34, v111
	v_mul_f32_e32 v34, v34, v110
	v_fma_f32 v34, -v38, v111, v34
	v_fma_f32 v38, v38, v110, v132
	v_mul_f32_e32 v133, v35, v115
	v_mul_f32_e32 v35, v35, v114
	v_fma_f32 v35, -v39, v115, v35
	v_fma_f32 v39, v39, v114, v133
	v_add_f32_e32 v88, v88, v178
	v_add_f32_e32 v92, v92, v179
	v_mul_f32_e32 v132, v92, v117
	v_mul_f32_e32 v179, v88, v117
	v_fma_f32 v178, v88, v116, -v132
	v_fma_f32 v179, v92, v116, v179
	v_add_f32_e32 v89, v89, v180
	v_add_f32_e32 v93, v93, v181
	v_mul_f32_e32 v133, v93, v121
	v_mul_f32_e32 v181, v89, v121
	v_fma_f32 v180, v89, v120, -v133
	v_fma_f32 v181, v93, v120, v181
	v_add_f32_e32 v90, v90, v182
	v_add_f32_e32 v94, v94, v183
	v_mul_f32_e32 v132, v94, v125
	v_mul_f32_e32 v183, v90, v125
	v_fma_f32 v182, v90, v124, -v132
	v_fma_f32 v183, v94, v124, v183
	v_add_f32_e32 v91, v91, v184
	v_add_f32_e32 v95, v95, v185
	v_mul_f32_e32 v133, v95, v129
	v_mul_f32_e32 v185, v91, v129
	v_fma_f32 v184, v91, v128, -v133
	v_fma_f32 v185, v95, v128, v185
	v_mul_f32_e32 v132, v40, v101
	v_mul_f32_e32 v40, v40, v100
	v_fma_f32 v40, -v44, v101, v40
	v_fma_f32 v44, v44, v100, v132
	v_mul_f32_e32 v133, v41, v105
	v_mul_f32_e32 v41, v41, v104
	v_fma_f32 v41, -v45, v105, v41
	v_fma_f32 v45, v45, v104, v133
	v_mul_f32_e32 v132, v42, v109
	v_mul_f32_e32 v42, v42, v108
	v_fma_f32 v42, -v46, v109, v42
	v_fma_f32 v46, v46, v108, v132
	v_mul_f32_e32 v133, v43, v113
	v_mul_f32_e32 v43, v43, v112
	v_fma_f32 v43, -v47, v113, v43
	v_fma_f32 v47, v47, v112, v133
	v_add_f32_dpp v40, v40, v40 row_shr:1 row_mask:0xf bank_mask:0xf bound_ctrl:1
	v_add_f32_dpp v41, v41, v41 row_shr:1 row_mask:0xf bank_mask:0xf bound_ctrl:1
	v_add_f32_dpp v42, v42, v42 row_shr:1 row_mask:0xf bank_mask:0xf bound_ctrl:1
	v_add_f32_dpp v43, v43, v43 row_shr:1 row_mask:0xf bank_mask:0xf bound_ctrl:1
	v_add_f32_dpp v44, v44, v44 row_shr:1 row_mask:0xf bank_mask:0xf bound_ctrl:1
	v_add_f32_dpp v45, v45, v45 row_shr:1 row_mask:0xf bank_mask:0xf bound_ctrl:1
	v_add_f32_dpp v46, v46, v46 row_shr:1 row_mask:0xf bank_mask:0xf bound_ctrl:1
	v_add_f32_dpp v47, v47, v47 row_shr:1 row_mask:0xf bank_mask:0xf bound_ctrl:1
	v_add_f32_dpp v40, v40, v40 row_shr:2 row_mask:0xf bank_mask:0xf bound_ctrl:1
	v_add_f32_dpp v41, v41, v41 row_shr:2 row_mask:0xf bank_mask:0xf bound_ctrl:1
	v_add_f32_dpp v42, v42, v42 row_shr:2 row_mask:0xf bank_mask:0xf bound_ctrl:1
	v_add_f32_dpp v43, v43, v43 row_shr:2 row_mask:0xf bank_mask:0xf bound_ctrl:1
	v_add_f32_dpp v44, v44, v44 row_shr:2 row_mask:0xf bank_mask:0xf bound_ctrl:1
	v_add_f32_dpp v45, v45, v45 row_shr:2 row_mask:0xf bank_mask:0xf bound_ctrl:1
	v_add_f32_dpp v46, v46, v46 row_shr:2 row_mask:0xf bank_mask:0xf bound_ctrl:1
	v_add_f32_dpp v47, v47, v47 row_shr:2 row_mask:0xf bank_mask:0xf bound_ctrl:1
	v_add_f32_dpp v40, v40, v40 row_shr:4 row_mask:0xf bank_mask:0xf bound_ctrl:1
	v_add_f32_dpp v41, v41, v41 row_shr:4 row_mask:0xf bank_mask:0xf bound_ctrl:1
	v_add_f32_dpp v42, v42, v42 row_shr:4 row_mask:0xf bank_mask:0xf bound_ctrl:1
	v_add_f32_dpp v43, v43, v43 row_shr:4 row_mask:0xf bank_mask:0xf bound_ctrl:1
	v_add_f32_dpp v44, v44, v44 row_shr:4 row_mask:0xf bank_mask:0xf bound_ctrl:1
	v_add_f32_dpp v45, v45, v45 row_shr:4 row_mask:0xf bank_mask:0xf bound_ctrl:1
	v_add_f32_dpp v46, v46, v46 row_shr:4 row_mask:0xf bank_mask:0xf bound_ctrl:1
	v_add_f32_dpp v47, v47, v47 row_shr:4 row_mask:0xf bank_mask:0xf bound_ctrl:1
	v_add_f32_dpp v40, v40, v40 row_shr:8 row_mask:0xf bank_mask:0xf bound_ctrl:1
	v_add_f32_dpp v41, v41, v41 row_shr:8 row_mask:0xf bank_mask:0xf bound_ctrl:1
	v_add_f32_dpp v42, v42, v42 row_shr:8 row_mask:0xf bank_mask:0xf bound_ctrl:1
	v_add_f32_dpp v43, v43, v43 row_shr:8 row_mask:0xf bank_mask:0xf bound_ctrl:1
	v_add_f32_dpp v44, v44, v44 row_shr:8 row_mask:0xf bank_mask:0xf bound_ctrl:1
	v_add_f32_dpp v45, v45, v45 row_shr:8 row_mask:0xf bank_mask:0xf bound_ctrl:1
	v_add_f32_dpp v46, v46, v46 row_shr:8 row_mask:0xf bank_mask:0xf bound_ctrl:1
	v_add_f32_dpp v47, v47, v47 row_shr:8 row_mask:0xf bank_mask:0xf bound_ctrl:1
	v_mov_b32_dpp v88, v40 row_newbcast:15 row_mask:0xf bank_mask:0xf
	v_mov_b32_dpp v89, v41 row_newbcast:15 row_mask:0xf bank_mask:0xf
	v_mov_b32_dpp v90, v42 row_newbcast:15 row_mask:0xf bank_mask:0xf
	v_mov_b32_dpp v91, v43 row_newbcast:15 row_mask:0xf bank_mask:0xf
	v_mov_b32_dpp v92, v44 row_newbcast:15 row_mask:0xf bank_mask:0xf
	v_mov_b32_dpp v93, v45 row_newbcast:15 row_mask:0xf bank_mask:0xf
	v_mov_b32_dpp v94, v46 row_newbcast:15 row_mask:0xf bank_mask:0xf
	v_mov_b32_dpp v95, v47 row_newbcast:15 row_mask:0xf bank_mask:0xf
	v_add_f32_e32 v40, v40, v178
	v_add_f32_e32 v44, v44, v179
	v_add_f32_e32 v41, v41, v180
	v_add_f32_e32 v45, v45, v181
	v_add_f32_e32 v42, v42, v182
	v_add_f32_e32 v46, v46, v183
	v_add_f32_e32 v43, v43, v184
	v_add_f32_e32 v47, v47, v185
	v_mul_f32_e32 v132, v40, v103
	v_mul_f32_e32 v40, v40, v102
	v_fma_f32 v40, -v44, v103, v40
	v_fma_f32 v44, v44, v102, v132
	v_mul_f32_e32 v133, v41, v107
	v_mul_f32_e32 v41, v41, v106
	v_fma_f32 v41, -v45, v107, v41
	v_fma_f32 v45, v45, v106, v133
	v_mul_f32_e32 v132, v42, v111
	v_mul_f32_e32 v42, v42, v110
	v_fma_f32 v42, -v46, v111, v42
	v_fma_f32 v46, v46, v110, v132
	v_mul_f32_e32 v133, v43, v115
	v_mul_f32_e32 v43, v43, v114
	v_fma_f32 v43, -v47, v115, v43
	v_fma_f32 v47, v47, v114, v133
	v_add_f32_e32 v88, v88, v178
	v_add_f32_e32 v92, v92, v179
	v_mul_f32_e32 v132, v92, v117
	v_mul_f32_e32 v179, v88, v117
	v_fma_f32 v178, v88, v116, -v132
	v_fma_f32 v179, v92, v116, v179
	v_add_f32_e32 v89, v89, v180
	v_add_f32_e32 v93, v93, v181
	v_mul_f32_e32 v133, v93, v121
	v_mul_f32_e32 v181, v89, v121
	v_fma_f32 v180, v89, v120, -v133
	v_fma_f32 v181, v93, v120, v181
	v_add_f32_e32 v90, v90, v182
	v_add_f32_e32 v94, v94, v183
	v_mul_f32_e32 v132, v94, v125
	v_mul_f32_e32 v183, v90, v125
	v_fma_f32 v182, v90, v124, -v132
	v_fma_f32 v183, v94, v124, v183
	v_add_f32_e32 v91, v91, v184
	v_add_f32_e32 v95, v95, v185
	v_mul_f32_e32 v133, v95, v129
	v_mul_f32_e32 v185, v91, v129
	v_fma_f32 v184, v91, v128, -v133
	v_fma_f32 v185, v95, v128, v185
	v_mul_f32_e32 v132, v48, v101
	v_mul_f32_e32 v48, v48, v100
	v_fma_f32 v48, -v52, v101, v48
	v_fma_f32 v52, v52, v100, v132
	v_mul_f32_e32 v133, v49, v105
	v_mul_f32_e32 v49, v49, v104
	v_fma_f32 v49, -v53, v105, v49
	v_fma_f32 v53, v53, v104, v133
	v_mul_f32_e32 v132, v50, v109
	v_mul_f32_e32 v50, v50, v108
	v_fma_f32 v50, -v54, v109, v50
	v_fma_f32 v54, v54, v108, v132
	v_mul_f32_e32 v133, v51, v113
	v_mul_f32_e32 v51, v51, v112
	v_fma_f32 v51, -v55, v113, v51
	v_fma_f32 v55, v55, v112, v133
	v_add_f32_dpp v48, v48, v48 row_shr:1 row_mask:0xf bank_mask:0xf bound_ctrl:1
	v_add_f32_dpp v49, v49, v49 row_shr:1 row_mask:0xf bank_mask:0xf bound_ctrl:1
	v_add_f32_dpp v50, v50, v50 row_shr:1 row_mask:0xf bank_mask:0xf bound_ctrl:1
	v_add_f32_dpp v51, v51, v51 row_shr:1 row_mask:0xf bank_mask:0xf bound_ctrl:1
	v_add_f32_dpp v52, v52, v52 row_shr:1 row_mask:0xf bank_mask:0xf bound_ctrl:1
	v_add_f32_dpp v53, v53, v53 row_shr:1 row_mask:0xf bank_mask:0xf bound_ctrl:1
	v_add_f32_dpp v54, v54, v54 row_shr:1 row_mask:0xf bank_mask:0xf bound_ctrl:1
	v_add_f32_dpp v55, v55, v55 row_shr:1 row_mask:0xf bank_mask:0xf bound_ctrl:1
	v_add_f32_dpp v48, v48, v48 row_shr:2 row_mask:0xf bank_mask:0xf bound_ctrl:1
	v_add_f32_dpp v49, v49, v49 row_shr:2 row_mask:0xf bank_mask:0xf bound_ctrl:1
	v_add_f32_dpp v50, v50, v50 row_shr:2 row_mask:0xf bank_mask:0xf bound_ctrl:1
	v_add_f32_dpp v51, v51, v51 row_shr:2 row_mask:0xf bank_mask:0xf bound_ctrl:1
	v_add_f32_dpp v52, v52, v52 row_shr:2 row_mask:0xf bank_mask:0xf bound_ctrl:1
	v_add_f32_dpp v53, v53, v53 row_shr:2 row_mask:0xf bank_mask:0xf bound_ctrl:1
	v_add_f32_dpp v54, v54, v54 row_shr:2 row_mask:0xf bank_mask:0xf bound_ctrl:1
	v_add_f32_dpp v55, v55, v55 row_shr:2 row_mask:0xf bank_mask:0xf bound_ctrl:1
	v_add_f32_dpp v48, v48, v48 row_shr:4 row_mask:0xf bank_mask:0xf bound_ctrl:1
	v_add_f32_dpp v49, v49, v49 row_shr:4 row_mask:0xf bank_mask:0xf bound_ctrl:1
	v_add_f32_dpp v50, v50, v50 row_shr:4 row_mask:0xf bank_mask:0xf bound_ctrl:1
	v_add_f32_dpp v51, v51, v51 row_shr:4 row_mask:0xf bank_mask:0xf bound_ctrl:1
	v_add_f32_dpp v52, v52, v52 row_shr:4 row_mask:0xf bank_mask:0xf bound_ctrl:1
	v_add_f32_dpp v53, v53, v53 row_shr:4 row_mask:0xf bank_mask:0xf bound_ctrl:1
	v_add_f32_dpp v54, v54, v54 row_shr:4 row_mask:0xf bank_mask:0xf bound_ctrl:1
	v_add_f32_dpp v55, v55, v55 row_shr:4 row_mask:0xf bank_mask:0xf bound_ctrl:1
	v_add_f32_dpp v48, v48, v48 row_shr:8 row_mask:0xf bank_mask:0xf bound_ctrl:1
	v_add_f32_dpp v49, v49, v49 row_shr:8 row_mask:0xf bank_mask:0xf bound_ctrl:1
	v_add_f32_dpp v50, v50, v50 row_shr:8 row_mask:0xf bank_mask:0xf bound_ctrl:1
	v_add_f32_dpp v51, v51, v51 row_shr:8 row_mask:0xf bank_mask:0xf bound_ctrl:1
	v_add_f32_dpp v52, v52, v52 row_shr:8 row_mask:0xf bank_mask:0xf bound_ctrl:1
	v_add_f32_dpp v53, v53, v53 row_shr:8 row_mask:0xf bank_mask:0xf bound_ctrl:1
	v_add_f32_dpp v54, v54, v54 row_shr:8 row_mask:0xf bank_mask:0xf bound_ctrl:1
	v_add_f32_dpp v55, v55, v55 row_shr:8 row_mask:0xf bank_mask:0xf bound_ctrl:1
	v_mov_b32_dpp v88, v48 row_newbcast:15 row_mask:0xf bank_mask:0xf
	v_mov_b32_dpp v89, v49 row_newbcast:15 row_mask:0xf bank_mask:0xf
	v_mov_b32_dpp v90, v50 row_newbcast:15 row_mask:0xf bank_mask:0xf
	v_mov_b32_dpp v91, v51 row_newbcast:15 row_mask:0xf bank_mask:0xf
	v_mov_b32_dpp v92, v52 row_newbcast:15 row_mask:0xf bank_mask:0xf
	v_mov_b32_dpp v93, v53 row_newbcast:15 row_mask:0xf bank_mask:0xf
	v_mov_b32_dpp v94, v54 row_newbcast:15 row_mask:0xf bank_mask:0xf
	v_mov_b32_dpp v95, v55 row_newbcast:15 row_mask:0xf bank_mask:0xf
	v_add_f32_e32 v48, v48, v178
	v_add_f32_e32 v52, v52, v179
	v_add_f32_e32 v49, v49, v180
	v_add_f32_e32 v53, v53, v181
	v_add_f32_e32 v50, v50, v182
	v_add_f32_e32 v54, v54, v183
	v_add_f32_e32 v51, v51, v184
	v_add_f32_e32 v55, v55, v185
	v_mul_f32_e32 v132, v48, v103
	v_mul_f32_e32 v48, v48, v102
	v_fma_f32 v48, -v52, v103, v48
	v_fma_f32 v52, v52, v102, v132
	v_mul_f32_e32 v133, v49, v107
	v_mul_f32_e32 v49, v49, v106
	v_fma_f32 v49, -v53, v107, v49
	v_fma_f32 v53, v53, v106, v133
	v_mul_f32_e32 v132, v50, v111
	v_mul_f32_e32 v50, v50, v110
	v_fma_f32 v50, -v54, v111, v50
	v_fma_f32 v54, v54, v110, v132
	v_mul_f32_e32 v133, v51, v115
	v_mul_f32_e32 v51, v51, v114
	v_fma_f32 v51, -v55, v115, v51
	v_fma_f32 v55, v55, v114, v133
	v_add_f32_e32 v88, v88, v178
	v_add_f32_e32 v92, v92, v179
	v_mul_f32_e32 v132, v92, v117
	v_mul_f32_e32 v179, v88, v117
	v_fma_f32 v178, v88, v116, -v132
	v_fma_f32 v179, v92, v116, v179
	v_add_f32_e32 v89, v89, v180
	v_add_f32_e32 v93, v93, v181
	v_mul_f32_e32 v133, v93, v121
	v_mul_f32_e32 v181, v89, v121
	v_fma_f32 v180, v89, v120, -v133
	v_fma_f32 v181, v93, v120, v181
	v_add_f32_e32 v90, v90, v182
	v_add_f32_e32 v94, v94, v183
	v_mul_f32_e32 v132, v94, v125
	v_mul_f32_e32 v183, v90, v125
	v_fma_f32 v182, v90, v124, -v132
	v_fma_f32 v183, v94, v124, v183
	v_add_f32_e32 v91, v91, v184
	v_add_f32_e32 v95, v95, v185
	v_mul_f32_e32 v133, v95, v129
	v_mul_f32_e32 v185, v91, v129
	v_fma_f32 v184, v91, v128, -v133
	v_fma_f32 v185, v95, v128, v185
	v_mul_f32_e32 v132, v56, v101
	v_mul_f32_e32 v56, v56, v100
	v_fma_f32 v56, -v60, v101, v56
	v_fma_f32 v60, v60, v100, v132
	v_mul_f32_e32 v133, v57, v105
	v_mul_f32_e32 v57, v57, v104
	v_fma_f32 v57, -v61, v105, v57
	v_fma_f32 v61, v61, v104, v133
	v_mul_f32_e32 v132, v58, v109
	v_mul_f32_e32 v58, v58, v108
	v_fma_f32 v58, -v62, v109, v58
	v_fma_f32 v62, v62, v108, v132
	v_mul_f32_e32 v133, v59, v113
	v_mul_f32_e32 v59, v59, v112
	v_fma_f32 v59, -v63, v113, v59
	v_fma_f32 v63, v63, v112, v133
	v_add_f32_dpp v56, v56, v56 row_shr:1 row_mask:0xf bank_mask:0xf bound_ctrl:1
	v_add_f32_dpp v57, v57, v57 row_shr:1 row_mask:0xf bank_mask:0xf bound_ctrl:1
	v_add_f32_dpp v58, v58, v58 row_shr:1 row_mask:0xf bank_mask:0xf bound_ctrl:1
	v_add_f32_dpp v59, v59, v59 row_shr:1 row_mask:0xf bank_mask:0xf bound_ctrl:1
	v_add_f32_dpp v60, v60, v60 row_shr:1 row_mask:0xf bank_mask:0xf bound_ctrl:1
	v_add_f32_dpp v61, v61, v61 row_shr:1 row_mask:0xf bank_mask:0xf bound_ctrl:1
	v_add_f32_dpp v62, v62, v62 row_shr:1 row_mask:0xf bank_mask:0xf bound_ctrl:1
	v_add_f32_dpp v63, v63, v63 row_shr:1 row_mask:0xf bank_mask:0xf bound_ctrl:1
	v_add_f32_dpp v56, v56, v56 row_shr:2 row_mask:0xf bank_mask:0xf bound_ctrl:1
	v_add_f32_dpp v57, v57, v57 row_shr:2 row_mask:0xf bank_mask:0xf bound_ctrl:1
	v_add_f32_dpp v58, v58, v58 row_shr:2 row_mask:0xf bank_mask:0xf bound_ctrl:1
	v_add_f32_dpp v59, v59, v59 row_shr:2 row_mask:0xf bank_mask:0xf bound_ctrl:1
	v_add_f32_dpp v60, v60, v60 row_shr:2 row_mask:0xf bank_mask:0xf bound_ctrl:1
	v_add_f32_dpp v61, v61, v61 row_shr:2 row_mask:0xf bank_mask:0xf bound_ctrl:1
	v_add_f32_dpp v62, v62, v62 row_shr:2 row_mask:0xf bank_mask:0xf bound_ctrl:1
	v_add_f32_dpp v63, v63, v63 row_shr:2 row_mask:0xf bank_mask:0xf bound_ctrl:1
	v_add_f32_dpp v56, v56, v56 row_shr:4 row_mask:0xf bank_mask:0xf bound_ctrl:1
	v_add_f32_dpp v57, v57, v57 row_shr:4 row_mask:0xf bank_mask:0xf bound_ctrl:1
	v_add_f32_dpp v58, v58, v58 row_shr:4 row_mask:0xf bank_mask:0xf bound_ctrl:1
	v_add_f32_dpp v59, v59, v59 row_shr:4 row_mask:0xf bank_mask:0xf bound_ctrl:1
	v_add_f32_dpp v60, v60, v60 row_shr:4 row_mask:0xf bank_mask:0xf bound_ctrl:1
	v_add_f32_dpp v61, v61, v61 row_shr:4 row_mask:0xf bank_mask:0xf bound_ctrl:1
	v_add_f32_dpp v62, v62, v62 row_shr:4 row_mask:0xf bank_mask:0xf bound_ctrl:1
	v_add_f32_dpp v63, v63, v63 row_shr:4 row_mask:0xf bank_mask:0xf bound_ctrl:1
	v_add_f32_dpp v56, v56, v56 row_shr:8 row_mask:0xf bank_mask:0xf bound_ctrl:1
	v_add_f32_dpp v57, v57, v57 row_shr:8 row_mask:0xf bank_mask:0xf bound_ctrl:1
	v_add_f32_dpp v58, v58, v58 row_shr:8 row_mask:0xf bank_mask:0xf bound_ctrl:1
	v_add_f32_dpp v59, v59, v59 row_shr:8 row_mask:0xf bank_mask:0xf bound_ctrl:1
	v_add_f32_dpp v60, v60, v60 row_shr:8 row_mask:0xf bank_mask:0xf bound_ctrl:1
	v_add_f32_dpp v61, v61, v61 row_shr:8 row_mask:0xf bank_mask:0xf bound_ctrl:1
	v_add_f32_dpp v62, v62, v62 row_shr:8 row_mask:0xf bank_mask:0xf bound_ctrl:1
	v_add_f32_dpp v63, v63, v63 row_shr:8 row_mask:0xf bank_mask:0xf bound_ctrl:1
	v_mov_b32_dpp v88, v56 row_newbcast:15 row_mask:0xf bank_mask:0xf
	v_mov_b32_dpp v89, v57 row_newbcast:15 row_mask:0xf bank_mask:0xf
	v_mov_b32_dpp v90, v58 row_newbcast:15 row_mask:0xf bank_mask:0xf
	v_mov_b32_dpp v91, v59 row_newbcast:15 row_mask:0xf bank_mask:0xf
	v_mov_b32_dpp v92, v60 row_newbcast:15 row_mask:0xf bank_mask:0xf
	v_mov_b32_dpp v93, v61 row_newbcast:15 row_mask:0xf bank_mask:0xf
	v_mov_b32_dpp v94, v62 row_newbcast:15 row_mask:0xf bank_mask:0xf
	v_mov_b32_dpp v95, v63 row_newbcast:15 row_mask:0xf bank_mask:0xf
	v_add_f32_e32 v56, v56, v178
	v_add_f32_e32 v60, v60, v179
	v_add_f32_e32 v57, v57, v180
	v_add_f32_e32 v61, v61, v181
	v_add_f32_e32 v58, v58, v182
	v_add_f32_e32 v62, v62, v183
	v_add_f32_e32 v59, v59, v184
	v_add_f32_e32 v63, v63, v185
	v_mul_f32_e32 v132, v56, v103
	v_mul_f32_e32 v56, v56, v102
	v_fma_f32 v56, -v60, v103, v56
	v_fma_f32 v60, v60, v102, v132
	v_mul_f32_e32 v133, v57, v107
	v_mul_f32_e32 v57, v57, v106
	v_fma_f32 v57, -v61, v107, v57
	v_fma_f32 v61, v61, v106, v133
	v_mul_f32_e32 v132, v58, v111
	v_mul_f32_e32 v58, v58, v110
	v_fma_f32 v58, -v62, v111, v58
	v_fma_f32 v62, v62, v110, v132
	v_mul_f32_e32 v133, v59, v115
	v_mul_f32_e32 v59, v59, v114
	v_fma_f32 v59, -v63, v115, v59
	v_fma_f32 v63, v63, v114, v133
	v_add_f32_e32 v88, v88, v178
	v_add_f32_e32 v92, v92, v179
	v_mul_f32_e32 v132, v92, v117
	v_mul_f32_e32 v179, v88, v117
	v_fma_f32 v178, v88, v116, -v132
	v_fma_f32 v179, v92, v116, v179
	v_add_f32_e32 v89, v89, v180
	v_add_f32_e32 v93, v93, v181
	v_mul_f32_e32 v133, v93, v121
	v_mul_f32_e32 v181, v89, v121
	v_fma_f32 v180, v89, v120, -v133
	v_fma_f32 v181, v93, v120, v181
	v_add_f32_e32 v90, v90, v182
	v_add_f32_e32 v94, v94, v183
	v_mul_f32_e32 v132, v94, v125
	v_mul_f32_e32 v183, v90, v125
	v_fma_f32 v182, v90, v124, -v132
	v_fma_f32 v183, v94, v124, v183
	v_add_f32_e32 v91, v91, v184
	v_add_f32_e32 v95, v95, v185
	v_mul_f32_e32 v133, v95, v129
	v_mul_f32_e32 v185, v91, v129
	v_fma_f32 v184, v91, v128, -v133
	v_fma_f32 v185, v95, v128, v185
	s_waitcnt vmcnt(12)
	v_cvt_pk_bf16_f32 v96, v32, v33
	v_cvt_pk_bf16_f32 v97, v34, v35
	v_cvt_pk_bf16_f32 v98, v36, v37
	v_cvt_pk_bf16_f32 v99, v38, v39
	s_nop 1
	v_mfma_f32_16x16x32_bf16 v[16:19], v[80:83], v[96:99], v[16:19]
	v_cvt_pk_bf16_f32 v96, v40, v41
	v_cvt_pk_bf16_f32 v97, v42, v43
	v_cvt_pk_bf16_f32 v98, v44, v45
	v_cvt_pk_bf16_f32 v99, v46, v47
	s_nop 1
	v_mfma_f32_16x16x32_bf16 v[20:23], v[80:83], v[96:99], v[20:23]
	v_cvt_pk_bf16_f32 v96, v48, v49
	v_cvt_pk_bf16_f32 v97, v50, v51
	v_cvt_pk_bf16_f32 v98, v52, v53
	v_cvt_pk_bf16_f32 v99, v54, v55
	s_nop 1
	v_mfma_f32_16x16x32_bf16 v[24:27], v[80:83], v[96:99], v[24:27]
	v_cvt_pk_bf16_f32 v96, v56, v57
	v_cvt_pk_bf16_f32 v97, v58, v59
	v_cvt_pk_bf16_f32 v98, v60, v61
	v_cvt_pk_bf16_f32 v99, v62, v63
	s_nop 1
	v_mfma_f32_16x16x32_bf16 v[28:31], v[80:83], v[96:99], v[28:31]
	s_waitcnt vmcnt(10)
	global_load_dwordx4 v[80:83], v134, s[38:39]
	s_add_u32 s38, s38, 0x400
	s_addc_u32 s39, s39, 0
	v_mfma_f32_16x16x32_bf16 v[32:35], v[64:67], v[0:3], 0
	v_mfma_f32_16x16x32_bf16 v[36:39], v[72:75], v[0:3], 0
	v_mfma_f32_16x16x32_bf16 v[40:43], v[64:67], v[4:7], 0
	v_mfma_f32_16x16x32_bf16 v[44:47], v[72:75], v[4:7], 0
	v_mfma_f32_16x16x32_bf16 v[48:51], v[64:67], v[8:11], 0
	v_mfma_f32_16x16x32_bf16 v[52:55], v[72:75], v[8:11], 0
	v_mfma_f32_16x16x32_bf16 v[56:59], v[64:67], v[12:15], 0
	v_mfma_f32_16x16x32_bf16 v[60:63], v[72:75], v[12:15], 0
	global_load_dwordx4 v[64:67], v134, s[20:21]
	global_load_dwordx4 v[72:75], v134, s[20:21] offset:1024
	global_load_dwordx4 v[100:103], v134, s[42:43] offset:0
	global_load_dwordx4 v[104:107], v134, s[42:43] offset:1024
	global_load_dwordx4 v[108:111], v134, s[42:43] offset:2048
	global_load_dwordx4 v[112:115], v134, s[42:43] offset:3072
	global_load_dwordx4 v[116:119], v208, s[42:43] offset:0
	global_load_dwordx4 v[120:123], v208, s[42:43] offset:1024
	global_load_dwordx4 v[124:127], v208, s[42:43] offset:2048
	global_load_dwordx4 v[128:131], v208, s[42:43] offset:3072
	global_load_dwordx4 v[178:181], v206, s[44:45]
	global_load_dwordx4 v[182:185], v206, s[44:45] offset:16
	s_waitcnt vmcnt(13)
	v_mul_f32_e32 v132, v171, v157
	v_mul_f32_e32 v133, v170, v157
	v_fma_f32 v170, v170, v156, -v132
	v_fma_f32 v171, v171, v156, v133
	v_mul_f32_e32 v132, v173, v161
	v_mul_f32_e32 v133, v172, v161
	v_fma_f32 v172, v172, v160, -v132
	v_fma_f32 v173, v173, v160, v133
	v_mul_f32_e32 v132, v175, v165
	v_mul_f32_e32 v133, v174, v165
	v_fma_f32 v174, v174, v164, -v132
	v_fma_f32 v175, v175, v164, v133
	v_mul_f32_e32 v132, v177, v169
	v_mul_f32_e32 v133, v176, v169
	v_fma_f32 v176, v176, v168, -v132
	v_fma_f32 v177, v177, v168, v133
	v_mul_f32_e32 v132, v32, v139
	v_mul_f32_e32 v32, v32, v138
	v_fma_f32 v32, -v36, v139, v32
	v_fma_f32 v36, v36, v138, v132
	v_mul_f32_e32 v133, v33, v143
	v_mul_f32_e32 v33, v33, v142
	v_fma_f32 v33, -v37, v143, v33
	v_fma_f32 v37, v37, v142, v133
	v_mul_f32_e32 v132, v34, v147
	v_mul_f32_e32 v34, v34, v146
	v_fma_f32 v34, -v38, v147, v34
	v_fma_f32 v38, v38, v146, v132
	v_mul_f32_e32 v133, v35, v151
	v_mul_f32_e32 v35, v35, v150
	v_fma_f32 v35, -v39, v151, v35
	v_fma_f32 v39, v39, v150, v133
	v_add_f32_dpp v32, v32, v32 row_shr:1 row_mask:0xf bank_mask:0xf bound_ctrl:1
	v_add_f32_dpp v33, v33, v33 row_shr:1 row_mask:0xf bank_mask:0xf bound_ctrl:1
	v_add_f32_dpp v34, v34, v34 row_shr:1 row_mask:0xf bank_mask:0xf bound_ctrl:1
	v_add_f32_dpp v35, v35, v35 row_shr:1 row_mask:0xf bank_mask:0xf bound_ctrl:1
	v_add_f32_dpp v36, v36, v36 row_shr:1 row_mask:0xf bank_mask:0xf bound_ctrl:1
	v_add_f32_dpp v37, v37, v37 row_shr:1 row_mask:0xf bank_mask:0xf bound_ctrl:1
	v_add_f32_dpp v38, v38, v38 row_shr:1 row_mask:0xf bank_mask:0xf bound_ctrl:1
	v_add_f32_dpp v39, v39, v39 row_shr:1 row_mask:0xf bank_mask:0xf bound_ctrl:1
	v_add_f32_dpp v32, v32, v32 row_shr:2 row_mask:0xf bank_mask:0xf bound_ctrl:1
	v_add_f32_dpp v33, v33, v33 row_shr:2 row_mask:0xf bank_mask:0xf bound_ctrl:1
	v_add_f32_dpp v34, v34, v34 row_shr:2 row_mask:0xf bank_mask:0xf bound_ctrl:1
	v_add_f32_dpp v35, v35, v35 row_shr:2 row_mask:0xf bank_mask:0xf bound_ctrl:1
	v_add_f32_dpp v36, v36, v36 row_shr:2 row_mask:0xf bank_mask:0xf bound_ctrl:1
	v_add_f32_dpp v37, v37, v37 row_shr:2 row_mask:0xf bank_mask:0xf bound_ctrl:1
	v_add_f32_dpp v38, v38, v38 row_shr:2 row_mask:0xf bank_mask:0xf bound_ctrl:1
	v_add_f32_dpp v39, v39, v39 row_shr:2 row_mask:0xf bank_mask:0xf bound_ctrl:1
	v_add_f32_dpp v32, v32, v32 row_shr:4 row_mask:0xf bank_mask:0xf bound_ctrl:1
	v_add_f32_dpp v33, v33, v33 row_shr:4 row_mask:0xf bank_mask:0xf bound_ctrl:1
	v_add_f32_dpp v34, v34, v34 row_shr:4 row_mask:0xf bank_mask:0xf bound_ctrl:1
	v_add_f32_dpp v35, v35, v35 row_shr:4 row_mask:0xf bank_mask:0xf bound_ctrl:1
	v_add_f32_dpp v36, v36, v36 row_shr:4 row_mask:0xf bank_mask:0xf bound_ctrl:1
	v_add_f32_dpp v37, v37, v37 row_shr:4 row_mask:0xf bank_mask:0xf bound_ctrl:1
	v_add_f32_dpp v38, v38, v38 row_shr:4 row_mask:0xf bank_mask:0xf bound_ctrl:1
	v_add_f32_dpp v39, v39, v39 row_shr:4 row_mask:0xf bank_mask:0xf bound_ctrl:1
	v_add_f32_dpp v32, v32, v32 row_shr:8 row_mask:0xf bank_mask:0xf bound_ctrl:1
	v_add_f32_dpp v33, v33, v33 row_shr:8 row_mask:0xf bank_mask:0xf bound_ctrl:1
	v_add_f32_dpp v34, v34, v34 row_shr:8 row_mask:0xf bank_mask:0xf bound_ctrl:1
	v_add_f32_dpp v35, v35, v35 row_shr:8 row_mask:0xf bank_mask:0xf bound_ctrl:1
	v_add_f32_dpp v36, v36, v36 row_shr:8 row_mask:0xf bank_mask:0xf bound_ctrl:1
	v_add_f32_dpp v37, v37, v37 row_shr:8 row_mask:0xf bank_mask:0xf bound_ctrl:1
	v_add_f32_dpp v38, v38, v38 row_shr:8 row_mask:0xf bank_mask:0xf bound_ctrl:1
	v_add_f32_dpp v39, v39, v39 row_shr:8 row_mask:0xf bank_mask:0xf bound_ctrl:1
	v_mov_b32_dpp v88, v32 row_newbcast:15 row_mask:0xf bank_mask:0xf
	v_mov_b32_dpp v89, v33 row_newbcast:15 row_mask:0xf bank_mask:0xf
	v_mov_b32_dpp v90, v34 row_newbcast:15 row_mask:0xf bank_mask:0xf
	v_mov_b32_dpp v91, v35 row_newbcast:15 row_mask:0xf bank_mask:0xf
	v_mov_b32_dpp v92, v36 row_newbcast:15 row_mask:0xf bank_mask:0xf
	v_mov_b32_dpp v93, v37 row_newbcast:15 row_mask:0xf bank_mask:0xf
	v_mov_b32_dpp v94, v38 row_newbcast:15 row_mask:0xf bank_mask:0xf
	v_mov_b32_dpp v95, v39 row_newbcast:15 row_mask:0xf bank_mask:0xf
	v_add_f32_e32 v32, v32, v170
	v_add_f32_e32 v36, v36, v171
	v_add_f32_e32 v33, v33, v172
	v_add_f32_e32 v37, v37, v173
	v_add_f32_e32 v34, v34, v174
	v_add_f32_e32 v38, v38, v175
	v_add_f32_e32 v35, v35, v176
	v_add_f32_e32 v39, v39, v177
	v_mul_f32_e32 v132, v32, v141
	v_mul_f32_e32 v32, v32, v140
	v_fma_f32 v32, -v36, v141, v32
	v_fma_f32 v36, v36, v140, v132
	v_mul_f32_e32 v133, v33, v145
	v_mul_f32_e32 v33, v33, v144
	v_fma_f32 v33, -v37, v145, v33
	v_fma_f32 v37, v37, v144, v133
	v_mul_f32_e32 v132, v34, v149
	v_mul_f32_e32 v34, v34, v148
	v_fma_f32 v34, -v38, v149, v34
	v_fma_f32 v38, v38, v148, v132
	v_mul_f32_e32 v133, v35, v153
	v_mul_f32_e32 v35, v35, v152
	v_fma_f32 v35, -v39, v153, v35
	v_fma_f32 v39, v39, v152, v133
	v_add_f32_e32 v88, v88, v170
	v_add_f32_e32 v92, v92, v171
	v_mul_f32_e32 v132, v92, v155
	v_mul_f32_e32 v171, v88, v155
	v_fma_f32 v170, v88, v154, -v132
	v_fma_f32 v171, v92, v154, v171
	v_add_f32_e32 v89, v89, v172
	v_add_f32_e32 v93, v93, v173
	v_mul_f32_e32 v133, v93, v159
	v_mul_f32_e32 v173, v89, v159
	v_fma_f32 v172, v89, v158, -v133
	v_fma_f32 v173, v93, v158, v173
	v_add_f32_e32 v90, v90, v174
	v_add_f32_e32 v94, v94, v175
	v_mul_f32_e32 v132, v94, v163
	v_mul_f32_e32 v175, v90, v163
	v_fma_f32 v174, v90, v162, -v132
	v_fma_f32 v175, v94, v162, v175
	v_add_f32_e32 v91, v91, v176
	v_add_f32_e32 v95, v95, v177
	v_mul_f32_e32 v133, v95, v167
	v_mul_f32_e32 v177, v91, v167
	v_fma_f32 v176, v91, v166, -v133
	v_fma_f32 v177, v95, v166, v177
	v_mul_f32_e32 v132, v40, v139
	v_mul_f32_e32 v40, v40, v138
	v_fma_f32 v40, -v44, v139, v40
	v_fma_f32 v44, v44, v138, v132
	v_mul_f32_e32 v133, v41, v143
	v_mul_f32_e32 v41, v41, v142
	v_fma_f32 v41, -v45, v143, v41
	v_fma_f32 v45, v45, v142, v133
	v_mul_f32_e32 v132, v42, v147
	v_mul_f32_e32 v42, v42, v146
	v_fma_f32 v42, -v46, v147, v42
	v_fma_f32 v46, v46, v146, v132
	v_mul_f32_e32 v133, v43, v151
	v_mul_f32_e32 v43, v43, v150
	v_fma_f32 v43, -v47, v151, v43
	v_fma_f32 v47, v47, v150, v133
	v_add_f32_dpp v40, v40, v40 row_shr:1 row_mask:0xf bank_mask:0xf bound_ctrl:1
	v_add_f32_dpp v41, v41, v41 row_shr:1 row_mask:0xf bank_mask:0xf bound_ctrl:1
	v_add_f32_dpp v42, v42, v42 row_shr:1 row_mask:0xf bank_mask:0xf bound_ctrl:1
	v_add_f32_dpp v43, v43, v43 row_shr:1 row_mask:0xf bank_mask:0xf bound_ctrl:1
	v_add_f32_dpp v44, v44, v44 row_shr:1 row_mask:0xf bank_mask:0xf bound_ctrl:1
	v_add_f32_dpp v45, v45, v45 row_shr:1 row_mask:0xf bank_mask:0xf bound_ctrl:1
	v_add_f32_dpp v46, v46, v46 row_shr:1 row_mask:0xf bank_mask:0xf bound_ctrl:1
	v_add_f32_dpp v47, v47, v47 row_shr:1 row_mask:0xf bank_mask:0xf bound_ctrl:1
	v_add_f32_dpp v40, v40, v40 row_shr:2 row_mask:0xf bank_mask:0xf bound_ctrl:1
	v_add_f32_dpp v41, v41, v41 row_shr:2 row_mask:0xf bank_mask:0xf bound_ctrl:1
	v_add_f32_dpp v42, v42, v42 row_shr:2 row_mask:0xf bank_mask:0xf bound_ctrl:1
	v_add_f32_dpp v43, v43, v43 row_shr:2 row_mask:0xf bank_mask:0xf bound_ctrl:1
	v_add_f32_dpp v44, v44, v44 row_shr:2 row_mask:0xf bank_mask:0xf bound_ctrl:1
	v_add_f32_dpp v45, v45, v45 row_shr:2 row_mask:0xf bank_mask:0xf bound_ctrl:1
	v_add_f32_dpp v46, v46, v46 row_shr:2 row_mask:0xf bank_mask:0xf bound_ctrl:1
	v_add_f32_dpp v47, v47, v47 row_shr:2 row_mask:0xf bank_mask:0xf bound_ctrl:1
	v_add_f32_dpp v40, v40, v40 row_shr:4 row_mask:0xf bank_mask:0xf bound_ctrl:1
	v_add_f32_dpp v41, v41, v41 row_shr:4 row_mask:0xf bank_mask:0xf bound_ctrl:1
	v_add_f32_dpp v42, v42, v42 row_shr:4 row_mask:0xf bank_mask:0xf bound_ctrl:1
	v_add_f32_dpp v43, v43, v43 row_shr:4 row_mask:0xf bank_mask:0xf bound_ctrl:1
	v_add_f32_dpp v44, v44, v44 row_shr:4 row_mask:0xf bank_mask:0xf bound_ctrl:1
	v_add_f32_dpp v45, v45, v45 row_shr:4 row_mask:0xf bank_mask:0xf bound_ctrl:1
	v_add_f32_dpp v46, v46, v46 row_shr:4 row_mask:0xf bank_mask:0xf bound_ctrl:1
	v_add_f32_dpp v47, v47, v47 row_shr:4 row_mask:0xf bank_mask:0xf bound_ctrl:1
	v_add_f32_dpp v40, v40, v40 row_shr:8 row_mask:0xf bank_mask:0xf bound_ctrl:1
	v_add_f32_dpp v41, v41, v41 row_shr:8 row_mask:0xf bank_mask:0xf bound_ctrl:1
	v_add_f32_dpp v42, v42, v42 row_shr:8 row_mask:0xf bank_mask:0xf bound_ctrl:1
	v_add_f32_dpp v43, v43, v43 row_shr:8 row_mask:0xf bank_mask:0xf bound_ctrl:1
	v_add_f32_dpp v44, v44, v44 row_shr:8 row_mask:0xf bank_mask:0xf bound_ctrl:1
	v_add_f32_dpp v45, v45, v45 row_shr:8 row_mask:0xf bank_mask:0xf bound_ctrl:1
	v_add_f32_dpp v46, v46, v46 row_shr:8 row_mask:0xf bank_mask:0xf bound_ctrl:1
	v_add_f32_dpp v47, v47, v47 row_shr:8 row_mask:0xf bank_mask:0xf bound_ctrl:1
	v_mov_b32_dpp v88, v40 row_newbcast:15 row_mask:0xf bank_mask:0xf
	v_mov_b32_dpp v89, v41 row_newbcast:15 row_mask:0xf bank_mask:0xf
	v_mov_b32_dpp v90, v42 row_newbcast:15 row_mask:0xf bank_mask:0xf
	v_mov_b32_dpp v91, v43 row_newbcast:15 row_mask:0xf bank_mask:0xf
	v_mov_b32_dpp v92, v44 row_newbcast:15 row_mask:0xf bank_mask:0xf
	v_mov_b32_dpp v93, v45 row_newbcast:15 row_mask:0xf bank_mask:0xf
	v_mov_b32_dpp v94, v46 row_newbcast:15 row_mask:0xf bank_mask:0xf
	v_mov_b32_dpp v95, v47 row_newbcast:15 row_mask:0xf bank_mask:0xf
	v_add_f32_e32 v40, v40, v170
	v_add_f32_e32 v44, v44, v171
	v_add_f32_e32 v41, v41, v172
	v_add_f32_e32 v45, v45, v173
	v_add_f32_e32 v42, v42, v174
	v_add_f32_e32 v46, v46, v175
	v_add_f32_e32 v43, v43, v176
	v_add_f32_e32 v47, v47, v177
	v_mul_f32_e32 v132, v40, v141
	v_mul_f32_e32 v40, v40, v140
	v_fma_f32 v40, -v44, v141, v40
	v_fma_f32 v44, v44, v140, v132
	v_mul_f32_e32 v133, v41, v145
	v_mul_f32_e32 v41, v41, v144
	v_fma_f32 v41, -v45, v145, v41
	v_fma_f32 v45, v45, v144, v133
	v_mul_f32_e32 v132, v42, v149
	v_mul_f32_e32 v42, v42, v148
	v_fma_f32 v42, -v46, v149, v42
	v_fma_f32 v46, v46, v148, v132
	v_mul_f32_e32 v133, v43, v153
	v_mul_f32_e32 v43, v43, v152
	v_fma_f32 v43, -v47, v153, v43
	v_fma_f32 v47, v47, v152, v133
	v_add_f32_e32 v88, v88, v170
	v_add_f32_e32 v92, v92, v171
	v_mul_f32_e32 v132, v92, v155
	v_mul_f32_e32 v171, v88, v155
	v_fma_f32 v170, v88, v154, -v132
	v_fma_f32 v171, v92, v154, v171
	v_add_f32_e32 v89, v89, v172
	v_add_f32_e32 v93, v93, v173
	v_mul_f32_e32 v133, v93, v159
	v_mul_f32_e32 v173, v89, v159
	v_fma_f32 v172, v89, v158, -v133
	v_fma_f32 v173, v93, v158, v173
	v_add_f32_e32 v90, v90, v174
	v_add_f32_e32 v94, v94, v175
	v_mul_f32_e32 v132, v94, v163
	v_mul_f32_e32 v175, v90, v163
	v_fma_f32 v174, v90, v162, -v132
	v_fma_f32 v175, v94, v162, v175
	v_add_f32_e32 v91, v91, v176
	v_add_f32_e32 v95, v95, v177
	v_mul_f32_e32 v133, v95, v167
	v_mul_f32_e32 v177, v91, v167
	v_fma_f32 v176, v91, v166, -v133
	v_fma_f32 v177, v95, v166, v177
	v_mul_f32_e32 v132, v48, v139
	v_mul_f32_e32 v48, v48, v138
	v_fma_f32 v48, -v52, v139, v48
	v_fma_f32 v52, v52, v138, v132
	v_mul_f32_e32 v133, v49, v143
	v_mul_f32_e32 v49, v49, v142
	v_fma_f32 v49, -v53, v143, v49
	v_fma_f32 v53, v53, v142, v133
	v_mul_f32_e32 v132, v50, v147
	v_mul_f32_e32 v50, v50, v146
	v_fma_f32 v50, -v54, v147, v50
	v_fma_f32 v54, v54, v146, v132
	v_mul_f32_e32 v133, v51, v151
	v_mul_f32_e32 v51, v51, v150
	v_fma_f32 v51, -v55, v151, v51
	v_fma_f32 v55, v55, v150, v133
	v_add_f32_dpp v48, v48, v48 row_shr:1 row_mask:0xf bank_mask:0xf bound_ctrl:1
	v_add_f32_dpp v49, v49, v49 row_shr:1 row_mask:0xf bank_mask:0xf bound_ctrl:1
	v_add_f32_dpp v50, v50, v50 row_shr:1 row_mask:0xf bank_mask:0xf bound_ctrl:1
	v_add_f32_dpp v51, v51, v51 row_shr:1 row_mask:0xf bank_mask:0xf bound_ctrl:1
	v_add_f32_dpp v52, v52, v52 row_shr:1 row_mask:0xf bank_mask:0xf bound_ctrl:1
	v_add_f32_dpp v53, v53, v53 row_shr:1 row_mask:0xf bank_mask:0xf bound_ctrl:1
	v_add_f32_dpp v54, v54, v54 row_shr:1 row_mask:0xf bank_mask:0xf bound_ctrl:1
	v_add_f32_dpp v55, v55, v55 row_shr:1 row_mask:0xf bank_mask:0xf bound_ctrl:1
	v_add_f32_dpp v48, v48, v48 row_shr:2 row_mask:0xf bank_mask:0xf bound_ctrl:1
	v_add_f32_dpp v49, v49, v49 row_shr:2 row_mask:0xf bank_mask:0xf bound_ctrl:1
	v_add_f32_dpp v50, v50, v50 row_shr:2 row_mask:0xf bank_mask:0xf bound_ctrl:1
	v_add_f32_dpp v51, v51, v51 row_shr:2 row_mask:0xf bank_mask:0xf bound_ctrl:1
	v_add_f32_dpp v52, v52, v52 row_shr:2 row_mask:0xf bank_mask:0xf bound_ctrl:1
	v_add_f32_dpp v53, v53, v53 row_shr:2 row_mask:0xf bank_mask:0xf bound_ctrl:1
	v_add_f32_dpp v54, v54, v54 row_shr:2 row_mask:0xf bank_mask:0xf bound_ctrl:1
	v_add_f32_dpp v55, v55, v55 row_shr:2 row_mask:0xf bank_mask:0xf bound_ctrl:1
	v_add_f32_dpp v48, v48, v48 row_shr:4 row_mask:0xf bank_mask:0xf bound_ctrl:1
	v_add_f32_dpp v49, v49, v49 row_shr:4 row_mask:0xf bank_mask:0xf bound_ctrl:1
	v_add_f32_dpp v50, v50, v50 row_shr:4 row_mask:0xf bank_mask:0xf bound_ctrl:1
	v_add_f32_dpp v51, v51, v51 row_shr:4 row_mask:0xf bank_mask:0xf bound_ctrl:1
	v_add_f32_dpp v52, v52, v52 row_shr:4 row_mask:0xf bank_mask:0xf bound_ctrl:1
	v_add_f32_dpp v53, v53, v53 row_shr:4 row_mask:0xf bank_mask:0xf bound_ctrl:1
	v_add_f32_dpp v54, v54, v54 row_shr:4 row_mask:0xf bank_mask:0xf bound_ctrl:1
	v_add_f32_dpp v55, v55, v55 row_shr:4 row_mask:0xf bank_mask:0xf bound_ctrl:1
	v_add_f32_dpp v48, v48, v48 row_shr:8 row_mask:0xf bank_mask:0xf bound_ctrl:1
	v_add_f32_dpp v49, v49, v49 row_shr:8 row_mask:0xf bank_mask:0xf bound_ctrl:1
	v_add_f32_dpp v50, v50, v50 row_shr:8 row_mask:0xf bank_mask:0xf bound_ctrl:1
	v_add_f32_dpp v51, v51, v51 row_shr:8 row_mask:0xf bank_mask:0xf bound_ctrl:1
	v_add_f32_dpp v52, v52, v52 row_shr:8 row_mask:0xf bank_mask:0xf bound_ctrl:1
	v_add_f32_dpp v53, v53, v53 row_shr:8 row_mask:0xf bank_mask:0xf bound_ctrl:1
	v_add_f32_dpp v54, v54, v54 row_shr:8 row_mask:0xf bank_mask:0xf bound_ctrl:1
	v_add_f32_dpp v55, v55, v55 row_shr:8 row_mask:0xf bank_mask:0xf bound_ctrl:1
	v_mov_b32_dpp v88, v48 row_newbcast:15 row_mask:0xf bank_mask:0xf
	v_mov_b32_dpp v89, v49 row_newbcast:15 row_mask:0xf bank_mask:0xf
	v_mov_b32_dpp v90, v50 row_newbcast:15 row_mask:0xf bank_mask:0xf
	v_mov_b32_dpp v91, v51 row_newbcast:15 row_mask:0xf bank_mask:0xf
	v_mov_b32_dpp v92, v52 row_newbcast:15 row_mask:0xf bank_mask:0xf
	v_mov_b32_dpp v93, v53 row_newbcast:15 row_mask:0xf bank_mask:0xf
	v_mov_b32_dpp v94, v54 row_newbcast:15 row_mask:0xf bank_mask:0xf
	v_mov_b32_dpp v95, v55 row_newbcast:15 row_mask:0xf bank_mask:0xf
	v_add_f32_e32 v48, v48, v170
	v_add_f32_e32 v52, v52, v171
	v_add_f32_e32 v49, v49, v172
	v_add_f32_e32 v53, v53, v173
	v_add_f32_e32 v50, v50, v174
	v_add_f32_e32 v54, v54, v175
	v_add_f32_e32 v51, v51, v176
	v_add_f32_e32 v55, v55, v177
	v_mul_f32_e32 v132, v48, v141
	v_mul_f32_e32 v48, v48, v140
	v_fma_f32 v48, -v52, v141, v48
	v_fma_f32 v52, v52, v140, v132
	v_mul_f32_e32 v133, v49, v145
	v_mul_f32_e32 v49, v49, v144
	v_fma_f32 v49, -v53, v145, v49
	v_fma_f32 v53, v53, v144, v133
	v_mul_f32_e32 v132, v50, v149
	v_mul_f32_e32 v50, v50, v148
	v_fma_f32 v50, -v54, v149, v50
	v_fma_f32 v54, v54, v148, v132
	v_mul_f32_e32 v133, v51, v153
	v_mul_f32_e32 v51, v51, v152
	v_fma_f32 v51, -v55, v153, v51
	v_fma_f32 v55, v55, v152, v133
	v_add_f32_e32 v88, v88, v170
	v_add_f32_e32 v92, v92, v171
	v_mul_f32_e32 v132, v92, v155
	v_mul_f32_e32 v171, v88, v155
	v_fma_f32 v170, v88, v154, -v132
	v_fma_f32 v171, v92, v154, v171
	v_add_f32_e32 v89, v89, v172
	v_add_f32_e32 v93, v93, v173
	v_mul_f32_e32 v133, v93, v159
	v_mul_f32_e32 v173, v89, v159
	v_fma_f32 v172, v89, v158, -v133
	v_fma_f32 v173, v93, v158, v173
	v_add_f32_e32 v90, v90, v174
	v_add_f32_e32 v94, v94, v175
	v_mul_f32_e32 v132, v94, v163
	v_mul_f32_e32 v175, v90, v163
	v_fma_f32 v174, v90, v162, -v132
	v_fma_f32 v175, v94, v162, v175
	v_add_f32_e32 v91, v91, v176
	v_add_f32_e32 v95, v95, v177
	v_mul_f32_e32 v133, v95, v167
	v_mul_f32_e32 v177, v91, v167
	v_fma_f32 v176, v91, v166, -v133
	v_fma_f32 v177, v95, v166, v177
	v_mul_f32_e32 v132, v56, v139
	v_mul_f32_e32 v56, v56, v138
	v_fma_f32 v56, -v60, v139, v56
	v_fma_f32 v60, v60, v138, v132
	v_mul_f32_e32 v133, v57, v143
	v_mul_f32_e32 v57, v57, v142
	v_fma_f32 v57, -v61, v143, v57
	v_fma_f32 v61, v61, v142, v133
	v_mul_f32_e32 v132, v58, v147
	v_mul_f32_e32 v58, v58, v146
	v_fma_f32 v58, -v62, v147, v58
	v_fma_f32 v62, v62, v146, v132
	v_mul_f32_e32 v133, v59, v151
	v_mul_f32_e32 v59, v59, v150
	v_fma_f32 v59, -v63, v151, v59
	v_fma_f32 v63, v63, v150, v133
	v_add_f32_dpp v56, v56, v56 row_shr:1 row_mask:0xf bank_mask:0xf bound_ctrl:1
	v_add_f32_dpp v57, v57, v57 row_shr:1 row_mask:0xf bank_mask:0xf bound_ctrl:1
	v_add_f32_dpp v58, v58, v58 row_shr:1 row_mask:0xf bank_mask:0xf bound_ctrl:1
	v_add_f32_dpp v59, v59, v59 row_shr:1 row_mask:0xf bank_mask:0xf bound_ctrl:1
	v_add_f32_dpp v60, v60, v60 row_shr:1 row_mask:0xf bank_mask:0xf bound_ctrl:1
	v_add_f32_dpp v61, v61, v61 row_shr:1 row_mask:0xf bank_mask:0xf bound_ctrl:1
	v_add_f32_dpp v62, v62, v62 row_shr:1 row_mask:0xf bank_mask:0xf bound_ctrl:1
	v_add_f32_dpp v63, v63, v63 row_shr:1 row_mask:0xf bank_mask:0xf bound_ctrl:1
	v_add_f32_dpp v56, v56, v56 row_shr:2 row_mask:0xf bank_mask:0xf bound_ctrl:1
	v_add_f32_dpp v57, v57, v57 row_shr:2 row_mask:0xf bank_mask:0xf bound_ctrl:1
	v_add_f32_dpp v58, v58, v58 row_shr:2 row_mask:0xf bank_mask:0xf bound_ctrl:1
	v_add_f32_dpp v59, v59, v59 row_shr:2 row_mask:0xf bank_mask:0xf bound_ctrl:1
	v_add_f32_dpp v60, v60, v60 row_shr:2 row_mask:0xf bank_mask:0xf bound_ctrl:1
	v_add_f32_dpp v61, v61, v61 row_shr:2 row_mask:0xf bank_mask:0xf bound_ctrl:1
	v_add_f32_dpp v62, v62, v62 row_shr:2 row_mask:0xf bank_mask:0xf bound_ctrl:1
	v_add_f32_dpp v63, v63, v63 row_shr:2 row_mask:0xf bank_mask:0xf bound_ctrl:1
	v_add_f32_dpp v56, v56, v56 row_shr:4 row_mask:0xf bank_mask:0xf bound_ctrl:1
	v_add_f32_dpp v57, v57, v57 row_shr:4 row_mask:0xf bank_mask:0xf bound_ctrl:1
	v_add_f32_dpp v58, v58, v58 row_shr:4 row_mask:0xf bank_mask:0xf bound_ctrl:1
	v_add_f32_dpp v59, v59, v59 row_shr:4 row_mask:0xf bank_mask:0xf bound_ctrl:1
	v_add_f32_dpp v60, v60, v60 row_shr:4 row_mask:0xf bank_mask:0xf bound_ctrl:1
	v_add_f32_dpp v61, v61, v61 row_shr:4 row_mask:0xf bank_mask:0xf bound_ctrl:1
	v_add_f32_dpp v62, v62, v62 row_shr:4 row_mask:0xf bank_mask:0xf bound_ctrl:1
	v_add_f32_dpp v63, v63, v63 row_shr:4 row_mask:0xf bank_mask:0xf bound_ctrl:1
	v_add_f32_dpp v56, v56, v56 row_shr:8 row_mask:0xf bank_mask:0xf bound_ctrl:1
	v_add_f32_dpp v57, v57, v57 row_shr:8 row_mask:0xf bank_mask:0xf bound_ctrl:1
	v_add_f32_dpp v58, v58, v58 row_shr:8 row_mask:0xf bank_mask:0xf bound_ctrl:1
	v_add_f32_dpp v59, v59, v59 row_shr:8 row_mask:0xf bank_mask:0xf bound_ctrl:1
	v_add_f32_dpp v60, v60, v60 row_shr:8 row_mask:0xf bank_mask:0xf bound_ctrl:1
	v_add_f32_dpp v61, v61, v61 row_shr:8 row_mask:0xf bank_mask:0xf bound_ctrl:1
	v_add_f32_dpp v62, v62, v62 row_shr:8 row_mask:0xf bank_mask:0xf bound_ctrl:1
	v_add_f32_dpp v63, v63, v63 row_shr:8 row_mask:0xf bank_mask:0xf bound_ctrl:1
	v_mov_b32_dpp v88, v56 row_newbcast:15 row_mask:0xf bank_mask:0xf
	v_mov_b32_dpp v89, v57 row_newbcast:15 row_mask:0xf bank_mask:0xf
	v_mov_b32_dpp v90, v58 row_newbcast:15 row_mask:0xf bank_mask:0xf
	v_mov_b32_dpp v91, v59 row_newbcast:15 row_mask:0xf bank_mask:0xf
	v_mov_b32_dpp v92, v60 row_newbcast:15 row_mask:0xf bank_mask:0xf
	v_mov_b32_dpp v93, v61 row_newbcast:15 row_mask:0xf bank_mask:0xf
	v_mov_b32_dpp v94, v62 row_newbcast:15 row_mask:0xf bank_mask:0xf
	v_mov_b32_dpp v95, v63 row_newbcast:15 row_mask:0xf bank_mask:0xf
	v_add_f32_e32 v56, v56, v170
	v_add_f32_e32 v60, v60, v171
	v_add_f32_e32 v57, v57, v172
	v_add_f32_e32 v61, v61, v173
	v_add_f32_e32 v58, v58, v174
	v_add_f32_e32 v62, v62, v175
	v_add_f32_e32 v59, v59, v176
	v_add_f32_e32 v63, v63, v177
	v_mul_f32_e32 v132, v56, v141
	v_mul_f32_e32 v56, v56, v140
	v_fma_f32 v56, -v60, v141, v56
	v_fma_f32 v60, v60, v140, v132
	v_mul_f32_e32 v133, v57, v145
	v_mul_f32_e32 v57, v57, v144
	v_fma_f32 v57, -v61, v145, v57
	v_fma_f32 v61, v61, v144, v133
	v_mul_f32_e32 v132, v58, v149
	v_mul_f32_e32 v58, v58, v148
	v_fma_f32 v58, -v62, v149, v58
	v_fma_f32 v62, v62, v148, v132
	v_mul_f32_e32 v133, v59, v153
	v_mul_f32_e32 v59, v59, v152
	v_fma_f32 v59, -v63, v153, v59
	v_fma_f32 v63, v63, v152, v133
	v_add_f32_e32 v88, v88, v170
	v_add_f32_e32 v92, v92, v171
	v_mul_f32_e32 v132, v92, v155
	v_mul_f32_e32 v171, v88, v155
	v_fma_f32 v170, v88, v154, -v132
	v_fma_f32 v171, v92, v154, v171
	v_add_f32_e32 v89, v89, v172
	v_add_f32_e32 v93, v93, v173
	v_mul_f32_e32 v133, v93, v159
	v_mul_f32_e32 v173, v89, v159
	v_fma_f32 v172, v89, v158, -v133
	v_fma_f32 v173, v93, v158, v173
	v_add_f32_e32 v90, v90, v174
	v_add_f32_e32 v94, v94, v175
	v_mul_f32_e32 v132, v94, v163
	v_mul_f32_e32 v175, v90, v163
	v_fma_f32 v174, v90, v162, -v132
	v_fma_f32 v175, v94, v162, v175
	v_add_f32_e32 v91, v91, v176
	v_add_f32_e32 v95, v95, v177
	v_mul_f32_e32 v133, v95, v167
	v_mul_f32_e32 v177, v91, v167
	v_fma_f32 v176, v91, v166, -v133
	v_fma_f32 v177, v95, v166, v177
	s_waitcnt vmcnt(12)
	v_cvt_pk_bf16_f32 v96, v32, v33
	v_cvt_pk_bf16_f32 v97, v34, v35
	v_cvt_pk_bf16_f32 v98, v36, v37
	v_cvt_pk_bf16_f32 v99, v38, v39
	s_nop 1
	v_mfma_f32_16x16x32_bf16 v[16:19], v[80:83], v[96:99], v[16:19]
	v_cvt_pk_bf16_f32 v96, v40, v41
	v_cvt_pk_bf16_f32 v97, v42, v43
	v_cvt_pk_bf16_f32 v98, v44, v45
	v_cvt_pk_bf16_f32 v99, v46, v47
	s_nop 1
	v_mfma_f32_16x16x32_bf16 v[20:23], v[80:83], v[96:99], v[20:23]
	v_cvt_pk_bf16_f32 v96, v48, v49
	v_cvt_pk_bf16_f32 v97, v50, v51
	v_cvt_pk_bf16_f32 v98, v52, v53
	v_cvt_pk_bf16_f32 v99, v54, v55
	s_nop 1
	v_mfma_f32_16x16x32_bf16 v[24:27], v[80:83], v[96:99], v[24:27]
	v_cvt_pk_bf16_f32 v96, v56, v57
	v_cvt_pk_bf16_f32 v97, v58, v59
	v_cvt_pk_bf16_f32 v98, v60, v61
	v_cvt_pk_bf16_f32 v99, v62, v63
	s_nop 1
	v_mfma_f32_16x16x32_bf16 v[28:31], v[80:83], v[96:99], v[28:31]
	s_waitcnt vmcnt(10)
	global_load_dwordx4 v[80:83], v134, s[38:39]
	v_mfma_f32_16x16x32_bf16 v[32:35], v[64:67], v[0:3], 0
	v_mfma_f32_16x16x32_bf16 v[36:39], v[72:75], v[0:3], 0
	v_mfma_f32_16x16x32_bf16 v[40:43], v[64:67], v[4:7], 0
	v_mfma_f32_16x16x32_bf16 v[44:47], v[72:75], v[4:7], 0
	v_mfma_f32_16x16x32_bf16 v[48:51], v[64:67], v[8:11], 0
	v_mfma_f32_16x16x32_bf16 v[52:55], v[72:75], v[8:11], 0
	v_mfma_f32_16x16x32_bf16 v[56:59], v[64:67], v[12:15], 0
	v_mfma_f32_16x16x32_bf16 v[60:63], v[72:75], v[12:15], 0
	v_readlane_b32 s10, v247, 28
	s_sub_i32 s11, 3, s8
	s_sub_i32 s17, 71, s8
	s_cmp_lt_u32 s8, 4
	s_cselect_b32 s11, s11, s17
	s_lshl_b32 s16, s10, 1
	s_add_i32 s16, s16, 1
	s_lshl_b32 s16, s16, 4
	s_add_i32 s16, s16, s7
	s_lshl_b32 s17, s6, 1
	s_add_i32 s17, s17, 1
	s_lshl_b32 s17, s17, 4
	s_add_i32 s17, s17, s7
	s_mul_i32 s17, s17, 68
	s_add_i32 s17, s17, s11
	s_lshl_b32 s17, s17, 6
	s_lshl_b32 s20, s16, 13
	s_add_u32 s20, s20, 0xfd00000
	s_add_u32 s20, s4, s20
	s_addc_u32 s21, s5, 0
	s_lshl_b32 s38, s16, 12
	s_add_u32 s38, s38, 0xfd80000
	s_add_u32 s38, s4, s38
	s_addc_u32 s39, s5, 0
	s_lshl_b32 s42, s16, 15
	s_add_u32 s42, s42, 0xf900000
	s_add_u32 s42, s4, s42
	s_addc_u32 s43, s5, 0
	s_lshl_b32 s44, s17, 3
	s_add_u32 s44, s44, 0x740000
	s_add_u32 s44, s4, s44
	s_addc_u32 s45, s5, 0
	global_load_dwordx4 v[64:67], v134, s[20:21]
	global_load_dwordx4 v[72:75], v134, s[20:21] offset:1024
	s_add_u32 s20, s20, 0x800
	s_addc_u32 s21, s21, 0
	global_load_dwordx4 v[138:141], v134, s[42:43] offset:0
	global_load_dwordx4 v[142:145], v134, s[42:43] offset:1024
	global_load_dwordx4 v[146:149], v134, s[42:43] offset:2048
	global_load_dwordx4 v[150:153], v134, s[42:43] offset:3072
	global_load_dwordx4 v[154:157], v208, s[42:43] offset:0
	global_load_dwordx4 v[158:161], v208, s[42:43] offset:1024
	global_load_dwordx4 v[162:165], v208, s[42:43] offset:2048
	global_load_dwordx4 v[166:169], v208, s[42:43] offset:3072
	global_load_dwordx4 v[170:173], v206, s[44:45]
	global_load_dwordx4 v[174:177], v206, s[44:45] offset:16
	s_add_u32 s42, s42, 0x2000
	s_addc_u32 s43, s43, 0
	s_add_u32 s44, s44, 0x80
	s_addc_u32 s45, s45, 0
	s_waitcnt vmcnt(13)
	v_mul_f32_e32 v132, v179, v119
	v_mul_f32_e32 v133, v178, v119
	v_fma_f32 v178, v178, v118, -v132
	v_fma_f32 v179, v179, v118, v133
	v_mul_f32_e32 v132, v181, v123
	v_mul_f32_e32 v133, v180, v123
	v_fma_f32 v180, v180, v122, -v132
	v_fma_f32 v181, v181, v122, v133
	v_mul_f32_e32 v132, v183, v127
	v_mul_f32_e32 v133, v182, v127
	v_fma_f32 v182, v182, v126, -v132
	v_fma_f32 v183, v183, v126, v133
	v_mul_f32_e32 v132, v185, v131
	v_mul_f32_e32 v133, v184, v131
	v_fma_f32 v184, v184, v130, -v132
	v_fma_f32 v185, v185, v130, v133
	v_mul_f32_e32 v132, v32, v101
	v_mul_f32_e32 v32, v32, v100
	v_fma_f32 v32, -v36, v101, v32
	v_fma_f32 v36, v36, v100, v132
	v_mul_f32_e32 v133, v33, v105
	v_mul_f32_e32 v33, v33, v104
	v_fma_f32 v33, -v37, v105, v33
	v_fma_f32 v37, v37, v104, v133
	v_mul_f32_e32 v132, v34, v109
	v_mul_f32_e32 v34, v34, v108
	v_fma_f32 v34, -v38, v109, v34
	v_fma_f32 v38, v38, v108, v132
	v_mul_f32_e32 v133, v35, v113
	v_mul_f32_e32 v35, v35, v112
	v_fma_f32 v35, -v39, v113, v35
	v_fma_f32 v39, v39, v112, v133
	v_add_f32_dpp v32, v32, v32 row_shr:1 row_mask:0xf bank_mask:0xf bound_ctrl:1
	v_add_f32_dpp v33, v33, v33 row_shr:1 row_mask:0xf bank_mask:0xf bound_ctrl:1
	v_add_f32_dpp v34, v34, v34 row_shr:1 row_mask:0xf bank_mask:0xf bound_ctrl:1
	v_add_f32_dpp v35, v35, v35 row_shr:1 row_mask:0xf bank_mask:0xf bound_ctrl:1
	v_add_f32_dpp v36, v36, v36 row_shr:1 row_mask:0xf bank_mask:0xf bound_ctrl:1
	v_add_f32_dpp v37, v37, v37 row_shr:1 row_mask:0xf bank_mask:0xf bound_ctrl:1
	v_add_f32_dpp v38, v38, v38 row_shr:1 row_mask:0xf bank_mask:0xf bound_ctrl:1
	v_add_f32_dpp v39, v39, v39 row_shr:1 row_mask:0xf bank_mask:0xf bound_ctrl:1
	v_add_f32_dpp v32, v32, v32 row_shr:2 row_mask:0xf bank_mask:0xf bound_ctrl:1
	v_add_f32_dpp v33, v33, v33 row_shr:2 row_mask:0xf bank_mask:0xf bound_ctrl:1
	v_add_f32_dpp v34, v34, v34 row_shr:2 row_mask:0xf bank_mask:0xf bound_ctrl:1
	v_add_f32_dpp v35, v35, v35 row_shr:2 row_mask:0xf bank_mask:0xf bound_ctrl:1
	v_add_f32_dpp v36, v36, v36 row_shr:2 row_mask:0xf bank_mask:0xf bound_ctrl:1
	v_add_f32_dpp v37, v37, v37 row_shr:2 row_mask:0xf bank_mask:0xf bound_ctrl:1
	v_add_f32_dpp v38, v38, v38 row_shr:2 row_mask:0xf bank_mask:0xf bound_ctrl:1
	v_add_f32_dpp v39, v39, v39 row_shr:2 row_mask:0xf bank_mask:0xf bound_ctrl:1
	v_add_f32_dpp v32, v32, v32 row_shr:4 row_mask:0xf bank_mask:0xf bound_ctrl:1
	v_add_f32_dpp v33, v33, v33 row_shr:4 row_mask:0xf bank_mask:0xf bound_ctrl:1
	v_add_f32_dpp v34, v34, v34 row_shr:4 row_mask:0xf bank_mask:0xf bound_ctrl:1
	v_add_f32_dpp v35, v35, v35 row_shr:4 row_mask:0xf bank_mask:0xf bound_ctrl:1
	v_add_f32_dpp v36, v36, v36 row_shr:4 row_mask:0xf bank_mask:0xf bound_ctrl:1
	v_add_f32_dpp v37, v37, v37 row_shr:4 row_mask:0xf bank_mask:0xf bound_ctrl:1
	v_add_f32_dpp v38, v38, v38 row_shr:4 row_mask:0xf bank_mask:0xf bound_ctrl:1
	v_add_f32_dpp v39, v39, v39 row_shr:4 row_mask:0xf bank_mask:0xf bound_ctrl:1
	v_add_f32_dpp v32, v32, v32 row_shr:8 row_mask:0xf bank_mask:0xf bound_ctrl:1
	v_add_f32_dpp v33, v33, v33 row_shr:8 row_mask:0xf bank_mask:0xf bound_ctrl:1
	v_add_f32_dpp v34, v34, v34 row_shr:8 row_mask:0xf bank_mask:0xf bound_ctrl:1
	v_add_f32_dpp v35, v35, v35 row_shr:8 row_mask:0xf bank_mask:0xf bound_ctrl:1
	v_add_f32_dpp v36, v36, v36 row_shr:8 row_mask:0xf bank_mask:0xf bound_ctrl:1
	v_add_f32_dpp v37, v37, v37 row_shr:8 row_mask:0xf bank_mask:0xf bound_ctrl:1
	v_add_f32_dpp v38, v38, v38 row_shr:8 row_mask:0xf bank_mask:0xf bound_ctrl:1
	v_add_f32_dpp v39, v39, v39 row_shr:8 row_mask:0xf bank_mask:0xf bound_ctrl:1
	v_mov_b32_dpp v88, v32 row_newbcast:15 row_mask:0xf bank_mask:0xf
	v_mov_b32_dpp v89, v33 row_newbcast:15 row_mask:0xf bank_mask:0xf
	v_mov_b32_dpp v90, v34 row_newbcast:15 row_mask:0xf bank_mask:0xf
	v_mov_b32_dpp v91, v35 row_newbcast:15 row_mask:0xf bank_mask:0xf
	v_mov_b32_dpp v92, v36 row_newbcast:15 row_mask:0xf bank_mask:0xf
	v_mov_b32_dpp v93, v37 row_newbcast:15 row_mask:0xf bank_mask:0xf
	v_mov_b32_dpp v94, v38 row_newbcast:15 row_mask:0xf bank_mask:0xf
	v_mov_b32_dpp v95, v39 row_newbcast:15 row_mask:0xf bank_mask:0xf
	v_add_f32_e32 v32, v32, v178
	v_add_f32_e32 v36, v36, v179
	v_add_f32_e32 v33, v33, v180
	v_add_f32_e32 v37, v37, v181
	v_add_f32_e32 v34, v34, v182
	v_add_f32_e32 v38, v38, v183
	v_add_f32_e32 v35, v35, v184
	v_add_f32_e32 v39, v39, v185
	v_mul_f32_e32 v132, v32, v103
	v_mul_f32_e32 v32, v32, v102
	v_fma_f32 v32, -v36, v103, v32
	v_fma_f32 v36, v36, v102, v132
	v_mul_f32_e32 v133, v33, v107
	v_mul_f32_e32 v33, v33, v106
	v_fma_f32 v33, -v37, v107, v33
	v_fma_f32 v37, v37, v106, v133
	v_mul_f32_e32 v132, v34, v111
	v_mul_f32_e32 v34, v34, v110
	v_fma_f32 v34, -v38, v111, v34
	v_fma_f32 v38, v38, v110, v132
	v_mul_f32_e32 v133, v35, v115
	v_mul_f32_e32 v35, v35, v114
	v_fma_f32 v35, -v39, v115, v35
	v_fma_f32 v39, v39, v114, v133
	v_add_f32_e32 v88, v88, v178
	v_add_f32_e32 v92, v92, v179
	v_mul_f32_e32 v132, v92, v117
	v_mul_f32_e32 v179, v88, v117
	v_fma_f32 v178, v88, v116, -v132
	v_fma_f32 v179, v92, v116, v179
	v_add_f32_e32 v89, v89, v180
	v_add_f32_e32 v93, v93, v181
	v_mul_f32_e32 v133, v93, v121
	v_mul_f32_e32 v181, v89, v121
	v_fma_f32 v180, v89, v120, -v133
	v_fma_f32 v181, v93, v120, v181
	v_add_f32_e32 v90, v90, v182
	v_add_f32_e32 v94, v94, v183
	v_mul_f32_e32 v132, v94, v125
	v_mul_f32_e32 v183, v90, v125
	v_fma_f32 v182, v90, v124, -v132
	v_fma_f32 v183, v94, v124, v183
	v_add_f32_e32 v91, v91, v184
	v_add_f32_e32 v95, v95, v185
	v_mul_f32_e32 v133, v95, v129
	v_mul_f32_e32 v185, v91, v129
	v_fma_f32 v184, v91, v128, -v133
	v_fma_f32 v185, v95, v128, v185
	v_mul_f32_e32 v132, v40, v101
	v_mul_f32_e32 v40, v40, v100
	v_fma_f32 v40, -v44, v101, v40
	v_fma_f32 v44, v44, v100, v132
	v_mul_f32_e32 v133, v41, v105
	v_mul_f32_e32 v41, v41, v104
	v_fma_f32 v41, -v45, v105, v41
	v_fma_f32 v45, v45, v104, v133
	v_mul_f32_e32 v132, v42, v109
	v_mul_f32_e32 v42, v42, v108
	v_fma_f32 v42, -v46, v109, v42
	v_fma_f32 v46, v46, v108, v132
	v_mul_f32_e32 v133, v43, v113
	v_mul_f32_e32 v43, v43, v112
	v_fma_f32 v43, -v47, v113, v43
	v_fma_f32 v47, v47, v112, v133
	v_add_f32_dpp v40, v40, v40 row_shr:1 row_mask:0xf bank_mask:0xf bound_ctrl:1
	v_add_f32_dpp v41, v41, v41 row_shr:1 row_mask:0xf bank_mask:0xf bound_ctrl:1
	v_add_f32_dpp v42, v42, v42 row_shr:1 row_mask:0xf bank_mask:0xf bound_ctrl:1
	v_add_f32_dpp v43, v43, v43 row_shr:1 row_mask:0xf bank_mask:0xf bound_ctrl:1
	v_add_f32_dpp v44, v44, v44 row_shr:1 row_mask:0xf bank_mask:0xf bound_ctrl:1
	v_add_f32_dpp v45, v45, v45 row_shr:1 row_mask:0xf bank_mask:0xf bound_ctrl:1
	v_add_f32_dpp v46, v46, v46 row_shr:1 row_mask:0xf bank_mask:0xf bound_ctrl:1
	v_add_f32_dpp v47, v47, v47 row_shr:1 row_mask:0xf bank_mask:0xf bound_ctrl:1
	v_add_f32_dpp v40, v40, v40 row_shr:2 row_mask:0xf bank_mask:0xf bound_ctrl:1
	v_add_f32_dpp v41, v41, v41 row_shr:2 row_mask:0xf bank_mask:0xf bound_ctrl:1
	v_add_f32_dpp v42, v42, v42 row_shr:2 row_mask:0xf bank_mask:0xf bound_ctrl:1
	v_add_f32_dpp v43, v43, v43 row_shr:2 row_mask:0xf bank_mask:0xf bound_ctrl:1
	v_add_f32_dpp v44, v44, v44 row_shr:2 row_mask:0xf bank_mask:0xf bound_ctrl:1
	v_add_f32_dpp v45, v45, v45 row_shr:2 row_mask:0xf bank_mask:0xf bound_ctrl:1
	v_add_f32_dpp v46, v46, v46 row_shr:2 row_mask:0xf bank_mask:0xf bound_ctrl:1
	v_add_f32_dpp v47, v47, v47 row_shr:2 row_mask:0xf bank_mask:0xf bound_ctrl:1
	v_add_f32_dpp v40, v40, v40 row_shr:4 row_mask:0xf bank_mask:0xf bound_ctrl:1
	v_add_f32_dpp v41, v41, v41 row_shr:4 row_mask:0xf bank_mask:0xf bound_ctrl:1
	v_add_f32_dpp v42, v42, v42 row_shr:4 row_mask:0xf bank_mask:0xf bound_ctrl:1
	v_add_f32_dpp v43, v43, v43 row_shr:4 row_mask:0xf bank_mask:0xf bound_ctrl:1
	v_add_f32_dpp v44, v44, v44 row_shr:4 row_mask:0xf bank_mask:0xf bound_ctrl:1
	v_add_f32_dpp v45, v45, v45 row_shr:4 row_mask:0xf bank_mask:0xf bound_ctrl:1
	v_add_f32_dpp v46, v46, v46 row_shr:4 row_mask:0xf bank_mask:0xf bound_ctrl:1
	v_add_f32_dpp v47, v47, v47 row_shr:4 row_mask:0xf bank_mask:0xf bound_ctrl:1
	v_add_f32_dpp v40, v40, v40 row_shr:8 row_mask:0xf bank_mask:0xf bound_ctrl:1
	v_add_f32_dpp v41, v41, v41 row_shr:8 row_mask:0xf bank_mask:0xf bound_ctrl:1
	v_add_f32_dpp v42, v42, v42 row_shr:8 row_mask:0xf bank_mask:0xf bound_ctrl:1
	v_add_f32_dpp v43, v43, v43 row_shr:8 row_mask:0xf bank_mask:0xf bound_ctrl:1
	v_add_f32_dpp v44, v44, v44 row_shr:8 row_mask:0xf bank_mask:0xf bound_ctrl:1
	v_add_f32_dpp v45, v45, v45 row_shr:8 row_mask:0xf bank_mask:0xf bound_ctrl:1
	v_add_f32_dpp v46, v46, v46 row_shr:8 row_mask:0xf bank_mask:0xf bound_ctrl:1
	v_add_f32_dpp v47, v47, v47 row_shr:8 row_mask:0xf bank_mask:0xf bound_ctrl:1
	v_mov_b32_dpp v88, v40 row_newbcast:15 row_mask:0xf bank_mask:0xf
	v_mov_b32_dpp v89, v41 row_newbcast:15 row_mask:0xf bank_mask:0xf
	v_mov_b32_dpp v90, v42 row_newbcast:15 row_mask:0xf bank_mask:0xf
	v_mov_b32_dpp v91, v43 row_newbcast:15 row_mask:0xf bank_mask:0xf
	v_mov_b32_dpp v92, v44 row_newbcast:15 row_mask:0xf bank_mask:0xf
	v_mov_b32_dpp v93, v45 row_newbcast:15 row_mask:0xf bank_mask:0xf
	v_mov_b32_dpp v94, v46 row_newbcast:15 row_mask:0xf bank_mask:0xf
	v_mov_b32_dpp v95, v47 row_newbcast:15 row_mask:0xf bank_mask:0xf
	v_add_f32_e32 v40, v40, v178
	v_add_f32_e32 v44, v44, v179
	v_add_f32_e32 v41, v41, v180
	v_add_f32_e32 v45, v45, v181
	v_add_f32_e32 v42, v42, v182
	v_add_f32_e32 v46, v46, v183
	v_add_f32_e32 v43, v43, v184
	v_add_f32_e32 v47, v47, v185
	v_mul_f32_e32 v132, v40, v103
	v_mul_f32_e32 v40, v40, v102
	v_fma_f32 v40, -v44, v103, v40
	v_fma_f32 v44, v44, v102, v132
	v_mul_f32_e32 v133, v41, v107
	v_mul_f32_e32 v41, v41, v106
	v_fma_f32 v41, -v45, v107, v41
	v_fma_f32 v45, v45, v106, v133
	v_mul_f32_e32 v132, v42, v111
	v_mul_f32_e32 v42, v42, v110
	v_fma_f32 v42, -v46, v111, v42
	v_fma_f32 v46, v46, v110, v132
	v_mul_f32_e32 v133, v43, v115
	v_mul_f32_e32 v43, v43, v114
	v_fma_f32 v43, -v47, v115, v43
	v_fma_f32 v47, v47, v114, v133
	v_add_f32_e32 v88, v88, v178
	v_add_f32_e32 v92, v92, v179
	v_mul_f32_e32 v132, v92, v117
	v_mul_f32_e32 v179, v88, v117
	v_fma_f32 v178, v88, v116, -v132
	v_fma_f32 v179, v92, v116, v179
	v_add_f32_e32 v89, v89, v180
	v_add_f32_e32 v93, v93, v181
	v_mul_f32_e32 v133, v93, v121
	v_mul_f32_e32 v181, v89, v121
	v_fma_f32 v180, v89, v120, -v133
	v_fma_f32 v181, v93, v120, v181
	v_add_f32_e32 v90, v90, v182
	v_add_f32_e32 v94, v94, v183
	v_mul_f32_e32 v132, v94, v125
	v_mul_f32_e32 v183, v90, v125
	v_fma_f32 v182, v90, v124, -v132
	v_fma_f32 v183, v94, v124, v183
	v_add_f32_e32 v91, v91, v184
	v_add_f32_e32 v95, v95, v185
	v_mul_f32_e32 v133, v95, v129
	v_mul_f32_e32 v185, v91, v129
	v_fma_f32 v184, v91, v128, -v133
	v_fma_f32 v185, v95, v128, v185
	v_mul_f32_e32 v132, v48, v101
	v_mul_f32_e32 v48, v48, v100
	v_fma_f32 v48, -v52, v101, v48
	v_fma_f32 v52, v52, v100, v132
	v_mul_f32_e32 v133, v49, v105
	v_mul_f32_e32 v49, v49, v104
	v_fma_f32 v49, -v53, v105, v49
	v_fma_f32 v53, v53, v104, v133
	v_mul_f32_e32 v132, v50, v109
	v_mul_f32_e32 v50, v50, v108
	v_fma_f32 v50, -v54, v109, v50
	v_fma_f32 v54, v54, v108, v132
	v_mul_f32_e32 v133, v51, v113
	v_mul_f32_e32 v51, v51, v112
	v_fma_f32 v51, -v55, v113, v51
	v_fma_f32 v55, v55, v112, v133
	v_add_f32_dpp v48, v48, v48 row_shr:1 row_mask:0xf bank_mask:0xf bound_ctrl:1
	v_add_f32_dpp v49, v49, v49 row_shr:1 row_mask:0xf bank_mask:0xf bound_ctrl:1
	v_add_f32_dpp v50, v50, v50 row_shr:1 row_mask:0xf bank_mask:0xf bound_ctrl:1
	v_add_f32_dpp v51, v51, v51 row_shr:1 row_mask:0xf bank_mask:0xf bound_ctrl:1
	v_add_f32_dpp v52, v52, v52 row_shr:1 row_mask:0xf bank_mask:0xf bound_ctrl:1
	v_add_f32_dpp v53, v53, v53 row_shr:1 row_mask:0xf bank_mask:0xf bound_ctrl:1
	v_add_f32_dpp v54, v54, v54 row_shr:1 row_mask:0xf bank_mask:0xf bound_ctrl:1
	v_add_f32_dpp v55, v55, v55 row_shr:1 row_mask:0xf bank_mask:0xf bound_ctrl:1
	v_add_f32_dpp v48, v48, v48 row_shr:2 row_mask:0xf bank_mask:0xf bound_ctrl:1
	v_add_f32_dpp v49, v49, v49 row_shr:2 row_mask:0xf bank_mask:0xf bound_ctrl:1
	v_add_f32_dpp v50, v50, v50 row_shr:2 row_mask:0xf bank_mask:0xf bound_ctrl:1
	v_add_f32_dpp v51, v51, v51 row_shr:2 row_mask:0xf bank_mask:0xf bound_ctrl:1
	v_add_f32_dpp v52, v52, v52 row_shr:2 row_mask:0xf bank_mask:0xf bound_ctrl:1
	v_add_f32_dpp v53, v53, v53 row_shr:2 row_mask:0xf bank_mask:0xf bound_ctrl:1
	v_add_f32_dpp v54, v54, v54 row_shr:2 row_mask:0xf bank_mask:0xf bound_ctrl:1
	v_add_f32_dpp v55, v55, v55 row_shr:2 row_mask:0xf bank_mask:0xf bound_ctrl:1
	v_add_f32_dpp v48, v48, v48 row_shr:4 row_mask:0xf bank_mask:0xf bound_ctrl:1
	v_add_f32_dpp v49, v49, v49 row_shr:4 row_mask:0xf bank_mask:0xf bound_ctrl:1
	v_add_f32_dpp v50, v50, v50 row_shr:4 row_mask:0xf bank_mask:0xf bound_ctrl:1
	v_add_f32_dpp v51, v51, v51 row_shr:4 row_mask:0xf bank_mask:0xf bound_ctrl:1
	v_add_f32_dpp v52, v52, v52 row_shr:4 row_mask:0xf bank_mask:0xf bound_ctrl:1
	v_add_f32_dpp v53, v53, v53 row_shr:4 row_mask:0xf bank_mask:0xf bound_ctrl:1
	v_add_f32_dpp v54, v54, v54 row_shr:4 row_mask:0xf bank_mask:0xf bound_ctrl:1
	v_add_f32_dpp v55, v55, v55 row_shr:4 row_mask:0xf bank_mask:0xf bound_ctrl:1
	v_add_f32_dpp v48, v48, v48 row_shr:8 row_mask:0xf bank_mask:0xf bound_ctrl:1
	v_add_f32_dpp v49, v49, v49 row_shr:8 row_mask:0xf bank_mask:0xf bound_ctrl:1
	v_add_f32_dpp v50, v50, v50 row_shr:8 row_mask:0xf bank_mask:0xf bound_ctrl:1
	v_add_f32_dpp v51, v51, v51 row_shr:8 row_mask:0xf bank_mask:0xf bound_ctrl:1
	v_add_f32_dpp v52, v52, v52 row_shr:8 row_mask:0xf bank_mask:0xf bound_ctrl:1
	v_add_f32_dpp v53, v53, v53 row_shr:8 row_mask:0xf bank_mask:0xf bound_ctrl:1
	v_add_f32_dpp v54, v54, v54 row_shr:8 row_mask:0xf bank_mask:0xf bound_ctrl:1
	v_add_f32_dpp v55, v55, v55 row_shr:8 row_mask:0xf bank_mask:0xf bound_ctrl:1
	v_mov_b32_dpp v88, v48 row_newbcast:15 row_mask:0xf bank_mask:0xf
	v_mov_b32_dpp v89, v49 row_newbcast:15 row_mask:0xf bank_mask:0xf
	v_mov_b32_dpp v90, v50 row_newbcast:15 row_mask:0xf bank_mask:0xf
	v_mov_b32_dpp v91, v51 row_newbcast:15 row_mask:0xf bank_mask:0xf
	v_mov_b32_dpp v92, v52 row_newbcast:15 row_mask:0xf bank_mask:0xf
	v_mov_b32_dpp v93, v53 row_newbcast:15 row_mask:0xf bank_mask:0xf
	v_mov_b32_dpp v94, v54 row_newbcast:15 row_mask:0xf bank_mask:0xf
	v_mov_b32_dpp v95, v55 row_newbcast:15 row_mask:0xf bank_mask:0xf
	v_add_f32_e32 v48, v48, v178
	v_add_f32_e32 v52, v52, v179
	v_add_f32_e32 v49, v49, v180
	v_add_f32_e32 v53, v53, v181
	v_add_f32_e32 v50, v50, v182
	v_add_f32_e32 v54, v54, v183
	v_add_f32_e32 v51, v51, v184
	v_add_f32_e32 v55, v55, v185
	v_mul_f32_e32 v132, v48, v103
	v_mul_f32_e32 v48, v48, v102
	v_fma_f32 v48, -v52, v103, v48
	v_fma_f32 v52, v52, v102, v132
	v_mul_f32_e32 v133, v49, v107
	v_mul_f32_e32 v49, v49, v106
	v_fma_f32 v49, -v53, v107, v49
	v_fma_f32 v53, v53, v106, v133
	v_mul_f32_e32 v132, v50, v111
	v_mul_f32_e32 v50, v50, v110
	v_fma_f32 v50, -v54, v111, v50
	v_fma_f32 v54, v54, v110, v132
	v_mul_f32_e32 v133, v51, v115
	v_mul_f32_e32 v51, v51, v114
	v_fma_f32 v51, -v55, v115, v51
	v_fma_f32 v55, v55, v114, v133
	v_add_f32_e32 v88, v88, v178
	v_add_f32_e32 v92, v92, v179
	v_mul_f32_e32 v132, v92, v117
	v_mul_f32_e32 v179, v88, v117
	v_fma_f32 v178, v88, v116, -v132
	v_fma_f32 v179, v92, v116, v179
	v_add_f32_e32 v89, v89, v180
	v_add_f32_e32 v93, v93, v181
	v_mul_f32_e32 v133, v93, v121
	v_mul_f32_e32 v181, v89, v121
	v_fma_f32 v180, v89, v120, -v133
	v_fma_f32 v181, v93, v120, v181
	v_add_f32_e32 v90, v90, v182
	v_add_f32_e32 v94, v94, v183
	v_mul_f32_e32 v132, v94, v125
	v_mul_f32_e32 v183, v90, v125
	v_fma_f32 v182, v90, v124, -v132
	v_fma_f32 v183, v94, v124, v183
	v_add_f32_e32 v91, v91, v184
	v_add_f32_e32 v95, v95, v185
	v_mul_f32_e32 v133, v95, v129
	v_mul_f32_e32 v185, v91, v129
	v_fma_f32 v184, v91, v128, -v133
	v_fma_f32 v185, v95, v128, v185
	v_mul_f32_e32 v132, v56, v101
	v_mul_f32_e32 v56, v56, v100
	v_fma_f32 v56, -v60, v101, v56
	v_fma_f32 v60, v60, v100, v132
	v_mul_f32_e32 v133, v57, v105
	v_mul_f32_e32 v57, v57, v104
	v_fma_f32 v57, -v61, v105, v57
	v_fma_f32 v61, v61, v104, v133
	v_mul_f32_e32 v132, v58, v109
	v_mul_f32_e32 v58, v58, v108
	v_fma_f32 v58, -v62, v109, v58
	v_fma_f32 v62, v62, v108, v132
	v_mul_f32_e32 v133, v59, v113
	v_mul_f32_e32 v59, v59, v112
	v_fma_f32 v59, -v63, v113, v59
	v_fma_f32 v63, v63, v112, v133
	v_add_f32_dpp v56, v56, v56 row_shr:1 row_mask:0xf bank_mask:0xf bound_ctrl:1
	v_add_f32_dpp v57, v57, v57 row_shr:1 row_mask:0xf bank_mask:0xf bound_ctrl:1
	v_add_f32_dpp v58, v58, v58 row_shr:1 row_mask:0xf bank_mask:0xf bound_ctrl:1
	v_add_f32_dpp v59, v59, v59 row_shr:1 row_mask:0xf bank_mask:0xf bound_ctrl:1
	v_add_f32_dpp v60, v60, v60 row_shr:1 row_mask:0xf bank_mask:0xf bound_ctrl:1
	v_add_f32_dpp v61, v61, v61 row_shr:1 row_mask:0xf bank_mask:0xf bound_ctrl:1
	v_add_f32_dpp v62, v62, v62 row_shr:1 row_mask:0xf bank_mask:0xf bound_ctrl:1
	v_add_f32_dpp v63, v63, v63 row_shr:1 row_mask:0xf bank_mask:0xf bound_ctrl:1
	v_add_f32_dpp v56, v56, v56 row_shr:2 row_mask:0xf bank_mask:0xf bound_ctrl:1
	v_add_f32_dpp v57, v57, v57 row_shr:2 row_mask:0xf bank_mask:0xf bound_ctrl:1
	v_add_f32_dpp v58, v58, v58 row_shr:2 row_mask:0xf bank_mask:0xf bound_ctrl:1
	v_add_f32_dpp v59, v59, v59 row_shr:2 row_mask:0xf bank_mask:0xf bound_ctrl:1
	v_add_f32_dpp v60, v60, v60 row_shr:2 row_mask:0xf bank_mask:0xf bound_ctrl:1
	v_add_f32_dpp v61, v61, v61 row_shr:2 row_mask:0xf bank_mask:0xf bound_ctrl:1
	v_add_f32_dpp v62, v62, v62 row_shr:2 row_mask:0xf bank_mask:0xf bound_ctrl:1
	v_add_f32_dpp v63, v63, v63 row_shr:2 row_mask:0xf bank_mask:0xf bound_ctrl:1
	v_add_f32_dpp v56, v56, v56 row_shr:4 row_mask:0xf bank_mask:0xf bound_ctrl:1
	v_add_f32_dpp v57, v57, v57 row_shr:4 row_mask:0xf bank_mask:0xf bound_ctrl:1
	v_add_f32_dpp v58, v58, v58 row_shr:4 row_mask:0xf bank_mask:0xf bound_ctrl:1
	v_add_f32_dpp v59, v59, v59 row_shr:4 row_mask:0xf bank_mask:0xf bound_ctrl:1
	v_add_f32_dpp v60, v60, v60 row_shr:4 row_mask:0xf bank_mask:0xf bound_ctrl:1
	v_add_f32_dpp v61, v61, v61 row_shr:4 row_mask:0xf bank_mask:0xf bound_ctrl:1
	v_add_f32_dpp v62, v62, v62 row_shr:4 row_mask:0xf bank_mask:0xf bound_ctrl:1
	v_add_f32_dpp v63, v63, v63 row_shr:4 row_mask:0xf bank_mask:0xf bound_ctrl:1
	v_add_f32_dpp v56, v56, v56 row_shr:8 row_mask:0xf bank_mask:0xf bound_ctrl:1
	v_add_f32_dpp v57, v57, v57 row_shr:8 row_mask:0xf bank_mask:0xf bound_ctrl:1
	v_add_f32_dpp v58, v58, v58 row_shr:8 row_mask:0xf bank_mask:0xf bound_ctrl:1
	v_add_f32_dpp v59, v59, v59 row_shr:8 row_mask:0xf bank_mask:0xf bound_ctrl:1
	v_add_f32_dpp v60, v60, v60 row_shr:8 row_mask:0xf bank_mask:0xf bound_ctrl:1
	v_add_f32_dpp v61, v61, v61 row_shr:8 row_mask:0xf bank_mask:0xf bound_ctrl:1
	v_add_f32_dpp v62, v62, v62 row_shr:8 row_mask:0xf bank_mask:0xf bound_ctrl:1
	v_add_f32_dpp v63, v63, v63 row_shr:8 row_mask:0xf bank_mask:0xf bound_ctrl:1
	v_mov_b32_dpp v88, v56 row_newbcast:15 row_mask:0xf bank_mask:0xf
	v_mov_b32_dpp v89, v57 row_newbcast:15 row_mask:0xf bank_mask:0xf
	v_mov_b32_dpp v90, v58 row_newbcast:15 row_mask:0xf bank_mask:0xf
	v_mov_b32_dpp v91, v59 row_newbcast:15 row_mask:0xf bank_mask:0xf
	v_mov_b32_dpp v92, v60 row_newbcast:15 row_mask:0xf bank_mask:0xf
	v_mov_b32_dpp v93, v61 row_newbcast:15 row_mask:0xf bank_mask:0xf
	v_mov_b32_dpp v94, v62 row_newbcast:15 row_mask:0xf bank_mask:0xf
	v_mov_b32_dpp v95, v63 row_newbcast:15 row_mask:0xf bank_mask:0xf
	v_add_f32_e32 v56, v56, v178
	v_add_f32_e32 v60, v60, v179
	v_add_f32_e32 v57, v57, v180
	v_add_f32_e32 v61, v61, v181
	v_add_f32_e32 v58, v58, v182
	v_add_f32_e32 v62, v62, v183
	v_add_f32_e32 v59, v59, v184
	v_add_f32_e32 v63, v63, v185
	v_mul_f32_e32 v132, v56, v103
	v_mul_f32_e32 v56, v56, v102
	v_fma_f32 v56, -v60, v103, v56
	v_fma_f32 v60, v60, v102, v132
	v_mul_f32_e32 v133, v57, v107
	v_mul_f32_e32 v57, v57, v106
	v_fma_f32 v57, -v61, v107, v57
	v_fma_f32 v61, v61, v106, v133
	v_mul_f32_e32 v132, v58, v111
	v_mul_f32_e32 v58, v58, v110
	v_fma_f32 v58, -v62, v111, v58
	v_fma_f32 v62, v62, v110, v132
	v_mul_f32_e32 v133, v59, v115
	v_mul_f32_e32 v59, v59, v114
	v_fma_f32 v59, -v63, v115, v59
	v_fma_f32 v63, v63, v114, v133
	v_add_f32_e32 v88, v88, v178
	v_add_f32_e32 v92, v92, v179
	v_mul_f32_e32 v132, v92, v117
	v_mul_f32_e32 v179, v88, v117
	v_fma_f32 v178, v88, v116, -v132
	v_fma_f32 v179, v92, v116, v179
	v_add_f32_e32 v89, v89, v180
	v_add_f32_e32 v93, v93, v181
	v_mul_f32_e32 v133, v93, v121
	v_mul_f32_e32 v181, v89, v121
	v_fma_f32 v180, v89, v120, -v133
	v_fma_f32 v181, v93, v120, v181
	v_add_f32_e32 v90, v90, v182
	v_add_f32_e32 v94, v94, v183
	v_mul_f32_e32 v132, v94, v125
	v_mul_f32_e32 v183, v90, v125
	v_fma_f32 v182, v90, v124, -v132
	v_fma_f32 v183, v94, v124, v183
	v_add_f32_e32 v91, v91, v184
	v_add_f32_e32 v95, v95, v185
	v_mul_f32_e32 v133, v95, v129
	v_mul_f32_e32 v185, v91, v129
	v_fma_f32 v184, v91, v128, -v133
	v_fma_f32 v185, v95, v128, v185
	s_waitcnt vmcnt(12)
	v_cvt_pk_bf16_f32 v96, v32, v33
	v_cvt_pk_bf16_f32 v97, v34, v35
	v_cvt_pk_bf16_f32 v98, v36, v37
	v_cvt_pk_bf16_f32 v99, v38, v39
	s_nop 1
	v_mfma_f32_16x16x32_bf16 v[16:19], v[80:83], v[96:99], v[16:19]
	v_cvt_pk_bf16_f32 v96, v40, v41
	v_cvt_pk_bf16_f32 v97, v42, v43
	v_cvt_pk_bf16_f32 v98, v44, v45
	v_cvt_pk_bf16_f32 v99, v46, v47
	s_nop 1
	v_mfma_f32_16x16x32_bf16 v[20:23], v[80:83], v[96:99], v[20:23]
	v_cvt_pk_bf16_f32 v96, v48, v49
	v_cvt_pk_bf16_f32 v97, v50, v51
	v_cvt_pk_bf16_f32 v98, v52, v53
	v_cvt_pk_bf16_f32 v99, v54, v55
	s_nop 1
	v_mfma_f32_16x16x32_bf16 v[24:27], v[80:83], v[96:99], v[24:27]
	v_cvt_pk_bf16_f32 v96, v56, v57
	v_cvt_pk_bf16_f32 v97, v58, v59
	v_cvt_pk_bf16_f32 v98, v60, v61
	v_cvt_pk_bf16_f32 v99, v62, v63
	s_nop 1
	v_mfma_f32_16x16x32_bf16 v[28:31], v[80:83], v[96:99], v[28:31]
	s_waitcnt vmcnt(10)
	global_load_dwordx4 v[80:83], v134, s[38:39]
	s_add_u32 s38, s38, 0x400
	s_addc_u32 s39, s39, 0
	v_mfma_f32_16x16x32_bf16 v[32:35], v[64:67], v[0:3], 0
	v_mfma_f32_16x16x32_bf16 v[36:39], v[72:75], v[0:3], 0
	v_mfma_f32_16x16x32_bf16 v[40:43], v[64:67], v[4:7], 0
	v_mfma_f32_16x16x32_bf16 v[44:47], v[72:75], v[4:7], 0
	v_mfma_f32_16x16x32_bf16 v[48:51], v[64:67], v[8:11], 0
	v_mfma_f32_16x16x32_bf16 v[52:55], v[72:75], v[8:11], 0
	v_mfma_f32_16x16x32_bf16 v[56:59], v[64:67], v[12:15], 0
	v_mfma_f32_16x16x32_bf16 v[60:63], v[72:75], v[12:15], 0
	global_load_dwordx4 v[64:67], v134, s[20:21]
	global_load_dwordx4 v[72:75], v134, s[20:21] offset:1024
	s_add_u32 s20, s20, 0x800
	s_addc_u32 s21, s21, 0
	global_load_dwordx4 v[100:103], v134, s[42:43] offset:0
	global_load_dwordx4 v[104:107], v134, s[42:43] offset:1024
	global_load_dwordx4 v[108:111], v134, s[42:43] offset:2048
	global_load_dwordx4 v[112:115], v134, s[42:43] offset:3072
	global_load_dwordx4 v[116:119], v208, s[42:43] offset:0
	global_load_dwordx4 v[120:123], v208, s[42:43] offset:1024
	global_load_dwordx4 v[124:127], v208, s[42:43] offset:2048
	global_load_dwordx4 v[128:131], v208, s[42:43] offset:3072
	global_load_dwordx4 v[178:181], v206, s[44:45]
	global_load_dwordx4 v[182:185], v206, s[44:45] offset:16
	s_add_u32 s42, s42, 0x2000
	s_addc_u32 s43, s43, 0
	s_add_u32 s44, s44, 0x80
	s_addc_u32 s45, s45, 0
	s_waitcnt vmcnt(13)
	v_mul_f32_e32 v132, v171, v157
	v_mul_f32_e32 v133, v170, v157
	v_fma_f32 v170, v170, v156, -v132
	v_fma_f32 v171, v171, v156, v133
	v_mul_f32_e32 v132, v173, v161
	v_mul_f32_e32 v133, v172, v161
	v_fma_f32 v172, v172, v160, -v132
	v_fma_f32 v173, v173, v160, v133
	v_mul_f32_e32 v132, v175, v165
	v_mul_f32_e32 v133, v174, v165
	v_fma_f32 v174, v174, v164, -v132
	v_fma_f32 v175, v175, v164, v133
	v_mul_f32_e32 v132, v177, v169
	v_mul_f32_e32 v133, v176, v169
	v_fma_f32 v176, v176, v168, -v132
	v_fma_f32 v177, v177, v168, v133
	v_mul_f32_e32 v132, v56, v139
	v_mul_f32_e32 v56, v56, v138
	v_fma_f32 v56, -v60, v139, v56
	v_fma_f32 v60, v60, v138, v132
	v_mul_f32_e32 v133, v57, v143
	v_mul_f32_e32 v57, v57, v142
	v_fma_f32 v57, -v61, v143, v57
	v_fma_f32 v61, v61, v142, v133
	v_mul_f32_e32 v132, v58, v147
	v_mul_f32_e32 v58, v58, v146
	v_fma_f32 v58, -v62, v147, v58
	v_fma_f32 v62, v62, v146, v132
	v_mul_f32_e32 v133, v59, v151
	v_mul_f32_e32 v59, v59, v150
	v_fma_f32 v59, -v63, v151, v59
	v_fma_f32 v63, v63, v150, v133
	v_add_f32_dpp v56, v56, v56 row_shl:1 row_mask:0xf bank_mask:0xf bound_ctrl:1
	v_add_f32_dpp v57, v57, v57 row_shl:1 row_mask:0xf bank_mask:0xf bound_ctrl:1
	v_add_f32_dpp v58, v58, v58 row_shl:1 row_mask:0xf bank_mask:0xf bound_ctrl:1
	v_add_f32_dpp v59, v59, v59 row_shl:1 row_mask:0xf bank_mask:0xf bound_ctrl:1
	v_add_f32_dpp v60, v60, v60 row_shl:1 row_mask:0xf bank_mask:0xf bound_ctrl:1
	v_add_f32_dpp v61, v61, v61 row_shl:1 row_mask:0xf bank_mask:0xf bound_ctrl:1
	v_add_f32_dpp v62, v62, v62 row_shl:1 row_mask:0xf bank_mask:0xf bound_ctrl:1
	v_add_f32_dpp v63, v63, v63 row_shl:1 row_mask:0xf bank_mask:0xf bound_ctrl:1
	v_add_f32_dpp v56, v56, v56 row_shl:2 row_mask:0xf bank_mask:0xf bound_ctrl:1
	v_add_f32_dpp v57, v57, v57 row_shl:2 row_mask:0xf bank_mask:0xf bound_ctrl:1
	v_add_f32_dpp v58, v58, v58 row_shl:2 row_mask:0xf bank_mask:0xf bound_ctrl:1
	v_add_f32_dpp v59, v59, v59 row_shl:2 row_mask:0xf bank_mask:0xf bound_ctrl:1
	v_add_f32_dpp v60, v60, v60 row_shl:2 row_mask:0xf bank_mask:0xf bound_ctrl:1
	v_add_f32_dpp v61, v61, v61 row_shl:2 row_mask:0xf bank_mask:0xf bound_ctrl:1
	v_add_f32_dpp v62, v62, v62 row_shl:2 row_mask:0xf bank_mask:0xf bound_ctrl:1
	v_add_f32_dpp v63, v63, v63 row_shl:2 row_mask:0xf bank_mask:0xf bound_ctrl:1
	v_add_f32_dpp v56, v56, v56 row_shl:4 row_mask:0xf bank_mask:0xf bound_ctrl:1
	v_add_f32_dpp v57, v57, v57 row_shl:4 row_mask:0xf bank_mask:0xf bound_ctrl:1
	v_add_f32_dpp v58, v58, v58 row_shl:4 row_mask:0xf bank_mask:0xf bound_ctrl:1
	v_add_f32_dpp v59, v59, v59 row_shl:4 row_mask:0xf bank_mask:0xf bound_ctrl:1
	v_add_f32_dpp v60, v60, v60 row_shl:4 row_mask:0xf bank_mask:0xf bound_ctrl:1
	v_add_f32_dpp v61, v61, v61 row_shl:4 row_mask:0xf bank_mask:0xf bound_ctrl:1
	v_add_f32_dpp v62, v62, v62 row_shl:4 row_mask:0xf bank_mask:0xf bound_ctrl:1
	v_add_f32_dpp v63, v63, v63 row_shl:4 row_mask:0xf bank_mask:0xf bound_ctrl:1
	v_add_f32_dpp v56, v56, v56 row_shl:8 row_mask:0xf bank_mask:0xf bound_ctrl:1
	v_add_f32_dpp v57, v57, v57 row_shl:8 row_mask:0xf bank_mask:0xf bound_ctrl:1
	v_add_f32_dpp v58, v58, v58 row_shl:8 row_mask:0xf bank_mask:0xf bound_ctrl:1
	v_add_f32_dpp v59, v59, v59 row_shl:8 row_mask:0xf bank_mask:0xf bound_ctrl:1
	v_add_f32_dpp v60, v60, v60 row_shl:8 row_mask:0xf bank_mask:0xf bound_ctrl:1
	v_add_f32_dpp v61, v61, v61 row_shl:8 row_mask:0xf bank_mask:0xf bound_ctrl:1
	v_add_f32_dpp v62, v62, v62 row_shl:8 row_mask:0xf bank_mask:0xf bound_ctrl:1
	v_add_f32_dpp v63, v63, v63 row_shl:8 row_mask:0xf bank_mask:0xf bound_ctrl:1
	v_mov_b32_dpp v88, v56 row_newbcast:0 row_mask:0xf bank_mask:0xf
	v_mov_b32_dpp v89, v57 row_newbcast:0 row_mask:0xf bank_mask:0xf
	v_mov_b32_dpp v90, v58 row_newbcast:0 row_mask:0xf bank_mask:0xf
	v_mov_b32_dpp v91, v59 row_newbcast:0 row_mask:0xf bank_mask:0xf
	v_mov_b32_dpp v92, v60 row_newbcast:0 row_mask:0xf bank_mask:0xf
	v_mov_b32_dpp v93, v61 row_newbcast:0 row_mask:0xf bank_mask:0xf
	v_mov_b32_dpp v94, v62 row_newbcast:0 row_mask:0xf bank_mask:0xf
	v_mov_b32_dpp v95, v63 row_newbcast:0 row_mask:0xf bank_mask:0xf
	v_add_f32_e32 v56, v56, v170
	v_add_f32_e32 v60, v60, v171
	v_add_f32_e32 v57, v57, v172
	v_add_f32_e32 v61, v61, v173
	v_add_f32_e32 v58, v58, v174
	v_add_f32_e32 v62, v62, v175
	v_add_f32_e32 v59, v59, v176
	v_add_f32_e32 v63, v63, v177
	v_mul_f32_e32 v132, v56, v141
	v_mul_f32_e32 v56, v56, v140
	v_fma_f32 v56, -v60, v141, v56
	v_fma_f32 v60, v60, v140, v132
	v_mul_f32_e32 v133, v57, v145
	v_mul_f32_e32 v57, v57, v144
	v_fma_f32 v57, -v61, v145, v57
	v_fma_f32 v61, v61, v144, v133
	v_mul_f32_e32 v132, v58, v149
	v_mul_f32_e32 v58, v58, v148
	v_fma_f32 v58, -v62, v149, v58
	v_fma_f32 v62, v62, v148, v132
	v_mul_f32_e32 v133, v59, v153
	v_mul_f32_e32 v59, v59, v152
	v_fma_f32 v59, -v63, v153, v59
	v_fma_f32 v63, v63, v152, v133
	v_add_f32_e32 v88, v88, v170
	v_add_f32_e32 v92, v92, v171
	v_mul_f32_e32 v132, v92, v155
	v_mul_f32_e32 v171, v88, v155
	v_fma_f32 v170, v88, v154, -v132
	v_fma_f32 v171, v92, v154, v171
	v_add_f32_e32 v89, v89, v172
	v_add_f32_e32 v93, v93, v173
	v_mul_f32_e32 v133, v93, v159
	v_mul_f32_e32 v173, v89, v159
	v_fma_f32 v172, v89, v158, -v133
	v_fma_f32 v173, v93, v158, v173
	v_add_f32_e32 v90, v90, v174
	v_add_f32_e32 v94, v94, v175
	v_mul_f32_e32 v132, v94, v163
	v_mul_f32_e32 v175, v90, v163
	v_fma_f32 v174, v90, v162, -v132
	v_fma_f32 v175, v94, v162, v175
	v_add_f32_e32 v91, v91, v176
	v_add_f32_e32 v95, v95, v177
	v_mul_f32_e32 v133, v95, v167
	v_mul_f32_e32 v177, v91, v167
	v_fma_f32 v176, v91, v166, -v133
	v_fma_f32 v177, v95, v166, v177
	v_mul_f32_e32 v132, v48, v139
	v_mul_f32_e32 v48, v48, v138
	v_fma_f32 v48, -v52, v139, v48
	v_fma_f32 v52, v52, v138, v132
	v_mul_f32_e32 v133, v49, v143
	v_mul_f32_e32 v49, v49, v142
	v_fma_f32 v49, -v53, v143, v49
	v_fma_f32 v53, v53, v142, v133
	v_mul_f32_e32 v132, v50, v147
	v_mul_f32_e32 v50, v50, v146
	v_fma_f32 v50, -v54, v147, v50
	v_fma_f32 v54, v54, v146, v132
	v_mul_f32_e32 v133, v51, v151
	v_mul_f32_e32 v51, v51, v150
	v_fma_f32 v51, -v55, v151, v51
	v_fma_f32 v55, v55, v150, v133
	v_add_f32_dpp v48, v48, v48 row_shl:1 row_mask:0xf bank_mask:0xf bound_ctrl:1
	v_add_f32_dpp v49, v49, v49 row_shl:1 row_mask:0xf bank_mask:0xf bound_ctrl:1
	v_add_f32_dpp v50, v50, v50 row_shl:1 row_mask:0xf bank_mask:0xf bound_ctrl:1
	v_add_f32_dpp v51, v51, v51 row_shl:1 row_mask:0xf bank_mask:0xf bound_ctrl:1
	v_add_f32_dpp v52, v52, v52 row_shl:1 row_mask:0xf bank_mask:0xf bound_ctrl:1
	v_add_f32_dpp v53, v53, v53 row_shl:1 row_mask:0xf bank_mask:0xf bound_ctrl:1
	v_add_f32_dpp v54, v54, v54 row_shl:1 row_mask:0xf bank_mask:0xf bound_ctrl:1
	v_add_f32_dpp v55, v55, v55 row_shl:1 row_mask:0xf bank_mask:0xf bound_ctrl:1
	v_add_f32_dpp v48, v48, v48 row_shl:2 row_mask:0xf bank_mask:0xf bound_ctrl:1
	v_add_f32_dpp v49, v49, v49 row_shl:2 row_mask:0xf bank_mask:0xf bound_ctrl:1
	v_add_f32_dpp v50, v50, v50 row_shl:2 row_mask:0xf bank_mask:0xf bound_ctrl:1
	v_add_f32_dpp v51, v51, v51 row_shl:2 row_mask:0xf bank_mask:0xf bound_ctrl:1
	v_add_f32_dpp v52, v52, v52 row_shl:2 row_mask:0xf bank_mask:0xf bound_ctrl:1
	v_add_f32_dpp v53, v53, v53 row_shl:2 row_mask:0xf bank_mask:0xf bound_ctrl:1
	v_add_f32_dpp v54, v54, v54 row_shl:2 row_mask:0xf bank_mask:0xf bound_ctrl:1
	v_add_f32_dpp v55, v55, v55 row_shl:2 row_mask:0xf bank_mask:0xf bound_ctrl:1
	v_add_f32_dpp v48, v48, v48 row_shl:4 row_mask:0xf bank_mask:0xf bound_ctrl:1
	v_add_f32_dpp v49, v49, v49 row_shl:4 row_mask:0xf bank_mask:0xf bound_ctrl:1
	v_add_f32_dpp v50, v50, v50 row_shl:4 row_mask:0xf bank_mask:0xf bound_ctrl:1
	v_add_f32_dpp v51, v51, v51 row_shl:4 row_mask:0xf bank_mask:0xf bound_ctrl:1
	v_add_f32_dpp v52, v52, v52 row_shl:4 row_mask:0xf bank_mask:0xf bound_ctrl:1
	v_add_f32_dpp v53, v53, v53 row_shl:4 row_mask:0xf bank_mask:0xf bound_ctrl:1
	v_add_f32_dpp v54, v54, v54 row_shl:4 row_mask:0xf bank_mask:0xf bound_ctrl:1
	v_add_f32_dpp v55, v55, v55 row_shl:4 row_mask:0xf bank_mask:0xf bound_ctrl:1
	v_add_f32_dpp v48, v48, v48 row_shl:8 row_mask:0xf bank_mask:0xf bound_ctrl:1
	v_add_f32_dpp v49, v49, v49 row_shl:8 row_mask:0xf bank_mask:0xf bound_ctrl:1
	v_add_f32_dpp v50, v50, v50 row_shl:8 row_mask:0xf bank_mask:0xf bound_ctrl:1
	v_add_f32_dpp v51, v51, v51 row_shl:8 row_mask:0xf bank_mask:0xf bound_ctrl:1
	v_add_f32_dpp v52, v52, v52 row_shl:8 row_mask:0xf bank_mask:0xf bound_ctrl:1
	v_add_f32_dpp v53, v53, v53 row_shl:8 row_mask:0xf bank_mask:0xf bound_ctrl:1
	v_add_f32_dpp v54, v54, v54 row_shl:8 row_mask:0xf bank_mask:0xf bound_ctrl:1
	v_add_f32_dpp v55, v55, v55 row_shl:8 row_mask:0xf bank_mask:0xf bound_ctrl:1
	v_mov_b32_dpp v88, v48 row_newbcast:0 row_mask:0xf bank_mask:0xf
	v_mov_b32_dpp v89, v49 row_newbcast:0 row_mask:0xf bank_mask:0xf
	v_mov_b32_dpp v90, v50 row_newbcast:0 row_mask:0xf bank_mask:0xf
	v_mov_b32_dpp v91, v51 row_newbcast:0 row_mask:0xf bank_mask:0xf
	v_mov_b32_dpp v92, v52 row_newbcast:0 row_mask:0xf bank_mask:0xf
	v_mov_b32_dpp v93, v53 row_newbcast:0 row_mask:0xf bank_mask:0xf
	v_mov_b32_dpp v94, v54 row_newbcast:0 row_mask:0xf bank_mask:0xf
	v_mov_b32_dpp v95, v55 row_newbcast:0 row_mask:0xf bank_mask:0xf
	v_add_f32_e32 v48, v48, v170
	v_add_f32_e32 v52, v52, v171
	v_add_f32_e32 v49, v49, v172
	v_add_f32_e32 v53, v53, v173
	v_add_f32_e32 v50, v50, v174
	v_add_f32_e32 v54, v54, v175
	v_add_f32_e32 v51, v51, v176
	v_add_f32_e32 v55, v55, v177
	v_mul_f32_e32 v132, v48, v141
	v_mul_f32_e32 v48, v48, v140
	v_fma_f32 v48, -v52, v141, v48
	v_fma_f32 v52, v52, v140, v132
	v_mul_f32_e32 v133, v49, v145
	v_mul_f32_e32 v49, v49, v144
	v_fma_f32 v49, -v53, v145, v49
	v_fma_f32 v53, v53, v144, v133
	v_mul_f32_e32 v132, v50, v149
	v_mul_f32_e32 v50, v50, v148
	v_fma_f32 v50, -v54, v149, v50
	v_fma_f32 v54, v54, v148, v132
	v_mul_f32_e32 v133, v51, v153
	v_mul_f32_e32 v51, v51, v152
	v_fma_f32 v51, -v55, v153, v51
	v_fma_f32 v55, v55, v152, v133
	v_add_f32_e32 v88, v88, v170
	v_add_f32_e32 v92, v92, v171
	v_mul_f32_e32 v132, v92, v155
	v_mul_f32_e32 v171, v88, v155
	v_fma_f32 v170, v88, v154, -v132
	v_fma_f32 v171, v92, v154, v171
	v_add_f32_e32 v89, v89, v172
	v_add_f32_e32 v93, v93, v173
	v_mul_f32_e32 v133, v93, v159
	v_mul_f32_e32 v173, v89, v159
	v_fma_f32 v172, v89, v158, -v133
	v_fma_f32 v173, v93, v158, v173
	v_add_f32_e32 v90, v90, v174
	v_add_f32_e32 v94, v94, v175
	v_mul_f32_e32 v132, v94, v163
	v_mul_f32_e32 v175, v90, v163
	v_fma_f32 v174, v90, v162, -v132
	v_fma_f32 v175, v94, v162, v175
	v_add_f32_e32 v91, v91, v176
	v_add_f32_e32 v95, v95, v177
	v_mul_f32_e32 v133, v95, v167
	v_mul_f32_e32 v177, v91, v167
	v_fma_f32 v176, v91, v166, -v133
	v_fma_f32 v177, v95, v166, v177
	v_mul_f32_e32 v132, v40, v139
	v_mul_f32_e32 v40, v40, v138
	v_fma_f32 v40, -v44, v139, v40
	v_fma_f32 v44, v44, v138, v132
	v_mul_f32_e32 v133, v41, v143
	v_mul_f32_e32 v41, v41, v142
	v_fma_f32 v41, -v45, v143, v41
	v_fma_f32 v45, v45, v142, v133
	v_mul_f32_e32 v132, v42, v147
	v_mul_f32_e32 v42, v42, v146
	v_fma_f32 v42, -v46, v147, v42
	v_fma_f32 v46, v46, v146, v132
	v_mul_f32_e32 v133, v43, v151
	v_mul_f32_e32 v43, v43, v150
	v_fma_f32 v43, -v47, v151, v43
	v_fma_f32 v47, v47, v150, v133
	v_add_f32_dpp v40, v40, v40 row_shl:1 row_mask:0xf bank_mask:0xf bound_ctrl:1
	v_add_f32_dpp v41, v41, v41 row_shl:1 row_mask:0xf bank_mask:0xf bound_ctrl:1
	v_add_f32_dpp v42, v42, v42 row_shl:1 row_mask:0xf bank_mask:0xf bound_ctrl:1
	v_add_f32_dpp v43, v43, v43 row_shl:1 row_mask:0xf bank_mask:0xf bound_ctrl:1
	v_add_f32_dpp v44, v44, v44 row_shl:1 row_mask:0xf bank_mask:0xf bound_ctrl:1
	v_add_f32_dpp v45, v45, v45 row_shl:1 row_mask:0xf bank_mask:0xf bound_ctrl:1
	v_add_f32_dpp v46, v46, v46 row_shl:1 row_mask:0xf bank_mask:0xf bound_ctrl:1
	v_add_f32_dpp v47, v47, v47 row_shl:1 row_mask:0xf bank_mask:0xf bound_ctrl:1
	v_add_f32_dpp v40, v40, v40 row_shl:2 row_mask:0xf bank_mask:0xf bound_ctrl:1
	v_add_f32_dpp v41, v41, v41 row_shl:2 row_mask:0xf bank_mask:0xf bound_ctrl:1
	v_add_f32_dpp v42, v42, v42 row_shl:2 row_mask:0xf bank_mask:0xf bound_ctrl:1
	v_add_f32_dpp v43, v43, v43 row_shl:2 row_mask:0xf bank_mask:0xf bound_ctrl:1
	v_add_f32_dpp v44, v44, v44 row_shl:2 row_mask:0xf bank_mask:0xf bound_ctrl:1
	v_add_f32_dpp v45, v45, v45 row_shl:2 row_mask:0xf bank_mask:0xf bound_ctrl:1
	v_add_f32_dpp v46, v46, v46 row_shl:2 row_mask:0xf bank_mask:0xf bound_ctrl:1
	v_add_f32_dpp v47, v47, v47 row_shl:2 row_mask:0xf bank_mask:0xf bound_ctrl:1
	v_add_f32_dpp v40, v40, v40 row_shl:4 row_mask:0xf bank_mask:0xf bound_ctrl:1
	v_add_f32_dpp v41, v41, v41 row_shl:4 row_mask:0xf bank_mask:0xf bound_ctrl:1
	v_add_f32_dpp v42, v42, v42 row_shl:4 row_mask:0xf bank_mask:0xf bound_ctrl:1
	v_add_f32_dpp v43, v43, v43 row_shl:4 row_mask:0xf bank_mask:0xf bound_ctrl:1
	v_add_f32_dpp v44, v44, v44 row_shl:4 row_mask:0xf bank_mask:0xf bound_ctrl:1
	v_add_f32_dpp v45, v45, v45 row_shl:4 row_mask:0xf bank_mask:0xf bound_ctrl:1
	v_add_f32_dpp v46, v46, v46 row_shl:4 row_mask:0xf bank_mask:0xf bound_ctrl:1
	v_add_f32_dpp v47, v47, v47 row_shl:4 row_mask:0xf bank_mask:0xf bound_ctrl:1
	v_add_f32_dpp v40, v40, v40 row_shl:8 row_mask:0xf bank_mask:0xf bound_ctrl:1
	v_add_f32_dpp v41, v41, v41 row_shl:8 row_mask:0xf bank_mask:0xf bound_ctrl:1
	v_add_f32_dpp v42, v42, v42 row_shl:8 row_mask:0xf bank_mask:0xf bound_ctrl:1
	v_add_f32_dpp v43, v43, v43 row_shl:8 row_mask:0xf bank_mask:0xf bound_ctrl:1
	v_add_f32_dpp v44, v44, v44 row_shl:8 row_mask:0xf bank_mask:0xf bound_ctrl:1
	v_add_f32_dpp v45, v45, v45 row_shl:8 row_mask:0xf bank_mask:0xf bound_ctrl:1
	v_add_f32_dpp v46, v46, v46 row_shl:8 row_mask:0xf bank_mask:0xf bound_ctrl:1
	v_add_f32_dpp v47, v47, v47 row_shl:8 row_mask:0xf bank_mask:0xf bound_ctrl:1
	v_mov_b32_dpp v88, v40 row_newbcast:0 row_mask:0xf bank_mask:0xf
	v_mov_b32_dpp v89, v41 row_newbcast:0 row_mask:0xf bank_mask:0xf
	v_mov_b32_dpp v90, v42 row_newbcast:0 row_mask:0xf bank_mask:0xf
	v_mov_b32_dpp v91, v43 row_newbcast:0 row_mask:0xf bank_mask:0xf
	v_mov_b32_dpp v92, v44 row_newbcast:0 row_mask:0xf bank_mask:0xf
	v_mov_b32_dpp v93, v45 row_newbcast:0 row_mask:0xf bank_mask:0xf
	v_mov_b32_dpp v94, v46 row_newbcast:0 row_mask:0xf bank_mask:0xf
	v_mov_b32_dpp v95, v47 row_newbcast:0 row_mask:0xf bank_mask:0xf
	v_add_f32_e32 v40, v40, v170
	v_add_f32_e32 v44, v44, v171
	v_add_f32_e32 v41, v41, v172
	v_add_f32_e32 v45, v45, v173
	v_add_f32_e32 v42, v42, v174
	v_add_f32_e32 v46, v46, v175
	v_add_f32_e32 v43, v43, v176
	v_add_f32_e32 v47, v47, v177
	v_mul_f32_e32 v132, v40, v141
	v_mul_f32_e32 v40, v40, v140
	v_fma_f32 v40, -v44, v141, v40
	v_fma_f32 v44, v44, v140, v132
	v_mul_f32_e32 v133, v41, v145
	v_mul_f32_e32 v41, v41, v144
	v_fma_f32 v41, -v45, v145, v41
	v_fma_f32 v45, v45, v144, v133
	v_mul_f32_e32 v132, v42, v149
	v_mul_f32_e32 v42, v42, v148
	v_fma_f32 v42, -v46, v149, v42
	v_fma_f32 v46, v46, v148, v132
	v_mul_f32_e32 v133, v43, v153
	v_mul_f32_e32 v43, v43, v152
	v_fma_f32 v43, -v47, v153, v43
	v_fma_f32 v47, v47, v152, v133
	v_add_f32_e32 v88, v88, v170
	v_add_f32_e32 v92, v92, v171
	v_mul_f32_e32 v132, v92, v155
	v_mul_f32_e32 v171, v88, v155
	v_fma_f32 v170, v88, v154, -v132
	v_fma_f32 v171, v92, v154, v171
	v_add_f32_e32 v89, v89, v172
	v_add_f32_e32 v93, v93, v173
	v_mul_f32_e32 v133, v93, v159
	v_mul_f32_e32 v173, v89, v159
	v_fma_f32 v172, v89, v158, -v133
	v_fma_f32 v173, v93, v158, v173
	v_add_f32_e32 v90, v90, v174
	v_add_f32_e32 v94, v94, v175
	v_mul_f32_e32 v132, v94, v163
	v_mul_f32_e32 v175, v90, v163
	v_fma_f32 v174, v90, v162, -v132
	v_fma_f32 v175, v94, v162, v175
	v_add_f32_e32 v91, v91, v176
	v_add_f32_e32 v95, v95, v177
	v_mul_f32_e32 v133, v95, v167
	v_mul_f32_e32 v177, v91, v167
	v_fma_f32 v176, v91, v166, -v133
	v_fma_f32 v177, v95, v166, v177
	v_mul_f32_e32 v132, v32, v139
	v_mul_f32_e32 v32, v32, v138
	v_fma_f32 v32, -v36, v139, v32
	v_fma_f32 v36, v36, v138, v132
	v_mul_f32_e32 v133, v33, v143
	v_mul_f32_e32 v33, v33, v142
	v_fma_f32 v33, -v37, v143, v33
	v_fma_f32 v37, v37, v142, v133
	v_mul_f32_e32 v132, v34, v147
	v_mul_f32_e32 v34, v34, v146
	v_fma_f32 v34, -v38, v147, v34
	v_fma_f32 v38, v38, v146, v132
	v_mul_f32_e32 v133, v35, v151
	v_mul_f32_e32 v35, v35, v150
	v_fma_f32 v35, -v39, v151, v35
	v_fma_f32 v39, v39, v150, v133
	v_add_f32_dpp v32, v32, v32 row_shl:1 row_mask:0xf bank_mask:0xf bound_ctrl:1
	v_add_f32_dpp v33, v33, v33 row_shl:1 row_mask:0xf bank_mask:0xf bound_ctrl:1
	v_add_f32_dpp v34, v34, v34 row_shl:1 row_mask:0xf bank_mask:0xf bound_ctrl:1
	v_add_f32_dpp v35, v35, v35 row_shl:1 row_mask:0xf bank_mask:0xf bound_ctrl:1
	v_add_f32_dpp v36, v36, v36 row_shl:1 row_mask:0xf bank_mask:0xf bound_ctrl:1
	v_add_f32_dpp v37, v37, v37 row_shl:1 row_mask:0xf bank_mask:0xf bound_ctrl:1
	v_add_f32_dpp v38, v38, v38 row_shl:1 row_mask:0xf bank_mask:0xf bound_ctrl:1
	v_add_f32_dpp v39, v39, v39 row_shl:1 row_mask:0xf bank_mask:0xf bound_ctrl:1
	v_add_f32_dpp v32, v32, v32 row_shl:2 row_mask:0xf bank_mask:0xf bound_ctrl:1
	v_add_f32_dpp v33, v33, v33 row_shl:2 row_mask:0xf bank_mask:0xf bound_ctrl:1
	v_add_f32_dpp v34, v34, v34 row_shl:2 row_mask:0xf bank_mask:0xf bound_ctrl:1
	v_add_f32_dpp v35, v35, v35 row_shl:2 row_mask:0xf bank_mask:0xf bound_ctrl:1
	v_add_f32_dpp v36, v36, v36 row_shl:2 row_mask:0xf bank_mask:0xf bound_ctrl:1
	v_add_f32_dpp v37, v37, v37 row_shl:2 row_mask:0xf bank_mask:0xf bound_ctrl:1
	v_add_f32_dpp v38, v38, v38 row_shl:2 row_mask:0xf bank_mask:0xf bound_ctrl:1
	v_add_f32_dpp v39, v39, v39 row_shl:2 row_mask:0xf bank_mask:0xf bound_ctrl:1
	v_add_f32_dpp v32, v32, v32 row_shl:4 row_mask:0xf bank_mask:0xf bound_ctrl:1
	v_add_f32_dpp v33, v33, v33 row_shl:4 row_mask:0xf bank_mask:0xf bound_ctrl:1
	v_add_f32_dpp v34, v34, v34 row_shl:4 row_mask:0xf bank_mask:0xf bound_ctrl:1
	v_add_f32_dpp v35, v35, v35 row_shl:4 row_mask:0xf bank_mask:0xf bound_ctrl:1
	v_add_f32_dpp v36, v36, v36 row_shl:4 row_mask:0xf bank_mask:0xf bound_ctrl:1
	v_add_f32_dpp v37, v37, v37 row_shl:4 row_mask:0xf bank_mask:0xf bound_ctrl:1
	v_add_f32_dpp v38, v38, v38 row_shl:4 row_mask:0xf bank_mask:0xf bound_ctrl:1
	v_add_f32_dpp v39, v39, v39 row_shl:4 row_mask:0xf bank_mask:0xf bound_ctrl:1
	v_add_f32_dpp v32, v32, v32 row_shl:8 row_mask:0xf bank_mask:0xf bound_ctrl:1
	v_add_f32_dpp v33, v33, v33 row_shl:8 row_mask:0xf bank_mask:0xf bound_ctrl:1
	v_add_f32_dpp v34, v34, v34 row_shl:8 row_mask:0xf bank_mask:0xf bound_ctrl:1
	v_add_f32_dpp v35, v35, v35 row_shl:8 row_mask:0xf bank_mask:0xf bound_ctrl:1
	v_add_f32_dpp v36, v36, v36 row_shl:8 row_mask:0xf bank_mask:0xf bound_ctrl:1
	v_add_f32_dpp v37, v37, v37 row_shl:8 row_mask:0xf bank_mask:0xf bound_ctrl:1
	v_add_f32_dpp v38, v38, v38 row_shl:8 row_mask:0xf bank_mask:0xf bound_ctrl:1
	v_add_f32_dpp v39, v39, v39 row_shl:8 row_mask:0xf bank_mask:0xf bound_ctrl:1
	v_mov_b32_dpp v88, v32 row_newbcast:0 row_mask:0xf bank_mask:0xf
	v_mov_b32_dpp v89, v33 row_newbcast:0 row_mask:0xf bank_mask:0xf
	v_mov_b32_dpp v90, v34 row_newbcast:0 row_mask:0xf bank_mask:0xf
	v_mov_b32_dpp v91, v35 row_newbcast:0 row_mask:0xf bank_mask:0xf
	v_mov_b32_dpp v92, v36 row_newbcast:0 row_mask:0xf bank_mask:0xf
	v_mov_b32_dpp v93, v37 row_newbcast:0 row_mask:0xf bank_mask:0xf
	v_mov_b32_dpp v94, v38 row_newbcast:0 row_mask:0xf bank_mask:0xf
	v_mov_b32_dpp v95, v39 row_newbcast:0 row_mask:0xf bank_mask:0xf
	v_add_f32_e32 v32, v32, v170
	v_add_f32_e32 v36, v36, v171
	v_add_f32_e32 v33, v33, v172
	v_add_f32_e32 v37, v37, v173
	v_add_f32_e32 v34, v34, v174
	v_add_f32_e32 v38, v38, v175
	v_add_f32_e32 v35, v35, v176
	v_add_f32_e32 v39, v39, v177
	v_mul_f32_e32 v132, v32, v141
	v_mul_f32_e32 v32, v32, v140
	v_fma_f32 v32, -v36, v141, v32
	v_fma_f32 v36, v36, v140, v132
	v_mul_f32_e32 v133, v33, v145
	v_mul_f32_e32 v33, v33, v144
	v_fma_f32 v33, -v37, v145, v33
	v_fma_f32 v37, v37, v144, v133
	v_mul_f32_e32 v132, v34, v149
	v_mul_f32_e32 v34, v34, v148
	v_fma_f32 v34, -v38, v149, v34
	v_fma_f32 v38, v38, v148, v132
	v_mul_f32_e32 v133, v35, v153
	v_mul_f32_e32 v35, v35, v152
	v_fma_f32 v35, -v39, v153, v35
	v_fma_f32 v39, v39, v152, v133
	v_add_f32_e32 v88, v88, v170
	v_add_f32_e32 v92, v92, v171
	v_mul_f32_e32 v132, v92, v155
	v_mul_f32_e32 v171, v88, v155
	v_fma_f32 v170, v88, v154, -v132
	v_fma_f32 v171, v92, v154, v171
	v_add_f32_e32 v89, v89, v172
	v_add_f32_e32 v93, v93, v173
	v_mul_f32_e32 v133, v93, v159
	v_mul_f32_e32 v173, v89, v159
	v_fma_f32 v172, v89, v158, -v133
	v_fma_f32 v173, v93, v158, v173
	v_add_f32_e32 v90, v90, v174
	v_add_f32_e32 v94, v94, v175
	v_mul_f32_e32 v132, v94, v163
	v_mul_f32_e32 v175, v90, v163
	v_fma_f32 v174, v90, v162, -v132
	v_fma_f32 v175, v94, v162, v175
	v_add_f32_e32 v91, v91, v176
	v_add_f32_e32 v95, v95, v177
	v_mul_f32_e32 v133, v95, v167
	v_mul_f32_e32 v177, v91, v167
	v_fma_f32 v176, v91, v166, -v133
	v_fma_f32 v177, v95, v166, v177
	s_waitcnt vmcnt(12)
	v_cvt_pk_bf16_f32 v96, v32, v33
	v_cvt_pk_bf16_f32 v97, v34, v35
	v_cvt_pk_bf16_f32 v98, v36, v37
	v_cvt_pk_bf16_f32 v99, v38, v39
	s_nop 1
	v_mfma_f32_16x16x32_bf16 v[16:19], v[80:83], v[96:99], v[16:19]
	v_cvt_pk_bf16_f32 v96, v40, v41
	v_cvt_pk_bf16_f32 v97, v42, v43
	v_cvt_pk_bf16_f32 v98, v44, v45
	v_cvt_pk_bf16_f32 v99, v46, v47
	s_nop 1
	v_mfma_f32_16x16x32_bf16 v[20:23], v[80:83], v[96:99], v[20:23]
	v_cvt_pk_bf16_f32 v96, v48, v49
	v_cvt_pk_bf16_f32 v97, v50, v51
	v_cvt_pk_bf16_f32 v98, v52, v53
	v_cvt_pk_bf16_f32 v99, v54, v55
	s_nop 1
	v_mfma_f32_16x16x32_bf16 v[24:27], v[80:83], v[96:99], v[24:27]
	v_cvt_pk_bf16_f32 v96, v56, v57
	v_cvt_pk_bf16_f32 v97, v58, v59
	v_cvt_pk_bf16_f32 v98, v60, v61
	v_cvt_pk_bf16_f32 v99, v62, v63
	s_nop 1
	v_mfma_f32_16x16x32_bf16 v[28:31], v[80:83], v[96:99], v[28:31]
	s_waitcnt vmcnt(10)
	global_load_dwordx4 v[80:83], v134, s[38:39]
	s_add_u32 s38, s38, 0x400
	s_addc_u32 s39, s39, 0
	v_mfma_f32_16x16x32_bf16 v[32:35], v[64:67], v[0:3], 0
	v_mfma_f32_16x16x32_bf16 v[36:39], v[72:75], v[0:3], 0
	v_mfma_f32_16x16x32_bf16 v[40:43], v[64:67], v[4:7], 0
	v_mfma_f32_16x16x32_bf16 v[44:47], v[72:75], v[4:7], 0
	v_mfma_f32_16x16x32_bf16 v[48:51], v[64:67], v[8:11], 0
	v_mfma_f32_16x16x32_bf16 v[52:55], v[72:75], v[8:11], 0
	v_mfma_f32_16x16x32_bf16 v[56:59], v[64:67], v[12:15], 0
	v_mfma_f32_16x16x32_bf16 v[60:63], v[72:75], v[12:15], 0
	global_load_dwordx4 v[64:67], v134, s[20:21]
	global_load_dwordx4 v[72:75], v134, s[20:21] offset:1024
	s_add_u32 s20, s20, 0x800
	s_addc_u32 s21, s21, 0
	global_load_dwordx4 v[138:141], v134, s[42:43] offset:0
	global_load_dwordx4 v[142:145], v134, s[42:43] offset:1024
	global_load_dwordx4 v[146:149], v134, s[42:43] offset:2048
	global_load_dwordx4 v[150:153], v134, s[42:43] offset:3072
	global_load_dwordx4 v[154:157], v208, s[42:43] offset:0
	global_load_dwordx4 v[158:161], v208, s[42:43] offset:1024
	global_load_dwordx4 v[162:165], v208, s[42:43] offset:2048
	global_load_dwordx4 v[166:169], v208, s[42:43] offset:3072
	global_load_dwordx4 v[170:173], v206, s[44:45]
	global_load_dwordx4 v[174:177], v206, s[44:45] offset:16
	s_add_u32 s42, s42, 0x2000
	s_addc_u32 s43, s43, 0
	s_add_u32 s44, s44, 0x80
	s_addc_u32 s45, s45, 0
	s_waitcnt vmcnt(13)
	v_mul_f32_e32 v132, v179, v119
	v_mul_f32_e32 v133, v178, v119
	v_fma_f32 v178, v178, v118, -v132
	v_fma_f32 v179, v179, v118, v133
	v_mul_f32_e32 v132, v181, v123
	v_mul_f32_e32 v133, v180, v123
	v_fma_f32 v180, v180, v122, -v132
	v_fma_f32 v181, v181, v122, v133
	v_mul_f32_e32 v132, v183, v127
	v_mul_f32_e32 v133, v182, v127
	v_fma_f32 v182, v182, v126, -v132
	v_fma_f32 v183, v183, v126, v133
	v_mul_f32_e32 v132, v185, v131
	v_mul_f32_e32 v133, v184, v131
	v_fma_f32 v184, v184, v130, -v132
	v_fma_f32 v185, v185, v130, v133
	v_mul_f32_e32 v132, v56, v101
	v_mul_f32_e32 v56, v56, v100
	v_fma_f32 v56, -v60, v101, v56
	v_fma_f32 v60, v60, v100, v132
	v_mul_f32_e32 v133, v57, v105
	v_mul_f32_e32 v57, v57, v104
	v_fma_f32 v57, -v61, v105, v57
	v_fma_f32 v61, v61, v104, v133
	v_mul_f32_e32 v132, v58, v109
	v_mul_f32_e32 v58, v58, v108
	v_fma_f32 v58, -v62, v109, v58
	v_fma_f32 v62, v62, v108, v132
	v_mul_f32_e32 v133, v59, v113
	v_mul_f32_e32 v59, v59, v112
	v_fma_f32 v59, -v63, v113, v59
	v_fma_f32 v63, v63, v112, v133
	v_add_f32_dpp v56, v56, v56 row_shl:1 row_mask:0xf bank_mask:0xf bound_ctrl:1
	v_add_f32_dpp v57, v57, v57 row_shl:1 row_mask:0xf bank_mask:0xf bound_ctrl:1
	v_add_f32_dpp v58, v58, v58 row_shl:1 row_mask:0xf bank_mask:0xf bound_ctrl:1
	v_add_f32_dpp v59, v59, v59 row_shl:1 row_mask:0xf bank_mask:0xf bound_ctrl:1
	v_add_f32_dpp v60, v60, v60 row_shl:1 row_mask:0xf bank_mask:0xf bound_ctrl:1
	v_add_f32_dpp v61, v61, v61 row_shl:1 row_mask:0xf bank_mask:0xf bound_ctrl:1
	v_add_f32_dpp v62, v62, v62 row_shl:1 row_mask:0xf bank_mask:0xf bound_ctrl:1
	v_add_f32_dpp v63, v63, v63 row_shl:1 row_mask:0xf bank_mask:0xf bound_ctrl:1
	v_add_f32_dpp v56, v56, v56 row_shl:2 row_mask:0xf bank_mask:0xf bound_ctrl:1
	v_add_f32_dpp v57, v57, v57 row_shl:2 row_mask:0xf bank_mask:0xf bound_ctrl:1
	v_add_f32_dpp v58, v58, v58 row_shl:2 row_mask:0xf bank_mask:0xf bound_ctrl:1
	v_add_f32_dpp v59, v59, v59 row_shl:2 row_mask:0xf bank_mask:0xf bound_ctrl:1
	v_add_f32_dpp v60, v60, v60 row_shl:2 row_mask:0xf bank_mask:0xf bound_ctrl:1
	v_add_f32_dpp v61, v61, v61 row_shl:2 row_mask:0xf bank_mask:0xf bound_ctrl:1
	v_add_f32_dpp v62, v62, v62 row_shl:2 row_mask:0xf bank_mask:0xf bound_ctrl:1
	v_add_f32_dpp v63, v63, v63 row_shl:2 row_mask:0xf bank_mask:0xf bound_ctrl:1
	v_add_f32_dpp v56, v56, v56 row_shl:4 row_mask:0xf bank_mask:0xf bound_ctrl:1
	v_add_f32_dpp v57, v57, v57 row_shl:4 row_mask:0xf bank_mask:0xf bound_ctrl:1
	v_add_f32_dpp v58, v58, v58 row_shl:4 row_mask:0xf bank_mask:0xf bound_ctrl:1
	v_add_f32_dpp v59, v59, v59 row_shl:4 row_mask:0xf bank_mask:0xf bound_ctrl:1
	v_add_f32_dpp v60, v60, v60 row_shl:4 row_mask:0xf bank_mask:0xf bound_ctrl:1
	v_add_f32_dpp v61, v61, v61 row_shl:4 row_mask:0xf bank_mask:0xf bound_ctrl:1
	v_add_f32_dpp v62, v62, v62 row_shl:4 row_mask:0xf bank_mask:0xf bound_ctrl:1
	v_add_f32_dpp v63, v63, v63 row_shl:4 row_mask:0xf bank_mask:0xf bound_ctrl:1
	v_add_f32_dpp v56, v56, v56 row_shl:8 row_mask:0xf bank_mask:0xf bound_ctrl:1
	v_add_f32_dpp v57, v57, v57 row_shl:8 row_mask:0xf bank_mask:0xf bound_ctrl:1
	v_add_f32_dpp v58, v58, v58 row_shl:8 row_mask:0xf bank_mask:0xf bound_ctrl:1
	v_add_f32_dpp v59, v59, v59 row_shl:8 row_mask:0xf bank_mask:0xf bound_ctrl:1
	v_add_f32_dpp v60, v60, v60 row_shl:8 row_mask:0xf bank_mask:0xf bound_ctrl:1
	v_add_f32_dpp v61, v61, v61 row_shl:8 row_mask:0xf bank_mask:0xf bound_ctrl:1
	v_add_f32_dpp v62, v62, v62 row_shl:8 row_mask:0xf bank_mask:0xf bound_ctrl:1
	v_add_f32_dpp v63, v63, v63 row_shl:8 row_mask:0xf bank_mask:0xf bound_ctrl:1
	v_mov_b32_dpp v88, v56 row_newbcast:0 row_mask:0xf bank_mask:0xf
	v_mov_b32_dpp v89, v57 row_newbcast:0 row_mask:0xf bank_mask:0xf
	v_mov_b32_dpp v90, v58 row_newbcast:0 row_mask:0xf bank_mask:0xf
	v_mov_b32_dpp v91, v59 row_newbcast:0 row_mask:0xf bank_mask:0xf
	v_mov_b32_dpp v92, v60 row_newbcast:0 row_mask:0xf bank_mask:0xf
	v_mov_b32_dpp v93, v61 row_newbcast:0 row_mask:0xf bank_mask:0xf
	v_mov_b32_dpp v94, v62 row_newbcast:0 row_mask:0xf bank_mask:0xf
	v_mov_b32_dpp v95, v63 row_newbcast:0 row_mask:0xf bank_mask:0xf
	v_add_f32_e32 v56, v56, v178
	v_add_f32_e32 v60, v60, v179
	v_add_f32_e32 v57, v57, v180
	v_add_f32_e32 v61, v61, v181
	v_add_f32_e32 v58, v58, v182
	v_add_f32_e32 v62, v62, v183
	v_add_f32_e32 v59, v59, v184
	v_add_f32_e32 v63, v63, v185
	v_mul_f32_e32 v132, v56, v103
	v_mul_f32_e32 v56, v56, v102
	v_fma_f32 v56, -v60, v103, v56
	v_fma_f32 v60, v60, v102, v132
	v_mul_f32_e32 v133, v57, v107
	v_mul_f32_e32 v57, v57, v106
	v_fma_f32 v57, -v61, v107, v57
	v_fma_f32 v61, v61, v106, v133
	v_mul_f32_e32 v132, v58, v111
	v_mul_f32_e32 v58, v58, v110
	v_fma_f32 v58, -v62, v111, v58
	v_fma_f32 v62, v62, v110, v132
	v_mul_f32_e32 v133, v59, v115
	v_mul_f32_e32 v59, v59, v114
	v_fma_f32 v59, -v63, v115, v59
	v_fma_f32 v63, v63, v114, v133
	v_add_f32_e32 v88, v88, v178
	v_add_f32_e32 v92, v92, v179
	v_mul_f32_e32 v132, v92, v117
	v_mul_f32_e32 v179, v88, v117
	v_fma_f32 v178, v88, v116, -v132
	v_fma_f32 v179, v92, v116, v179
	v_add_f32_e32 v89, v89, v180
	v_add_f32_e32 v93, v93, v181
	v_mul_f32_e32 v133, v93, v121
	v_mul_f32_e32 v181, v89, v121
	v_fma_f32 v180, v89, v120, -v133
	v_fma_f32 v181, v93, v120, v181
	v_add_f32_e32 v90, v90, v182
	v_add_f32_e32 v94, v94, v183
	v_mul_f32_e32 v132, v94, v125
	v_mul_f32_e32 v183, v90, v125
	v_fma_f32 v182, v90, v124, -v132
	v_fma_f32 v183, v94, v124, v183
	v_add_f32_e32 v91, v91, v184
	v_add_f32_e32 v95, v95, v185
	v_mul_f32_e32 v133, v95, v129
	v_mul_f32_e32 v185, v91, v129
	v_fma_f32 v184, v91, v128, -v133
	v_fma_f32 v185, v95, v128, v185
	v_mul_f32_e32 v132, v48, v101
	v_mul_f32_e32 v48, v48, v100
	v_fma_f32 v48, -v52, v101, v48
	v_fma_f32 v52, v52, v100, v132
	v_mul_f32_e32 v133, v49, v105
	v_mul_f32_e32 v49, v49, v104
	v_fma_f32 v49, -v53, v105, v49
	v_fma_f32 v53, v53, v104, v133
	v_mul_f32_e32 v132, v50, v109
	v_mul_f32_e32 v50, v50, v108
	v_fma_f32 v50, -v54, v109, v50
	v_fma_f32 v54, v54, v108, v132
	v_mul_f32_e32 v133, v51, v113
	v_mul_f32_e32 v51, v51, v112
	v_fma_f32 v51, -v55, v113, v51
	v_fma_f32 v55, v55, v112, v133
	v_add_f32_dpp v48, v48, v48 row_shl:1 row_mask:0xf bank_mask:0xf bound_ctrl:1
	v_add_f32_dpp v49, v49, v49 row_shl:1 row_mask:0xf bank_mask:0xf bound_ctrl:1
	v_add_f32_dpp v50, v50, v50 row_shl:1 row_mask:0xf bank_mask:0xf bound_ctrl:1
	v_add_f32_dpp v51, v51, v51 row_shl:1 row_mask:0xf bank_mask:0xf bound_ctrl:1
	v_add_f32_dpp v52, v52, v52 row_shl:1 row_mask:0xf bank_mask:0xf bound_ctrl:1
	v_add_f32_dpp v53, v53, v53 row_shl:1 row_mask:0xf bank_mask:0xf bound_ctrl:1
	v_add_f32_dpp v54, v54, v54 row_shl:1 row_mask:0xf bank_mask:0xf bound_ctrl:1
	v_add_f32_dpp v55, v55, v55 row_shl:1 row_mask:0xf bank_mask:0xf bound_ctrl:1
	v_add_f32_dpp v48, v48, v48 row_shl:2 row_mask:0xf bank_mask:0xf bound_ctrl:1
	v_add_f32_dpp v49, v49, v49 row_shl:2 row_mask:0xf bank_mask:0xf bound_ctrl:1
	v_add_f32_dpp v50, v50, v50 row_shl:2 row_mask:0xf bank_mask:0xf bound_ctrl:1
	v_add_f32_dpp v51, v51, v51 row_shl:2 row_mask:0xf bank_mask:0xf bound_ctrl:1
	v_add_f32_dpp v52, v52, v52 row_shl:2 row_mask:0xf bank_mask:0xf bound_ctrl:1
	v_add_f32_dpp v53, v53, v53 row_shl:2 row_mask:0xf bank_mask:0xf bound_ctrl:1
	v_add_f32_dpp v54, v54, v54 row_shl:2 row_mask:0xf bank_mask:0xf bound_ctrl:1
	v_add_f32_dpp v55, v55, v55 row_shl:2 row_mask:0xf bank_mask:0xf bound_ctrl:1
	v_add_f32_dpp v48, v48, v48 row_shl:4 row_mask:0xf bank_mask:0xf bound_ctrl:1
	v_add_f32_dpp v49, v49, v49 row_shl:4 row_mask:0xf bank_mask:0xf bound_ctrl:1
	v_add_f32_dpp v50, v50, v50 row_shl:4 row_mask:0xf bank_mask:0xf bound_ctrl:1
	v_add_f32_dpp v51, v51, v51 row_shl:4 row_mask:0xf bank_mask:0xf bound_ctrl:1
	v_add_f32_dpp v52, v52, v52 row_shl:4 row_mask:0xf bank_mask:0xf bound_ctrl:1
	v_add_f32_dpp v53, v53, v53 row_shl:4 row_mask:0xf bank_mask:0xf bound_ctrl:1
	v_add_f32_dpp v54, v54, v54 row_shl:4 row_mask:0xf bank_mask:0xf bound_ctrl:1
	v_add_f32_dpp v55, v55, v55 row_shl:4 row_mask:0xf bank_mask:0xf bound_ctrl:1
	v_add_f32_dpp v48, v48, v48 row_shl:8 row_mask:0xf bank_mask:0xf bound_ctrl:1
	v_add_f32_dpp v49, v49, v49 row_shl:8 row_mask:0xf bank_mask:0xf bound_ctrl:1
	v_add_f32_dpp v50, v50, v50 row_shl:8 row_mask:0xf bank_mask:0xf bound_ctrl:1
	v_add_f32_dpp v51, v51, v51 row_shl:8 row_mask:0xf bank_mask:0xf bound_ctrl:1
	v_add_f32_dpp v52, v52, v52 row_shl:8 row_mask:0xf bank_mask:0xf bound_ctrl:1
	v_add_f32_dpp v53, v53, v53 row_shl:8 row_mask:0xf bank_mask:0xf bound_ctrl:1
	v_add_f32_dpp v54, v54, v54 row_shl:8 row_mask:0xf bank_mask:0xf bound_ctrl:1
	v_add_f32_dpp v55, v55, v55 row_shl:8 row_mask:0xf bank_mask:0xf bound_ctrl:1
	v_mov_b32_dpp v88, v48 row_newbcast:0 row_mask:0xf bank_mask:0xf
	v_mov_b32_dpp v89, v49 row_newbcast:0 row_mask:0xf bank_mask:0xf
	v_mov_b32_dpp v90, v50 row_newbcast:0 row_mask:0xf bank_mask:0xf
	v_mov_b32_dpp v91, v51 row_newbcast:0 row_mask:0xf bank_mask:0xf
	v_mov_b32_dpp v92, v52 row_newbcast:0 row_mask:0xf bank_mask:0xf
	v_mov_b32_dpp v93, v53 row_newbcast:0 row_mask:0xf bank_mask:0xf
	v_mov_b32_dpp v94, v54 row_newbcast:0 row_mask:0xf bank_mask:0xf
	v_mov_b32_dpp v95, v55 row_newbcast:0 row_mask:0xf bank_mask:0xf
	v_add_f32_e32 v48, v48, v178
	v_add_f32_e32 v52, v52, v179
	v_add_f32_e32 v49, v49, v180
	v_add_f32_e32 v53, v53, v181
	v_add_f32_e32 v50, v50, v182
	v_add_f32_e32 v54, v54, v183
	v_add_f32_e32 v51, v51, v184
	v_add_f32_e32 v55, v55, v185
	v_mul_f32_e32 v132, v48, v103
	v_mul_f32_e32 v48, v48, v102
	v_fma_f32 v48, -v52, v103, v48
	v_fma_f32 v52, v52, v102, v132
	v_mul_f32_e32 v133, v49, v107
	v_mul_f32_e32 v49, v49, v106
	v_fma_f32 v49, -v53, v107, v49
	v_fma_f32 v53, v53, v106, v133
	v_mul_f32_e32 v132, v50, v111
	v_mul_f32_e32 v50, v50, v110
	v_fma_f32 v50, -v54, v111, v50
	v_fma_f32 v54, v54, v110, v132
	v_mul_f32_e32 v133, v51, v115
	v_mul_f32_e32 v51, v51, v114
	v_fma_f32 v51, -v55, v115, v51
	v_fma_f32 v55, v55, v114, v133
	v_add_f32_e32 v88, v88, v178
	v_add_f32_e32 v92, v92, v179
	v_mul_f32_e32 v132, v92, v117
	v_mul_f32_e32 v179, v88, v117
	v_fma_f32 v178, v88, v116, -v132
	v_fma_f32 v179, v92, v116, v179
	v_add_f32_e32 v89, v89, v180
	v_add_f32_e32 v93, v93, v181
	v_mul_f32_e32 v133, v93, v121
	v_mul_f32_e32 v181, v89, v121
	v_fma_f32 v180, v89, v120, -v133
	v_fma_f32 v181, v93, v120, v181
	v_add_f32_e32 v90, v90, v182
	v_add_f32_e32 v94, v94, v183
	v_mul_f32_e32 v132, v94, v125
	v_mul_f32_e32 v183, v90, v125
	v_fma_f32 v182, v90, v124, -v132
	v_fma_f32 v183, v94, v124, v183
	v_add_f32_e32 v91, v91, v184
	v_add_f32_e32 v95, v95, v185
	v_mul_f32_e32 v133, v95, v129
	v_mul_f32_e32 v185, v91, v129
	v_fma_f32 v184, v91, v128, -v133
	v_fma_f32 v185, v95, v128, v185
	v_mul_f32_e32 v132, v40, v101
	v_mul_f32_e32 v40, v40, v100
	v_fma_f32 v40, -v44, v101, v40
	v_fma_f32 v44, v44, v100, v132
	v_mul_f32_e32 v133, v41, v105
	v_mul_f32_e32 v41, v41, v104
	v_fma_f32 v41, -v45, v105, v41
	v_fma_f32 v45, v45, v104, v133
	v_mul_f32_e32 v132, v42, v109
	v_mul_f32_e32 v42, v42, v108
	v_fma_f32 v42, -v46, v109, v42
	v_fma_f32 v46, v46, v108, v132
	v_mul_f32_e32 v133, v43, v113
	v_mul_f32_e32 v43, v43, v112
	v_fma_f32 v43, -v47, v113, v43
	v_fma_f32 v47, v47, v112, v133
	v_add_f32_dpp v40, v40, v40 row_shl:1 row_mask:0xf bank_mask:0xf bound_ctrl:1
	v_add_f32_dpp v41, v41, v41 row_shl:1 row_mask:0xf bank_mask:0xf bound_ctrl:1
	v_add_f32_dpp v42, v42, v42 row_shl:1 row_mask:0xf bank_mask:0xf bound_ctrl:1
	v_add_f32_dpp v43, v43, v43 row_shl:1 row_mask:0xf bank_mask:0xf bound_ctrl:1
	v_add_f32_dpp v44, v44, v44 row_shl:1 row_mask:0xf bank_mask:0xf bound_ctrl:1
	v_add_f32_dpp v45, v45, v45 row_shl:1 row_mask:0xf bank_mask:0xf bound_ctrl:1
	v_add_f32_dpp v46, v46, v46 row_shl:1 row_mask:0xf bank_mask:0xf bound_ctrl:1
	v_add_f32_dpp v47, v47, v47 row_shl:1 row_mask:0xf bank_mask:0xf bound_ctrl:1
	v_add_f32_dpp v40, v40, v40 row_shl:2 row_mask:0xf bank_mask:0xf bound_ctrl:1
	v_add_f32_dpp v41, v41, v41 row_shl:2 row_mask:0xf bank_mask:0xf bound_ctrl:1
	v_add_f32_dpp v42, v42, v42 row_shl:2 row_mask:0xf bank_mask:0xf bound_ctrl:1
	v_add_f32_dpp v43, v43, v43 row_shl:2 row_mask:0xf bank_mask:0xf bound_ctrl:1
	v_add_f32_dpp v44, v44, v44 row_shl:2 row_mask:0xf bank_mask:0xf bound_ctrl:1
	v_add_f32_dpp v45, v45, v45 row_shl:2 row_mask:0xf bank_mask:0xf bound_ctrl:1
	v_add_f32_dpp v46, v46, v46 row_shl:2 row_mask:0xf bank_mask:0xf bound_ctrl:1
	v_add_f32_dpp v47, v47, v47 row_shl:2 row_mask:0xf bank_mask:0xf bound_ctrl:1
	v_add_f32_dpp v40, v40, v40 row_shl:4 row_mask:0xf bank_mask:0xf bound_ctrl:1
	v_add_f32_dpp v41, v41, v41 row_shl:4 row_mask:0xf bank_mask:0xf bound_ctrl:1
	v_add_f32_dpp v42, v42, v42 row_shl:4 row_mask:0xf bank_mask:0xf bound_ctrl:1
	v_add_f32_dpp v43, v43, v43 row_shl:4 row_mask:0xf bank_mask:0xf bound_ctrl:1
	v_add_f32_dpp v44, v44, v44 row_shl:4 row_mask:0xf bank_mask:0xf bound_ctrl:1
	v_add_f32_dpp v45, v45, v45 row_shl:4 row_mask:0xf bank_mask:0xf bound_ctrl:1
	v_add_f32_dpp v46, v46, v46 row_shl:4 row_mask:0xf bank_mask:0xf bound_ctrl:1
	v_add_f32_dpp v47, v47, v47 row_shl:4 row_mask:0xf bank_mask:0xf bound_ctrl:1
	v_add_f32_dpp v40, v40, v40 row_shl:8 row_mask:0xf bank_mask:0xf bound_ctrl:1
	v_add_f32_dpp v41, v41, v41 row_shl:8 row_mask:0xf bank_mask:0xf bound_ctrl:1
	v_add_f32_dpp v42, v42, v42 row_shl:8 row_mask:0xf bank_mask:0xf bound_ctrl:1
	v_add_f32_dpp v43, v43, v43 row_shl:8 row_mask:0xf bank_mask:0xf bound_ctrl:1
	v_add_f32_dpp v44, v44, v44 row_shl:8 row_mask:0xf bank_mask:0xf bound_ctrl:1
	v_add_f32_dpp v45, v45, v45 row_shl:8 row_mask:0xf bank_mask:0xf bound_ctrl:1
	v_add_f32_dpp v46, v46, v46 row_shl:8 row_mask:0xf bank_mask:0xf bound_ctrl:1
	v_add_f32_dpp v47, v47, v47 row_shl:8 row_mask:0xf bank_mask:0xf bound_ctrl:1
	v_mov_b32_dpp v88, v40 row_newbcast:0 row_mask:0xf bank_mask:0xf
	v_mov_b32_dpp v89, v41 row_newbcast:0 row_mask:0xf bank_mask:0xf
	v_mov_b32_dpp v90, v42 row_newbcast:0 row_mask:0xf bank_mask:0xf
	v_mov_b32_dpp v91, v43 row_newbcast:0 row_mask:0xf bank_mask:0xf
	v_mov_b32_dpp v92, v44 row_newbcast:0 row_mask:0xf bank_mask:0xf
	v_mov_b32_dpp v93, v45 row_newbcast:0 row_mask:0xf bank_mask:0xf
	v_mov_b32_dpp v94, v46 row_newbcast:0 row_mask:0xf bank_mask:0xf
	v_mov_b32_dpp v95, v47 row_newbcast:0 row_mask:0xf bank_mask:0xf
	v_add_f32_e32 v40, v40, v178
	v_add_f32_e32 v44, v44, v179
	v_add_f32_e32 v41, v41, v180
	v_add_f32_e32 v45, v45, v181
	v_add_f32_e32 v42, v42, v182
	v_add_f32_e32 v46, v46, v183
	v_add_f32_e32 v43, v43, v184
	v_add_f32_e32 v47, v47, v185
	v_mul_f32_e32 v132, v40, v103
	v_mul_f32_e32 v40, v40, v102
	v_fma_f32 v40, -v44, v103, v40
	v_fma_f32 v44, v44, v102, v132
	v_mul_f32_e32 v133, v41, v107
	v_mul_f32_e32 v41, v41, v106
	v_fma_f32 v41, -v45, v107, v41
	v_fma_f32 v45, v45, v106, v133
	v_mul_f32_e32 v132, v42, v111
	v_mul_f32_e32 v42, v42, v110
	v_fma_f32 v42, -v46, v111, v42
	v_fma_f32 v46, v46, v110, v132
	v_mul_f32_e32 v133, v43, v115
	v_mul_f32_e32 v43, v43, v114
	v_fma_f32 v43, -v47, v115, v43
	v_fma_f32 v47, v47, v114, v133
	v_add_f32_e32 v88, v88, v178
	v_add_f32_e32 v92, v92, v179
	v_mul_f32_e32 v132, v92, v117
	v_mul_f32_e32 v179, v88, v117
	v_fma_f32 v178, v88, v116, -v132
	v_fma_f32 v179, v92, v116, v179
	v_add_f32_e32 v89, v89, v180
	v_add_f32_e32 v93, v93, v181
	v_mul_f32_e32 v133, v93, v121
	v_mul_f32_e32 v181, v89, v121
	v_fma_f32 v180, v89, v120, -v133
	v_fma_f32 v181, v93, v120, v181
	v_add_f32_e32 v90, v90, v182
	v_add_f32_e32 v94, v94, v183
	v_mul_f32_e32 v132, v94, v125
	v_mul_f32_e32 v183, v90, v125
	v_fma_f32 v182, v90, v124, -v132
	v_fma_f32 v183, v94, v124, v183
	v_add_f32_e32 v91, v91, v184
	v_add_f32_e32 v95, v95, v185
	v_mul_f32_e32 v133, v95, v129
	v_mul_f32_e32 v185, v91, v129
	v_fma_f32 v184, v91, v128, -v133
	v_fma_f32 v185, v95, v128, v185
	v_mul_f32_e32 v132, v32, v101
	v_mul_f32_e32 v32, v32, v100
	v_fma_f32 v32, -v36, v101, v32
	v_fma_f32 v36, v36, v100, v132
	v_mul_f32_e32 v133, v33, v105
	v_mul_f32_e32 v33, v33, v104
	v_fma_f32 v33, -v37, v105, v33
	v_fma_f32 v37, v37, v104, v133
	v_mul_f32_e32 v132, v34, v109
	v_mul_f32_e32 v34, v34, v108
	v_fma_f32 v34, -v38, v109, v34
	v_fma_f32 v38, v38, v108, v132
	v_mul_f32_e32 v133, v35, v113
	v_mul_f32_e32 v35, v35, v112
	v_fma_f32 v35, -v39, v113, v35
	v_fma_f32 v39, v39, v112, v133
	v_add_f32_dpp v32, v32, v32 row_shl:1 row_mask:0xf bank_mask:0xf bound_ctrl:1
	v_add_f32_dpp v33, v33, v33 row_shl:1 row_mask:0xf bank_mask:0xf bound_ctrl:1
	v_add_f32_dpp v34, v34, v34 row_shl:1 row_mask:0xf bank_mask:0xf bound_ctrl:1
	v_add_f32_dpp v35, v35, v35 row_shl:1 row_mask:0xf bank_mask:0xf bound_ctrl:1
	v_add_f32_dpp v36, v36, v36 row_shl:1 row_mask:0xf bank_mask:0xf bound_ctrl:1
	v_add_f32_dpp v37, v37, v37 row_shl:1 row_mask:0xf bank_mask:0xf bound_ctrl:1
	v_add_f32_dpp v38, v38, v38 row_shl:1 row_mask:0xf bank_mask:0xf bound_ctrl:1
	v_add_f32_dpp v39, v39, v39 row_shl:1 row_mask:0xf bank_mask:0xf bound_ctrl:1
	v_add_f32_dpp v32, v32, v32 row_shl:2 row_mask:0xf bank_mask:0xf bound_ctrl:1
	v_add_f32_dpp v33, v33, v33 row_shl:2 row_mask:0xf bank_mask:0xf bound_ctrl:1
	v_add_f32_dpp v34, v34, v34 row_shl:2 row_mask:0xf bank_mask:0xf bound_ctrl:1
	v_add_f32_dpp v35, v35, v35 row_shl:2 row_mask:0xf bank_mask:0xf bound_ctrl:1
	v_add_f32_dpp v36, v36, v36 row_shl:2 row_mask:0xf bank_mask:0xf bound_ctrl:1
	v_add_f32_dpp v37, v37, v37 row_shl:2 row_mask:0xf bank_mask:0xf bound_ctrl:1
	v_add_f32_dpp v38, v38, v38 row_shl:2 row_mask:0xf bank_mask:0xf bound_ctrl:1
	v_add_f32_dpp v39, v39, v39 row_shl:2 row_mask:0xf bank_mask:0xf bound_ctrl:1
	v_add_f32_dpp v32, v32, v32 row_shl:4 row_mask:0xf bank_mask:0xf bound_ctrl:1
	v_add_f32_dpp v33, v33, v33 row_shl:4 row_mask:0xf bank_mask:0xf bound_ctrl:1
	v_add_f32_dpp v34, v34, v34 row_shl:4 row_mask:0xf bank_mask:0xf bound_ctrl:1
	v_add_f32_dpp v35, v35, v35 row_shl:4 row_mask:0xf bank_mask:0xf bound_ctrl:1
	v_add_f32_dpp v36, v36, v36 row_shl:4 row_mask:0xf bank_mask:0xf bound_ctrl:1
	v_add_f32_dpp v37, v37, v37 row_shl:4 row_mask:0xf bank_mask:0xf bound_ctrl:1
	v_add_f32_dpp v38, v38, v38 row_shl:4 row_mask:0xf bank_mask:0xf bound_ctrl:1
	v_add_f32_dpp v39, v39, v39 row_shl:4 row_mask:0xf bank_mask:0xf bound_ctrl:1
	v_add_f32_dpp v32, v32, v32 row_shl:8 row_mask:0xf bank_mask:0xf bound_ctrl:1
	v_add_f32_dpp v33, v33, v33 row_shl:8 row_mask:0xf bank_mask:0xf bound_ctrl:1
	v_add_f32_dpp v34, v34, v34 row_shl:8 row_mask:0xf bank_mask:0xf bound_ctrl:1
	v_add_f32_dpp v35, v35, v35 row_shl:8 row_mask:0xf bank_mask:0xf bound_ctrl:1
	v_add_f32_dpp v36, v36, v36 row_shl:8 row_mask:0xf bank_mask:0xf bound_ctrl:1
	v_add_f32_dpp v37, v37, v37 row_shl:8 row_mask:0xf bank_mask:0xf bound_ctrl:1
	v_add_f32_dpp v38, v38, v38 row_shl:8 row_mask:0xf bank_mask:0xf bound_ctrl:1
	v_add_f32_dpp v39, v39, v39 row_shl:8 row_mask:0xf bank_mask:0xf bound_ctrl:1
	v_mov_b32_dpp v88, v32 row_newbcast:0 row_mask:0xf bank_mask:0xf
	v_mov_b32_dpp v89, v33 row_newbcast:0 row_mask:0xf bank_mask:0xf
	v_mov_b32_dpp v90, v34 row_newbcast:0 row_mask:0xf bank_mask:0xf
	v_mov_b32_dpp v91, v35 row_newbcast:0 row_mask:0xf bank_mask:0xf
	v_mov_b32_dpp v92, v36 row_newbcast:0 row_mask:0xf bank_mask:0xf
	v_mov_b32_dpp v93, v37 row_newbcast:0 row_mask:0xf bank_mask:0xf
	v_mov_b32_dpp v94, v38 row_newbcast:0 row_mask:0xf bank_mask:0xf
	v_mov_b32_dpp v95, v39 row_newbcast:0 row_mask:0xf bank_mask:0xf
	v_add_f32_e32 v32, v32, v178
	v_add_f32_e32 v36, v36, v179
	v_add_f32_e32 v33, v33, v180
	v_add_f32_e32 v37, v37, v181
	v_add_f32_e32 v34, v34, v182
	v_add_f32_e32 v38, v38, v183
	v_add_f32_e32 v35, v35, v184
	v_add_f32_e32 v39, v39, v185
	v_mul_f32_e32 v132, v32, v103
	v_mul_f32_e32 v32, v32, v102
	v_fma_f32 v32, -v36, v103, v32
	v_fma_f32 v36, v36, v102, v132
	v_mul_f32_e32 v133, v33, v107
	v_mul_f32_e32 v33, v33, v106
	v_fma_f32 v33, -v37, v107, v33
	v_fma_f32 v37, v37, v106, v133
	v_mul_f32_e32 v132, v34, v111
	v_mul_f32_e32 v34, v34, v110
	v_fma_f32 v34, -v38, v111, v34
	v_fma_f32 v38, v38, v110, v132
	v_mul_f32_e32 v133, v35, v115
	v_mul_f32_e32 v35, v35, v114
	v_fma_f32 v35, -v39, v115, v35
	v_fma_f32 v39, v39, v114, v133
	v_add_f32_e32 v88, v88, v178
	v_add_f32_e32 v92, v92, v179
	v_mul_f32_e32 v132, v92, v117
	v_mul_f32_e32 v179, v88, v117
	v_fma_f32 v178, v88, v116, -v132
	v_fma_f32 v179, v92, v116, v179
	v_add_f32_e32 v89, v89, v180
	v_add_f32_e32 v93, v93, v181
	v_mul_f32_e32 v133, v93, v121
	v_mul_f32_e32 v181, v89, v121
	v_fma_f32 v180, v89, v120, -v133
	v_fma_f32 v181, v93, v120, v181
	v_add_f32_e32 v90, v90, v182
	v_add_f32_e32 v94, v94, v183
	v_mul_f32_e32 v132, v94, v125
	v_mul_f32_e32 v183, v90, v125
	v_fma_f32 v182, v90, v124, -v132
	v_fma_f32 v183, v94, v124, v183
	v_add_f32_e32 v91, v91, v184
	v_add_f32_e32 v95, v95, v185
	v_mul_f32_e32 v133, v95, v129
	v_mul_f32_e32 v185, v91, v129
	v_fma_f32 v184, v91, v128, -v133
	v_fma_f32 v185, v95, v128, v185
	s_waitcnt vmcnt(12)
	v_cvt_pk_bf16_f32 v96, v32, v33
	v_cvt_pk_bf16_f32 v97, v34, v35
	v_cvt_pk_bf16_f32 v98, v36, v37
	v_cvt_pk_bf16_f32 v99, v38, v39
	s_nop 1
	v_mfma_f32_16x16x32_bf16 v[16:19], v[80:83], v[96:99], v[16:19]
	v_cvt_pk_bf16_f32 v96, v40, v41
	v_cvt_pk_bf16_f32 v97, v42, v43
	v_cvt_pk_bf16_f32 v98, v44, v45
	v_cvt_pk_bf16_f32 v99, v46, v47
	s_nop 1
	v_mfma_f32_16x16x32_bf16 v[20:23], v[80:83], v[96:99], v[20:23]
	v_cvt_pk_bf16_f32 v96, v48, v49
	v_cvt_pk_bf16_f32 v97, v50, v51
	v_cvt_pk_bf16_f32 v98, v52, v53
	v_cvt_pk_bf16_f32 v99, v54, v55
	s_nop 1
	v_mfma_f32_16x16x32_bf16 v[24:27], v[80:83], v[96:99], v[24:27]
	v_cvt_pk_bf16_f32 v96, v56, v57
	v_cvt_pk_bf16_f32 v97, v58, v59
	v_cvt_pk_bf16_f32 v98, v60, v61
	v_cvt_pk_bf16_f32 v99, v62, v63
	s_nop 1
	v_mfma_f32_16x16x32_bf16 v[28:31], v[80:83], v[96:99], v[28:31]
	s_waitcnt vmcnt(10)
	global_load_dwordx4 v[80:83], v134, s[38:39]
	s_add_u32 s38, s38, 0x400
	s_addc_u32 s39, s39, 0
	v_mfma_f32_16x16x32_bf16 v[32:35], v[64:67], v[0:3], 0
	v_mfma_f32_16x16x32_bf16 v[36:39], v[72:75], v[0:3], 0
	v_mfma_f32_16x16x32_bf16 v[40:43], v[64:67], v[4:7], 0
	v_mfma_f32_16x16x32_bf16 v[44:47], v[72:75], v[4:7], 0
	v_mfma_f32_16x16x32_bf16 v[48:51], v[64:67], v[8:11], 0
	v_mfma_f32_16x16x32_bf16 v[52:55], v[72:75], v[8:11], 0
	v_mfma_f32_16x16x32_bf16 v[56:59], v[64:67], v[12:15], 0
	v_mfma_f32_16x16x32_bf16 v[60:63], v[72:75], v[12:15], 0
	global_load_dwordx4 v[64:67], v134, s[20:21]
	global_load_dwordx4 v[72:75], v134, s[20:21] offset:1024
	global_load_dwordx4 v[100:103], v134, s[42:43] offset:0
	global_load_dwordx4 v[104:107], v134, s[42:43] offset:1024
	global_load_dwordx4 v[108:111], v134, s[42:43] offset:2048
	global_load_dwordx4 v[112:115], v134, s[42:43] offset:3072
	global_load_dwordx4 v[116:119], v208, s[42:43] offset:0
	global_load_dwordx4 v[120:123], v208, s[42:43] offset:1024
	global_load_dwordx4 v[124:127], v208, s[42:43] offset:2048
	global_load_dwordx4 v[128:131], v208, s[42:43] offset:3072
	global_load_dwordx4 v[178:181], v206, s[44:45]
	global_load_dwordx4 v[182:185], v206, s[44:45] offset:16
	s_waitcnt vmcnt(13)
	v_mul_f32_e32 v132, v171, v157
	v_mul_f32_e32 v133, v170, v157
	v_fma_f32 v170, v170, v156, -v132
	v_fma_f32 v171, v171, v156, v133
	v_mul_f32_e32 v132, v173, v161
	v_mul_f32_e32 v133, v172, v161
	v_fma_f32 v172, v172, v160, -v132
	v_fma_f32 v173, v173, v160, v133
	v_mul_f32_e32 v132, v175, v165
	v_mul_f32_e32 v133, v174, v165
	v_fma_f32 v174, v174, v164, -v132
	v_fma_f32 v175, v175, v164, v133
	v_mul_f32_e32 v132, v177, v169
	v_mul_f32_e32 v133, v176, v169
	v_fma_f32 v176, v176, v168, -v132
	v_fma_f32 v177, v177, v168, v133
	v_mul_f32_e32 v132, v56, v139
	v_mul_f32_e32 v56, v56, v138
	v_fma_f32 v56, -v60, v139, v56
	v_fma_f32 v60, v60, v138, v132
	v_mul_f32_e32 v133, v57, v143
	v_mul_f32_e32 v57, v57, v142
	v_fma_f32 v57, -v61, v143, v57
	v_fma_f32 v61, v61, v142, v133
	v_mul_f32_e32 v132, v58, v147
	v_mul_f32_e32 v58, v58, v146
	v_fma_f32 v58, -v62, v147, v58
	v_fma_f32 v62, v62, v146, v132
	v_mul_f32_e32 v133, v59, v151
	v_mul_f32_e32 v59, v59, v150
	v_fma_f32 v59, -v63, v151, v59
	v_fma_f32 v63, v63, v150, v133
	v_add_f32_dpp v56, v56, v56 row_shl:1 row_mask:0xf bank_mask:0xf bound_ctrl:1
	v_add_f32_dpp v57, v57, v57 row_shl:1 row_mask:0xf bank_mask:0xf bound_ctrl:1
	v_add_f32_dpp v58, v58, v58 row_shl:1 row_mask:0xf bank_mask:0xf bound_ctrl:1
	v_add_f32_dpp v59, v59, v59 row_shl:1 row_mask:0xf bank_mask:0xf bound_ctrl:1
	v_add_f32_dpp v60, v60, v60 row_shl:1 row_mask:0xf bank_mask:0xf bound_ctrl:1
	v_add_f32_dpp v61, v61, v61 row_shl:1 row_mask:0xf bank_mask:0xf bound_ctrl:1
	v_add_f32_dpp v62, v62, v62 row_shl:1 row_mask:0xf bank_mask:0xf bound_ctrl:1
	v_add_f32_dpp v63, v63, v63 row_shl:1 row_mask:0xf bank_mask:0xf bound_ctrl:1
	v_add_f32_dpp v56, v56, v56 row_shl:2 row_mask:0xf bank_mask:0xf bound_ctrl:1
	v_add_f32_dpp v57, v57, v57 row_shl:2 row_mask:0xf bank_mask:0xf bound_ctrl:1
	v_add_f32_dpp v58, v58, v58 row_shl:2 row_mask:0xf bank_mask:0xf bound_ctrl:1
	v_add_f32_dpp v59, v59, v59 row_shl:2 row_mask:0xf bank_mask:0xf bound_ctrl:1
	v_add_f32_dpp v60, v60, v60 row_shl:2 row_mask:0xf bank_mask:0xf bound_ctrl:1
	v_add_f32_dpp v61, v61, v61 row_shl:2 row_mask:0xf bank_mask:0xf bound_ctrl:1
	v_add_f32_dpp v62, v62, v62 row_shl:2 row_mask:0xf bank_mask:0xf bound_ctrl:1
	v_add_f32_dpp v63, v63, v63 row_shl:2 row_mask:0xf bank_mask:0xf bound_ctrl:1
	v_add_f32_dpp v56, v56, v56 row_shl:4 row_mask:0xf bank_mask:0xf bound_ctrl:1
	v_add_f32_dpp v57, v57, v57 row_shl:4 row_mask:0xf bank_mask:0xf bound_ctrl:1
	v_add_f32_dpp v58, v58, v58 row_shl:4 row_mask:0xf bank_mask:0xf bound_ctrl:1
	v_add_f32_dpp v59, v59, v59 row_shl:4 row_mask:0xf bank_mask:0xf bound_ctrl:1
	v_add_f32_dpp v60, v60, v60 row_shl:4 row_mask:0xf bank_mask:0xf bound_ctrl:1
	v_add_f32_dpp v61, v61, v61 row_shl:4 row_mask:0xf bank_mask:0xf bound_ctrl:1
	v_add_f32_dpp v62, v62, v62 row_shl:4 row_mask:0xf bank_mask:0xf bound_ctrl:1
	v_add_f32_dpp v63, v63, v63 row_shl:4 row_mask:0xf bank_mask:0xf bound_ctrl:1
	v_add_f32_dpp v56, v56, v56 row_shl:8 row_mask:0xf bank_mask:0xf bound_ctrl:1
	v_add_f32_dpp v57, v57, v57 row_shl:8 row_mask:0xf bank_mask:0xf bound_ctrl:1
	v_add_f32_dpp v58, v58, v58 row_shl:8 row_mask:0xf bank_mask:0xf bound_ctrl:1
	v_add_f32_dpp v59, v59, v59 row_shl:8 row_mask:0xf bank_mask:0xf bound_ctrl:1
	v_add_f32_dpp v60, v60, v60 row_shl:8 row_mask:0xf bank_mask:0xf bound_ctrl:1
	v_add_f32_dpp v61, v61, v61 row_shl:8 row_mask:0xf bank_mask:0xf bound_ctrl:1
	v_add_f32_dpp v62, v62, v62 row_shl:8 row_mask:0xf bank_mask:0xf bound_ctrl:1
	v_add_f32_dpp v63, v63, v63 row_shl:8 row_mask:0xf bank_mask:0xf bound_ctrl:1
	v_mov_b32_dpp v88, v56 row_newbcast:0 row_mask:0xf bank_mask:0xf
	v_mov_b32_dpp v89, v57 row_newbcast:0 row_mask:0xf bank_mask:0xf
	v_mov_b32_dpp v90, v58 row_newbcast:0 row_mask:0xf bank_mask:0xf
	v_mov_b32_dpp v91, v59 row_newbcast:0 row_mask:0xf bank_mask:0xf
	v_mov_b32_dpp v92, v60 row_newbcast:0 row_mask:0xf bank_mask:0xf
	v_mov_b32_dpp v93, v61 row_newbcast:0 row_mask:0xf bank_mask:0xf
	v_mov_b32_dpp v94, v62 row_newbcast:0 row_mask:0xf bank_mask:0xf
	v_mov_b32_dpp v95, v63 row_newbcast:0 row_mask:0xf bank_mask:0xf
	v_add_f32_e32 v56, v56, v170
	v_add_f32_e32 v60, v60, v171
	v_add_f32_e32 v57, v57, v172
	v_add_f32_e32 v61, v61, v173
	v_add_f32_e32 v58, v58, v174
	v_add_f32_e32 v62, v62, v175
	v_add_f32_e32 v59, v59, v176
	v_add_f32_e32 v63, v63, v177
	v_mul_f32_e32 v132, v56, v141
	v_mul_f32_e32 v56, v56, v140
	v_fma_f32 v56, -v60, v141, v56
	v_fma_f32 v60, v60, v140, v132
	v_mul_f32_e32 v133, v57, v145
	v_mul_f32_e32 v57, v57, v144
	v_fma_f32 v57, -v61, v145, v57
	v_fma_f32 v61, v61, v144, v133
	v_mul_f32_e32 v132, v58, v149
	v_mul_f32_e32 v58, v58, v148
	v_fma_f32 v58, -v62, v149, v58
	v_fma_f32 v62, v62, v148, v132
	v_mul_f32_e32 v133, v59, v153
	v_mul_f32_e32 v59, v59, v152
	v_fma_f32 v59, -v63, v153, v59
	v_fma_f32 v63, v63, v152, v133
	v_add_f32_e32 v88, v88, v170
	v_add_f32_e32 v92, v92, v171
	v_mul_f32_e32 v132, v92, v155
	v_mul_f32_e32 v171, v88, v155
	v_fma_f32 v170, v88, v154, -v132
	v_fma_f32 v171, v92, v154, v171
	v_add_f32_e32 v89, v89, v172
	v_add_f32_e32 v93, v93, v173
	v_mul_f32_e32 v133, v93, v159
	v_mul_f32_e32 v173, v89, v159
	v_fma_f32 v172, v89, v158, -v133
	v_fma_f32 v173, v93, v158, v173
	v_add_f32_e32 v90, v90, v174
	v_add_f32_e32 v94, v94, v175
	v_mul_f32_e32 v132, v94, v163
	v_mul_f32_e32 v175, v90, v163
	v_fma_f32 v174, v90, v162, -v132
	v_fma_f32 v175, v94, v162, v175
	v_add_f32_e32 v91, v91, v176
	v_add_f32_e32 v95, v95, v177
	v_mul_f32_e32 v133, v95, v167
	v_mul_f32_e32 v177, v91, v167
	v_fma_f32 v176, v91, v166, -v133
	v_fma_f32 v177, v95, v166, v177
	v_mul_f32_e32 v132, v48, v139
	v_mul_f32_e32 v48, v48, v138
	v_fma_f32 v48, -v52, v139, v48
	v_fma_f32 v52, v52, v138, v132
	v_mul_f32_e32 v133, v49, v143
	v_mul_f32_e32 v49, v49, v142
	v_fma_f32 v49, -v53, v143, v49
	v_fma_f32 v53, v53, v142, v133
	v_mul_f32_e32 v132, v50, v147
	v_mul_f32_e32 v50, v50, v146
	v_fma_f32 v50, -v54, v147, v50
	v_fma_f32 v54, v54, v146, v132
	v_mul_f32_e32 v133, v51, v151
	v_mul_f32_e32 v51, v51, v150
	v_fma_f32 v51, -v55, v151, v51
	v_fma_f32 v55, v55, v150, v133
	v_add_f32_dpp v48, v48, v48 row_shl:1 row_mask:0xf bank_mask:0xf bound_ctrl:1
	v_add_f32_dpp v49, v49, v49 row_shl:1 row_mask:0xf bank_mask:0xf bound_ctrl:1
	v_add_f32_dpp v50, v50, v50 row_shl:1 row_mask:0xf bank_mask:0xf bound_ctrl:1
	v_add_f32_dpp v51, v51, v51 row_shl:1 row_mask:0xf bank_mask:0xf bound_ctrl:1
	v_add_f32_dpp v52, v52, v52 row_shl:1 row_mask:0xf bank_mask:0xf bound_ctrl:1
	v_add_f32_dpp v53, v53, v53 row_shl:1 row_mask:0xf bank_mask:0xf bound_ctrl:1
	v_add_f32_dpp v54, v54, v54 row_shl:1 row_mask:0xf bank_mask:0xf bound_ctrl:1
	v_add_f32_dpp v55, v55, v55 row_shl:1 row_mask:0xf bank_mask:0xf bound_ctrl:1
	v_add_f32_dpp v48, v48, v48 row_shl:2 row_mask:0xf bank_mask:0xf bound_ctrl:1
	v_add_f32_dpp v49, v49, v49 row_shl:2 row_mask:0xf bank_mask:0xf bound_ctrl:1
	v_add_f32_dpp v50, v50, v50 row_shl:2 row_mask:0xf bank_mask:0xf bound_ctrl:1
	v_add_f32_dpp v51, v51, v51 row_shl:2 row_mask:0xf bank_mask:0xf bound_ctrl:1
	v_add_f32_dpp v52, v52, v52 row_shl:2 row_mask:0xf bank_mask:0xf bound_ctrl:1
	v_add_f32_dpp v53, v53, v53 row_shl:2 row_mask:0xf bank_mask:0xf bound_ctrl:1
	v_add_f32_dpp v54, v54, v54 row_shl:2 row_mask:0xf bank_mask:0xf bound_ctrl:1
	v_add_f32_dpp v55, v55, v55 row_shl:2 row_mask:0xf bank_mask:0xf bound_ctrl:1
	v_add_f32_dpp v48, v48, v48 row_shl:4 row_mask:0xf bank_mask:0xf bound_ctrl:1
	v_add_f32_dpp v49, v49, v49 row_shl:4 row_mask:0xf bank_mask:0xf bound_ctrl:1
	v_add_f32_dpp v50, v50, v50 row_shl:4 row_mask:0xf bank_mask:0xf bound_ctrl:1
	v_add_f32_dpp v51, v51, v51 row_shl:4 row_mask:0xf bank_mask:0xf bound_ctrl:1
	v_add_f32_dpp v52, v52, v52 row_shl:4 row_mask:0xf bank_mask:0xf bound_ctrl:1
	v_add_f32_dpp v53, v53, v53 row_shl:4 row_mask:0xf bank_mask:0xf bound_ctrl:1
	v_add_f32_dpp v54, v54, v54 row_shl:4 row_mask:0xf bank_mask:0xf bound_ctrl:1
	v_add_f32_dpp v55, v55, v55 row_shl:4 row_mask:0xf bank_mask:0xf bound_ctrl:1
	v_add_f32_dpp v48, v48, v48 row_shl:8 row_mask:0xf bank_mask:0xf bound_ctrl:1
	v_add_f32_dpp v49, v49, v49 row_shl:8 row_mask:0xf bank_mask:0xf bound_ctrl:1
	v_add_f32_dpp v50, v50, v50 row_shl:8 row_mask:0xf bank_mask:0xf bound_ctrl:1
	v_add_f32_dpp v51, v51, v51 row_shl:8 row_mask:0xf bank_mask:0xf bound_ctrl:1
	v_add_f32_dpp v52, v52, v52 row_shl:8 row_mask:0xf bank_mask:0xf bound_ctrl:1
	v_add_f32_dpp v53, v53, v53 row_shl:8 row_mask:0xf bank_mask:0xf bound_ctrl:1
	v_add_f32_dpp v54, v54, v54 row_shl:8 row_mask:0xf bank_mask:0xf bound_ctrl:1
	v_add_f32_dpp v55, v55, v55 row_shl:8 row_mask:0xf bank_mask:0xf bound_ctrl:1
	v_mov_b32_dpp v88, v48 row_newbcast:0 row_mask:0xf bank_mask:0xf
	v_mov_b32_dpp v89, v49 row_newbcast:0 row_mask:0xf bank_mask:0xf
	v_mov_b32_dpp v90, v50 row_newbcast:0 row_mask:0xf bank_mask:0xf
	v_mov_b32_dpp v91, v51 row_newbcast:0 row_mask:0xf bank_mask:0xf
	v_mov_b32_dpp v92, v52 row_newbcast:0 row_mask:0xf bank_mask:0xf
	v_mov_b32_dpp v93, v53 row_newbcast:0 row_mask:0xf bank_mask:0xf
	v_mov_b32_dpp v94, v54 row_newbcast:0 row_mask:0xf bank_mask:0xf
	v_mov_b32_dpp v95, v55 row_newbcast:0 row_mask:0xf bank_mask:0xf
	v_add_f32_e32 v48, v48, v170
	v_add_f32_e32 v52, v52, v171
	v_add_f32_e32 v49, v49, v172
	v_add_f32_e32 v53, v53, v173
	v_add_f32_e32 v50, v50, v174
	v_add_f32_e32 v54, v54, v175
	v_add_f32_e32 v51, v51, v176
	v_add_f32_e32 v55, v55, v177
	v_mul_f32_e32 v132, v48, v141
	v_mul_f32_e32 v48, v48, v140
	v_fma_f32 v48, -v52, v141, v48
	v_fma_f32 v52, v52, v140, v132
	v_mul_f32_e32 v133, v49, v145
	v_mul_f32_e32 v49, v49, v144
	v_fma_f32 v49, -v53, v145, v49
	v_fma_f32 v53, v53, v144, v133
	v_mul_f32_e32 v132, v50, v149
	v_mul_f32_e32 v50, v50, v148
	v_fma_f32 v50, -v54, v149, v50
	v_fma_f32 v54, v54, v148, v132
	v_mul_f32_e32 v133, v51, v153
	v_mul_f32_e32 v51, v51, v152
	v_fma_f32 v51, -v55, v153, v51
	v_fma_f32 v55, v55, v152, v133
	v_add_f32_e32 v88, v88, v170
	v_add_f32_e32 v92, v92, v171
	v_mul_f32_e32 v132, v92, v155
	v_mul_f32_e32 v171, v88, v155
	v_fma_f32 v170, v88, v154, -v132
	v_fma_f32 v171, v92, v154, v171
	v_add_f32_e32 v89, v89, v172
	v_add_f32_e32 v93, v93, v173
	v_mul_f32_e32 v133, v93, v159
	v_mul_f32_e32 v173, v89, v159
	v_fma_f32 v172, v89, v158, -v133
	v_fma_f32 v173, v93, v158, v173
	v_add_f32_e32 v90, v90, v174
	v_add_f32_e32 v94, v94, v175
	v_mul_f32_e32 v132, v94, v163
	v_mul_f32_e32 v175, v90, v163
	v_fma_f32 v174, v90, v162, -v132
	v_fma_f32 v175, v94, v162, v175
	v_add_f32_e32 v91, v91, v176
	v_add_f32_e32 v95, v95, v177
	v_mul_f32_e32 v133, v95, v167
	v_mul_f32_e32 v177, v91, v167
	v_fma_f32 v176, v91, v166, -v133
	v_fma_f32 v177, v95, v166, v177
	v_mul_f32_e32 v132, v40, v139
	v_mul_f32_e32 v40, v40, v138
	v_fma_f32 v40, -v44, v139, v40
	v_fma_f32 v44, v44, v138, v132
	v_mul_f32_e32 v133, v41, v143
	v_mul_f32_e32 v41, v41, v142
	v_fma_f32 v41, -v45, v143, v41
	v_fma_f32 v45, v45, v142, v133
	v_mul_f32_e32 v132, v42, v147
	v_mul_f32_e32 v42, v42, v146
	v_fma_f32 v42, -v46, v147, v42
	v_fma_f32 v46, v46, v146, v132
	v_mul_f32_e32 v133, v43, v151
	v_mul_f32_e32 v43, v43, v150
	v_fma_f32 v43, -v47, v151, v43
	v_fma_f32 v47, v47, v150, v133
	v_add_f32_dpp v40, v40, v40 row_shl:1 row_mask:0xf bank_mask:0xf bound_ctrl:1
	v_add_f32_dpp v41, v41, v41 row_shl:1 row_mask:0xf bank_mask:0xf bound_ctrl:1
	v_add_f32_dpp v42, v42, v42 row_shl:1 row_mask:0xf bank_mask:0xf bound_ctrl:1
	v_add_f32_dpp v43, v43, v43 row_shl:1 row_mask:0xf bank_mask:0xf bound_ctrl:1
	v_add_f32_dpp v44, v44, v44 row_shl:1 row_mask:0xf bank_mask:0xf bound_ctrl:1
	v_add_f32_dpp v45, v45, v45 row_shl:1 row_mask:0xf bank_mask:0xf bound_ctrl:1
	v_add_f32_dpp v46, v46, v46 row_shl:1 row_mask:0xf bank_mask:0xf bound_ctrl:1
	v_add_f32_dpp v47, v47, v47 row_shl:1 row_mask:0xf bank_mask:0xf bound_ctrl:1
	v_add_f32_dpp v40, v40, v40 row_shl:2 row_mask:0xf bank_mask:0xf bound_ctrl:1
	v_add_f32_dpp v41, v41, v41 row_shl:2 row_mask:0xf bank_mask:0xf bound_ctrl:1
	v_add_f32_dpp v42, v42, v42 row_shl:2 row_mask:0xf bank_mask:0xf bound_ctrl:1
	v_add_f32_dpp v43, v43, v43 row_shl:2 row_mask:0xf bank_mask:0xf bound_ctrl:1
	v_add_f32_dpp v44, v44, v44 row_shl:2 row_mask:0xf bank_mask:0xf bound_ctrl:1
	v_add_f32_dpp v45, v45, v45 row_shl:2 row_mask:0xf bank_mask:0xf bound_ctrl:1
	v_add_f32_dpp v46, v46, v46 row_shl:2 row_mask:0xf bank_mask:0xf bound_ctrl:1
	v_add_f32_dpp v47, v47, v47 row_shl:2 row_mask:0xf bank_mask:0xf bound_ctrl:1
	v_add_f32_dpp v40, v40, v40 row_shl:4 row_mask:0xf bank_mask:0xf bound_ctrl:1
	v_add_f32_dpp v41, v41, v41 row_shl:4 row_mask:0xf bank_mask:0xf bound_ctrl:1
	v_add_f32_dpp v42, v42, v42 row_shl:4 row_mask:0xf bank_mask:0xf bound_ctrl:1
	v_add_f32_dpp v43, v43, v43 row_shl:4 row_mask:0xf bank_mask:0xf bound_ctrl:1
	v_add_f32_dpp v44, v44, v44 row_shl:4 row_mask:0xf bank_mask:0xf bound_ctrl:1
	v_add_f32_dpp v45, v45, v45 row_shl:4 row_mask:0xf bank_mask:0xf bound_ctrl:1
	v_add_f32_dpp v46, v46, v46 row_shl:4 row_mask:0xf bank_mask:0xf bound_ctrl:1
	v_add_f32_dpp v47, v47, v47 row_shl:4 row_mask:0xf bank_mask:0xf bound_ctrl:1
	v_add_f32_dpp v40, v40, v40 row_shl:8 row_mask:0xf bank_mask:0xf bound_ctrl:1
	v_add_f32_dpp v41, v41, v41 row_shl:8 row_mask:0xf bank_mask:0xf bound_ctrl:1
	v_add_f32_dpp v42, v42, v42 row_shl:8 row_mask:0xf bank_mask:0xf bound_ctrl:1
	v_add_f32_dpp v43, v43, v43 row_shl:8 row_mask:0xf bank_mask:0xf bound_ctrl:1
	v_add_f32_dpp v44, v44, v44 row_shl:8 row_mask:0xf bank_mask:0xf bound_ctrl:1
	v_add_f32_dpp v45, v45, v45 row_shl:8 row_mask:0xf bank_mask:0xf bound_ctrl:1
	v_add_f32_dpp v46, v46, v46 row_shl:8 row_mask:0xf bank_mask:0xf bound_ctrl:1
	v_add_f32_dpp v47, v47, v47 row_shl:8 row_mask:0xf bank_mask:0xf bound_ctrl:1
	v_mov_b32_dpp v88, v40 row_newbcast:0 row_mask:0xf bank_mask:0xf
	v_mov_b32_dpp v89, v41 row_newbcast:0 row_mask:0xf bank_mask:0xf
	v_mov_b32_dpp v90, v42 row_newbcast:0 row_mask:0xf bank_mask:0xf
	v_mov_b32_dpp v91, v43 row_newbcast:0 row_mask:0xf bank_mask:0xf
	v_mov_b32_dpp v92, v44 row_newbcast:0 row_mask:0xf bank_mask:0xf
	v_mov_b32_dpp v93, v45 row_newbcast:0 row_mask:0xf bank_mask:0xf
	v_mov_b32_dpp v94, v46 row_newbcast:0 row_mask:0xf bank_mask:0xf
	v_mov_b32_dpp v95, v47 row_newbcast:0 row_mask:0xf bank_mask:0xf
	v_add_f32_e32 v40, v40, v170
	v_add_f32_e32 v44, v44, v171
	v_add_f32_e32 v41, v41, v172
	v_add_f32_e32 v45, v45, v173
	v_add_f32_e32 v42, v42, v174
	v_add_f32_e32 v46, v46, v175
	v_add_f32_e32 v43, v43, v176
	v_add_f32_e32 v47, v47, v177
	v_mul_f32_e32 v132, v40, v141
	v_mul_f32_e32 v40, v40, v140
	v_fma_f32 v40, -v44, v141, v40
	v_fma_f32 v44, v44, v140, v132
	v_mul_f32_e32 v133, v41, v145
	v_mul_f32_e32 v41, v41, v144
	v_fma_f32 v41, -v45, v145, v41
	v_fma_f32 v45, v45, v144, v133
	v_mul_f32_e32 v132, v42, v149
	v_mul_f32_e32 v42, v42, v148
	v_fma_f32 v42, -v46, v149, v42
	v_fma_f32 v46, v46, v148, v132
	v_mul_f32_e32 v133, v43, v153
	v_mul_f32_e32 v43, v43, v152
	v_fma_f32 v43, -v47, v153, v43
	v_fma_f32 v47, v47, v152, v133
	v_add_f32_e32 v88, v88, v170
	v_add_f32_e32 v92, v92, v171
	v_mul_f32_e32 v132, v92, v155
	v_mul_f32_e32 v171, v88, v155
	v_fma_f32 v170, v88, v154, -v132
	v_fma_f32 v171, v92, v154, v171
	v_add_f32_e32 v89, v89, v172
	v_add_f32_e32 v93, v93, v173
	v_mul_f32_e32 v133, v93, v159
	v_mul_f32_e32 v173, v89, v159
	v_fma_f32 v172, v89, v158, -v133
	v_fma_f32 v173, v93, v158, v173
	v_add_f32_e32 v90, v90, v174
	v_add_f32_e32 v94, v94, v175
	v_mul_f32_e32 v132, v94, v163
	v_mul_f32_e32 v175, v90, v163
	v_fma_f32 v174, v90, v162, -v132
	v_fma_f32 v175, v94, v162, v175
	v_add_f32_e32 v91, v91, v176
	v_add_f32_e32 v95, v95, v177
	v_mul_f32_e32 v133, v95, v167
	v_mul_f32_e32 v177, v91, v167
	v_fma_f32 v176, v91, v166, -v133
	v_fma_f32 v177, v95, v166, v177
	v_mul_f32_e32 v132, v32, v139
	v_mul_f32_e32 v32, v32, v138
	v_fma_f32 v32, -v36, v139, v32
	v_fma_f32 v36, v36, v138, v132
	v_mul_f32_e32 v133, v33, v143
	v_mul_f32_e32 v33, v33, v142
	v_fma_f32 v33, -v37, v143, v33
	v_fma_f32 v37, v37, v142, v133
	v_mul_f32_e32 v132, v34, v147
	v_mul_f32_e32 v34, v34, v146
	v_fma_f32 v34, -v38, v147, v34
	v_fma_f32 v38, v38, v146, v132
	v_mul_f32_e32 v133, v35, v151
	v_mul_f32_e32 v35, v35, v150
	v_fma_f32 v35, -v39, v151, v35
	v_fma_f32 v39, v39, v150, v133
	v_add_f32_dpp v32, v32, v32 row_shl:1 row_mask:0xf bank_mask:0xf bound_ctrl:1
	v_add_f32_dpp v33, v33, v33 row_shl:1 row_mask:0xf bank_mask:0xf bound_ctrl:1
	v_add_f32_dpp v34, v34, v34 row_shl:1 row_mask:0xf bank_mask:0xf bound_ctrl:1
	v_add_f32_dpp v35, v35, v35 row_shl:1 row_mask:0xf bank_mask:0xf bound_ctrl:1
	v_add_f32_dpp v36, v36, v36 row_shl:1 row_mask:0xf bank_mask:0xf bound_ctrl:1
	v_add_f32_dpp v37, v37, v37 row_shl:1 row_mask:0xf bank_mask:0xf bound_ctrl:1
	v_add_f32_dpp v38, v38, v38 row_shl:1 row_mask:0xf bank_mask:0xf bound_ctrl:1
	v_add_f32_dpp v39, v39, v39 row_shl:1 row_mask:0xf bank_mask:0xf bound_ctrl:1
	v_add_f32_dpp v32, v32, v32 row_shl:2 row_mask:0xf bank_mask:0xf bound_ctrl:1
	v_add_f32_dpp v33, v33, v33 row_shl:2 row_mask:0xf bank_mask:0xf bound_ctrl:1
	v_add_f32_dpp v34, v34, v34 row_shl:2 row_mask:0xf bank_mask:0xf bound_ctrl:1
	v_add_f32_dpp v35, v35, v35 row_shl:2 row_mask:0xf bank_mask:0xf bound_ctrl:1
	v_add_f32_dpp v36, v36, v36 row_shl:2 row_mask:0xf bank_mask:0xf bound_ctrl:1
	v_add_f32_dpp v37, v37, v37 row_shl:2 row_mask:0xf bank_mask:0xf bound_ctrl:1
	v_add_f32_dpp v38, v38, v38 row_shl:2 row_mask:0xf bank_mask:0xf bound_ctrl:1
	v_add_f32_dpp v39, v39, v39 row_shl:2 row_mask:0xf bank_mask:0xf bound_ctrl:1
	v_add_f32_dpp v32, v32, v32 row_shl:4 row_mask:0xf bank_mask:0xf bound_ctrl:1
	v_add_f32_dpp v33, v33, v33 row_shl:4 row_mask:0xf bank_mask:0xf bound_ctrl:1
	v_add_f32_dpp v34, v34, v34 row_shl:4 row_mask:0xf bank_mask:0xf bound_ctrl:1
	v_add_f32_dpp v35, v35, v35 row_shl:4 row_mask:0xf bank_mask:0xf bound_ctrl:1
	v_add_f32_dpp v36, v36, v36 row_shl:4 row_mask:0xf bank_mask:0xf bound_ctrl:1
	v_add_f32_dpp v37, v37, v37 row_shl:4 row_mask:0xf bank_mask:0xf bound_ctrl:1
	v_add_f32_dpp v38, v38, v38 row_shl:4 row_mask:0xf bank_mask:0xf bound_ctrl:1
	v_add_f32_dpp v39, v39, v39 row_shl:4 row_mask:0xf bank_mask:0xf bound_ctrl:1
	v_add_f32_dpp v32, v32, v32 row_shl:8 row_mask:0xf bank_mask:0xf bound_ctrl:1
	v_add_f32_dpp v33, v33, v33 row_shl:8 row_mask:0xf bank_mask:0xf bound_ctrl:1
	v_add_f32_dpp v34, v34, v34 row_shl:8 row_mask:0xf bank_mask:0xf bound_ctrl:1
	v_add_f32_dpp v35, v35, v35 row_shl:8 row_mask:0xf bank_mask:0xf bound_ctrl:1
	v_add_f32_dpp v36, v36, v36 row_shl:8 row_mask:0xf bank_mask:0xf bound_ctrl:1
	v_add_f32_dpp v37, v37, v37 row_shl:8 row_mask:0xf bank_mask:0xf bound_ctrl:1
	v_add_f32_dpp v38, v38, v38 row_shl:8 row_mask:0xf bank_mask:0xf bound_ctrl:1
	v_add_f32_dpp v39, v39, v39 row_shl:8 row_mask:0xf bank_mask:0xf bound_ctrl:1
	v_mov_b32_dpp v88, v32 row_newbcast:0 row_mask:0xf bank_mask:0xf
	v_mov_b32_dpp v89, v33 row_newbcast:0 row_mask:0xf bank_mask:0xf
	v_mov_b32_dpp v90, v34 row_newbcast:0 row_mask:0xf bank_mask:0xf
	v_mov_b32_dpp v91, v35 row_newbcast:0 row_mask:0xf bank_mask:0xf
	v_mov_b32_dpp v92, v36 row_newbcast:0 row_mask:0xf bank_mask:0xf
	v_mov_b32_dpp v93, v37 row_newbcast:0 row_mask:0xf bank_mask:0xf
	v_mov_b32_dpp v94, v38 row_newbcast:0 row_mask:0xf bank_mask:0xf
	v_mov_b32_dpp v95, v39 row_newbcast:0 row_mask:0xf bank_mask:0xf
	v_add_f32_e32 v32, v32, v170
	v_add_f32_e32 v36, v36, v171
	v_add_f32_e32 v33, v33, v172
	v_add_f32_e32 v37, v37, v173
	v_add_f32_e32 v34, v34, v174
	v_add_f32_e32 v38, v38, v175
	v_add_f32_e32 v35, v35, v176
	v_add_f32_e32 v39, v39, v177
	v_mul_f32_e32 v132, v32, v141
	v_mul_f32_e32 v32, v32, v140
	v_fma_f32 v32, -v36, v141, v32
	v_fma_f32 v36, v36, v140, v132
	v_mul_f32_e32 v133, v33, v145
	v_mul_f32_e32 v33, v33, v144
	v_fma_f32 v33, -v37, v145, v33
	v_fma_f32 v37, v37, v144, v133
	v_mul_f32_e32 v132, v34, v149
	v_mul_f32_e32 v34, v34, v148
	v_fma_f32 v34, -v38, v149, v34
	v_fma_f32 v38, v38, v148, v132
	v_mul_f32_e32 v133, v35, v153
	v_mul_f32_e32 v35, v35, v152
	v_fma_f32 v35, -v39, v153, v35
	v_fma_f32 v39, v39, v152, v133
	v_add_f32_e32 v88, v88, v170
	v_add_f32_e32 v92, v92, v171
	v_mul_f32_e32 v132, v92, v155
	v_mul_f32_e32 v171, v88, v155
	v_fma_f32 v170, v88, v154, -v132
	v_fma_f32 v171, v92, v154, v171
	v_add_f32_e32 v89, v89, v172
	v_add_f32_e32 v93, v93, v173
	v_mul_f32_e32 v133, v93, v159
	v_mul_f32_e32 v173, v89, v159
	v_fma_f32 v172, v89, v158, -v133
	v_fma_f32 v173, v93, v158, v173
	v_add_f32_e32 v90, v90, v174
	v_add_f32_e32 v94, v94, v175
	v_mul_f32_e32 v132, v94, v163
	v_mul_f32_e32 v175, v90, v163
	v_fma_f32 v174, v90, v162, -v132
	v_fma_f32 v175, v94, v162, v175
	v_add_f32_e32 v91, v91, v176
	v_add_f32_e32 v95, v95, v177
	v_mul_f32_e32 v133, v95, v167
	v_mul_f32_e32 v177, v91, v167
	v_fma_f32 v176, v91, v166, -v133
	v_fma_f32 v177, v95, v166, v177
	s_waitcnt vmcnt(12)
	v_cvt_pk_bf16_f32 v96, v32, v33
	v_cvt_pk_bf16_f32 v97, v34, v35
	v_cvt_pk_bf16_f32 v98, v36, v37
	v_cvt_pk_bf16_f32 v99, v38, v39
	s_nop 1
	v_mfma_f32_16x16x32_bf16 v[16:19], v[80:83], v[96:99], v[16:19]
	v_cvt_pk_bf16_f32 v96, v40, v41
	v_cvt_pk_bf16_f32 v97, v42, v43
	v_cvt_pk_bf16_f32 v98, v44, v45
	v_cvt_pk_bf16_f32 v99, v46, v47
	s_nop 1
	v_mfma_f32_16x16x32_bf16 v[20:23], v[80:83], v[96:99], v[20:23]
	v_cvt_pk_bf16_f32 v96, v48, v49
	v_cvt_pk_bf16_f32 v97, v50, v51
	v_cvt_pk_bf16_f32 v98, v52, v53
	v_cvt_pk_bf16_f32 v99, v54, v55
	s_nop 1
	v_mfma_f32_16x16x32_bf16 v[24:27], v[80:83], v[96:99], v[24:27]
	v_cvt_pk_bf16_f32 v96, v56, v57
	v_cvt_pk_bf16_f32 v97, v58, v59
	v_cvt_pk_bf16_f32 v98, v60, v61
	v_cvt_pk_bf16_f32 v99, v62, v63
	s_nop 1
	v_mfma_f32_16x16x32_bf16 v[28:31], v[80:83], v[96:99], v[28:31]
	s_waitcnt vmcnt(10)
	global_load_dwordx4 v[80:83], v134, s[38:39]
	v_mfma_f32_16x16x32_bf16 v[32:35], v[64:67], v[0:3], 0
	v_mfma_f32_16x16x32_bf16 v[36:39], v[72:75], v[0:3], 0
	v_mfma_f32_16x16x32_bf16 v[40:43], v[64:67], v[4:7], 0
	v_mfma_f32_16x16x32_bf16 v[44:47], v[72:75], v[4:7], 0
	v_mfma_f32_16x16x32_bf16 v[48:51], v[64:67], v[8:11], 0
	v_mfma_f32_16x16x32_bf16 v[52:55], v[72:75], v[8:11], 0
	v_mfma_f32_16x16x32_bf16 v[56:59], v[64:67], v[12:15], 0
	v_mfma_f32_16x16x32_bf16 v[60:63], v[72:75], v[12:15], 0
	s_waitcnt vmcnt(1)
	v_mul_f32_e32 v132, v179, v119
	v_mul_f32_e32 v133, v178, v119
	v_fma_f32 v178, v178, v118, -v132
	v_fma_f32 v179, v179, v118, v133
	v_mul_f32_e32 v132, v181, v123
	v_mul_f32_e32 v133, v180, v123
	v_fma_f32 v180, v180, v122, -v132
	v_fma_f32 v181, v181, v122, v133
	v_mul_f32_e32 v132, v183, v127
	v_mul_f32_e32 v133, v182, v127
	v_fma_f32 v182, v182, v126, -v132
	v_fma_f32 v183, v183, v126, v133
	v_mul_f32_e32 v132, v185, v131
	v_mul_f32_e32 v133, v184, v131
	v_fma_f32 v184, v184, v130, -v132
	v_fma_f32 v185, v185, v130, v133
	v_mul_f32_e32 v132, v56, v101
	v_mul_f32_e32 v56, v56, v100
	v_fma_f32 v56, -v60, v101, v56
	v_fma_f32 v60, v60, v100, v132
	v_mul_f32_e32 v133, v57, v105
	v_mul_f32_e32 v57, v57, v104
	v_fma_f32 v57, -v61, v105, v57
	v_fma_f32 v61, v61, v104, v133
	v_mul_f32_e32 v132, v58, v109
	v_mul_f32_e32 v58, v58, v108
	v_fma_f32 v58, -v62, v109, v58
	v_fma_f32 v62, v62, v108, v132
	v_mul_f32_e32 v133, v59, v113
	v_mul_f32_e32 v59, v59, v112
	v_fma_f32 v59, -v63, v113, v59
	v_fma_f32 v63, v63, v112, v133
	v_add_f32_dpp v56, v56, v56 row_shl:1 row_mask:0xf bank_mask:0xf bound_ctrl:1
	v_add_f32_dpp v57, v57, v57 row_shl:1 row_mask:0xf bank_mask:0xf bound_ctrl:1
	v_add_f32_dpp v58, v58, v58 row_shl:1 row_mask:0xf bank_mask:0xf bound_ctrl:1
	v_add_f32_dpp v59, v59, v59 row_shl:1 row_mask:0xf bank_mask:0xf bound_ctrl:1
	v_add_f32_dpp v60, v60, v60 row_shl:1 row_mask:0xf bank_mask:0xf bound_ctrl:1
	v_add_f32_dpp v61, v61, v61 row_shl:1 row_mask:0xf bank_mask:0xf bound_ctrl:1
	v_add_f32_dpp v62, v62, v62 row_shl:1 row_mask:0xf bank_mask:0xf bound_ctrl:1
	v_add_f32_dpp v63, v63, v63 row_shl:1 row_mask:0xf bank_mask:0xf bound_ctrl:1
	v_add_f32_dpp v56, v56, v56 row_shl:2 row_mask:0xf bank_mask:0xf bound_ctrl:1
	v_add_f32_dpp v57, v57, v57 row_shl:2 row_mask:0xf bank_mask:0xf bound_ctrl:1
	v_add_f32_dpp v58, v58, v58 row_shl:2 row_mask:0xf bank_mask:0xf bound_ctrl:1
	v_add_f32_dpp v59, v59, v59 row_shl:2 row_mask:0xf bank_mask:0xf bound_ctrl:1
	v_add_f32_dpp v60, v60, v60 row_shl:2 row_mask:0xf bank_mask:0xf bound_ctrl:1
	v_add_f32_dpp v61, v61, v61 row_shl:2 row_mask:0xf bank_mask:0xf bound_ctrl:1
	v_add_f32_dpp v62, v62, v62 row_shl:2 row_mask:0xf bank_mask:0xf bound_ctrl:1
	v_add_f32_dpp v63, v63, v63 row_shl:2 row_mask:0xf bank_mask:0xf bound_ctrl:1
	v_add_f32_dpp v56, v56, v56 row_shl:4 row_mask:0xf bank_mask:0xf bound_ctrl:1
	v_add_f32_dpp v57, v57, v57 row_shl:4 row_mask:0xf bank_mask:0xf bound_ctrl:1
	v_add_f32_dpp v58, v58, v58 row_shl:4 row_mask:0xf bank_mask:0xf bound_ctrl:1
	v_add_f32_dpp v59, v59, v59 row_shl:4 row_mask:0xf bank_mask:0xf bound_ctrl:1
	v_add_f32_dpp v60, v60, v60 row_shl:4 row_mask:0xf bank_mask:0xf bound_ctrl:1
	v_add_f32_dpp v61, v61, v61 row_shl:4 row_mask:0xf bank_mask:0xf bound_ctrl:1
	v_add_f32_dpp v62, v62, v62 row_shl:4 row_mask:0xf bank_mask:0xf bound_ctrl:1
	v_add_f32_dpp v63, v63, v63 row_shl:4 row_mask:0xf bank_mask:0xf bound_ctrl:1
	v_add_f32_dpp v56, v56, v56 row_shl:8 row_mask:0xf bank_mask:0xf bound_ctrl:1
	v_add_f32_dpp v57, v57, v57 row_shl:8 row_mask:0xf bank_mask:0xf bound_ctrl:1
	v_add_f32_dpp v58, v58, v58 row_shl:8 row_mask:0xf bank_mask:0xf bound_ctrl:1
	v_add_f32_dpp v59, v59, v59 row_shl:8 row_mask:0xf bank_mask:0xf bound_ctrl:1
	v_add_f32_dpp v60, v60, v60 row_shl:8 row_mask:0xf bank_mask:0xf bound_ctrl:1
	v_add_f32_dpp v61, v61, v61 row_shl:8 row_mask:0xf bank_mask:0xf bound_ctrl:1
	v_add_f32_dpp v62, v62, v62 row_shl:8 row_mask:0xf bank_mask:0xf bound_ctrl:1
	v_add_f32_dpp v63, v63, v63 row_shl:8 row_mask:0xf bank_mask:0xf bound_ctrl:1
	v_mov_b32_dpp v88, v56 row_newbcast:0 row_mask:0xf bank_mask:0xf
	v_mov_b32_dpp v89, v57 row_newbcast:0 row_mask:0xf bank_mask:0xf
	v_mov_b32_dpp v90, v58 row_newbcast:0 row_mask:0xf bank_mask:0xf
	v_mov_b32_dpp v91, v59 row_newbcast:0 row_mask:0xf bank_mask:0xf
	v_mov_b32_dpp v92, v60 row_newbcast:0 row_mask:0xf bank_mask:0xf
	v_mov_b32_dpp v93, v61 row_newbcast:0 row_mask:0xf bank_mask:0xf
	v_mov_b32_dpp v94, v62 row_newbcast:0 row_mask:0xf bank_mask:0xf
	v_mov_b32_dpp v95, v63 row_newbcast:0 row_mask:0xf bank_mask:0xf
	v_add_f32_e32 v56, v56, v178
	v_add_f32_e32 v60, v60, v179
	v_add_f32_e32 v57, v57, v180
	v_add_f32_e32 v61, v61, v181
	v_add_f32_e32 v58, v58, v182
	v_add_f32_e32 v62, v62, v183
	v_add_f32_e32 v59, v59, v184
	v_add_f32_e32 v63, v63, v185
	v_mul_f32_e32 v132, v56, v103
	v_mul_f32_e32 v56, v56, v102
	v_fma_f32 v56, -v60, v103, v56
	v_fma_f32 v60, v60, v102, v132
	v_mul_f32_e32 v133, v57, v107
	v_mul_f32_e32 v57, v57, v106
	v_fma_f32 v57, -v61, v107, v57
	v_fma_f32 v61, v61, v106, v133
	v_mul_f32_e32 v132, v58, v111
	v_mul_f32_e32 v58, v58, v110
	v_fma_f32 v58, -v62, v111, v58
	v_fma_f32 v62, v62, v110, v132
	v_mul_f32_e32 v133, v59, v115
	v_mul_f32_e32 v59, v59, v114
	v_fma_f32 v59, -v63, v115, v59
	v_fma_f32 v63, v63, v114, v133
	v_add_f32_e32 v88, v88, v178
	v_add_f32_e32 v92, v92, v179
	v_mul_f32_e32 v132, v92, v117
	v_mul_f32_e32 v179, v88, v117
	v_fma_f32 v178, v88, v116, -v132
	v_fma_f32 v179, v92, v116, v179
	v_add_f32_e32 v89, v89, v180
	v_add_f32_e32 v93, v93, v181
	v_mul_f32_e32 v133, v93, v121
	v_mul_f32_e32 v181, v89, v121
	v_fma_f32 v180, v89, v120, -v133
	v_fma_f32 v181, v93, v120, v181
	v_add_f32_e32 v90, v90, v182
	v_add_f32_e32 v94, v94, v183
	v_mul_f32_e32 v132, v94, v125
	v_mul_f32_e32 v183, v90, v125
	v_fma_f32 v182, v90, v124, -v132
	v_fma_f32 v183, v94, v124, v183
	v_add_f32_e32 v91, v91, v184
	v_add_f32_e32 v95, v95, v185
	v_mul_f32_e32 v133, v95, v129
	v_mul_f32_e32 v185, v91, v129
	v_fma_f32 v184, v91, v128, -v133
	v_fma_f32 v185, v95, v128, v185
	v_mul_f32_e32 v132, v48, v101
	v_mul_f32_e32 v48, v48, v100
	v_fma_f32 v48, -v52, v101, v48
	v_fma_f32 v52, v52, v100, v132
	v_mul_f32_e32 v133, v49, v105
	v_mul_f32_e32 v49, v49, v104
	v_fma_f32 v49, -v53, v105, v49
	v_fma_f32 v53, v53, v104, v133
	v_mul_f32_e32 v132, v50, v109
	v_mul_f32_e32 v50, v50, v108
	v_fma_f32 v50, -v54, v109, v50
	v_fma_f32 v54, v54, v108, v132
	v_mul_f32_e32 v133, v51, v113
	v_mul_f32_e32 v51, v51, v112
	v_fma_f32 v51, -v55, v113, v51
	v_fma_f32 v55, v55, v112, v133
	v_add_f32_dpp v48, v48, v48 row_shl:1 row_mask:0xf bank_mask:0xf bound_ctrl:1
	v_add_f32_dpp v49, v49, v49 row_shl:1 row_mask:0xf bank_mask:0xf bound_ctrl:1
	v_add_f32_dpp v50, v50, v50 row_shl:1 row_mask:0xf bank_mask:0xf bound_ctrl:1
	v_add_f32_dpp v51, v51, v51 row_shl:1 row_mask:0xf bank_mask:0xf bound_ctrl:1
	v_add_f32_dpp v52, v52, v52 row_shl:1 row_mask:0xf bank_mask:0xf bound_ctrl:1
	v_add_f32_dpp v53, v53, v53 row_shl:1 row_mask:0xf bank_mask:0xf bound_ctrl:1
	v_add_f32_dpp v54, v54, v54 row_shl:1 row_mask:0xf bank_mask:0xf bound_ctrl:1
	v_add_f32_dpp v55, v55, v55 row_shl:1 row_mask:0xf bank_mask:0xf bound_ctrl:1
	v_add_f32_dpp v48, v48, v48 row_shl:2 row_mask:0xf bank_mask:0xf bound_ctrl:1
	v_add_f32_dpp v49, v49, v49 row_shl:2 row_mask:0xf bank_mask:0xf bound_ctrl:1
	v_add_f32_dpp v50, v50, v50 row_shl:2 row_mask:0xf bank_mask:0xf bound_ctrl:1
	v_add_f32_dpp v51, v51, v51 row_shl:2 row_mask:0xf bank_mask:0xf bound_ctrl:1
	v_add_f32_dpp v52, v52, v52 row_shl:2 row_mask:0xf bank_mask:0xf bound_ctrl:1
	v_add_f32_dpp v53, v53, v53 row_shl:2 row_mask:0xf bank_mask:0xf bound_ctrl:1
	v_add_f32_dpp v54, v54, v54 row_shl:2 row_mask:0xf bank_mask:0xf bound_ctrl:1
	v_add_f32_dpp v55, v55, v55 row_shl:2 row_mask:0xf bank_mask:0xf bound_ctrl:1
	v_add_f32_dpp v48, v48, v48 row_shl:4 row_mask:0xf bank_mask:0xf bound_ctrl:1
	v_add_f32_dpp v49, v49, v49 row_shl:4 row_mask:0xf bank_mask:0xf bound_ctrl:1
	v_add_f32_dpp v50, v50, v50 row_shl:4 row_mask:0xf bank_mask:0xf bound_ctrl:1
	v_add_f32_dpp v51, v51, v51 row_shl:4 row_mask:0xf bank_mask:0xf bound_ctrl:1
	v_add_f32_dpp v52, v52, v52 row_shl:4 row_mask:0xf bank_mask:0xf bound_ctrl:1
	v_add_f32_dpp v53, v53, v53 row_shl:4 row_mask:0xf bank_mask:0xf bound_ctrl:1
	v_add_f32_dpp v54, v54, v54 row_shl:4 row_mask:0xf bank_mask:0xf bound_ctrl:1
	v_add_f32_dpp v55, v55, v55 row_shl:4 row_mask:0xf bank_mask:0xf bound_ctrl:1
	v_add_f32_dpp v48, v48, v48 row_shl:8 row_mask:0xf bank_mask:0xf bound_ctrl:1
	v_add_f32_dpp v49, v49, v49 row_shl:8 row_mask:0xf bank_mask:0xf bound_ctrl:1
	v_add_f32_dpp v50, v50, v50 row_shl:8 row_mask:0xf bank_mask:0xf bound_ctrl:1
	v_add_f32_dpp v51, v51, v51 row_shl:8 row_mask:0xf bank_mask:0xf bound_ctrl:1
	v_add_f32_dpp v52, v52, v52 row_shl:8 row_mask:0xf bank_mask:0xf bound_ctrl:1
	v_add_f32_dpp v53, v53, v53 row_shl:8 row_mask:0xf bank_mask:0xf bound_ctrl:1
	v_add_f32_dpp v54, v54, v54 row_shl:8 row_mask:0xf bank_mask:0xf bound_ctrl:1
	v_add_f32_dpp v55, v55, v55 row_shl:8 row_mask:0xf bank_mask:0xf bound_ctrl:1
	v_mov_b32_dpp v88, v48 row_newbcast:0 row_mask:0xf bank_mask:0xf
	v_mov_b32_dpp v89, v49 row_newbcast:0 row_mask:0xf bank_mask:0xf
	v_mov_b32_dpp v90, v50 row_newbcast:0 row_mask:0xf bank_mask:0xf
	v_mov_b32_dpp v91, v51 row_newbcast:0 row_mask:0xf bank_mask:0xf
	v_mov_b32_dpp v92, v52 row_newbcast:0 row_mask:0xf bank_mask:0xf
	v_mov_b32_dpp v93, v53 row_newbcast:0 row_mask:0xf bank_mask:0xf
	v_mov_b32_dpp v94, v54 row_newbcast:0 row_mask:0xf bank_mask:0xf
	v_mov_b32_dpp v95, v55 row_newbcast:0 row_mask:0xf bank_mask:0xf
	v_add_f32_e32 v48, v48, v178
	v_add_f32_e32 v52, v52, v179
	v_add_f32_e32 v49, v49, v180
	v_add_f32_e32 v53, v53, v181
	v_add_f32_e32 v50, v50, v182
	v_add_f32_e32 v54, v54, v183
	v_add_f32_e32 v51, v51, v184
	v_add_f32_e32 v55, v55, v185
	v_mul_f32_e32 v132, v48, v103
	v_mul_f32_e32 v48, v48, v102
	v_fma_f32 v48, -v52, v103, v48
	v_fma_f32 v52, v52, v102, v132
	v_mul_f32_e32 v133, v49, v107
	v_mul_f32_e32 v49, v49, v106
	v_fma_f32 v49, -v53, v107, v49
	v_fma_f32 v53, v53, v106, v133
	v_mul_f32_e32 v132, v50, v111
	v_mul_f32_e32 v50, v50, v110
	v_fma_f32 v50, -v54, v111, v50
	v_fma_f32 v54, v54, v110, v132
	v_mul_f32_e32 v133, v51, v115
	v_mul_f32_e32 v51, v51, v114
	v_fma_f32 v51, -v55, v115, v51
	v_fma_f32 v55, v55, v114, v133
	v_add_f32_e32 v88, v88, v178
	v_add_f32_e32 v92, v92, v179
	v_mul_f32_e32 v132, v92, v117
	v_mul_f32_e32 v179, v88, v117
	v_fma_f32 v178, v88, v116, -v132
	v_fma_f32 v179, v92, v116, v179
	v_add_f32_e32 v89, v89, v180
	v_add_f32_e32 v93, v93, v181
	v_mul_f32_e32 v133, v93, v121
	v_mul_f32_e32 v181, v89, v121
	v_fma_f32 v180, v89, v120, -v133
	v_fma_f32 v181, v93, v120, v181
	v_add_f32_e32 v90, v90, v182
	v_add_f32_e32 v94, v94, v183
	v_mul_f32_e32 v132, v94, v125
	v_mul_f32_e32 v183, v90, v125
	v_fma_f32 v182, v90, v124, -v132
	v_fma_f32 v183, v94, v124, v183
	v_add_f32_e32 v91, v91, v184
	v_add_f32_e32 v95, v95, v185
	v_mul_f32_e32 v133, v95, v129
	v_mul_f32_e32 v185, v91, v129
	v_fma_f32 v184, v91, v128, -v133
	v_fma_f32 v185, v95, v128, v185
	v_mul_f32_e32 v132, v40, v101
	v_mul_f32_e32 v40, v40, v100
	v_fma_f32 v40, -v44, v101, v40
	v_fma_f32 v44, v44, v100, v132
	v_mul_f32_e32 v133, v41, v105
	v_mul_f32_e32 v41, v41, v104
	v_fma_f32 v41, -v45, v105, v41
	v_fma_f32 v45, v45, v104, v133
	v_mul_f32_e32 v132, v42, v109
	v_mul_f32_e32 v42, v42, v108
	v_fma_f32 v42, -v46, v109, v42
	v_fma_f32 v46, v46, v108, v132
	v_mul_f32_e32 v133, v43, v113
	v_mul_f32_e32 v43, v43, v112
	v_fma_f32 v43, -v47, v113, v43
	v_fma_f32 v47, v47, v112, v133
	v_add_f32_dpp v40, v40, v40 row_shl:1 row_mask:0xf bank_mask:0xf bound_ctrl:1
	v_add_f32_dpp v41, v41, v41 row_shl:1 row_mask:0xf bank_mask:0xf bound_ctrl:1
	v_add_f32_dpp v42, v42, v42 row_shl:1 row_mask:0xf bank_mask:0xf bound_ctrl:1
	v_add_f32_dpp v43, v43, v43 row_shl:1 row_mask:0xf bank_mask:0xf bound_ctrl:1
	v_add_f32_dpp v44, v44, v44 row_shl:1 row_mask:0xf bank_mask:0xf bound_ctrl:1
	v_add_f32_dpp v45, v45, v45 row_shl:1 row_mask:0xf bank_mask:0xf bound_ctrl:1
	v_add_f32_dpp v46, v46, v46 row_shl:1 row_mask:0xf bank_mask:0xf bound_ctrl:1
	v_add_f32_dpp v47, v47, v47 row_shl:1 row_mask:0xf bank_mask:0xf bound_ctrl:1
	v_add_f32_dpp v40, v40, v40 row_shl:2 row_mask:0xf bank_mask:0xf bound_ctrl:1
	v_add_f32_dpp v41, v41, v41 row_shl:2 row_mask:0xf bank_mask:0xf bound_ctrl:1
	v_add_f32_dpp v42, v42, v42 row_shl:2 row_mask:0xf bank_mask:0xf bound_ctrl:1
	v_add_f32_dpp v43, v43, v43 row_shl:2 row_mask:0xf bank_mask:0xf bound_ctrl:1
	v_add_f32_dpp v44, v44, v44 row_shl:2 row_mask:0xf bank_mask:0xf bound_ctrl:1
	v_add_f32_dpp v45, v45, v45 row_shl:2 row_mask:0xf bank_mask:0xf bound_ctrl:1
	v_add_f32_dpp v46, v46, v46 row_shl:2 row_mask:0xf bank_mask:0xf bound_ctrl:1
	v_add_f32_dpp v47, v47, v47 row_shl:2 row_mask:0xf bank_mask:0xf bound_ctrl:1
	v_add_f32_dpp v40, v40, v40 row_shl:4 row_mask:0xf bank_mask:0xf bound_ctrl:1
	v_add_f32_dpp v41, v41, v41 row_shl:4 row_mask:0xf bank_mask:0xf bound_ctrl:1
	v_add_f32_dpp v42, v42, v42 row_shl:4 row_mask:0xf bank_mask:0xf bound_ctrl:1
	v_add_f32_dpp v43, v43, v43 row_shl:4 row_mask:0xf bank_mask:0xf bound_ctrl:1
	v_add_f32_dpp v44, v44, v44 row_shl:4 row_mask:0xf bank_mask:0xf bound_ctrl:1
	v_add_f32_dpp v45, v45, v45 row_shl:4 row_mask:0xf bank_mask:0xf bound_ctrl:1
	v_add_f32_dpp v46, v46, v46 row_shl:4 row_mask:0xf bank_mask:0xf bound_ctrl:1
	v_add_f32_dpp v47, v47, v47 row_shl:4 row_mask:0xf bank_mask:0xf bound_ctrl:1
	v_add_f32_dpp v40, v40, v40 row_shl:8 row_mask:0xf bank_mask:0xf bound_ctrl:1
	v_add_f32_dpp v41, v41, v41 row_shl:8 row_mask:0xf bank_mask:0xf bound_ctrl:1
	v_add_f32_dpp v42, v42, v42 row_shl:8 row_mask:0xf bank_mask:0xf bound_ctrl:1
	v_add_f32_dpp v43, v43, v43 row_shl:8 row_mask:0xf bank_mask:0xf bound_ctrl:1
	v_add_f32_dpp v44, v44, v44 row_shl:8 row_mask:0xf bank_mask:0xf bound_ctrl:1
	v_add_f32_dpp v45, v45, v45 row_shl:8 row_mask:0xf bank_mask:0xf bound_ctrl:1
	v_add_f32_dpp v46, v46, v46 row_shl:8 row_mask:0xf bank_mask:0xf bound_ctrl:1
	v_add_f32_dpp v47, v47, v47 row_shl:8 row_mask:0xf bank_mask:0xf bound_ctrl:1
	v_mov_b32_dpp v88, v40 row_newbcast:0 row_mask:0xf bank_mask:0xf
	v_mov_b32_dpp v89, v41 row_newbcast:0 row_mask:0xf bank_mask:0xf
	v_mov_b32_dpp v90, v42 row_newbcast:0 row_mask:0xf bank_mask:0xf
	v_mov_b32_dpp v91, v43 row_newbcast:0 row_mask:0xf bank_mask:0xf
	v_mov_b32_dpp v92, v44 row_newbcast:0 row_mask:0xf bank_mask:0xf
	v_mov_b32_dpp v93, v45 row_newbcast:0 row_mask:0xf bank_mask:0xf
	v_mov_b32_dpp v94, v46 row_newbcast:0 row_mask:0xf bank_mask:0xf
	v_mov_b32_dpp v95, v47 row_newbcast:0 row_mask:0xf bank_mask:0xf
	v_add_f32_e32 v40, v40, v178
	v_add_f32_e32 v44, v44, v179
	v_add_f32_e32 v41, v41, v180
	v_add_f32_e32 v45, v45, v181
	v_add_f32_e32 v42, v42, v182
	v_add_f32_e32 v46, v46, v183
	v_add_f32_e32 v43, v43, v184
	v_add_f32_e32 v47, v47, v185
	v_mul_f32_e32 v132, v40, v103
	v_mul_f32_e32 v40, v40, v102
	v_fma_f32 v40, -v44, v103, v40
	v_fma_f32 v44, v44, v102, v132
	v_mul_f32_e32 v133, v41, v107
	v_mul_f32_e32 v41, v41, v106
	v_fma_f32 v41, -v45, v107, v41
	v_fma_f32 v45, v45, v106, v133
	v_mul_f32_e32 v132, v42, v111
	v_mul_f32_e32 v42, v42, v110
	v_fma_f32 v42, -v46, v111, v42
	v_fma_f32 v46, v46, v110, v132
	v_mul_f32_e32 v133, v43, v115
	v_mul_f32_e32 v43, v43, v114
	v_fma_f32 v43, -v47, v115, v43
	v_fma_f32 v47, v47, v114, v133
	v_add_f32_e32 v88, v88, v178
	v_add_f32_e32 v92, v92, v179
	v_mul_f32_e32 v132, v92, v117
	v_mul_f32_e32 v179, v88, v117
	v_fma_f32 v178, v88, v116, -v132
	v_fma_f32 v179, v92, v116, v179
	v_add_f32_e32 v89, v89, v180
	v_add_f32_e32 v93, v93, v181
	v_mul_f32_e32 v133, v93, v121
	v_mul_f32_e32 v181, v89, v121
	v_fma_f32 v180, v89, v120, -v133
	v_fma_f32 v181, v93, v120, v181
	v_add_f32_e32 v90, v90, v182
	v_add_f32_e32 v94, v94, v183
	v_mul_f32_e32 v132, v94, v125
	v_mul_f32_e32 v183, v90, v125
	v_fma_f32 v182, v90, v124, -v132
	v_fma_f32 v183, v94, v124, v183
	v_add_f32_e32 v91, v91, v184
	v_add_f32_e32 v95, v95, v185
	v_mul_f32_e32 v133, v95, v129
	v_mul_f32_e32 v185, v91, v129
	v_fma_f32 v184, v91, v128, -v133
	v_fma_f32 v185, v95, v128, v185
	v_mul_f32_e32 v132, v32, v101
	v_mul_f32_e32 v32, v32, v100
	v_fma_f32 v32, -v36, v101, v32
	v_fma_f32 v36, v36, v100, v132
	v_mul_f32_e32 v133, v33, v105
	v_mul_f32_e32 v33, v33, v104
	v_fma_f32 v33, -v37, v105, v33
	v_fma_f32 v37, v37, v104, v133
	v_mul_f32_e32 v132, v34, v109
	v_mul_f32_e32 v34, v34, v108
	v_fma_f32 v34, -v38, v109, v34
	v_fma_f32 v38, v38, v108, v132
	v_mul_f32_e32 v133, v35, v113
	v_mul_f32_e32 v35, v35, v112
	v_fma_f32 v35, -v39, v113, v35
	v_fma_f32 v39, v39, v112, v133
	v_add_f32_dpp v32, v32, v32 row_shl:1 row_mask:0xf bank_mask:0xf bound_ctrl:1
	v_add_f32_dpp v33, v33, v33 row_shl:1 row_mask:0xf bank_mask:0xf bound_ctrl:1
	v_add_f32_dpp v34, v34, v34 row_shl:1 row_mask:0xf bank_mask:0xf bound_ctrl:1
	v_add_f32_dpp v35, v35, v35 row_shl:1 row_mask:0xf bank_mask:0xf bound_ctrl:1
	v_add_f32_dpp v36, v36, v36 row_shl:1 row_mask:0xf bank_mask:0xf bound_ctrl:1
	v_add_f32_dpp v37, v37, v37 row_shl:1 row_mask:0xf bank_mask:0xf bound_ctrl:1
	v_add_f32_dpp v38, v38, v38 row_shl:1 row_mask:0xf bank_mask:0xf bound_ctrl:1
	v_add_f32_dpp v39, v39, v39 row_shl:1 row_mask:0xf bank_mask:0xf bound_ctrl:1
	v_add_f32_dpp v32, v32, v32 row_shl:2 row_mask:0xf bank_mask:0xf bound_ctrl:1
	v_add_f32_dpp v33, v33, v33 row_shl:2 row_mask:0xf bank_mask:0xf bound_ctrl:1
	v_add_f32_dpp v34, v34, v34 row_shl:2 row_mask:0xf bank_mask:0xf bound_ctrl:1
	v_add_f32_dpp v35, v35, v35 row_shl:2 row_mask:0xf bank_mask:0xf bound_ctrl:1
	v_add_f32_dpp v36, v36, v36 row_shl:2 row_mask:0xf bank_mask:0xf bound_ctrl:1
	v_add_f32_dpp v37, v37, v37 row_shl:2 row_mask:0xf bank_mask:0xf bound_ctrl:1
	v_add_f32_dpp v38, v38, v38 row_shl:2 row_mask:0xf bank_mask:0xf bound_ctrl:1
	v_add_f32_dpp v39, v39, v39 row_shl:2 row_mask:0xf bank_mask:0xf bound_ctrl:1
	v_add_f32_dpp v32, v32, v32 row_shl:4 row_mask:0xf bank_mask:0xf bound_ctrl:1
	v_add_f32_dpp v33, v33, v33 row_shl:4 row_mask:0xf bank_mask:0xf bound_ctrl:1
	v_add_f32_dpp v34, v34, v34 row_shl:4 row_mask:0xf bank_mask:0xf bound_ctrl:1
	v_add_f32_dpp v35, v35, v35 row_shl:4 row_mask:0xf bank_mask:0xf bound_ctrl:1
	v_add_f32_dpp v36, v36, v36 row_shl:4 row_mask:0xf bank_mask:0xf bound_ctrl:1
	v_add_f32_dpp v37, v37, v37 row_shl:4 row_mask:0xf bank_mask:0xf bound_ctrl:1
	v_add_f32_dpp v38, v38, v38 row_shl:4 row_mask:0xf bank_mask:0xf bound_ctrl:1
	v_add_f32_dpp v39, v39, v39 row_shl:4 row_mask:0xf bank_mask:0xf bound_ctrl:1
	v_add_f32_dpp v32, v32, v32 row_shl:8 row_mask:0xf bank_mask:0xf bound_ctrl:1
	v_add_f32_dpp v33, v33, v33 row_shl:8 row_mask:0xf bank_mask:0xf bound_ctrl:1
	v_add_f32_dpp v34, v34, v34 row_shl:8 row_mask:0xf bank_mask:0xf bound_ctrl:1
	v_add_f32_dpp v35, v35, v35 row_shl:8 row_mask:0xf bank_mask:0xf bound_ctrl:1
	v_add_f32_dpp v36, v36, v36 row_shl:8 row_mask:0xf bank_mask:0xf bound_ctrl:1
	v_add_f32_dpp v37, v37, v37 row_shl:8 row_mask:0xf bank_mask:0xf bound_ctrl:1
	v_add_f32_dpp v38, v38, v38 row_shl:8 row_mask:0xf bank_mask:0xf bound_ctrl:1
	v_add_f32_dpp v39, v39, v39 row_shl:8 row_mask:0xf bank_mask:0xf bound_ctrl:1
	v_mov_b32_dpp v88, v32 row_newbcast:0 row_mask:0xf bank_mask:0xf
	v_mov_b32_dpp v89, v33 row_newbcast:0 row_mask:0xf bank_mask:0xf
	v_mov_b32_dpp v90, v34 row_newbcast:0 row_mask:0xf bank_mask:0xf
	v_mov_b32_dpp v91, v35 row_newbcast:0 row_mask:0xf bank_mask:0xf
	v_mov_b32_dpp v92, v36 row_newbcast:0 row_mask:0xf bank_mask:0xf
	v_mov_b32_dpp v93, v37 row_newbcast:0 row_mask:0xf bank_mask:0xf
	v_mov_b32_dpp v94, v38 row_newbcast:0 row_mask:0xf bank_mask:0xf
	v_mov_b32_dpp v95, v39 row_newbcast:0 row_mask:0xf bank_mask:0xf
	v_add_f32_e32 v32, v32, v178
	v_add_f32_e32 v36, v36, v179
	v_add_f32_e32 v33, v33, v180
	v_add_f32_e32 v37, v37, v181
	v_add_f32_e32 v34, v34, v182
	v_add_f32_e32 v38, v38, v183
	v_add_f32_e32 v35, v35, v184
	v_add_f32_e32 v39, v39, v185
	v_mul_f32_e32 v132, v32, v103
	v_mul_f32_e32 v32, v32, v102
	v_fma_f32 v32, -v36, v103, v32
	v_fma_f32 v36, v36, v102, v132
	v_mul_f32_e32 v133, v33, v107
	v_mul_f32_e32 v33, v33, v106
	v_fma_f32 v33, -v37, v107, v33
	v_fma_f32 v37, v37, v106, v133
	v_mul_f32_e32 v132, v34, v111
	v_mul_f32_e32 v34, v34, v110
	v_fma_f32 v34, -v38, v111, v34
	v_fma_f32 v38, v38, v110, v132
	v_mul_f32_e32 v133, v35, v115
	v_mul_f32_e32 v35, v35, v114
	v_fma_f32 v35, -v39, v115, v35
	v_fma_f32 v39, v39, v114, v133
	v_add_f32_e32 v88, v88, v178
	v_add_f32_e32 v92, v92, v179
	v_mul_f32_e32 v132, v92, v117
	v_mul_f32_e32 v179, v88, v117
	v_fma_f32 v178, v88, v116, -v132
	v_fma_f32 v179, v92, v116, v179
	v_add_f32_e32 v89, v89, v180
	v_add_f32_e32 v93, v93, v181
	v_mul_f32_e32 v133, v93, v121
	v_mul_f32_e32 v181, v89, v121
	v_fma_f32 v180, v89, v120, -v133
	v_fma_f32 v181, v93, v120, v181
	v_add_f32_e32 v90, v90, v182
	v_add_f32_e32 v94, v94, v183
	v_mul_f32_e32 v132, v94, v125
	v_mul_f32_e32 v183, v90, v125
	v_fma_f32 v182, v90, v124, -v132
	v_fma_f32 v183, v94, v124, v183
	v_add_f32_e32 v91, v91, v184
	v_add_f32_e32 v95, v95, v185
	v_mul_f32_e32 v133, v95, v129
	v_mul_f32_e32 v185, v91, v129
	v_fma_f32 v184, v91, v128, -v133
	v_fma_f32 v185, v95, v128, v185
	s_waitcnt vmcnt(0)
	v_cvt_pk_bf16_f32 v96, v32, v33
	v_cvt_pk_bf16_f32 v97, v34, v35
	v_cvt_pk_bf16_f32 v98, v36, v37
	v_cvt_pk_bf16_f32 v99, v38, v39
	s_nop 1
	v_mfma_f32_16x16x32_bf16 v[16:19], v[80:83], v[96:99], v[16:19]
	v_cvt_pk_bf16_f32 v96, v40, v41
	v_cvt_pk_bf16_f32 v97, v42, v43
	v_cvt_pk_bf16_f32 v98, v44, v45
	v_cvt_pk_bf16_f32 v99, v46, v47
	s_nop 1
	v_mfma_f32_16x16x32_bf16 v[20:23], v[80:83], v[96:99], v[20:23]
	v_cvt_pk_bf16_f32 v96, v48, v49
	v_cvt_pk_bf16_f32 v97, v50, v51
	v_cvt_pk_bf16_f32 v98, v52, v53
	v_cvt_pk_bf16_f32 v99, v54, v55
	s_nop 1
	v_mfma_f32_16x16x32_bf16 v[24:27], v[80:83], v[96:99], v[24:27]
	v_cvt_pk_bf16_f32 v96, v56, v57
	v_cvt_pk_bf16_f32 v97, v58, v59
	v_cvt_pk_bf16_f32 v98, v60, v61
	v_cvt_pk_bf16_f32 v99, v62, v63
	s_nop 1
	v_mfma_f32_16x16x32_bf16 v[28:31], v[80:83], v[96:99], v[28:31]
	v_and_b32_e32 v100, 15, v205
	v_lshrrev_b32_e32 v101, 4, v205
	v_mul_u32_u24_e32 v102, 0xe00, v100
	v_lshl_add_u32 v102, v101, 3, v102
	v_lshlrev_b32_e32 v103, 9, v100
	v_lshl_add_u32 v103, v101, 3, v103
	v_lshlrev_b32_e32 v104, 4, v101
	s_mul_i32 s18, s9, 0xe00
	s_lshl_b32 s19, s7, 5
	s_add_i32 s18, s18, s19
	s_add_u32 s18, s18, 0x5e00c00
	s_add_u32 s18, s4, s18
	s_addc_u32 s19, s5, 0
	global_load_dwordx2 v[108:109], v102, s[18:19]
	s_add_u32 s18, s18, 0xe000
	s_addc_u32 s19, s19, 0
	global_load_dwordx2 v[110:111], v102, s[18:19]
	s_add_u32 s18, s18, 0xe000
	s_addc_u32 s19, s19, 0
	global_load_dwordx2 v[112:113], v102, s[18:19]
	s_add_u32 s18, s18, 0xe000
	s_addc_u32 s19, s19, 0
	global_load_dwordx2 v[114:115], v102, s[18:19]
	v_readlane_b32 s10, v247, 28
	s_lshl_b32 s10, s10, 10
	s_lshl_b32 s11, s7, 6
	s_add_i32 s10, s10, s11
	s_add_u32 s10, s10, 0x21fb20
	s_add_u32 s20, s4, s10
	s_addc_u32 s21, s5, 0
	global_load_dwordx4 v[116:119], v104, s[20:21]
	s_lshl_b32 s10, s9, 9
	s_add_i32 s10, s10, s11
	s_lshr_b32 s11, s11, 1
	s_sub_i32 s10, s10, s11
	s_add_u32 s10, s10, 0xc500000
	s_add_u32 s22, s4, s10
	s_addc_u32 s23, s5, 0
	s_waitcnt vmcnt(0)
	s_nop 4
	v_lshlrev_b32_e32 v120, 16, v108
	v_and_b32_e32 v121, 0xffff0000, v108
	v_lshlrev_b32_e32 v122, 16, v109
	v_and_b32_e32 v123, 0xffff0000, v109
	v_fmac_f32_e32 v16, v116, v120
	v_fmac_f32_e32 v17, v117, v121
	v_fmac_f32_e32 v18, v118, v122
	v_fmac_f32_e32 v19, v119, v123
	v_cvt_pk_bf16_f32 v124, v16, v17
	v_cvt_pk_bf16_f32 v125, v18, v19
	global_store_dwordx2 v103, v[124:125], s[22:23] offset:0
	s_add_u32 s22, s22, 0x2000
	s_addc_u32 s23, s23, 0
	v_lshlrev_b32_e32 v120, 16, v110
	v_and_b32_e32 v121, 0xffff0000, v110
	v_lshlrev_b32_e32 v122, 16, v111
	v_and_b32_e32 v123, 0xffff0000, v111
	v_fmac_f32_e32 v20, v116, v120
	v_fmac_f32_e32 v21, v117, v121
	v_fmac_f32_e32 v22, v118, v122
	v_fmac_f32_e32 v23, v119, v123
	v_cvt_pk_bf16_f32 v124, v20, v21
	v_cvt_pk_bf16_f32 v125, v22, v23
	global_store_dwordx2 v103, v[124:125], s[22:23] offset:0
	s_add_u32 s22, s22, 0x2000
	s_addc_u32 s23, s23, 0
	v_lshlrev_b32_e32 v120, 16, v112
	v_and_b32_e32 v121, 0xffff0000, v112
	v_lshlrev_b32_e32 v122, 16, v113
	v_and_b32_e32 v123, 0xffff0000, v113
	v_fmac_f32_e32 v24, v116, v120
	v_fmac_f32_e32 v25, v117, v121
	v_fmac_f32_e32 v26, v118, v122
	v_fmac_f32_e32 v27, v119, v123
	v_cvt_pk_bf16_f32 v124, v24, v25
	v_cvt_pk_bf16_f32 v125, v26, v27
	global_store_dwordx2 v103, v[124:125], s[22:23] offset:0
	s_add_u32 s22, s22, 0x2000
	s_addc_u32 s23, s23, 0
	v_lshlrev_b32_e32 v120, 16, v114
	v_and_b32_e32 v121, 0xffff0000, v114
	v_lshlrev_b32_e32 v122, 16, v115
	v_and_b32_e32 v123, 0xffff0000, v115
	v_fmac_f32_e32 v28, v116, v120
	v_fmac_f32_e32 v29, v117, v121
	v_fmac_f32_e32 v30, v118, v122
	v_fmac_f32_e32 v31, v119, v123
	v_cvt_pk_bf16_f32 v124, v28, v29
	v_cvt_pk_bf16_f32 v125, v30, v31
	global_store_dwordx2 v103, v[124:125], s[22:23] offset:0
	s_cmp_eq_u32 s37, 1
	s_cbranch_scc1 .Lss3_done
	s_add_i32 s36, s36, s30
	s_branch .Lss3_top

.LBB0_449:
	s_andn2_b64 vcc, exec, s[0:1]
	s_cbranch_vccnz .LBB0_478
	s_sub_i32 s86, s12, s60
	s_mul_i32 s10, s86, 0xf0f1
	s_lshr_b32 s10, s10, 22
	s_mul_i32 s11, s10, 68
	s_sub_i32 s8, s86, s11
	s_and_b32 s7, s10, 15
	s_lshr_b32 s6, s10, 4
	s_lshl_b32 s10, s8, 6
	s_lshl_b32 s11, s6, 8
	s_add_i32 s9, s10, s11
	s_lshl_b32 s11, s6, 12
	s_add_i32 s11, s11, s10
	s_add_i32 s11, s11, 0x300
	s_cmp_lt_u32 s8, 4
	s_cselect_b32 s9, s9, s11
	v_mov_b32_e32 v0, 0
	v_mov_b32_e32 v1, 0
	v_mov_b32_e32 v2, 0
	v_mov_b32_e32 v3, 0
	v_mov_b32_e32 v4, 0
	v_mov_b32_e32 v5, 0
	v_mov_b32_e32 v6, 0
	v_mov_b32_e32 v7, 0
	v_mov_b32_e32 v8, 0
	v_mov_b32_e32 v9, 0
	v_mov_b32_e32 v10, 0
	v_mov_b32_e32 v11, 0
	v_mov_b32_e32 v12, 0
	v_mov_b32_e32 v13, 0
	v_mov_b32_e32 v14, 0
	v_mov_b32_e32 v15, 0
	v_and_b32_e32 v100, 15, v205
	v_mul_u32_u24_e32 v100, 0xe00, v100
	v_and_b32_e32 v101, 16, v205
	v_add_u32_e32 v100, v100, v101
	s_mul_i32 s18, s9, 0xe00
	s_lshl_b32 s19, s7, 5
	s_add_i32 s18, s18, s19
	s_add_u32 s18, s18, 0x5e00c00
	s_add_u32 s18, s4, s18
	s_addc_u32 s19, s5, 0
	s_mov_b32 exec_hi, 0
	global_load_dwordx4 v[0:3], v100, s[18:19]
	s_add_u32 s18, s18, 0xe000
	s_addc_u32 s19, s19, 0
	global_load_dwordx4 v[4:7], v100, s[18:19]
	s_add_u32 s18, s18, 0xe000
	s_addc_u32 s19, s19, 0
	global_load_dwordx4 v[8:11], v100, s[18:19]
	s_add_u32 s18, s18, 0xe000
	s_addc_u32 s19, s19, 0
	global_load_dwordx4 v[12:15], v100, s[18:19]
	s_mov_b64 exec, -1
	v_and_b32_e32 v112, 15, v205
	v_lshlrev_b32_e32 v112, 6, v112
	v_and_b32_e32 v113, 16, v205
	v_lshl_add_u32 v112, v113, 1, v112
	v_lshlrev_b32_e32 v113, 4, v205
	v_lshrrev_b32_e32 v114, 4, v205
	v_lshlrev_b32_e32 v114, 5, v114
	v_readlane_b32 s10, v247, 28
	s_mov_b32 s11, s8
	s_lshl_b32 s16, s10, 1
	s_add_i32 s16, s16, 0
	s_lshl_b32 s16, s16, 4
	s_add_i32 s16, s16, s7
	s_lshl_b32 s17, s6, 1
	s_add_i32 s17, s17, 0
	s_lshl_b32 s17, s17, 4
	s_add_i32 s17, s17, s7
	s_mul_i32 s17, s17, 68
	s_add_i32 s17, s17, s11
	s_lshl_b32 s17, s17, 6
	s_lshl_b32 s20, s16, 13
	s_add_u32 s20, s20, 0xfd00000
	s_add_u32 s20, s4, s20
	s_addc_u32 s21, s5, 0
	s_lshl_b32 s24, s16, 14
	s_add_u32 s24, s24, 0xfc00000
	s_add_u32 s24, s4, s24
	s_addc_u32 s25, s5, 0
	s_lshl_b32 s26, s17, 3
	s_add_u32 s26, s26, 0x300000
	s_add_u32 s26, s4, s26
	s_addc_u32 s27, s5, 0
	global_load_dwordx4 v[48:51], v113, s[20:21]
	global_load_dwordx4 v[56:59], v113, s[20:21] offset:1024
	global_load_dwordx4 v[80:83], v113, s[24:25] offset:0
	global_load_dwordx4 v[84:87], v113, s[24:25] offset:1024
	global_load_dwordx4 v[88:91], v113, s[24:25] offset:2048
	global_load_dwordx4 v[92:95], v113, s[24:25] offset:3072
	s_add_u32 s20, s20, 0x800
	s_addc_u32 s21, s21, 0
	s_add_u32 s24, s24, 0x1000
	s_addc_u32 s25, s25, 0
	s_waitcnt vmcnt(6)
	s_waitcnt vmcnt(4)
	global_load_dwordx4 v[64:67], v113, s[20:21]
	global_load_dwordx4 v[72:75], v113, s[20:21] offset:1024
	global_load_dwordx4 v[96:99], v113, s[24:25] offset:0
	global_load_dwordx4 v[100:103], v113, s[24:25] offset:1024
	global_load_dwordx4 v[104:107], v113, s[24:25] offset:2048
	global_load_dwordx4 v[108:111], v113, s[24:25] offset:3072
	s_add_u32 s20, s20, 0x800
	s_addc_u32 s21, s21, 0
	s_add_u32 s24, s24, 0x1000
	s_addc_u32 s25, s25, 0
	v_mfma_f32_16x16x32_bf16 v[16:19], v[48:51], v[0:3], 0
	v_mfma_f32_16x16x32_bf16 v[20:23], v[56:59], v[0:3], 0
	v_mfma_f32_16x16x32_bf16 v[24:27], v[48:51], v[4:7], 0
	v_mfma_f32_16x16x32_bf16 v[28:31], v[56:59], v[4:7], 0
	v_mfma_f32_16x16x32_bf16 v[32:35], v[48:51], v[8:11], 0
	v_mfma_f32_16x16x32_bf16 v[36:39], v[56:59], v[8:11], 0
	v_mfma_f32_16x16x32_bf16 v[40:43], v[48:51], v[12:15], 0
	v_mfma_f32_16x16x32_bf16 v[44:47], v[56:59], v[12:15], 0
	s_waitcnt vmcnt(6)
	s_nop 7
	v_mul_f32_e32 v116, v81, v20
	v_fma_f32 v120, v80, v16, -v116
	v_mul_f32_e32 v116, v80, v20
	v_fma_f32 v124, v81, v16, v116
	v_mul_f32_e32 v116, v85, v21
	v_fma_f32 v121, v84, v17, -v116
	v_mul_f32_e32 v116, v84, v21
	v_fma_f32 v125, v85, v17, v116
	v_mul_f32_e32 v116, v89, v22
	v_fma_f32 v122, v88, v18, -v116
	v_mul_f32_e32 v116, v88, v22
	v_fma_f32 v126, v89, v18, v116
	v_mul_f32_e32 v116, v93, v23
	v_fma_f32 v123, v92, v19, -v116
	v_mul_f32_e32 v116, v92, v23
	v_fma_f32 v127, v93, v19, v116
	v_mul_f32_e32 v116, v81, v28
	v_fma_f32 v117, v80, v24, -v116
	v_mul_f32_e32 v116, v80, v28
	v_fma_f32 v118, v81, v24, v116
	v_fma_f32 v117, v120, v82, v117
	v_fma_f32 v118, v120, v83, v118
	v_fma_f32 v117, -v124, v83, v117
	v_fma_f32 v124, v124, v82, v118
	v_mov_b32_e32 v120, v117
	v_mul_f32_e32 v116, v85, v29
	v_fma_f32 v117, v84, v25, -v116
	v_mul_f32_e32 v116, v84, v29
	v_fma_f32 v118, v85, v25, v116
	v_fma_f32 v117, v121, v86, v117
	v_fma_f32 v118, v121, v87, v118
	v_fma_f32 v117, -v125, v87, v117
	v_fma_f32 v125, v125, v86, v118
	v_mov_b32_e32 v121, v117
	v_mul_f32_e32 v116, v89, v30
	v_fma_f32 v117, v88, v26, -v116
	v_mul_f32_e32 v116, v88, v30
	v_fma_f32 v118, v89, v26, v116
	v_fma_f32 v117, v122, v90, v117
	v_fma_f32 v118, v122, v91, v118
	v_fma_f32 v117, -v126, v91, v117
	v_fma_f32 v126, v126, v90, v118
	v_mov_b32_e32 v122, v117
	v_mul_f32_e32 v116, v93, v31
	v_fma_f32 v117, v92, v27, -v116
	v_mul_f32_e32 v116, v92, v31
	v_fma_f32 v118, v93, v27, v116
	v_fma_f32 v117, v123, v94, v117
	v_fma_f32 v118, v123, v95, v118
	v_fma_f32 v117, -v127, v95, v117
	v_fma_f32 v127, v127, v94, v118
	v_mov_b32_e32 v123, v117
	v_mul_f32_e32 v116, v81, v36
	v_fma_f32 v117, v80, v32, -v116
	v_mul_f32_e32 v116, v80, v36
	v_fma_f32 v118, v81, v32, v116
	v_fma_f32 v117, v120, v82, v117
	v_fma_f32 v118, v120, v83, v118
	v_fma_f32 v117, -v124, v83, v117
	v_fma_f32 v124, v124, v82, v118
	v_mov_b32_e32 v120, v117
	v_mul_f32_e32 v116, v85, v37
	v_fma_f32 v117, v84, v33, -v116
	v_mul_f32_e32 v116, v84, v37
	v_fma_f32 v118, v85, v33, v116
	v_fma_f32 v117, v121, v86, v117
	v_fma_f32 v118, v121, v87, v118
	v_fma_f32 v117, -v125, v87, v117
	v_fma_f32 v125, v125, v86, v118
	v_mov_b32_e32 v121, v117
	v_mul_f32_e32 v116, v89, v38
	v_fma_f32 v117, v88, v34, -v116
	v_mul_f32_e32 v116, v88, v38
	v_fma_f32 v118, v89, v34, v116
	v_fma_f32 v117, v122, v90, v117
	v_fma_f32 v118, v122, v91, v118
	v_fma_f32 v117, -v126, v91, v117
	v_fma_f32 v126, v126, v90, v118
	v_mov_b32_e32 v122, v117
	v_mul_f32_e32 v116, v93, v39
	v_fma_f32 v117, v92, v35, -v116
	v_mul_f32_e32 v116, v92, v39
	v_fma_f32 v118, v93, v35, v116
	v_fma_f32 v117, v123, v94, v117
	v_fma_f32 v118, v123, v95, v118
	v_fma_f32 v117, -v127, v95, v117
	v_fma_f32 v127, v127, v94, v118
	v_mov_b32_e32 v123, v117
	v_mul_f32_e32 v116, v81, v44
	v_fma_f32 v117, v80, v40, -v116
	v_mul_f32_e32 v116, v80, v44
	v_fma_f32 v118, v81, v40, v116
	v_fma_f32 v117, v120, v82, v117
	v_fma_f32 v118, v120, v83, v118
	v_fma_f32 v117, -v124, v83, v117
	v_fma_f32 v124, v124, v82, v118
	v_mov_b32_e32 v120, v117
	v_mul_f32_e32 v116, v85, v45
	v_fma_f32 v117, v84, v41, -v116
	v_mul_f32_e32 v116, v84, v45
	v_fma_f32 v118, v85, v41, v116
	v_fma_f32 v117, v121, v86, v117
	v_fma_f32 v118, v121, v87, v118
	v_fma_f32 v117, -v125, v87, v117
	v_fma_f32 v125, v125, v86, v118
	v_mov_b32_e32 v121, v117
	v_mul_f32_e32 v116, v89, v46
	v_fma_f32 v117, v88, v42, -v116
	v_mul_f32_e32 v116, v88, v46
	v_fma_f32 v118, v89, v42, v116
	v_fma_f32 v117, v122, v90, v117
	v_fma_f32 v118, v122, v91, v118
	v_fma_f32 v117, -v126, v91, v117
	v_fma_f32 v126, v126, v90, v118
	v_mov_b32_e32 v122, v117
	v_mul_f32_e32 v116, v93, v47
	v_fma_f32 v117, v92, v43, -v116
	v_mul_f32_e32 v116, v92, v47
	v_fma_f32 v118, v93, v43, v116
	v_fma_f32 v117, v123, v94, v117
	v_fma_f32 v118, v123, v95, v118
	v_fma_f32 v117, -v127, v95, v117
	v_fma_f32 v127, v127, v94, v118
	v_mov_b32_e32 v123, v117
	v_add_f32_dpp v120, v120, v120 row_ror:8 row_mask:0xf bank_mask:0xf
	v_add_f32_dpp v121, v121, v121 row_ror:8 row_mask:0xf bank_mask:0xf
	v_add_f32_dpp v122, v122, v122 row_ror:8 row_mask:0xf bank_mask:0xf
	v_add_f32_dpp v123, v123, v123 row_ror:8 row_mask:0xf bank_mask:0xf
	v_add_f32_dpp v124, v124, v124 row_ror:8 row_mask:0xf bank_mask:0xf
	v_add_f32_dpp v125, v125, v125 row_ror:8 row_mask:0xf bank_mask:0xf
	v_add_f32_dpp v126, v126, v126 row_ror:8 row_mask:0xf bank_mask:0xf
	v_add_f32_dpp v127, v127, v127 row_ror:8 row_mask:0xf bank_mask:0xf
	v_add_f32_dpp v120, v120, v120 row_ror:4 row_mask:0xf bank_mask:0xf
	v_add_f32_dpp v121, v121, v121 row_ror:4 row_mask:0xf bank_mask:0xf
	v_add_f32_dpp v122, v122, v122 row_ror:4 row_mask:0xf bank_mask:0xf
	v_add_f32_dpp v123, v123, v123 row_ror:4 row_mask:0xf bank_mask:0xf
	v_add_f32_dpp v124, v124, v124 row_ror:4 row_mask:0xf bank_mask:0xf
	v_add_f32_dpp v125, v125, v125 row_ror:4 row_mask:0xf bank_mask:0xf
	v_add_f32_dpp v126, v126, v126 row_ror:4 row_mask:0xf bank_mask:0xf
	v_add_f32_dpp v127, v127, v127 row_ror:4 row_mask:0xf bank_mask:0xf
	v_add_f32_dpp v120, v120, v120 row_ror:2 row_mask:0xf bank_mask:0xf
	v_add_f32_dpp v121, v121, v121 row_ror:2 row_mask:0xf bank_mask:0xf
	v_add_f32_dpp v122, v122, v122 row_ror:2 row_mask:0xf bank_mask:0xf
	v_add_f32_dpp v123, v123, v123 row_ror:2 row_mask:0xf bank_mask:0xf
	v_add_f32_dpp v124, v124, v124 row_ror:2 row_mask:0xf bank_mask:0xf
	v_add_f32_dpp v125, v125, v125 row_ror:2 row_mask:0xf bank_mask:0xf
	v_add_f32_dpp v126, v126, v126 row_ror:2 row_mask:0xf bank_mask:0xf
	v_add_f32_dpp v127, v127, v127 row_ror:2 row_mask:0xf bank_mask:0xf
	v_add_f32_dpp v120, v120, v120 row_ror:1 row_mask:0xf bank_mask:0xf
	v_add_f32_dpp v121, v121, v121 row_ror:1 row_mask:0xf bank_mask:0xf
	v_add_f32_dpp v122, v122, v122 row_ror:1 row_mask:0xf bank_mask:0xf
	v_add_f32_dpp v123, v123, v123 row_ror:1 row_mask:0xf bank_mask:0xf
	v_add_f32_dpp v124, v124, v124 row_ror:1 row_mask:0xf bank_mask:0xf
	v_add_f32_dpp v125, v125, v125 row_ror:1 row_mask:0xf bank_mask:0xf
	v_add_f32_dpp v126, v126, v126 row_ror:1 row_mask:0xf bank_mask:0xf
	v_add_f32_dpp v127, v127, v127 row_ror:1 row_mask:0xf bank_mask:0xf
	s_add_u32 s18, s26, 0
	s_addc_u32 s19, s27, 0
	v_mov_b32_e32 v128, v120
	v_mov_b32_e32 v129, v124
	v_mov_b32_e32 v130, v121
	v_mov_b32_e32 v131, v125
	v_mov_b32_e32 v132, v122
	v_mov_b32_e32 v133, v126
	v_mov_b32_e32 v134, v123
	v_mov_b32_e32 v135, v127
	s_mov_b32 exec_lo, 0x10001
	s_mov_b32 exec_hi, 0x10001
	global_store_dwordx4 v114, v[128:131], s[18:19]
	global_store_dwordx4 v114, v[132:135], s[18:19] offset:16
	s_mov_b64 exec, -1
	s_nop 1
	s_waitcnt vmcnt(4)
	global_load_dwordx4 v[48:51], v113, s[20:21]
	global_load_dwordx4 v[56:59], v113, s[20:21] offset:1024
	global_load_dwordx4 v[80:83], v113, s[24:25] offset:0
	global_load_dwordx4 v[84:87], v113, s[24:25] offset:1024
	global_load_dwordx4 v[88:91], v113, s[24:25] offset:2048
	global_load_dwordx4 v[92:95], v113, s[24:25] offset:3072
	s_add_u32 s20, s20, 0x800
	s_addc_u32 s21, s21, 0
	s_add_u32 s24, s24, 0x1000
	s_addc_u32 s25, s25, 0
	v_mfma_f32_16x16x32_bf16 v[16:19], v[64:67], v[0:3], 0
	v_mfma_f32_16x16x32_bf16 v[20:23], v[72:75], v[0:3], 0
	v_mfma_f32_16x16x32_bf16 v[24:27], v[64:67], v[4:7], 0
	v_mfma_f32_16x16x32_bf16 v[28:31], v[72:75], v[4:7], 0
	v_mfma_f32_16x16x32_bf16 v[32:35], v[64:67], v[8:11], 0
	v_mfma_f32_16x16x32_bf16 v[36:39], v[72:75], v[8:11], 0
	v_mfma_f32_16x16x32_bf16 v[40:43], v[64:67], v[12:15], 0
	v_mfma_f32_16x16x32_bf16 v[44:47], v[72:75], v[12:15], 0
	s_waitcnt vmcnt(6)
	s_nop 7
	v_mul_f32_e32 v116, v97, v20
	v_fma_f32 v120, v96, v16, -v116
	v_mul_f32_e32 v116, v96, v20
	v_fma_f32 v124, v97, v16, v116
	v_mul_f32_e32 v116, v101, v21
	v_fma_f32 v121, v100, v17, -v116
	v_mul_f32_e32 v116, v100, v21
	v_fma_f32 v125, v101, v17, v116
	v_mul_f32_e32 v116, v105, v22
	v_fma_f32 v122, v104, v18, -v116
	v_mul_f32_e32 v116, v104, v22
	v_fma_f32 v126, v105, v18, v116
	v_mul_f32_e32 v116, v109, v23
	v_fma_f32 v123, v108, v19, -v116
	v_mul_f32_e32 v116, v108, v23
	v_fma_f32 v127, v109, v19, v116
	v_mul_f32_e32 v116, v97, v28
	v_fma_f32 v117, v96, v24, -v116
	v_mul_f32_e32 v116, v96, v28
	v_fma_f32 v118, v97, v24, v116
	v_fma_f32 v117, v120, v98, v117
	v_fma_f32 v118, v120, v99, v118
	v_fma_f32 v117, -v124, v99, v117
	v_fma_f32 v124, v124, v98, v118
	v_mov_b32_e32 v120, v117
	v_mul_f32_e32 v116, v101, v29
	v_fma_f32 v117, v100, v25, -v116
	v_mul_f32_e32 v116, v100, v29
	v_fma_f32 v118, v101, v25, v116
	v_fma_f32 v117, v121, v102, v117
	v_fma_f32 v118, v121, v103, v118
	v_fma_f32 v117, -v125, v103, v117
	v_fma_f32 v125, v125, v102, v118
	v_mov_b32_e32 v121, v117
	v_mul_f32_e32 v116, v105, v30
	v_fma_f32 v117, v104, v26, -v116
	v_mul_f32_e32 v116, v104, v30
	v_fma_f32 v118, v105, v26, v116
	v_fma_f32 v117, v122, v106, v117
	v_fma_f32 v118, v122, v107, v118
	v_fma_f32 v117, -v126, v107, v117
	v_fma_f32 v126, v126, v106, v118
	v_mov_b32_e32 v122, v117
	v_mul_f32_e32 v116, v109, v31
	v_fma_f32 v117, v108, v27, -v116
	v_mul_f32_e32 v116, v108, v31
	v_fma_f32 v118, v109, v27, v116
	v_fma_f32 v117, v123, v110, v117
	v_fma_f32 v118, v123, v111, v118
	v_fma_f32 v117, -v127, v111, v117
	v_fma_f32 v127, v127, v110, v118
	v_mov_b32_e32 v123, v117
	v_mul_f32_e32 v116, v97, v36
	v_fma_f32 v117, v96, v32, -v116
	v_mul_f32_e32 v116, v96, v36
	v_fma_f32 v118, v97, v32, v116
	v_fma_f32 v117, v120, v98, v117
	v_fma_f32 v118, v120, v99, v118
	v_fma_f32 v117, -v124, v99, v117
	v_fma_f32 v124, v124, v98, v118
	v_mov_b32_e32 v120, v117
	v_mul_f32_e32 v116, v101, v37
	v_fma_f32 v117, v100, v33, -v116
	v_mul_f32_e32 v116, v100, v37
	v_fma_f32 v118, v101, v33, v116
	v_fma_f32 v117, v121, v102, v117
	v_fma_f32 v118, v121, v103, v118
	v_fma_f32 v117, -v125, v103, v117
	v_fma_f32 v125, v125, v102, v118
	v_mov_b32_e32 v121, v117
	v_mul_f32_e32 v116, v105, v38
	v_fma_f32 v117, v104, v34, -v116
	v_mul_f32_e32 v116, v104, v38
	v_fma_f32 v118, v105, v34, v116
	v_fma_f32 v117, v122, v106, v117
	v_fma_f32 v118, v122, v107, v118
	v_fma_f32 v117, -v126, v107, v117
	v_fma_f32 v126, v126, v106, v118
	v_mov_b32_e32 v122, v117
	v_mul_f32_e32 v116, v109, v39
	v_fma_f32 v117, v108, v35, -v116
	v_mul_f32_e32 v116, v108, v39
	v_fma_f32 v118, v109, v35, v116
	v_fma_f32 v117, v123, v110, v117
	v_fma_f32 v118, v123, v111, v118
	v_fma_f32 v117, -v127, v111, v117
	v_fma_f32 v127, v127, v110, v118
	v_mov_b32_e32 v123, v117
	v_mul_f32_e32 v116, v97, v44
	v_fma_f32 v117, v96, v40, -v116
	v_mul_f32_e32 v116, v96, v44
	v_fma_f32 v118, v97, v40, v116
	v_fma_f32 v117, v120, v98, v117
	v_fma_f32 v118, v120, v99, v118
	v_fma_f32 v117, -v124, v99, v117
	v_fma_f32 v124, v124, v98, v118
	v_mov_b32_e32 v120, v117
	v_mul_f32_e32 v116, v101, v45
	v_fma_f32 v117, v100, v41, -v116
	v_mul_f32_e32 v116, v100, v45
	v_fma_f32 v118, v101, v41, v116
	v_fma_f32 v117, v121, v102, v117
	v_fma_f32 v118, v121, v103, v118
	v_fma_f32 v117, -v125, v103, v117
	v_fma_f32 v125, v125, v102, v118
	v_mov_b32_e32 v121, v117
	v_mul_f32_e32 v116, v105, v46
	v_fma_f32 v117, v104, v42, -v116
	v_mul_f32_e32 v116, v104, v46
	v_fma_f32 v118, v105, v42, v116
	v_fma_f32 v117, v122, v106, v117
	v_fma_f32 v118, v122, v107, v118
	v_fma_f32 v117, -v126, v107, v117
	v_fma_f32 v126, v126, v106, v118
	v_mov_b32_e32 v122, v117
	v_mul_f32_e32 v116, v109, v47
	v_fma_f32 v117, v108, v43, -v116
	v_mul_f32_e32 v116, v108, v47
	v_fma_f32 v118, v109, v43, v116
	v_fma_f32 v117, v123, v110, v117
	v_fma_f32 v118, v123, v111, v118
	v_fma_f32 v117, -v127, v111, v117
	v_fma_f32 v127, v127, v110, v118
	v_mov_b32_e32 v123, v117
	v_add_f32_dpp v120, v120, v120 row_ror:8 row_mask:0xf bank_mask:0xf
	v_add_f32_dpp v121, v121, v121 row_ror:8 row_mask:0xf bank_mask:0xf
	v_add_f32_dpp v122, v122, v122 row_ror:8 row_mask:0xf bank_mask:0xf
	v_add_f32_dpp v123, v123, v123 row_ror:8 row_mask:0xf bank_mask:0xf
	v_add_f32_dpp v124, v124, v124 row_ror:8 row_mask:0xf bank_mask:0xf
	v_add_f32_dpp v125, v125, v125 row_ror:8 row_mask:0xf bank_mask:0xf
	v_add_f32_dpp v126, v126, v126 row_ror:8 row_mask:0xf bank_mask:0xf
	v_add_f32_dpp v127, v127, v127 row_ror:8 row_mask:0xf bank_mask:0xf
	v_add_f32_dpp v120, v120, v120 row_ror:4 row_mask:0xf bank_mask:0xf
	v_add_f32_dpp v121, v121, v121 row_ror:4 row_mask:0xf bank_mask:0xf
	v_add_f32_dpp v122, v122, v122 row_ror:4 row_mask:0xf bank_mask:0xf
	v_add_f32_dpp v123, v123, v123 row_ror:4 row_mask:0xf bank_mask:0xf
	v_add_f32_dpp v124, v124, v124 row_ror:4 row_mask:0xf bank_mask:0xf
	v_add_f32_dpp v125, v125, v125 row_ror:4 row_mask:0xf bank_mask:0xf
	v_add_f32_dpp v126, v126, v126 row_ror:4 row_mask:0xf bank_mask:0xf
	v_add_f32_dpp v127, v127, v127 row_ror:4 row_mask:0xf bank_mask:0xf
	v_add_f32_dpp v120, v120, v120 row_ror:2 row_mask:0xf bank_mask:0xf
	v_add_f32_dpp v121, v121, v121 row_ror:2 row_mask:0xf bank_mask:0xf
	v_add_f32_dpp v122, v122, v122 row_ror:2 row_mask:0xf bank_mask:0xf
	v_add_f32_dpp v123, v123, v123 row_ror:2 row_mask:0xf bank_mask:0xf
	v_add_f32_dpp v124, v124, v124 row_ror:2 row_mask:0xf bank_mask:0xf
	v_add_f32_dpp v125, v125, v125 row_ror:2 row_mask:0xf bank_mask:0xf
	v_add_f32_dpp v126, v126, v126 row_ror:2 row_mask:0xf bank_mask:0xf
	v_add_f32_dpp v127, v127, v127 row_ror:2 row_mask:0xf bank_mask:0xf
	v_add_f32_dpp v120, v120, v120 row_ror:1 row_mask:0xf bank_mask:0xf
	v_add_f32_dpp v121, v121, v121 row_ror:1 row_mask:0xf bank_mask:0xf
	v_add_f32_dpp v122, v122, v122 row_ror:1 row_mask:0xf bank_mask:0xf
	v_add_f32_dpp v123, v123, v123 row_ror:1 row_mask:0xf bank_mask:0xf
	v_add_f32_dpp v124, v124, v124 row_ror:1 row_mask:0xf bank_mask:0xf
	v_add_f32_dpp v125, v125, v125 row_ror:1 row_mask:0xf bank_mask:0xf
	v_add_f32_dpp v126, v126, v126 row_ror:1 row_mask:0xf bank_mask:0xf
	v_add_f32_dpp v127, v127, v127 row_ror:1 row_mask:0xf bank_mask:0xf
	s_add_u32 s18, s26, 128
	s_addc_u32 s19, s27, 0
	v_mov_b32_e32 v128, v120
	v_mov_b32_e32 v129, v124
	v_mov_b32_e32 v130, v121
	v_mov_b32_e32 v131, v125
	v_mov_b32_e32 v132, v122
	v_mov_b32_e32 v133, v126
	v_mov_b32_e32 v134, v123
	v_mov_b32_e32 v135, v127
	s_mov_b32 exec_lo, 0x10001
	s_mov_b32 exec_hi, 0x10001
	global_store_dwordx4 v114, v[128:131], s[18:19]
	global_store_dwordx4 v114, v[132:135], s[18:19] offset:16
	s_mov_b64 exec, -1
	s_nop 1
	s_waitcnt vmcnt(4)
	global_load_dwordx4 v[64:67], v113, s[20:21]
	global_load_dwordx4 v[72:75], v113, s[20:21] offset:1024
	global_load_dwordx4 v[96:99], v113, s[24:25] offset:0
	global_load_dwordx4 v[100:103], v113, s[24:25] offset:1024
	global_load_dwordx4 v[104:107], v113, s[24:25] offset:2048
	global_load_dwordx4 v[108:111], v113, s[24:25] offset:3072
	v_mfma_f32_16x16x32_bf16 v[16:19], v[48:51], v[0:3], 0
	v_mfma_f32_16x16x32_bf16 v[20:23], v[56:59], v[0:3], 0
	v_mfma_f32_16x16x32_bf16 v[24:27], v[48:51], v[4:7], 0
	v_mfma_f32_16x16x32_bf16 v[28:31], v[56:59], v[4:7], 0
	v_mfma_f32_16x16x32_bf16 v[32:35], v[48:51], v[8:11], 0
	v_mfma_f32_16x16x32_bf16 v[36:39], v[56:59], v[8:11], 0
	v_mfma_f32_16x16x32_bf16 v[40:43], v[48:51], v[12:15], 0
	v_mfma_f32_16x16x32_bf16 v[44:47], v[56:59], v[12:15], 0
	s_waitcnt vmcnt(6)
	s_nop 7
	v_mul_f32_e32 v116, v81, v20
	v_fma_f32 v120, v80, v16, -v116
	v_mul_f32_e32 v116, v80, v20
	v_fma_f32 v124, v81, v16, v116
	v_mul_f32_e32 v116, v85, v21
	v_fma_f32 v121, v84, v17, -v116
	v_mul_f32_e32 v116, v84, v21
	v_fma_f32 v125, v85, v17, v116
	v_mul_f32_e32 v116, v89, v22
	v_fma_f32 v122, v88, v18, -v116
	v_mul_f32_e32 v116, v88, v22
	v_fma_f32 v126, v89, v18, v116
	v_mul_f32_e32 v116, v93, v23
	v_fma_f32 v123, v92, v19, -v116
	v_mul_f32_e32 v116, v92, v23
	v_fma_f32 v127, v93, v19, v116
	v_mul_f32_e32 v116, v81, v28
	v_fma_f32 v117, v80, v24, -v116
	v_mul_f32_e32 v116, v80, v28
	v_fma_f32 v118, v81, v24, v116
	v_fma_f32 v117, v120, v82, v117
	v_fma_f32 v118, v120, v83, v118
	v_fma_f32 v117, -v124, v83, v117
	v_fma_f32 v124, v124, v82, v118
	v_mov_b32_e32 v120, v117
	v_mul_f32_e32 v116, v85, v29
	v_fma_f32 v117, v84, v25, -v116
	v_mul_f32_e32 v116, v84, v29
	v_fma_f32 v118, v85, v25, v116
	v_fma_f32 v117, v121, v86, v117
	v_fma_f32 v118, v121, v87, v118
	v_fma_f32 v117, -v125, v87, v117
	v_fma_f32 v125, v125, v86, v118
	v_mov_b32_e32 v121, v117
	v_mul_f32_e32 v116, v89, v30
	v_fma_f32 v117, v88, v26, -v116
	v_mul_f32_e32 v116, v88, v30
	v_fma_f32 v118, v89, v26, v116
	v_fma_f32 v117, v122, v90, v117
	v_fma_f32 v118, v122, v91, v118
	v_fma_f32 v117, -v126, v91, v117
	v_fma_f32 v126, v126, v90, v118
	v_mov_b32_e32 v122, v117
	v_mul_f32_e32 v116, v93, v31
	v_fma_f32 v117, v92, v27, -v116
	v_mul_f32_e32 v116, v92, v31
	v_fma_f32 v118, v93, v27, v116
	v_fma_f32 v117, v123, v94, v117
	v_fma_f32 v118, v123, v95, v118
	v_fma_f32 v117, -v127, v95, v117
	v_fma_f32 v127, v127, v94, v118
	v_mov_b32_e32 v123, v117
	v_mul_f32_e32 v116, v81, v36
	v_fma_f32 v117, v80, v32, -v116
	v_mul_f32_e32 v116, v80, v36
	v_fma_f32 v118, v81, v32, v116
	v_fma_f32 v117, v120, v82, v117
	v_fma_f32 v118, v120, v83, v118
	v_fma_f32 v117, -v124, v83, v117
	v_fma_f32 v124, v124, v82, v118
	v_mov_b32_e32 v120, v117
	v_mul_f32_e32 v116, v85, v37
	v_fma_f32 v117, v84, v33, -v116
	v_mul_f32_e32 v116, v84, v37
	v_fma_f32 v118, v85, v33, v116
	v_fma_f32 v117, v121, v86, v117
	v_fma_f32 v118, v121, v87, v118
	v_fma_f32 v117, -v125, v87, v117
	v_fma_f32 v125, v125, v86, v118
	v_mov_b32_e32 v121, v117
	v_mul_f32_e32 v116, v89, v38
	v_fma_f32 v117, v88, v34, -v116
	v_mul_f32_e32 v116, v88, v38
	v_fma_f32 v118, v89, v34, v116
	v_fma_f32 v117, v122, v90, v117
	v_fma_f32 v118, v122, v91, v118
	v_fma_f32 v117, -v126, v91, v117
	v_fma_f32 v126, v126, v90, v118
	v_mov_b32_e32 v122, v117
	v_mul_f32_e32 v116, v93, v39
	v_fma_f32 v117, v92, v35, -v116
	v_mul_f32_e32 v116, v92, v39
	v_fma_f32 v118, v93, v35, v116
	v_fma_f32 v117, v123, v94, v117
	v_fma_f32 v118, v123, v95, v118
	v_fma_f32 v117, -v127, v95, v117
	v_fma_f32 v127, v127, v94, v118
	v_mov_b32_e32 v123, v117
	v_mul_f32_e32 v116, v81, v44
	v_fma_f32 v117, v80, v40, -v116
	v_mul_f32_e32 v116, v80, v44
	v_fma_f32 v118, v81, v40, v116
	v_fma_f32 v117, v120, v82, v117
	v_fma_f32 v118, v120, v83, v118
	v_fma_f32 v117, -v124, v83, v117
	v_fma_f32 v124, v124, v82, v118
	v_mov_b32_e32 v120, v117
	v_mul_f32_e32 v116, v85, v45
	v_fma_f32 v117, v84, v41, -v116
	v_mul_f32_e32 v116, v84, v45
	v_fma_f32 v118, v85, v41, v116
	v_fma_f32 v117, v121, v86, v117
	v_fma_f32 v118, v121, v87, v118
	v_fma_f32 v117, -v125, v87, v117
	v_fma_f32 v125, v125, v86, v118
	v_mov_b32_e32 v121, v117
	v_mul_f32_e32 v116, v89, v46
	v_fma_f32 v117, v88, v42, -v116
	v_mul_f32_e32 v116, v88, v46
	v_fma_f32 v118, v89, v42, v116
	v_fma_f32 v117, v122, v90, v117
	v_fma_f32 v118, v122, v91, v118
	v_fma_f32 v117, -v126, v91, v117
	v_fma_f32 v126, v126, v90, v118
	v_mov_b32_e32 v122, v117
	v_mul_f32_e32 v116, v93, v47
	v_fma_f32 v117, v92, v43, -v116
	v_mul_f32_e32 v116, v92, v47
	v_fma_f32 v118, v93, v43, v116
	v_fma_f32 v117, v123, v94, v117
	v_fma_f32 v118, v123, v95, v118
	v_fma_f32 v117, -v127, v95, v117
	v_fma_f32 v127, v127, v94, v118
	v_mov_b32_e32 v123, v117
	v_add_f32_dpp v120, v120, v120 row_ror:8 row_mask:0xf bank_mask:0xf
	v_add_f32_dpp v121, v121, v121 row_ror:8 row_mask:0xf bank_mask:0xf
	v_add_f32_dpp v122, v122, v122 row_ror:8 row_mask:0xf bank_mask:0xf
	v_add_f32_dpp v123, v123, v123 row_ror:8 row_mask:0xf bank_mask:0xf
	v_add_f32_dpp v124, v124, v124 row_ror:8 row_mask:0xf bank_mask:0xf
	v_add_f32_dpp v125, v125, v125 row_ror:8 row_mask:0xf bank_mask:0xf
	v_add_f32_dpp v126, v126, v126 row_ror:8 row_mask:0xf bank_mask:0xf
	v_add_f32_dpp v127, v127, v127 row_ror:8 row_mask:0xf bank_mask:0xf
	v_add_f32_dpp v120, v120, v120 row_ror:4 row_mask:0xf bank_mask:0xf
	v_add_f32_dpp v121, v121, v121 row_ror:4 row_mask:0xf bank_mask:0xf
	v_add_f32_dpp v122, v122, v122 row_ror:4 row_mask:0xf bank_mask:0xf
	v_add_f32_dpp v123, v123, v123 row_ror:4 row_mask:0xf bank_mask:0xf
	v_add_f32_dpp v124, v124, v124 row_ror:4 row_mask:0xf bank_mask:0xf
	v_add_f32_dpp v125, v125, v125 row_ror:4 row_mask:0xf bank_mask:0xf
	v_add_f32_dpp v126, v126, v126 row_ror:4 row_mask:0xf bank_mask:0xf
	v_add_f32_dpp v127, v127, v127 row_ror:4 row_mask:0xf bank_mask:0xf
	v_add_f32_dpp v120, v120, v120 row_ror:2 row_mask:0xf bank_mask:0xf
	v_add_f32_dpp v121, v121, v121 row_ror:2 row_mask:0xf bank_mask:0xf
	v_add_f32_dpp v122, v122, v122 row_ror:2 row_mask:0xf bank_mask:0xf
	v_add_f32_dpp v123, v123, v123 row_ror:2 row_mask:0xf bank_mask:0xf
	v_add_f32_dpp v124, v124, v124 row_ror:2 row_mask:0xf bank_mask:0xf
	v_add_f32_dpp v125, v125, v125 row_ror:2 row_mask:0xf bank_mask:0xf
	v_add_f32_dpp v126, v126, v126 row_ror:2 row_mask:0xf bank_mask:0xf
	v_add_f32_dpp v127, v127, v127 row_ror:2 row_mask:0xf bank_mask:0xf
	v_add_f32_dpp v120, v120, v120 row_ror:1 row_mask:0xf bank_mask:0xf
	v_add_f32_dpp v121, v121, v121 row_ror:1 row_mask:0xf bank_mask:0xf
	v_add_f32_dpp v122, v122, v122 row_ror:1 row_mask:0xf bank_mask:0xf
	v_add_f32_dpp v123, v123, v123 row_ror:1 row_mask:0xf bank_mask:0xf
	v_add_f32_dpp v124, v124, v124 row_ror:1 row_mask:0xf bank_mask:0xf
	v_add_f32_dpp v125, v125, v125 row_ror:1 row_mask:0xf bank_mask:0xf
	v_add_f32_dpp v126, v126, v126 row_ror:1 row_mask:0xf bank_mask:0xf
	v_add_f32_dpp v127, v127, v127 row_ror:1 row_mask:0xf bank_mask:0xf
	s_add_u32 s18, s26, 256
	s_addc_u32 s19, s27, 0
	v_mov_b32_e32 v128, v120
	v_mov_b32_e32 v129, v124
	v_mov_b32_e32 v130, v121
	v_mov_b32_e32 v131, v125
	v_mov_b32_e32 v132, v122
	v_mov_b32_e32 v133, v126
	v_mov_b32_e32 v134, v123
	v_mov_b32_e32 v135, v127
	s_mov_b32 exec_lo, 0x10001
	s_mov_b32 exec_hi, 0x10001
	global_store_dwordx4 v114, v[128:131], s[18:19]
	global_store_dwordx4 v114, v[132:135], s[18:19] offset:16
	s_mov_b64 exec, -1
	s_nop 1
	s_waitcnt vmcnt(4)
	v_readlane_b32 s10, v247, 28
	s_sub_i32 s11, 3, s8
	s_sub_i32 s17, 71, s8
	s_cmp_lt_u32 s8, 4
	s_cselect_b32 s11, s11, s17
	s_lshl_b32 s16, s10, 1
	s_add_i32 s16, s16, 1
	s_lshl_b32 s16, s16, 4
	s_add_i32 s16, s16, s7
	s_lshl_b32 s17, s6, 1
	s_add_i32 s17, s17, 1
	s_lshl_b32 s17, s17, 4
	s_add_i32 s17, s17, s7
	s_mul_i32 s17, s17, 68
	s_add_i32 s17, s17, s11
	s_lshl_b32 s17, s17, 6
	s_lshl_b32 s20, s16, 13
	s_add_u32 s20, s20, 0xfd00000
	s_add_u32 s20, s4, s20
	s_addc_u32 s21, s5, 0
	s_lshl_b32 s24, s16, 14
	s_add_u32 s24, s24, 0xfc00000
	s_add_u32 s24, s4, s24
	s_addc_u32 s25, s5, 0
	s_lshl_b32 s36, s17, 3
	s_add_u32 s36, s36, 0x300000
	s_add_u32 s36, s4, s36
	s_addc_u32 s37, s5, 0
	global_load_dwordx4 v[48:51], v113, s[20:21]
	global_load_dwordx4 v[56:59], v113, s[20:21] offset:1024
	global_load_dwordx4 v[80:83], v113, s[24:25] offset:0
	global_load_dwordx4 v[84:87], v113, s[24:25] offset:1024
	global_load_dwordx4 v[88:91], v113, s[24:25] offset:2048
	global_load_dwordx4 v[92:95], v113, s[24:25] offset:3072
	s_add_u32 s20, s20, 0x800
	s_addc_u32 s21, s21, 0
	s_add_u32 s24, s24, 0x1000
	s_addc_u32 s25, s25, 0
	v_mfma_f32_16x16x32_bf16 v[16:19], v[64:67], v[0:3], 0
	v_mfma_f32_16x16x32_bf16 v[20:23], v[72:75], v[0:3], 0
	v_mfma_f32_16x16x32_bf16 v[24:27], v[64:67], v[4:7], 0
	v_mfma_f32_16x16x32_bf16 v[28:31], v[72:75], v[4:7], 0
	v_mfma_f32_16x16x32_bf16 v[32:35], v[64:67], v[8:11], 0
	v_mfma_f32_16x16x32_bf16 v[36:39], v[72:75], v[8:11], 0
	v_mfma_f32_16x16x32_bf16 v[40:43], v[64:67], v[12:15], 0
	v_mfma_f32_16x16x32_bf16 v[44:47], v[72:75], v[12:15], 0
	s_waitcnt vmcnt(6)
	s_nop 7
	v_mul_f32_e32 v116, v97, v20
	v_fma_f32 v120, v96, v16, -v116
	v_mul_f32_e32 v116, v96, v20
	v_fma_f32 v124, v97, v16, v116
	v_mul_f32_e32 v116, v101, v21
	v_fma_f32 v121, v100, v17, -v116
	v_mul_f32_e32 v116, v100, v21
	v_fma_f32 v125, v101, v17, v116
	v_mul_f32_e32 v116, v105, v22
	v_fma_f32 v122, v104, v18, -v116
	v_mul_f32_e32 v116, v104, v22
	v_fma_f32 v126, v105, v18, v116
	v_mul_f32_e32 v116, v109, v23
	v_fma_f32 v123, v108, v19, -v116
	v_mul_f32_e32 v116, v108, v23
	v_fma_f32 v127, v109, v19, v116
	v_mul_f32_e32 v116, v97, v28
	v_fma_f32 v117, v96, v24, -v116
	v_mul_f32_e32 v116, v96, v28
	v_fma_f32 v118, v97, v24, v116
	v_fma_f32 v117, v120, v98, v117
	v_fma_f32 v118, v120, v99, v118
	v_fma_f32 v117, -v124, v99, v117
	v_fma_f32 v124, v124, v98, v118
	v_mov_b32_e32 v120, v117
	v_mul_f32_e32 v116, v101, v29
	v_fma_f32 v117, v100, v25, -v116
	v_mul_f32_e32 v116, v100, v29
	v_fma_f32 v118, v101, v25, v116
	v_fma_f32 v117, v121, v102, v117
	v_fma_f32 v118, v121, v103, v118
	v_fma_f32 v117, -v125, v103, v117
	v_fma_f32 v125, v125, v102, v118
	v_mov_b32_e32 v121, v117
	v_mul_f32_e32 v116, v105, v30
	v_fma_f32 v117, v104, v26, -v116
	v_mul_f32_e32 v116, v104, v30
	v_fma_f32 v118, v105, v26, v116
	v_fma_f32 v117, v122, v106, v117
	v_fma_f32 v118, v122, v107, v118
	v_fma_f32 v117, -v126, v107, v117
	v_fma_f32 v126, v126, v106, v118
	v_mov_b32_e32 v122, v117
	v_mul_f32_e32 v116, v109, v31
	v_fma_f32 v117, v108, v27, -v116
	v_mul_f32_e32 v116, v108, v31
	v_fma_f32 v118, v109, v27, v116
	v_fma_f32 v117, v123, v110, v117
	v_fma_f32 v118, v123, v111, v118
	v_fma_f32 v117, -v127, v111, v117
	v_fma_f32 v127, v127, v110, v118
	v_mov_b32_e32 v123, v117
	v_mul_f32_e32 v116, v97, v36
	v_fma_f32 v117, v96, v32, -v116
	v_mul_f32_e32 v116, v96, v36
	v_fma_f32 v118, v97, v32, v116
	v_fma_f32 v117, v120, v98, v117
	v_fma_f32 v118, v120, v99, v118
	v_fma_f32 v117, -v124, v99, v117
	v_fma_f32 v124, v124, v98, v118
	v_mov_b32_e32 v120, v117
	v_mul_f32_e32 v116, v101, v37
	v_fma_f32 v117, v100, v33, -v116
	v_mul_f32_e32 v116, v100, v37
	v_fma_f32 v118, v101, v33, v116
	v_fma_f32 v117, v121, v102, v117
	v_fma_f32 v118, v121, v103, v118
	v_fma_f32 v117, -v125, v103, v117
	v_fma_f32 v125, v125, v102, v118
	v_mov_b32_e32 v121, v117
	v_mul_f32_e32 v116, v105, v38
	v_fma_f32 v117, v104, v34, -v116
	v_mul_f32_e32 v116, v104, v38
	v_fma_f32 v118, v105, v34, v116
	v_fma_f32 v117, v122, v106, v117
	v_fma_f32 v118, v122, v107, v118
	v_fma_f32 v117, -v126, v107, v117
	v_fma_f32 v126, v126, v106, v118
	v_mov_b32_e32 v122, v117
	v_mul_f32_e32 v116, v109, v39
	v_fma_f32 v117, v108, v35, -v116
	v_mul_f32_e32 v116, v108, v39
	v_fma_f32 v118, v109, v35, v116
	v_fma_f32 v117, v123, v110, v117
	v_fma_f32 v118, v123, v111, v118
	v_fma_f32 v117, -v127, v111, v117
	v_fma_f32 v127, v127, v110, v118
	v_mov_b32_e32 v123, v117
	v_mul_f32_e32 v116, v97, v44
	v_fma_f32 v117, v96, v40, -v116
	v_mul_f32_e32 v116, v96, v44
	v_fma_f32 v118, v97, v40, v116
	v_fma_f32 v117, v120, v98, v117
	v_fma_f32 v118, v120, v99, v118
	v_fma_f32 v117, -v124, v99, v117
	v_fma_f32 v124, v124, v98, v118
	v_mov_b32_e32 v120, v117
	v_mul_f32_e32 v116, v101, v45
	v_fma_f32 v117, v100, v41, -v116
	v_mul_f32_e32 v116, v100, v45
	v_fma_f32 v118, v101, v41, v116
	v_fma_f32 v117, v121, v102, v117
	v_fma_f32 v118, v121, v103, v118
	v_fma_f32 v117, -v125, v103, v117
	v_fma_f32 v125, v125, v102, v118
	v_mov_b32_e32 v121, v117
	v_mul_f32_e32 v116, v105, v46
	v_fma_f32 v117, v104, v42, -v116
	v_mul_f32_e32 v116, v104, v46
	v_fma_f32 v118, v105, v42, v116
	v_fma_f32 v117, v122, v106, v117
	v_fma_f32 v118, v122, v107, v118
	v_fma_f32 v117, -v126, v107, v117
	v_fma_f32 v126, v126, v106, v118
	v_mov_b32_e32 v122, v117
	v_mul_f32_e32 v116, v109, v47
	v_fma_f32 v117, v108, v43, -v116
	v_mul_f32_e32 v116, v108, v47
	v_fma_f32 v118, v109, v43, v116
	v_fma_f32 v117, v123, v110, v117
	v_fma_f32 v118, v123, v111, v118
	v_fma_f32 v117, -v127, v111, v117
	v_fma_f32 v127, v127, v110, v118
	v_mov_b32_e32 v123, v117
	v_add_f32_dpp v120, v120, v120 row_ror:8 row_mask:0xf bank_mask:0xf
	v_add_f32_dpp v121, v121, v121 row_ror:8 row_mask:0xf bank_mask:0xf
	v_add_f32_dpp v122, v122, v122 row_ror:8 row_mask:0xf bank_mask:0xf
	v_add_f32_dpp v123, v123, v123 row_ror:8 row_mask:0xf bank_mask:0xf
	v_add_f32_dpp v124, v124, v124 row_ror:8 row_mask:0xf bank_mask:0xf
	v_add_f32_dpp v125, v125, v125 row_ror:8 row_mask:0xf bank_mask:0xf
	v_add_f32_dpp v126, v126, v126 row_ror:8 row_mask:0xf bank_mask:0xf
	v_add_f32_dpp v127, v127, v127 row_ror:8 row_mask:0xf bank_mask:0xf
	v_add_f32_dpp v120, v120, v120 row_ror:4 row_mask:0xf bank_mask:0xf
	v_add_f32_dpp v121, v121, v121 row_ror:4 row_mask:0xf bank_mask:0xf
	v_add_f32_dpp v122, v122, v122 row_ror:4 row_mask:0xf bank_mask:0xf
	v_add_f32_dpp v123, v123, v123 row_ror:4 row_mask:0xf bank_mask:0xf
	v_add_f32_dpp v124, v124, v124 row_ror:4 row_mask:0xf bank_mask:0xf
	v_add_f32_dpp v125, v125, v125 row_ror:4 row_mask:0xf bank_mask:0xf
	v_add_f32_dpp v126, v126, v126 row_ror:4 row_mask:0xf bank_mask:0xf
	v_add_f32_dpp v127, v127, v127 row_ror:4 row_mask:0xf bank_mask:0xf
	v_add_f32_dpp v120, v120, v120 row_ror:2 row_mask:0xf bank_mask:0xf
	v_add_f32_dpp v121, v121, v121 row_ror:2 row_mask:0xf bank_mask:0xf
	v_add_f32_dpp v122, v122, v122 row_ror:2 row_mask:0xf bank_mask:0xf
	v_add_f32_dpp v123, v123, v123 row_ror:2 row_mask:0xf bank_mask:0xf
	v_add_f32_dpp v124, v124, v124 row_ror:2 row_mask:0xf bank_mask:0xf
	v_add_f32_dpp v125, v125, v125 row_ror:2 row_mask:0xf bank_mask:0xf
	v_add_f32_dpp v126, v126, v126 row_ror:2 row_mask:0xf bank_mask:0xf
	v_add_f32_dpp v127, v127, v127 row_ror:2 row_mask:0xf bank_mask:0xf
	v_add_f32_dpp v120, v120, v120 row_ror:1 row_mask:0xf bank_mask:0xf
	v_add_f32_dpp v121, v121, v121 row_ror:1 row_mask:0xf bank_mask:0xf
	v_add_f32_dpp v122, v122, v122 row_ror:1 row_mask:0xf bank_mask:0xf
	v_add_f32_dpp v123, v123, v123 row_ror:1 row_mask:0xf bank_mask:0xf
	v_add_f32_dpp v124, v124, v124 row_ror:1 row_mask:0xf bank_mask:0xf
	v_add_f32_dpp v125, v125, v125 row_ror:1 row_mask:0xf bank_mask:0xf
	v_add_f32_dpp v126, v126, v126 row_ror:1 row_mask:0xf bank_mask:0xf
	v_add_f32_dpp v127, v127, v127 row_ror:1 row_mask:0xf bank_mask:0xf
	s_add_u32 s18, s26, 384
	s_addc_u32 s19, s27, 0
	v_mov_b32_e32 v128, v120
	v_mov_b32_e32 v129, v124
	v_mov_b32_e32 v130, v121
	v_mov_b32_e32 v131, v125
	v_mov_b32_e32 v132, v122
	v_mov_b32_e32 v133, v126
	v_mov_b32_e32 v134, v123
	v_mov_b32_e32 v135, v127
	s_mov_b32 exec_lo, 0x10001
	s_mov_b32 exec_hi, 0x10001
	global_store_dwordx4 v114, v[128:131], s[18:19]
	global_store_dwordx4 v114, v[132:135], s[18:19] offset:16
	s_mov_b64 exec, -1
	s_nop 1
	s_waitcnt vmcnt(4)
	global_load_dwordx4 v[64:67], v113, s[20:21]
	global_load_dwordx4 v[72:75], v113, s[20:21] offset:1024
	global_load_dwordx4 v[96:99], v113, s[24:25] offset:0
	global_load_dwordx4 v[100:103], v113, s[24:25] offset:1024
	global_load_dwordx4 v[104:107], v113, s[24:25] offset:2048
	global_load_dwordx4 v[108:111], v113, s[24:25] offset:3072
	s_add_u32 s20, s20, 0x800
	s_addc_u32 s21, s21, 0
	s_add_u32 s24, s24, 0x1000
	s_addc_u32 s25, s25, 0
	v_mfma_f32_16x16x32_bf16 v[16:19], v[48:51], v[0:3], 0
	v_mfma_f32_16x16x32_bf16 v[20:23], v[56:59], v[0:3], 0
	v_mfma_f32_16x16x32_bf16 v[24:27], v[48:51], v[4:7], 0
	v_mfma_f32_16x16x32_bf16 v[28:31], v[56:59], v[4:7], 0
	v_mfma_f32_16x16x32_bf16 v[32:35], v[48:51], v[8:11], 0
	v_mfma_f32_16x16x32_bf16 v[36:39], v[56:59], v[8:11], 0
	v_mfma_f32_16x16x32_bf16 v[40:43], v[48:51], v[12:15], 0
	v_mfma_f32_16x16x32_bf16 v[44:47], v[56:59], v[12:15], 0
	s_waitcnt vmcnt(6)
	s_nop 7
	v_mul_f32_e32 v116, v81, v44
	v_fma_f32 v120, v80, v40, -v116
	v_mul_f32_e32 v116, v80, v44
	v_fma_f32 v124, v81, v40, v116
	v_mul_f32_e32 v116, v85, v45
	v_fma_f32 v121, v84, v41, -v116
	v_mul_f32_e32 v116, v84, v45
	v_fma_f32 v125, v85, v41, v116
	v_mul_f32_e32 v116, v89, v46
	v_fma_f32 v122, v88, v42, -v116
	v_mul_f32_e32 v116, v88, v46
	v_fma_f32 v126, v89, v42, v116
	v_mul_f32_e32 v116, v93, v47
	v_fma_f32 v123, v92, v43, -v116
	v_mul_f32_e32 v116, v92, v47
	v_fma_f32 v127, v93, v43, v116
	v_mul_f32_e32 v116, v81, v36
	v_fma_f32 v117, v80, v32, -v116
	v_mul_f32_e32 v116, v80, v36
	v_fma_f32 v118, v81, v32, v116
	v_fma_f32 v117, v120, v82, v117
	v_fma_f32 v118, v120, v83, v118
	v_fma_f32 v117, -v124, v83, v117
	v_fma_f32 v124, v124, v82, v118
	v_mov_b32_e32 v120, v117
	v_mul_f32_e32 v116, v85, v37
	v_fma_f32 v117, v84, v33, -v116
	v_mul_f32_e32 v116, v84, v37
	v_fma_f32 v118, v85, v33, v116
	v_fma_f32 v117, v121, v86, v117
	v_fma_f32 v118, v121, v87, v118
	v_fma_f32 v117, -v125, v87, v117
	v_fma_f32 v125, v125, v86, v118
	v_mov_b32_e32 v121, v117
	v_mul_f32_e32 v116, v89, v38
	v_fma_f32 v117, v88, v34, -v116
	v_mul_f32_e32 v116, v88, v38
	v_fma_f32 v118, v89, v34, v116
	v_fma_f32 v117, v122, v90, v117
	v_fma_f32 v118, v122, v91, v118
	v_fma_f32 v117, -v126, v91, v117
	v_fma_f32 v126, v126, v90, v118
	v_mov_b32_e32 v122, v117
	v_mul_f32_e32 v116, v93, v39
	v_fma_f32 v117, v92, v35, -v116
	v_mul_f32_e32 v116, v92, v39
	v_fma_f32 v118, v93, v35, v116
	v_fma_f32 v117, v123, v94, v117
	v_fma_f32 v118, v123, v95, v118
	v_fma_f32 v117, -v127, v95, v117
	v_fma_f32 v127, v127, v94, v118
	v_mov_b32_e32 v123, v117
	v_mul_f32_e32 v116, v81, v28
	v_fma_f32 v117, v80, v24, -v116
	v_mul_f32_e32 v116, v80, v28
	v_fma_f32 v118, v81, v24, v116
	v_fma_f32 v117, v120, v82, v117
	v_fma_f32 v118, v120, v83, v118
	v_fma_f32 v117, -v124, v83, v117
	v_fma_f32 v124, v124, v82, v118
	v_mov_b32_e32 v120, v117
	v_mul_f32_e32 v116, v85, v29
	v_fma_f32 v117, v84, v25, -v116
	v_mul_f32_e32 v116, v84, v29
	v_fma_f32 v118, v85, v25, v116
	v_fma_f32 v117, v121, v86, v117
	v_fma_f32 v118, v121, v87, v118
	v_fma_f32 v117, -v125, v87, v117
	v_fma_f32 v125, v125, v86, v118
	v_mov_b32_e32 v121, v117
	v_mul_f32_e32 v116, v89, v30
	v_fma_f32 v117, v88, v26, -v116
	v_mul_f32_e32 v116, v88, v30
	v_fma_f32 v118, v89, v26, v116
	v_fma_f32 v117, v122, v90, v117
	v_fma_f32 v118, v122, v91, v118
	v_fma_f32 v117, -v126, v91, v117
	v_fma_f32 v126, v126, v90, v118
	v_mov_b32_e32 v122, v117
	v_mul_f32_e32 v116, v93, v31
	v_fma_f32 v117, v92, v27, -v116
	v_mul_f32_e32 v116, v92, v31
	v_fma_f32 v118, v93, v27, v116
	v_fma_f32 v117, v123, v94, v117
	v_fma_f32 v118, v123, v95, v118
	v_fma_f32 v117, -v127, v95, v117
	v_fma_f32 v127, v127, v94, v118
	v_mov_b32_e32 v123, v117
	v_mul_f32_e32 v116, v81, v20
	v_fma_f32 v117, v80, v16, -v116
	v_mul_f32_e32 v116, v80, v20
	v_fma_f32 v118, v81, v16, v116
	v_fma_f32 v117, v120, v82, v117
	v_fma_f32 v118, v120, v83, v118
	v_fma_f32 v117, -v124, v83, v117
	v_fma_f32 v124, v124, v82, v118
	v_mov_b32_e32 v120, v117
	v_mul_f32_e32 v116, v85, v21
	v_fma_f32 v117, v84, v17, -v116
	v_mul_f32_e32 v116, v84, v21
	v_fma_f32 v118, v85, v17, v116
	v_fma_f32 v117, v121, v86, v117
	v_fma_f32 v118, v121, v87, v118
	v_fma_f32 v117, -v125, v87, v117
	v_fma_f32 v125, v125, v86, v118
	v_mov_b32_e32 v121, v117
	v_mul_f32_e32 v116, v89, v22
	v_fma_f32 v117, v88, v18, -v116
	v_mul_f32_e32 v116, v88, v22
	v_fma_f32 v118, v89, v18, v116
	v_fma_f32 v117, v122, v90, v117
	v_fma_f32 v118, v122, v91, v118
	v_fma_f32 v117, -v126, v91, v117
	v_fma_f32 v126, v126, v90, v118
	v_mov_b32_e32 v122, v117
	v_mul_f32_e32 v116, v93, v23
	v_fma_f32 v117, v92, v19, -v116
	v_mul_f32_e32 v116, v92, v23
	v_fma_f32 v118, v93, v19, v116
	v_fma_f32 v117, v123, v94, v117
	v_fma_f32 v118, v123, v95, v118
	v_fma_f32 v117, -v127, v95, v117
	v_fma_f32 v127, v127, v94, v118
	v_mov_b32_e32 v123, v117
	v_add_f32_dpp v120, v120, v120 row_ror:8 row_mask:0xf bank_mask:0xf
	v_add_f32_dpp v121, v121, v121 row_ror:8 row_mask:0xf bank_mask:0xf
	v_add_f32_dpp v122, v122, v122 row_ror:8 row_mask:0xf bank_mask:0xf
	v_add_f32_dpp v123, v123, v123 row_ror:8 row_mask:0xf bank_mask:0xf
	v_add_f32_dpp v124, v124, v124 row_ror:8 row_mask:0xf bank_mask:0xf
	v_add_f32_dpp v125, v125, v125 row_ror:8 row_mask:0xf bank_mask:0xf
	v_add_f32_dpp v126, v126, v126 row_ror:8 row_mask:0xf bank_mask:0xf
	v_add_f32_dpp v127, v127, v127 row_ror:8 row_mask:0xf bank_mask:0xf
	v_add_f32_dpp v120, v120, v120 row_ror:4 row_mask:0xf bank_mask:0xf
	v_add_f32_dpp v121, v121, v121 row_ror:4 row_mask:0xf bank_mask:0xf
	v_add_f32_dpp v122, v122, v122 row_ror:4 row_mask:0xf bank_mask:0xf
	v_add_f32_dpp v123, v123, v123 row_ror:4 row_mask:0xf bank_mask:0xf
	v_add_f32_dpp v124, v124, v124 row_ror:4 row_mask:0xf bank_mask:0xf
	v_add_f32_dpp v125, v125, v125 row_ror:4 row_mask:0xf bank_mask:0xf
	v_add_f32_dpp v126, v126, v126 row_ror:4 row_mask:0xf bank_mask:0xf
	v_add_f32_dpp v127, v127, v127 row_ror:4 row_mask:0xf bank_mask:0xf
	v_add_f32_dpp v120, v120, v120 row_ror:2 row_mask:0xf bank_mask:0xf
	v_add_f32_dpp v121, v121, v121 row_ror:2 row_mask:0xf bank_mask:0xf
	v_add_f32_dpp v122, v122, v122 row_ror:2 row_mask:0xf bank_mask:0xf
	v_add_f32_dpp v123, v123, v123 row_ror:2 row_mask:0xf bank_mask:0xf
	v_add_f32_dpp v124, v124, v124 row_ror:2 row_mask:0xf bank_mask:0xf
	v_add_f32_dpp v125, v125, v125 row_ror:2 row_mask:0xf bank_mask:0xf
	v_add_f32_dpp v126, v126, v126 row_ror:2 row_mask:0xf bank_mask:0xf
	v_add_f32_dpp v127, v127, v127 row_ror:2 row_mask:0xf bank_mask:0xf
	v_add_f32_dpp v120, v120, v120 row_ror:1 row_mask:0xf bank_mask:0xf
	v_add_f32_dpp v121, v121, v121 row_ror:1 row_mask:0xf bank_mask:0xf
	v_add_f32_dpp v122, v122, v122 row_ror:1 row_mask:0xf bank_mask:0xf
	v_add_f32_dpp v123, v123, v123 row_ror:1 row_mask:0xf bank_mask:0xf
	v_add_f32_dpp v124, v124, v124 row_ror:1 row_mask:0xf bank_mask:0xf
	v_add_f32_dpp v125, v125, v125 row_ror:1 row_mask:0xf bank_mask:0xf
	v_add_f32_dpp v126, v126, v126 row_ror:1 row_mask:0xf bank_mask:0xf
	v_add_f32_dpp v127, v127, v127 row_ror:1 row_mask:0xf bank_mask:0xf
	s_add_u32 s18, s36, 0
	s_addc_u32 s19, s37, 0
	v_mov_b32_e32 v128, v120
	v_mov_b32_e32 v129, v124
	v_mov_b32_e32 v130, v121
	v_mov_b32_e32 v131, v125
	v_mov_b32_e32 v132, v122
	v_mov_b32_e32 v133, v126
	v_mov_b32_e32 v134, v123
	v_mov_b32_e32 v135, v127
	s_mov_b32 exec_lo, 0x10001
	s_mov_b32 exec_hi, 0x10001
	global_store_dwordx4 v114, v[128:131], s[18:19]
	global_store_dwordx4 v114, v[132:135], s[18:19] offset:16
	s_mov_b64 exec, -1
	s_nop 1
	s_waitcnt vmcnt(4)
	global_load_dwordx4 v[48:51], v113, s[20:21]
	global_load_dwordx4 v[56:59], v113, s[20:21] offset:1024
	global_load_dwordx4 v[80:83], v113, s[24:25] offset:0
	global_load_dwordx4 v[84:87], v113, s[24:25] offset:1024
	global_load_dwordx4 v[88:91], v113, s[24:25] offset:2048
	global_load_dwordx4 v[92:95], v113, s[24:25] offset:3072
	s_add_u32 s20, s20, 0x800
	s_addc_u32 s21, s21, 0
	s_add_u32 s24, s24, 0x1000
	s_addc_u32 s25, s25, 0
	v_mfma_f32_16x16x32_bf16 v[16:19], v[64:67], v[0:3], 0
	v_mfma_f32_16x16x32_bf16 v[20:23], v[72:75], v[0:3], 0
	v_mfma_f32_16x16x32_bf16 v[24:27], v[64:67], v[4:7], 0
	v_mfma_f32_16x16x32_bf16 v[28:31], v[72:75], v[4:7], 0
	v_mfma_f32_16x16x32_bf16 v[32:35], v[64:67], v[8:11], 0
	v_mfma_f32_16x16x32_bf16 v[36:39], v[72:75], v[8:11], 0
	v_mfma_f32_16x16x32_bf16 v[40:43], v[64:67], v[12:15], 0
	v_mfma_f32_16x16x32_bf16 v[44:47], v[72:75], v[12:15], 0
	s_waitcnt vmcnt(6)
	s_nop 7
	v_mul_f32_e32 v116, v97, v44
	v_fma_f32 v120, v96, v40, -v116
	v_mul_f32_e32 v116, v96, v44
	v_fma_f32 v124, v97, v40, v116
	v_mul_f32_e32 v116, v101, v45
	v_fma_f32 v121, v100, v41, -v116
	v_mul_f32_e32 v116, v100, v45
	v_fma_f32 v125, v101, v41, v116
	v_mul_f32_e32 v116, v105, v46
	v_fma_f32 v122, v104, v42, -v116
	v_mul_f32_e32 v116, v104, v46
	v_fma_f32 v126, v105, v42, v116
	v_mul_f32_e32 v116, v109, v47
	v_fma_f32 v123, v108, v43, -v116
	v_mul_f32_e32 v116, v108, v47
	v_fma_f32 v127, v109, v43, v116
	v_mul_f32_e32 v116, v97, v36
	v_fma_f32 v117, v96, v32, -v116
	v_mul_f32_e32 v116, v96, v36
	v_fma_f32 v118, v97, v32, v116
	v_fma_f32 v117, v120, v98, v117
	v_fma_f32 v118, v120, v99, v118
	v_fma_f32 v117, -v124, v99, v117
	v_fma_f32 v124, v124, v98, v118
	v_mov_b32_e32 v120, v117
	v_mul_f32_e32 v116, v101, v37
	v_fma_f32 v117, v100, v33, -v116
	v_mul_f32_e32 v116, v100, v37
	v_fma_f32 v118, v101, v33, v116
	v_fma_f32 v117, v121, v102, v117
	v_fma_f32 v118, v121, v103, v118
	v_fma_f32 v117, -v125, v103, v117
	v_fma_f32 v125, v125, v102, v118
	v_mov_b32_e32 v121, v117
	v_mul_f32_e32 v116, v105, v38
	v_fma_f32 v117, v104, v34, -v116
	v_mul_f32_e32 v116, v104, v38
	v_fma_f32 v118, v105, v34, v116
	v_fma_f32 v117, v122, v106, v117
	v_fma_f32 v118, v122, v107, v118
	v_fma_f32 v117, -v126, v107, v117
	v_fma_f32 v126, v126, v106, v118
	v_mov_b32_e32 v122, v117
	v_mul_f32_e32 v116, v109, v39
	v_fma_f32 v117, v108, v35, -v116
	v_mul_f32_e32 v116, v108, v39
	v_fma_f32 v118, v109, v35, v116
	v_fma_f32 v117, v123, v110, v117
	v_fma_f32 v118, v123, v111, v118
	v_fma_f32 v117, -v127, v111, v117
	v_fma_f32 v127, v127, v110, v118
	v_mov_b32_e32 v123, v117
	v_mul_f32_e32 v116, v97, v28
	v_fma_f32 v117, v96, v24, -v116
	v_mul_f32_e32 v116, v96, v28
	v_fma_f32 v118, v97, v24, v116
	v_fma_f32 v117, v120, v98, v117
	v_fma_f32 v118, v120, v99, v118
	v_fma_f32 v117, -v124, v99, v117
	v_fma_f32 v124, v124, v98, v118
	v_mov_b32_e32 v120, v117
	v_mul_f32_e32 v116, v101, v29
	v_fma_f32 v117, v100, v25, -v116
	v_mul_f32_e32 v116, v100, v29
	v_fma_f32 v118, v101, v25, v116
	v_fma_f32 v117, v121, v102, v117
	v_fma_f32 v118, v121, v103, v118
	v_fma_f32 v117, -v125, v103, v117
	v_fma_f32 v125, v125, v102, v118
	v_mov_b32_e32 v121, v117
	v_mul_f32_e32 v116, v105, v30
	v_fma_f32 v117, v104, v26, -v116
	v_mul_f32_e32 v116, v104, v30
	v_fma_f32 v118, v105, v26, v116
	v_fma_f32 v117, v122, v106, v117
	v_fma_f32 v118, v122, v107, v118
	v_fma_f32 v117, -v126, v107, v117
	v_fma_f32 v126, v126, v106, v118
	v_mov_b32_e32 v122, v117
	v_mul_f32_e32 v116, v109, v31
	v_fma_f32 v117, v108, v27, -v116
	v_mul_f32_e32 v116, v108, v31
	v_fma_f32 v118, v109, v27, v116
	v_fma_f32 v117, v123, v110, v117
	v_fma_f32 v118, v123, v111, v118
	v_fma_f32 v117, -v127, v111, v117
	v_fma_f32 v127, v127, v110, v118
	v_mov_b32_e32 v123, v117
	v_mul_f32_e32 v116, v97, v20
	v_fma_f32 v117, v96, v16, -v116
	v_mul_f32_e32 v116, v96, v20
	v_fma_f32 v118, v97, v16, v116
	v_fma_f32 v117, v120, v98, v117
	v_fma_f32 v118, v120, v99, v118
	v_fma_f32 v117, -v124, v99, v117
	v_fma_f32 v124, v124, v98, v118
	v_mov_b32_e32 v120, v117
	v_mul_f32_e32 v116, v101, v21
	v_fma_f32 v117, v100, v17, -v116
	v_mul_f32_e32 v116, v100, v21
	v_fma_f32 v118, v101, v17, v116
	v_fma_f32 v117, v121, v102, v117
	v_fma_f32 v118, v121, v103, v118
	v_fma_f32 v117, -v125, v103, v117
	v_fma_f32 v125, v125, v102, v118
	v_mov_b32_e32 v121, v117
	v_mul_f32_e32 v116, v105, v22
	v_fma_f32 v117, v104, v18, -v116
	v_mul_f32_e32 v116, v104, v22
	v_fma_f32 v118, v105, v18, v116
	v_fma_f32 v117, v122, v106, v117
	v_fma_f32 v118, v122, v107, v118
	v_fma_f32 v117, -v126, v107, v117
	v_fma_f32 v126, v126, v106, v118
	v_mov_b32_e32 v122, v117
	v_mul_f32_e32 v116, v109, v23
	v_fma_f32 v117, v108, v19, -v116
	v_mul_f32_e32 v116, v108, v23
	v_fma_f32 v118, v109, v19, v116
	v_fma_f32 v117, v123, v110, v117
	v_fma_f32 v118, v123, v111, v118
	v_fma_f32 v117, -v127, v111, v117
	v_fma_f32 v127, v127, v110, v118
	v_mov_b32_e32 v123, v117
	v_add_f32_dpp v120, v120, v120 row_ror:8 row_mask:0xf bank_mask:0xf
	v_add_f32_dpp v121, v121, v121 row_ror:8 row_mask:0xf bank_mask:0xf
	v_add_f32_dpp v122, v122, v122 row_ror:8 row_mask:0xf bank_mask:0xf
	v_add_f32_dpp v123, v123, v123 row_ror:8 row_mask:0xf bank_mask:0xf
	v_add_f32_dpp v124, v124, v124 row_ror:8 row_mask:0xf bank_mask:0xf
	v_add_f32_dpp v125, v125, v125 row_ror:8 row_mask:0xf bank_mask:0xf
	v_add_f32_dpp v126, v126, v126 row_ror:8 row_mask:0xf bank_mask:0xf
	v_add_f32_dpp v127, v127, v127 row_ror:8 row_mask:0xf bank_mask:0xf
	v_add_f32_dpp v120, v120, v120 row_ror:4 row_mask:0xf bank_mask:0xf
	v_add_f32_dpp v121, v121, v121 row_ror:4 row_mask:0xf bank_mask:0xf
	v_add_f32_dpp v122, v122, v122 row_ror:4 row_mask:0xf bank_mask:0xf
	v_add_f32_dpp v123, v123, v123 row_ror:4 row_mask:0xf bank_mask:0xf
	v_add_f32_dpp v124, v124, v124 row_ror:4 row_mask:0xf bank_mask:0xf
	v_add_f32_dpp v125, v125, v125 row_ror:4 row_mask:0xf bank_mask:0xf
	v_add_f32_dpp v126, v126, v126 row_ror:4 row_mask:0xf bank_mask:0xf
	v_add_f32_dpp v127, v127, v127 row_ror:4 row_mask:0xf bank_mask:0xf
	v_add_f32_dpp v120, v120, v120 row_ror:2 row_mask:0xf bank_mask:0xf
	v_add_f32_dpp v121, v121, v121 row_ror:2 row_mask:0xf bank_mask:0xf
	v_add_f32_dpp v122, v122, v122 row_ror:2 row_mask:0xf bank_mask:0xf
	v_add_f32_dpp v123, v123, v123 row_ror:2 row_mask:0xf bank_mask:0xf
	v_add_f32_dpp v124, v124, v124 row_ror:2 row_mask:0xf bank_mask:0xf
	v_add_f32_dpp v125, v125, v125 row_ror:2 row_mask:0xf bank_mask:0xf
	v_add_f32_dpp v126, v126, v126 row_ror:2 row_mask:0xf bank_mask:0xf
	v_add_f32_dpp v127, v127, v127 row_ror:2 row_mask:0xf bank_mask:0xf
	v_add_f32_dpp v120, v120, v120 row_ror:1 row_mask:0xf bank_mask:0xf
	v_add_f32_dpp v121, v121, v121 row_ror:1 row_mask:0xf bank_mask:0xf
	v_add_f32_dpp v122, v122, v122 row_ror:1 row_mask:0xf bank_mask:0xf
	v_add_f32_dpp v123, v123, v123 row_ror:1 row_mask:0xf bank_mask:0xf
	v_add_f32_dpp v124, v124, v124 row_ror:1 row_mask:0xf bank_mask:0xf
	v_add_f32_dpp v125, v125, v125 row_ror:1 row_mask:0xf bank_mask:0xf
	v_add_f32_dpp v126, v126, v126 row_ror:1 row_mask:0xf bank_mask:0xf
	v_add_f32_dpp v127, v127, v127 row_ror:1 row_mask:0xf bank_mask:0xf
	s_add_u32 s18, s36, 128
	s_addc_u32 s19, s37, 0
	v_mov_b32_e32 v128, v120
	v_mov_b32_e32 v129, v124
	v_mov_b32_e32 v130, v121
	v_mov_b32_e32 v131, v125
	v_mov_b32_e32 v132, v122
	v_mov_b32_e32 v133, v126
	v_mov_b32_e32 v134, v123
	v_mov_b32_e32 v135, v127
	s_mov_b32 exec_lo, 0x10001
	s_mov_b32 exec_hi, 0x10001
	global_store_dwordx4 v114, v[128:131], s[18:19]
	global_store_dwordx4 v114, v[132:135], s[18:19] offset:16
	s_mov_b64 exec, -1
	s_nop 1
	s_waitcnt vmcnt(4)
	global_load_dwordx4 v[64:67], v113, s[20:21]
	global_load_dwordx4 v[72:75], v113, s[20:21] offset:1024
	global_load_dwordx4 v[96:99], v113, s[24:25] offset:0
	global_load_dwordx4 v[100:103], v113, s[24:25] offset:1024
	global_load_dwordx4 v[104:107], v113, s[24:25] offset:2048
	global_load_dwordx4 v[108:111], v113, s[24:25] offset:3072
	v_mfma_f32_16x16x32_bf16 v[16:19], v[48:51], v[0:3], 0
	v_mfma_f32_16x16x32_bf16 v[20:23], v[56:59], v[0:3], 0
	v_mfma_f32_16x16x32_bf16 v[24:27], v[48:51], v[4:7], 0
	v_mfma_f32_16x16x32_bf16 v[28:31], v[56:59], v[4:7], 0
	v_mfma_f32_16x16x32_bf16 v[32:35], v[48:51], v[8:11], 0
	v_mfma_f32_16x16x32_bf16 v[36:39], v[56:59], v[8:11], 0
	v_mfma_f32_16x16x32_bf16 v[40:43], v[48:51], v[12:15], 0
	v_mfma_f32_16x16x32_bf16 v[44:47], v[56:59], v[12:15], 0
	s_waitcnt vmcnt(6)
	s_nop 7
	v_mul_f32_e32 v116, v81, v44
	v_fma_f32 v120, v80, v40, -v116
	v_mul_f32_e32 v116, v80, v44
	v_fma_f32 v124, v81, v40, v116
	v_mul_f32_e32 v116, v85, v45
	v_fma_f32 v121, v84, v41, -v116
	v_mul_f32_e32 v116, v84, v45
	v_fma_f32 v125, v85, v41, v116
	v_mul_f32_e32 v116, v89, v46
	v_fma_f32 v122, v88, v42, -v116
	v_mul_f32_e32 v116, v88, v46
	v_fma_f32 v126, v89, v42, v116
	v_mul_f32_e32 v116, v93, v47
	v_fma_f32 v123, v92, v43, -v116
	v_mul_f32_e32 v116, v92, v47
	v_fma_f32 v127, v93, v43, v116
	v_mul_f32_e32 v116, v81, v36
	v_fma_f32 v117, v80, v32, -v116
	v_mul_f32_e32 v116, v80, v36
	v_fma_f32 v118, v81, v32, v116
	v_fma_f32 v117, v120, v82, v117
	v_fma_f32 v118, v120, v83, v118
	v_fma_f32 v117, -v124, v83, v117
	v_fma_f32 v124, v124, v82, v118
	v_mov_b32_e32 v120, v117
	v_mul_f32_e32 v116, v85, v37
	v_fma_f32 v117, v84, v33, -v116
	v_mul_f32_e32 v116, v84, v37
	v_fma_f32 v118, v85, v33, v116
	v_fma_f32 v117, v121, v86, v117
	v_fma_f32 v118, v121, v87, v118
	v_fma_f32 v117, -v125, v87, v117
	v_fma_f32 v125, v125, v86, v118
	v_mov_b32_e32 v121, v117
	v_mul_f32_e32 v116, v89, v38
	v_fma_f32 v117, v88, v34, -v116
	v_mul_f32_e32 v116, v88, v38
	v_fma_f32 v118, v89, v34, v116
	v_fma_f32 v117, v122, v90, v117
	v_fma_f32 v118, v122, v91, v118
	v_fma_f32 v117, -v126, v91, v117
	v_fma_f32 v126, v126, v90, v118
	v_mov_b32_e32 v122, v117
	v_mul_f32_e32 v116, v93, v39
	v_fma_f32 v117, v92, v35, -v116
	v_mul_f32_e32 v116, v92, v39
	v_fma_f32 v118, v93, v35, v116
	v_fma_f32 v117, v123, v94, v117
	v_fma_f32 v118, v123, v95, v118
	v_fma_f32 v117, -v127, v95, v117
	v_fma_f32 v127, v127, v94, v118
	v_mov_b32_e32 v123, v117
	v_mul_f32_e32 v116, v81, v28
	v_fma_f32 v117, v80, v24, -v116
	v_mul_f32_e32 v116, v80, v28
	v_fma_f32 v118, v81, v24, v116
	v_fma_f32 v117, v120, v82, v117
	v_fma_f32 v118, v120, v83, v118
	v_fma_f32 v117, -v124, v83, v117
	v_fma_f32 v124, v124, v82, v118
	v_mov_b32_e32 v120, v117
	v_mul_f32_e32 v116, v85, v29
	v_fma_f32 v117, v84, v25, -v116
	v_mul_f32_e32 v116, v84, v29
	v_fma_f32 v118, v85, v25, v116
	v_fma_f32 v117, v121, v86, v117
	v_fma_f32 v118, v121, v87, v118
	v_fma_f32 v117, -v125, v87, v117
	v_fma_f32 v125, v125, v86, v118
	v_mov_b32_e32 v121, v117
	v_mul_f32_e32 v116, v89, v30
	v_fma_f32 v117, v88, v26, -v116
	v_mul_f32_e32 v116, v88, v30
	v_fma_f32 v118, v89, v26, v116
	v_fma_f32 v117, v122, v90, v117
	v_fma_f32 v118, v122, v91, v118
	v_fma_f32 v117, -v126, v91, v117
	v_fma_f32 v126, v126, v90, v118
	v_mov_b32_e32 v122, v117
	v_mul_f32_e32 v116, v93, v31
	v_fma_f32 v117, v92, v27, -v116
	v_mul_f32_e32 v116, v92, v31
	v_fma_f32 v118, v93, v27, v116
	v_fma_f32 v117, v123, v94, v117
	v_fma_f32 v118, v123, v95, v118
	v_fma_f32 v117, -v127, v95, v117
	v_fma_f32 v127, v127, v94, v118
	v_mov_b32_e32 v123, v117
	v_mul_f32_e32 v116, v81, v20
	v_fma_f32 v117, v80, v16, -v116
	v_mul_f32_e32 v116, v80, v20
	v_fma_f32 v118, v81, v16, v116
	v_fma_f32 v117, v120, v82, v117
	v_fma_f32 v118, v120, v83, v118
	v_fma_f32 v117, -v124, v83, v117
	v_fma_f32 v124, v124, v82, v118
	v_mov_b32_e32 v120, v117
	v_mul_f32_e32 v116, v85, v21
	v_fma_f32 v117, v84, v17, -v116
	v_mul_f32_e32 v116, v84, v21
	v_fma_f32 v118, v85, v17, v116
	v_fma_f32 v117, v121, v86, v117
	v_fma_f32 v118, v121, v87, v118
	v_fma_f32 v117, -v125, v87, v117
	v_fma_f32 v125, v125, v86, v118
	v_mov_b32_e32 v121, v117
	v_mul_f32_e32 v116, v89, v22
	v_fma_f32 v117, v88, v18, -v116
	v_mul_f32_e32 v116, v88, v22
	v_fma_f32 v118, v89, v18, v116
	v_fma_f32 v117, v122, v90, v117
	v_fma_f32 v118, v122, v91, v118
	v_fma_f32 v117, -v126, v91, v117
	v_fma_f32 v126, v126, v90, v118
	v_mov_b32_e32 v122, v117
	v_mul_f32_e32 v116, v93, v23
	v_fma_f32 v117, v92, v19, -v116
	v_mul_f32_e32 v116, v92, v23
	v_fma_f32 v118, v93, v19, v116
	v_fma_f32 v117, v123, v94, v117
	v_fma_f32 v118, v123, v95, v118
	v_fma_f32 v117, -v127, v95, v117
	v_fma_f32 v127, v127, v94, v118
	v_mov_b32_e32 v123, v117
	v_add_f32_dpp v120, v120, v120 row_ror:8 row_mask:0xf bank_mask:0xf
	v_add_f32_dpp v121, v121, v121 row_ror:8 row_mask:0xf bank_mask:0xf
	v_add_f32_dpp v122, v122, v122 row_ror:8 row_mask:0xf bank_mask:0xf
	v_add_f32_dpp v123, v123, v123 row_ror:8 row_mask:0xf bank_mask:0xf
	v_add_f32_dpp v124, v124, v124 row_ror:8 row_mask:0xf bank_mask:0xf
	v_add_f32_dpp v125, v125, v125 row_ror:8 row_mask:0xf bank_mask:0xf
	v_add_f32_dpp v126, v126, v126 row_ror:8 row_mask:0xf bank_mask:0xf
	v_add_f32_dpp v127, v127, v127 row_ror:8 row_mask:0xf bank_mask:0xf
	v_add_f32_dpp v120, v120, v120 row_ror:4 row_mask:0xf bank_mask:0xf
	v_add_f32_dpp v121, v121, v121 row_ror:4 row_mask:0xf bank_mask:0xf
	v_add_f32_dpp v122, v122, v122 row_ror:4 row_mask:0xf bank_mask:0xf
	v_add_f32_dpp v123, v123, v123 row_ror:4 row_mask:0xf bank_mask:0xf
	v_add_f32_dpp v124, v124, v124 row_ror:4 row_mask:0xf bank_mask:0xf
	v_add_f32_dpp v125, v125, v125 row_ror:4 row_mask:0xf bank_mask:0xf
	v_add_f32_dpp v126, v126, v126 row_ror:4 row_mask:0xf bank_mask:0xf
	v_add_f32_dpp v127, v127, v127 row_ror:4 row_mask:0xf bank_mask:0xf
	v_add_f32_dpp v120, v120, v120 row_ror:2 row_mask:0xf bank_mask:0xf
	v_add_f32_dpp v121, v121, v121 row_ror:2 row_mask:0xf bank_mask:0xf
	v_add_f32_dpp v122, v122, v122 row_ror:2 row_mask:0xf bank_mask:0xf
	v_add_f32_dpp v123, v123, v123 row_ror:2 row_mask:0xf bank_mask:0xf
	v_add_f32_dpp v124, v124, v124 row_ror:2 row_mask:0xf bank_mask:0xf
	v_add_f32_dpp v125, v125, v125 row_ror:2 row_mask:0xf bank_mask:0xf
	v_add_f32_dpp v126, v126, v126 row_ror:2 row_mask:0xf bank_mask:0xf
	v_add_f32_dpp v127, v127, v127 row_ror:2 row_mask:0xf bank_mask:0xf
	v_add_f32_dpp v120, v120, v120 row_ror:1 row_mask:0xf bank_mask:0xf
	v_add_f32_dpp v121, v121, v121 row_ror:1 row_mask:0xf bank_mask:0xf
	v_add_f32_dpp v122, v122, v122 row_ror:1 row_mask:0xf bank_mask:0xf
	v_add_f32_dpp v123, v123, v123 row_ror:1 row_mask:0xf bank_mask:0xf
	v_add_f32_dpp v124, v124, v124 row_ror:1 row_mask:0xf bank_mask:0xf
	v_add_f32_dpp v125, v125, v125 row_ror:1 row_mask:0xf bank_mask:0xf
	v_add_f32_dpp v126, v126, v126 row_ror:1 row_mask:0xf bank_mask:0xf
	v_add_f32_dpp v127, v127, v127 row_ror:1 row_mask:0xf bank_mask:0xf
	s_add_u32 s18, s36, 256
	s_addc_u32 s19, s37, 0
	v_mov_b32_e32 v128, v120
	v_mov_b32_e32 v129, v124
	v_mov_b32_e32 v130, v121
	v_mov_b32_e32 v131, v125
	v_mov_b32_e32 v132, v122
	v_mov_b32_e32 v133, v126
	v_mov_b32_e32 v134, v123
	v_mov_b32_e32 v135, v127
	s_mov_b32 exec_lo, 0x10001
	s_mov_b32 exec_hi, 0x10001
	global_store_dwordx4 v114, v[128:131], s[18:19]
	global_store_dwordx4 v114, v[132:135], s[18:19] offset:16
	s_mov_b64 exec, -1
	s_nop 1
	s_waitcnt vmcnt(4)
	v_mfma_f32_16x16x32_bf16 v[16:19], v[64:67], v[0:3], 0
	v_mfma_f32_16x16x32_bf16 v[20:23], v[72:75], v[0:3], 0
	v_mfma_f32_16x16x32_bf16 v[24:27], v[64:67], v[4:7], 0
	v_mfma_f32_16x16x32_bf16 v[28:31], v[72:75], v[4:7], 0
	v_mfma_f32_16x16x32_bf16 v[32:35], v[64:67], v[8:11], 0
	v_mfma_f32_16x16x32_bf16 v[36:39], v[72:75], v[8:11], 0
	v_mfma_f32_16x16x32_bf16 v[40:43], v[64:67], v[12:15], 0
	v_mfma_f32_16x16x32_bf16 v[44:47], v[72:75], v[12:15], 0
	s_waitcnt vmcnt(0)
	s_nop 7
	v_mul_f32_e32 v116, v97, v44
	v_fma_f32 v120, v96, v40, -v116
	v_mul_f32_e32 v116, v96, v44
	v_fma_f32 v124, v97, v40, v116
	v_mul_f32_e32 v116, v101, v45
	v_fma_f32 v121, v100, v41, -v116
	v_mul_f32_e32 v116, v100, v45
	v_fma_f32 v125, v101, v41, v116
	v_mul_f32_e32 v116, v105, v46
	v_fma_f32 v122, v104, v42, -v116
	v_mul_f32_e32 v116, v104, v46
	v_fma_f32 v126, v105, v42, v116
	v_mul_f32_e32 v116, v109, v47
	v_fma_f32 v123, v108, v43, -v116
	v_mul_f32_e32 v116, v108, v47
	v_fma_f32 v127, v109, v43, v116
	v_mul_f32_e32 v116, v97, v36
	v_fma_f32 v117, v96, v32, -v116
	v_mul_f32_e32 v116, v96, v36
	v_fma_f32 v118, v97, v32, v116
	v_fma_f32 v117, v120, v98, v117
	v_fma_f32 v118, v120, v99, v118
	v_fma_f32 v117, -v124, v99, v117
	v_fma_f32 v124, v124, v98, v118
	v_mov_b32_e32 v120, v117
	v_mul_f32_e32 v116, v101, v37
	v_fma_f32 v117, v100, v33, -v116
	v_mul_f32_e32 v116, v100, v37
	v_fma_f32 v118, v101, v33, v116
	v_fma_f32 v117, v121, v102, v117
	v_fma_f32 v118, v121, v103, v118
	v_fma_f32 v117, -v125, v103, v117
	v_fma_f32 v125, v125, v102, v118
	v_mov_b32_e32 v121, v117
	v_mul_f32_e32 v116, v105, v38
	v_fma_f32 v117, v104, v34, -v116
	v_mul_f32_e32 v116, v104, v38
	v_fma_f32 v118, v105, v34, v116
	v_fma_f32 v117, v122, v106, v117
	v_fma_f32 v118, v122, v107, v118
	v_fma_f32 v117, -v126, v107, v117
	v_fma_f32 v126, v126, v106, v118
	v_mov_b32_e32 v122, v117
	v_mul_f32_e32 v116, v109, v39
	v_fma_f32 v117, v108, v35, -v116
	v_mul_f32_e32 v116, v108, v39
	v_fma_f32 v118, v109, v35, v116
	v_fma_f32 v117, v123, v110, v117
	v_fma_f32 v118, v123, v111, v118
	v_fma_f32 v117, -v127, v111, v117
	v_fma_f32 v127, v127, v110, v118
	v_mov_b32_e32 v123, v117
	v_mul_f32_e32 v116, v97, v28
	v_fma_f32 v117, v96, v24, -v116
	v_mul_f32_e32 v116, v96, v28
	v_fma_f32 v118, v97, v24, v116
	v_fma_f32 v117, v120, v98, v117
	v_fma_f32 v118, v120, v99, v118
	v_fma_f32 v117, -v124, v99, v117
	v_fma_f32 v124, v124, v98, v118
	v_mov_b32_e32 v120, v117
	v_mul_f32_e32 v116, v101, v29
	v_fma_f32 v117, v100, v25, -v116
	v_mul_f32_e32 v116, v100, v29
	v_fma_f32 v118, v101, v25, v116
	v_fma_f32 v117, v121, v102, v117
	v_fma_f32 v118, v121, v103, v118
	v_fma_f32 v117, -v125, v103, v117
	v_fma_f32 v125, v125, v102, v118
	v_mov_b32_e32 v121, v117
	v_mul_f32_e32 v116, v105, v30
	v_fma_f32 v117, v104, v26, -v116
	v_mul_f32_e32 v116, v104, v30
	v_fma_f32 v118, v105, v26, v116
	v_fma_f32 v117, v122, v106, v117
	v_fma_f32 v118, v122, v107, v118
	v_fma_f32 v117, -v126, v107, v117
	v_fma_f32 v126, v126, v106, v118
	v_mov_b32_e32 v122, v117
	v_mul_f32_e32 v116, v109, v31
	v_fma_f32 v117, v108, v27, -v116
	v_mul_f32_e32 v116, v108, v31
	v_fma_f32 v118, v109, v27, v116
	v_fma_f32 v117, v123, v110, v117
	v_fma_f32 v118, v123, v111, v118
	v_fma_f32 v117, -v127, v111, v117
	v_fma_f32 v127, v127, v110, v118
	v_mov_b32_e32 v123, v117
	v_mul_f32_e32 v116, v97, v20
	v_fma_f32 v117, v96, v16, -v116
	v_mul_f32_e32 v116, v96, v20
	v_fma_f32 v118, v97, v16, v116
	v_fma_f32 v117, v120, v98, v117
	v_fma_f32 v118, v120, v99, v118
	v_fma_f32 v117, -v124, v99, v117
	v_fma_f32 v124, v124, v98, v118
	v_mov_b32_e32 v120, v117
	v_mul_f32_e32 v116, v101, v21
	v_fma_f32 v117, v100, v17, -v116
	v_mul_f32_e32 v116, v100, v21
	v_fma_f32 v118, v101, v17, v116
	v_fma_f32 v117, v121, v102, v117
	v_fma_f32 v118, v121, v103, v118
	v_fma_f32 v117, -v125, v103, v117
	v_fma_f32 v125, v125, v102, v118
	v_mov_b32_e32 v121, v117
	v_mul_f32_e32 v116, v105, v22
	v_fma_f32 v117, v104, v18, -v116
	v_mul_f32_e32 v116, v104, v22
	v_fma_f32 v118, v105, v18, v116
	v_fma_f32 v117, v122, v106, v117
	v_fma_f32 v118, v122, v107, v118
	v_fma_f32 v117, -v126, v107, v117
	v_fma_f32 v126, v126, v106, v118
	v_mov_b32_e32 v122, v117
	v_mul_f32_e32 v116, v109, v23
	v_fma_f32 v117, v108, v19, -v116
	v_mul_f32_e32 v116, v108, v23
	v_fma_f32 v118, v109, v19, v116
	v_fma_f32 v117, v123, v110, v117
	v_fma_f32 v118, v123, v111, v118
	v_fma_f32 v117, -v127, v111, v117
	v_fma_f32 v127, v127, v110, v118
	v_mov_b32_e32 v123, v117
	v_add_f32_dpp v120, v120, v120 row_ror:8 row_mask:0xf bank_mask:0xf
	v_add_f32_dpp v121, v121, v121 row_ror:8 row_mask:0xf bank_mask:0xf
	v_add_f32_dpp v122, v122, v122 row_ror:8 row_mask:0xf bank_mask:0xf
	v_add_f32_dpp v123, v123, v123 row_ror:8 row_mask:0xf bank_mask:0xf
	v_add_f32_dpp v124, v124, v124 row_ror:8 row_mask:0xf bank_mask:0xf
	v_add_f32_dpp v125, v125, v125 row_ror:8 row_mask:0xf bank_mask:0xf
	v_add_f32_dpp v126, v126, v126 row_ror:8 row_mask:0xf bank_mask:0xf
	v_add_f32_dpp v127, v127, v127 row_ror:8 row_mask:0xf bank_mask:0xf
	v_add_f32_dpp v120, v120, v120 row_ror:4 row_mask:0xf bank_mask:0xf
	v_add_f32_dpp v121, v121, v121 row_ror:4 row_mask:0xf bank_mask:0xf
	v_add_f32_dpp v122, v122, v122 row_ror:4 row_mask:0xf bank_mask:0xf
	v_add_f32_dpp v123, v123, v123 row_ror:4 row_mask:0xf bank_mask:0xf
	v_add_f32_dpp v124, v124, v124 row_ror:4 row_mask:0xf bank_mask:0xf
	v_add_f32_dpp v125, v125, v125 row_ror:4 row_mask:0xf bank_mask:0xf
	v_add_f32_dpp v126, v126, v126 row_ror:4 row_mask:0xf bank_mask:0xf
	v_add_f32_dpp v127, v127, v127 row_ror:4 row_mask:0xf bank_mask:0xf
	v_add_f32_dpp v120, v120, v120 row_ror:2 row_mask:0xf bank_mask:0xf
	v_add_f32_dpp v121, v121, v121 row_ror:2 row_mask:0xf bank_mask:0xf
	v_add_f32_dpp v122, v122, v122 row_ror:2 row_mask:0xf bank_mask:0xf
	v_add_f32_dpp v123, v123, v123 row_ror:2 row_mask:0xf bank_mask:0xf
	v_add_f32_dpp v124, v124, v124 row_ror:2 row_mask:0xf bank_mask:0xf
	v_add_f32_dpp v125, v125, v125 row_ror:2 row_mask:0xf bank_mask:0xf
	v_add_f32_dpp v126, v126, v126 row_ror:2 row_mask:0xf bank_mask:0xf
	v_add_f32_dpp v127, v127, v127 row_ror:2 row_mask:0xf bank_mask:0xf
	v_add_f32_dpp v120, v120, v120 row_ror:1 row_mask:0xf bank_mask:0xf
	v_add_f32_dpp v121, v121, v121 row_ror:1 row_mask:0xf bank_mask:0xf
	v_add_f32_dpp v122, v122, v122 row_ror:1 row_mask:0xf bank_mask:0xf
	v_add_f32_dpp v123, v123, v123 row_ror:1 row_mask:0xf bank_mask:0xf
	v_add_f32_dpp v124, v124, v124 row_ror:1 row_mask:0xf bank_mask:0xf
	v_add_f32_dpp v125, v125, v125 row_ror:1 row_mask:0xf bank_mask:0xf
	v_add_f32_dpp v126, v126, v126 row_ror:1 row_mask:0xf bank_mask:0xf
	v_add_f32_dpp v127, v127, v127 row_ror:1 row_mask:0xf bank_mask:0xf
	s_add_u32 s18, s36, 384
	s_addc_u32 s19, s37, 0
	v_mov_b32_e32 v128, v120
	v_mov_b32_e32 v129, v124
	v_mov_b32_e32 v130, v121
	v_mov_b32_e32 v131, v125
	v_mov_b32_e32 v132, v122
	v_mov_b32_e32 v133, v126
	v_mov_b32_e32 v134, v123
	v_mov_b32_e32 v135, v127
	s_mov_b32 exec_lo, 0x10001
	s_mov_b32 exec_hi, 0x10001
	global_store_dwordx4 v114, v[128:131], s[18:19]
	global_store_dwordx4 v114, v[132:135], s[18:19] offset:16
	s_mov_b64 exec, -1
	s_nop 1

.LBB0_612:
	v_readlane_b32 s78, v247, 22
	s_bitcmp0_b32 s94, 0
	v_readlane_b32 s79, v247, 23
	v_readlane_b32 s24, v247, 28
	v_readlane_b32 s25, v244, 30
	v_readlane_b32 s26, v244, 31
	v_readlane_b32 s27, v245, 40
	s_cbranch_scc1 .LBB0_620
	v_readlane_b32 s0, v246, 3
	v_readlane_b32 s1, v246, 4
	s_andn2_b64 vcc, exec, s[0:1]
	s_cbranch_vccnz .LBB0_620
	v_readlane_b32 s0, v245, 21
	s_nop 0
	s_cmp_ge_u32 s0, 0x80
	s_cbranch_scc1 .Lstab_end
	s_lshr_b32 s1, s0, 2
	s_and_b32 s6, s0, 3
	s_lshl_b32 s7, s24, 5
	s_add_i32 s7, s7, s1
	s_bfe_u32 s8, s1, 0x10004
	s_mul_i32 s9, s8, 15
	v_and_b32_e32 v0, 15, v205
	v_lshrrev_b32_e32 v1, 4, v205
	v_xor_b32_e32 v2, s9, v0
	v_and_b32_e32 v3, 1, v2
	v_cmp_ne_u32_e64 s[10:11], 0, v3
	v_and_b32_e32 v3, 2, v2
	v_cmp_ne_u32_e64 s[12:13], 0, v3
	v_and_b32_e32 v3, 4, v2
	v_cmp_ne_u32_e64 s[14:15], 0, v3
	v_and_b32_e32 v3, 8, v2
	v_cmp_ne_u32_e64 s[16:17], 0, v3
	s_lshl_b32 s18, s7, 6
	s_lshl_b32 s19, s6, 4
	s_add_i32 s18, s18, s19
	s_lshl_b32 s18, s18, 2
	s_add_u32 s18, s18, 0x117a20
	s_add_u32 s20, s4, s18
	s_addc_u32 s21, s5, 0
	s_add_u32 s22, s20, 0x4000
	s_addc_u32 s23, s21, 0
	v_lshlrev_b32_e32 v3, 4, v1
	global_load_dwordx4 v[4:7], v3, s[20:21]
	global_load_dwordx4 v[8:11], v3, s[22:23]
	s_lshl_b32 s19, s7, 2
	s_add_u32 s19, s19, 0x11fa20
	s_add_u32 s0, s4, s19
	s_addc_u32 s1, s5, 0
	global_load_dword v12, v137, s[0:1]
	s_lshl_b32 s18, s7, 2
	s_add_i32 s18, s18, s6
	s_lshl_b32 s19, s18, 13
	s_add_u32 s19, s19, 0xf900000
	s_add_u32 s20, s4, s19
	s_addc_u32 s21, s5, 0
	s_lshl_b32 s19, s18, 12
	s_add_u32 s19, s19, 0xfc00000
	s_add_u32 s22, s4, s19
	s_addc_u32 s23, s5, 0
	v_lshlrev_b32_e32 v13, 4, v205
	v_lshlrev_b32_e32 v14, 4, v205
	v_add_u32_e32 v44, 0x1000, v13
	s_waitcnt vmcnt(0)
	v_mul_f32_e32 v12, 0x3fb8aa3b, v12
	v_exp_f32_e32 v12, v12
	s_nop 0
	v_mul_f32_e32 v15, v12, v4
	v_mul_f32_e32 v16, 0x3fb8aa3b, v15
	v_mul_f32_e32 v17, 0xbfb8aa3b, v15
	v_exp_f32_e32 v16, v16
	v_exp_f32_e32 v17, v17
	v_mul_f32_e32 v18, v12, v8
	v_mul_f32_e32 v19, 0.15915494, v18
	v_rndne_f32_e32 v19, v19
	v_fma_f32 v18, v18, 0.15915494, -v19
	v_cos_f32_e32 v19, v18
	v_sin_f32_e32 v20, v18
	s_nop 0
	v_mul_f32_e32 v22, v16, v19
	v_mul_f32_e32 v23, v16, v20
	v_mul_f32_e32 v24, v17, v19
	v_mul_f32_e64 v25, -v17, v20
	v_add_f32_e32 v26, -1.0, v22
	v_mul_f32_e32 v27, v8, v8
	v_fmac_f32_e32 v27, v4, v4
	v_rcp_f32_e32 v27, v27
	v_mul_f32_e32 v28, v26, v4
	v_fmac_f32_e32 v28, v23, v8
	v_mul_f32_e32 v29, v23, v4
	v_fma_f32 v29, -v26, v8, v29
	v_mul_f32_e32 v28, v28, v27
	v_mul_f32_e32 v29, v29, v27
	v_mul_f32_e32 v42, v23, v23
	v_mul_f32_e32 v43, v22, v23
	v_fma_f32 v30, v22, v22, -v42
	v_add_f32_e32 v31, v43, v43
	v_mul_f32_e32 v42, v31, v31
	v_mul_f32_e32 v43, v30, v31
	v_fma_f32 v32, v30, v30, -v42
	v_add_f32_e32 v33, v43, v43
	v_mul_f32_e32 v42, v33, v33
	v_mul_f32_e32 v43, v32, v33
	v_fma_f32 v34, v32, v32, -v42
	v_add_f32_e32 v35, v43, v43
	v_mul_f32_e32 v42, v35, v35
	v_mul_f32_e32 v43, v34, v35
	v_fma_f32 v36, v34, v34, -v42
	v_add_f32_e32 v37, v43, v43
	v_mov_b32_e32 v38, 1.0
	v_mov_b32_e32 v39, 0
	v_mov_b32_e32 v40, 1.0
	v_mov_b32_e32 v41, 0
	v_mul_f32_e32 v15, v39, v23
	v_fma_f32 v42, v38, v22, -v15
	v_mul_f32_e32 v15, v38, v23
	v_fma_f32 v43, v39, v22, v15
	v_cndmask_b32_e64 v38, v38, v42, s[10:11]
	v_cndmask_b32_e64 v39, v39, v43, s[10:11]
	v_mul_f32_e32 v15, v41, v23
	v_fma_f32 v42, v40, v22, -v15
	v_mul_f32_e32 v15, v40, v23
	v_fma_f32 v43, v41, v22, v15
	v_cndmask_b32_e64 v40, v42, v40, s[10:11]
	v_cndmask_b32_e64 v41, v43, v41, s[10:11]
	v_mul_f32_e32 v15, v39, v31
	v_fma_f32 v42, v38, v30, -v15
	v_mul_f32_e32 v15, v38, v31
	v_fma_f32 v43, v39, v30, v15
	v_cndmask_b32_e64 v38, v38, v42, s[12:13]
	v_cndmask_b32_e64 v39, v39, v43, s[12:13]
	v_mul_f32_e32 v15, v41, v31
	v_fma_f32 v42, v40, v30, -v15
	v_mul_f32_e32 v15, v40, v31
	v_fma_f32 v43, v41, v30, v15
	v_cndmask_b32_e64 v40, v42, v40, s[12:13]
	v_cndmask_b32_e64 v41, v43, v41, s[12:13]
	v_mul_f32_e32 v15, v39, v33
	v_fma_f32 v42, v38, v32, -v15
	v_mul_f32_e32 v15, v38, v33
	v_fma_f32 v43, v39, v32, v15
	v_cndmask_b32_e64 v38, v38, v42, s[14:15]
	v_cndmask_b32_e64 v39, v39, v43, s[14:15]
	v_mul_f32_e32 v15, v41, v33
	v_fma_f32 v42, v40, v32, -v15
	v_mul_f32_e32 v15, v40, v33
	v_fma_f32 v43, v41, v32, v15
	v_cndmask_b32_e64 v40, v42, v40, s[14:15]
	v_cndmask_b32_e64 v41, v43, v41, s[14:15]
	v_mul_f32_e32 v15, v39, v35
	v_fma_f32 v42, v38, v34, -v15
	v_mul_f32_e32 v15, v38, v35
	v_fma_f32 v43, v39, v34, v15
	v_cndmask_b32_e64 v38, v38, v42, s[16:17]
	v_cndmask_b32_e64 v39, v39, v43, s[16:17]
	v_mul_f32_e32 v15, v41, v35
	v_fma_f32 v42, v40, v34, -v15
	v_mul_f32_e32 v15, v40, v35
	v_fma_f32 v43, v41, v34, v15
	v_cndmask_b32_e64 v40, v42, v40, s[16:17]
	v_cndmask_b32_e64 v41, v43, v41, s[16:17]
	v_mul_f32_e32 v42, v25, v25
	v_mul_f32_e32 v43, v24, v25
	v_fma_f32 v30, v24, v24, -v42
	v_add_f32_e32 v31, v43, v43
	v_mul_f32_e32 v42, v31, v31
	v_mul_f32_e32 v43, v30, v31
	v_fma_f32 v32, v30, v30, -v42
	v_add_f32_e32 v33, v43, v43
	v_mul_f32_e32 v42, v33, v33
	v_mul_f32_e32 v43, v32, v33
	v_fma_f32 v34, v32, v32, -v42
	v_add_f32_e32 v35, v43, v43
	v_mov_b32_e32 v16, 1.0
	v_mov_b32_e32 v17, 0
	v_mul_f32_e32 v15, v17, v25
	v_fma_f32 v42, v16, v24, -v15
	v_mul_f32_e32 v15, v16, v25
	v_fma_f32 v43, v17, v24, v15
	v_cndmask_b32_e64 v16, v16, v42, s[10:11]
	v_cndmask_b32_e64 v17, v17, v43, s[10:11]
	v_mul_f32_e32 v15, v17, v31
	v_fma_f32 v42, v16, v30, -v15
	v_mul_f32_e32 v15, v16, v31
	v_fma_f32 v43, v17, v30, v15
	v_cndmask_b32_e64 v16, v16, v42, s[12:13]
	v_cndmask_b32_e64 v17, v17, v43, s[12:13]
	v_mul_f32_e32 v15, v17, v33
	v_fma_f32 v42, v16, v32, -v15
	v_mul_f32_e32 v15, v16, v33
	v_fma_f32 v43, v17, v32, v15
	v_cndmask_b32_e64 v16, v16, v42, s[14:15]
	v_cndmask_b32_e64 v17, v17, v43, s[14:15]
	v_mul_f32_e32 v15, v17, v35
	v_fma_f32 v42, v16, v34, -v15
	v_mul_f32_e32 v15, v16, v35
	v_fma_f32 v43, v17, v34, v15
	v_cndmask_b32_e64 v16, v16, v42, s[16:17]
	v_cndmask_b32_e64 v17, v17, v43, s[16:17]
	v_mul_f32_e32 v15, v29, v17
	v_fma_f32 v18, v28, v16, -v15
	v_mul_f32_e32 v15, v28, v17
	v_fma_f32 v19, v29, v16, v15
	v_mul_f32_e32 v15, v29, v41
	v_fma_f32 v20, v28, v40, -v15
	v_mul_f32_e32 v15, v28, v41
	v_fma_f32 v21, v29, v40, v15
	global_store_dwordx2 v13, v[18:19], s[20:21] offset:0
	global_store_dwordx2 v13, v[38:39], s[20:21] offset:8
	global_store_dwordx2 v44, v[36:37], s[20:21] offset:0
	global_store_dwordx2 v44, v[22:23], s[20:21] offset:8
	global_store_dwordx2 v14, v[20:21], s[22:23] offset:0
	global_store_dwordx2 v14, v[36:37], s[22:23] offset:8
	s_nop 1
	v_mul_f32_e32 v15, v12, v5
	v_mul_f32_e32 v16, 0x3fb8aa3b, v15
	v_mul_f32_e32 v17, 0xbfb8aa3b, v15
	v_exp_f32_e32 v16, v16
	v_exp_f32_e32 v17, v17
	v_mul_f32_e32 v18, v12, v9
	v_mul_f32_e32 v19, 0.15915494, v18
	v_rndne_f32_e32 v19, v19
	v_fma_f32 v18, v18, 0.15915494, -v19
	v_cos_f32_e32 v19, v18
	v_sin_f32_e32 v20, v18
	s_nop 0
	v_mul_f32_e32 v22, v16, v19
	v_mul_f32_e32 v23, v16, v20
	v_mul_f32_e32 v24, v17, v19
	v_mul_f32_e64 v25, -v17, v20
	v_add_f32_e32 v26, -1.0, v22
	v_mul_f32_e32 v27, v9, v9
	v_fmac_f32_e32 v27, v5, v5
	v_rcp_f32_e32 v27, v27
	v_mul_f32_e32 v28, v26, v5
	v_fmac_f32_e32 v28, v23, v9
	v_mul_f32_e32 v29, v23, v5
	v_fma_f32 v29, -v26, v9, v29
	v_mul_f32_e32 v28, v28, v27
	v_mul_f32_e32 v29, v29, v27
	v_mul_f32_e32 v42, v23, v23
	v_mul_f32_e32 v43, v22, v23
	v_fma_f32 v30, v22, v22, -v42
	v_add_f32_e32 v31, v43, v43
	v_mul_f32_e32 v42, v31, v31
	v_mul_f32_e32 v43, v30, v31
	v_fma_f32 v32, v30, v30, -v42
	v_add_f32_e32 v33, v43, v43
	v_mul_f32_e32 v42, v33, v33
	v_mul_f32_e32 v43, v32, v33
	v_fma_f32 v34, v32, v32, -v42
	v_add_f32_e32 v35, v43, v43
	v_mul_f32_e32 v42, v35, v35
	v_mul_f32_e32 v43, v34, v35
	v_fma_f32 v36, v34, v34, -v42
	v_add_f32_e32 v37, v43, v43
	v_mov_b32_e32 v38, 1.0
	v_mov_b32_e32 v39, 0
	v_mov_b32_e32 v40, 1.0
	v_mov_b32_e32 v41, 0
	v_mul_f32_e32 v15, v39, v23
	v_fma_f32 v42, v38, v22, -v15
	v_mul_f32_e32 v15, v38, v23
	v_fma_f32 v43, v39, v22, v15
	v_cndmask_b32_e64 v38, v38, v42, s[10:11]
	v_cndmask_b32_e64 v39, v39, v43, s[10:11]
	v_mul_f32_e32 v15, v41, v23
	v_fma_f32 v42, v40, v22, -v15
	v_mul_f32_e32 v15, v40, v23
	v_fma_f32 v43, v41, v22, v15
	v_cndmask_b32_e64 v40, v42, v40, s[10:11]
	v_cndmask_b32_e64 v41, v43, v41, s[10:11]
	v_mul_f32_e32 v15, v39, v31
	v_fma_f32 v42, v38, v30, -v15
	v_mul_f32_e32 v15, v38, v31
	v_fma_f32 v43, v39, v30, v15
	v_cndmask_b32_e64 v38, v38, v42, s[12:13]
	v_cndmask_b32_e64 v39, v39, v43, s[12:13]
	v_mul_f32_e32 v15, v41, v31
	v_fma_f32 v42, v40, v30, -v15
	v_mul_f32_e32 v15, v40, v31
	v_fma_f32 v43, v41, v30, v15
	v_cndmask_b32_e64 v40, v42, v40, s[12:13]
	v_cndmask_b32_e64 v41, v43, v41, s[12:13]
	v_mul_f32_e32 v15, v39, v33
	v_fma_f32 v42, v38, v32, -v15
	v_mul_f32_e32 v15, v38, v33
	v_fma_f32 v43, v39, v32, v15
	v_cndmask_b32_e64 v38, v38, v42, s[14:15]
	v_cndmask_b32_e64 v39, v39, v43, s[14:15]
	v_mul_f32_e32 v15, v41, v33
	v_fma_f32 v42, v40, v32, -v15
	v_mul_f32_e32 v15, v40, v33
	v_fma_f32 v43, v41, v32, v15
	v_cndmask_b32_e64 v40, v42, v40, s[14:15]
	v_cndmask_b32_e64 v41, v43, v41, s[14:15]
	v_mul_f32_e32 v15, v39, v35
	v_fma_f32 v42, v38, v34, -v15
	v_mul_f32_e32 v15, v38, v35
	v_fma_f32 v43, v39, v34, v15
	v_cndmask_b32_e64 v38, v38, v42, s[16:17]
	v_cndmask_b32_e64 v39, v39, v43, s[16:17]
	v_mul_f32_e32 v15, v41, v35
	v_fma_f32 v42, v40, v34, -v15
	v_mul_f32_e32 v15, v40, v35
	v_fma_f32 v43, v41, v34, v15
	v_cndmask_b32_e64 v40, v42, v40, s[16:17]
	v_cndmask_b32_e64 v41, v43, v41, s[16:17]
	v_mul_f32_e32 v42, v25, v25
	v_mul_f32_e32 v43, v24, v25
	v_fma_f32 v30, v24, v24, -v42
	v_add_f32_e32 v31, v43, v43
	v_mul_f32_e32 v42, v31, v31
	v_mul_f32_e32 v43, v30, v31
	v_fma_f32 v32, v30, v30, -v42
	v_add_f32_e32 v33, v43, v43
	v_mul_f32_e32 v42, v33, v33
	v_mul_f32_e32 v43, v32, v33
	v_fma_f32 v34, v32, v32, -v42
	v_add_f32_e32 v35, v43, v43
	v_mov_b32_e32 v16, 1.0
	v_mov_b32_e32 v17, 0
	v_mul_f32_e32 v15, v17, v25
	v_fma_f32 v42, v16, v24, -v15
	v_mul_f32_e32 v15, v16, v25
	v_fma_f32 v43, v17, v24, v15
	v_cndmask_b32_e64 v16, v16, v42, s[10:11]
	v_cndmask_b32_e64 v17, v17, v43, s[10:11]
	v_mul_f32_e32 v15, v17, v31
	v_fma_f32 v42, v16, v30, -v15
	v_mul_f32_e32 v15, v16, v31
	v_fma_f32 v43, v17, v30, v15
	v_cndmask_b32_e64 v16, v16, v42, s[12:13]
	v_cndmask_b32_e64 v17, v17, v43, s[12:13]
	v_mul_f32_e32 v15, v17, v33
	v_fma_f32 v42, v16, v32, -v15
	v_mul_f32_e32 v15, v16, v33
	v_fma_f32 v43, v17, v32, v15
	v_cndmask_b32_e64 v16, v16, v42, s[14:15]
	v_cndmask_b32_e64 v17, v17, v43, s[14:15]
	v_mul_f32_e32 v15, v17, v35
	v_fma_f32 v42, v16, v34, -v15
	v_mul_f32_e32 v15, v16, v35
	v_fma_f32 v43, v17, v34, v15
	v_cndmask_b32_e64 v16, v16, v42, s[16:17]
	v_cndmask_b32_e64 v17, v17, v43, s[16:17]
	v_mul_f32_e32 v15, v29, v17
	v_fma_f32 v18, v28, v16, -v15
	v_mul_f32_e32 v15, v28, v17
	v_fma_f32 v19, v29, v16, v15
	v_mul_f32_e32 v15, v29, v41
	v_fma_f32 v20, v28, v40, -v15
	v_mul_f32_e32 v15, v28, v41
	v_fma_f32 v21, v29, v40, v15
	global_store_dwordx2 v13, v[18:19], s[20:21] offset:1024
	global_store_dwordx2 v13, v[38:39], s[20:21] offset:1032
	global_store_dwordx2 v44, v[36:37], s[20:21] offset:1024
	global_store_dwordx2 v44, v[22:23], s[20:21] offset:1032
	global_store_dwordx2 v14, v[20:21], s[22:23] offset:1024
	global_store_dwordx2 v14, v[36:37], s[22:23] offset:1032
	s_nop 1
	v_mul_f32_e32 v15, v12, v6
	v_mul_f32_e32 v16, 0x3fb8aa3b, v15
	v_mul_f32_e32 v17, 0xbfb8aa3b, v15
	v_exp_f32_e32 v16, v16
	v_exp_f32_e32 v17, v17
	v_mul_f32_e32 v18, v12, v10
	v_mul_f32_e32 v19, 0.15915494, v18
	v_rndne_f32_e32 v19, v19
	v_fma_f32 v18, v18, 0.15915494, -v19
	v_cos_f32_e32 v19, v18
	v_sin_f32_e32 v20, v18
	s_nop 0
	v_mul_f32_e32 v22, v16, v19
	v_mul_f32_e32 v23, v16, v20
	v_mul_f32_e32 v24, v17, v19
	v_mul_f32_e64 v25, -v17, v20
	v_add_f32_e32 v26, -1.0, v22
	v_mul_f32_e32 v27, v10, v10
	v_fmac_f32_e32 v27, v6, v6
	v_rcp_f32_e32 v27, v27
	v_mul_f32_e32 v28, v26, v6
	v_fmac_f32_e32 v28, v23, v10
	v_mul_f32_e32 v29, v23, v6
	v_fma_f32 v29, -v26, v10, v29
	v_mul_f32_e32 v28, v28, v27
	v_mul_f32_e32 v29, v29, v27
	v_mul_f32_e32 v42, v23, v23
	v_mul_f32_e32 v43, v22, v23
	v_fma_f32 v30, v22, v22, -v42
	v_add_f32_e32 v31, v43, v43
	v_mul_f32_e32 v42, v31, v31
	v_mul_f32_e32 v43, v30, v31
	v_fma_f32 v32, v30, v30, -v42
	v_add_f32_e32 v33, v43, v43
	v_mul_f32_e32 v42, v33, v33
	v_mul_f32_e32 v43, v32, v33
	v_fma_f32 v34, v32, v32, -v42
	v_add_f32_e32 v35, v43, v43
	v_mul_f32_e32 v42, v35, v35
	v_mul_f32_e32 v43, v34, v35
	v_fma_f32 v36, v34, v34, -v42
	v_add_f32_e32 v37, v43, v43
	v_mov_b32_e32 v38, 1.0
	v_mov_b32_e32 v39, 0
	v_mov_b32_e32 v40, 1.0
	v_mov_b32_e32 v41, 0
	v_mul_f32_e32 v15, v39, v23
	v_fma_f32 v42, v38, v22, -v15
	v_mul_f32_e32 v15, v38, v23
	v_fma_f32 v43, v39, v22, v15
	v_cndmask_b32_e64 v38, v38, v42, s[10:11]
	v_cndmask_b32_e64 v39, v39, v43, s[10:11]
	v_mul_f32_e32 v15, v41, v23
	v_fma_f32 v42, v40, v22, -v15
	v_mul_f32_e32 v15, v40, v23
	v_fma_f32 v43, v41, v22, v15
	v_cndmask_b32_e64 v40, v42, v40, s[10:11]
	v_cndmask_b32_e64 v41, v43, v41, s[10:11]
	v_mul_f32_e32 v15, v39, v31
	v_fma_f32 v42, v38, v30, -v15
	v_mul_f32_e32 v15, v38, v31
	v_fma_f32 v43, v39, v30, v15
	v_cndmask_b32_e64 v38, v38, v42, s[12:13]
	v_cndmask_b32_e64 v39, v39, v43, s[12:13]
	v_mul_f32_e32 v15, v41, v31
	v_fma_f32 v42, v40, v30, -v15
	v_mul_f32_e32 v15, v40, v31
	v_fma_f32 v43, v41, v30, v15
	v_cndmask_b32_e64 v40, v42, v40, s[12:13]
	v_cndmask_b32_e64 v41, v43, v41, s[12:13]
	v_mul_f32_e32 v15, v39, v33
	v_fma_f32 v42, v38, v32, -v15
	v_mul_f32_e32 v15, v38, v33
	v_fma_f32 v43, v39, v32, v15
	v_cndmask_b32_e64 v38, v38, v42, s[14:15]
	v_cndmask_b32_e64 v39, v39, v43, s[14:15]
	v_mul_f32_e32 v15, v41, v33
	v_fma_f32 v42, v40, v32, -v15
	v_mul_f32_e32 v15, v40, v33
	v_fma_f32 v43, v41, v32, v15
	v_cndmask_b32_e64 v40, v42, v40, s[14:15]
	v_cndmask_b32_e64 v41, v43, v41, s[14:15]
	v_mul_f32_e32 v15, v39, v35
	v_fma_f32 v42, v38, v34, -v15
	v_mul_f32_e32 v15, v38, v35
	v_fma_f32 v43, v39, v34, v15
	v_cndmask_b32_e64 v38, v38, v42, s[16:17]
	v_cndmask_b32_e64 v39, v39, v43, s[16:17]
	v_mul_f32_e32 v15, v41, v35
	v_fma_f32 v42, v40, v34, -v15
	v_mul_f32_e32 v15, v40, v35
	v_fma_f32 v43, v41, v34, v15
	v_cndmask_b32_e64 v40, v42, v40, s[16:17]
	v_cndmask_b32_e64 v41, v43, v41, s[16:17]
	v_mul_f32_e32 v42, v25, v25
	v_mul_f32_e32 v43, v24, v25
	v_fma_f32 v30, v24, v24, -v42
	v_add_f32_e32 v31, v43, v43
	v_mul_f32_e32 v42, v31, v31
	v_mul_f32_e32 v43, v30, v31
	v_fma_f32 v32, v30, v30, -v42
	v_add_f32_e32 v33, v43, v43
	v_mul_f32_e32 v42, v33, v33
	v_mul_f32_e32 v43, v32, v33
	v_fma_f32 v34, v32, v32, -v42
	v_add_f32_e32 v35, v43, v43
	v_mov_b32_e32 v16, 1.0
	v_mov_b32_e32 v17, 0
	v_mul_f32_e32 v15, v17, v25
	v_fma_f32 v42, v16, v24, -v15
	v_mul_f32_e32 v15, v16, v25
	v_fma_f32 v43, v17, v24, v15
	v_cndmask_b32_e64 v16, v16, v42, s[10:11]
	v_cndmask_b32_e64 v17, v17, v43, s[10:11]
	v_mul_f32_e32 v15, v17, v31
	v_fma_f32 v42, v16, v30, -v15
	v_mul_f32_e32 v15, v16, v31
	v_fma_f32 v43, v17, v30, v15
	v_cndmask_b32_e64 v16, v16, v42, s[12:13]
	v_cndmask_b32_e64 v17, v17, v43, s[12:13]
	v_mul_f32_e32 v15, v17, v33
	v_fma_f32 v42, v16, v32, -v15
	v_mul_f32_e32 v15, v16, v33
	v_fma_f32 v43, v17, v32, v15
	v_cndmask_b32_e64 v16, v16, v42, s[14:15]
	v_cndmask_b32_e64 v17, v17, v43, s[14:15]
	v_mul_f32_e32 v15, v17, v35
	v_fma_f32 v42, v16, v34, -v15
	v_mul_f32_e32 v15, v16, v35
	v_fma_f32 v43, v17, v34, v15
	v_cndmask_b32_e64 v16, v16, v42, s[16:17]
	v_cndmask_b32_e64 v17, v17, v43, s[16:17]
	v_mul_f32_e32 v15, v29, v17
	v_fma_f32 v18, v28, v16, -v15
	v_mul_f32_e32 v15, v28, v17
	v_fma_f32 v19, v29, v16, v15
	v_mul_f32_e32 v15, v29, v41
	v_fma_f32 v20, v28, v40, -v15
	v_mul_f32_e32 v15, v28, v41
	v_fma_f32 v21, v29, v40, v15
	global_store_dwordx2 v13, v[18:19], s[20:21] offset:2048
	global_store_dwordx2 v13, v[38:39], s[20:21] offset:2056
	global_store_dwordx2 v44, v[36:37], s[20:21] offset:2048
	global_store_dwordx2 v44, v[22:23], s[20:21] offset:2056
	global_store_dwordx2 v14, v[20:21], s[22:23] offset:2048
	global_store_dwordx2 v14, v[36:37], s[22:23] offset:2056
	s_nop 1
	v_mul_f32_e32 v15, v12, v7
	v_mul_f32_e32 v16, 0x3fb8aa3b, v15
	v_mul_f32_e32 v17, 0xbfb8aa3b, v15
	v_exp_f32_e32 v16, v16
	v_exp_f32_e32 v17, v17
	v_mul_f32_e32 v18, v12, v11
	v_mul_f32_e32 v19, 0.15915494, v18
	v_rndne_f32_e32 v19, v19
	v_fma_f32 v18, v18, 0.15915494, -v19
	v_cos_f32_e32 v19, v18
	v_sin_f32_e32 v20, v18
	s_nop 0
	v_mul_f32_e32 v22, v16, v19
	v_mul_f32_e32 v23, v16, v20
	v_mul_f32_e32 v24, v17, v19
	v_mul_f32_e64 v25, -v17, v20
	v_add_f32_e32 v26, -1.0, v22
	v_mul_f32_e32 v27, v11, v11
	v_fmac_f32_e32 v27, v7, v7
	v_rcp_f32_e32 v27, v27
	v_mul_f32_e32 v28, v26, v7
	v_fmac_f32_e32 v28, v23, v11
	v_mul_f32_e32 v29, v23, v7
	v_fma_f32 v29, -v26, v11, v29
	v_mul_f32_e32 v28, v28, v27
	v_mul_f32_e32 v29, v29, v27
	v_mul_f32_e32 v42, v23, v23
	v_mul_f32_e32 v43, v22, v23
	v_fma_f32 v30, v22, v22, -v42
	v_add_f32_e32 v31, v43, v43
	v_mul_f32_e32 v42, v31, v31
	v_mul_f32_e32 v43, v30, v31
	v_fma_f32 v32, v30, v30, -v42
	v_add_f32_e32 v33, v43, v43
	v_mul_f32_e32 v42, v33, v33
	v_mul_f32_e32 v43, v32, v33
	v_fma_f32 v34, v32, v32, -v42
	v_add_f32_e32 v35, v43, v43
	v_mul_f32_e32 v42, v35, v35
	v_mul_f32_e32 v43, v34, v35
	v_fma_f32 v36, v34, v34, -v42
	v_add_f32_e32 v37, v43, v43
	v_mov_b32_e32 v38, 1.0
	v_mov_b32_e32 v39, 0
	v_mov_b32_e32 v40, 1.0
	v_mov_b32_e32 v41, 0
	v_mul_f32_e32 v15, v39, v23
	v_fma_f32 v42, v38, v22, -v15
	v_mul_f32_e32 v15, v38, v23
	v_fma_f32 v43, v39, v22, v15
	v_cndmask_b32_e64 v38, v38, v42, s[10:11]
	v_cndmask_b32_e64 v39, v39, v43, s[10:11]
	v_mul_f32_e32 v15, v41, v23
	v_fma_f32 v42, v40, v22, -v15
	v_mul_f32_e32 v15, v40, v23
	v_fma_f32 v43, v41, v22, v15
	v_cndmask_b32_e64 v40, v42, v40, s[10:11]
	v_cndmask_b32_e64 v41, v43, v41, s[10:11]
	v_mul_f32_e32 v15, v39, v31
	v_fma_f32 v42, v38, v30, -v15
	v_mul_f32_e32 v15, v38, v31
	v_fma_f32 v43, v39, v30, v15
	v_cndmask_b32_e64 v38, v38, v42, s[12:13]
	v_cndmask_b32_e64 v39, v39, v43, s[12:13]
	v_mul_f32_e32 v15, v41, v31
	v_fma_f32 v42, v40, v30, -v15
	v_mul_f32_e32 v15, v40, v31
	v_fma_f32 v43, v41, v30, v15
	v_cndmask_b32_e64 v40, v42, v40, s[12:13]
	v_cndmask_b32_e64 v41, v43, v41, s[12:13]
	v_mul_f32_e32 v15, v39, v33
	v_fma_f32 v42, v38, v32, -v15
	v_mul_f32_e32 v15, v38, v33
	v_fma_f32 v43, v39, v32, v15
	v_cndmask_b32_e64 v38, v38, v42, s[14:15]
	v_cndmask_b32_e64 v39, v39, v43, s[14:15]
	v_mul_f32_e32 v15, v41, v33
	v_fma_f32 v42, v40, v32, -v15
	v_mul_f32_e32 v15, v40, v33
	v_fma_f32 v43, v41, v32, v15
	v_cndmask_b32_e64 v40, v42, v40, s[14:15]
	v_cndmask_b32_e64 v41, v43, v41, s[14:15]
	v_mul_f32_e32 v15, v39, v35
	v_fma_f32 v42, v38, v34, -v15
	v_mul_f32_e32 v15, v38, v35
	v_fma_f32 v43, v39, v34, v15
	v_cndmask_b32_e64 v38, v38, v42, s[16:17]
	v_cndmask_b32_e64 v39, v39, v43, s[16:17]
	v_mul_f32_e32 v15, v41, v35
	v_fma_f32 v42, v40, v34, -v15
	v_mul_f32_e32 v15, v40, v35
	v_fma_f32 v43, v41, v34, v15
	v_cndmask_b32_e64 v40, v42, v40, s[16:17]
	v_cndmask_b32_e64 v41, v43, v41, s[16:17]
	v_mul_f32_e32 v42, v25, v25
	v_mul_f32_e32 v43, v24, v25
	v_fma_f32 v30, v24, v24, -v42
	v_add_f32_e32 v31, v43, v43
	v_mul_f32_e32 v42, v31, v31
	v_mul_f32_e32 v43, v30, v31
	v_fma_f32 v32, v30, v30, -v42
	v_add_f32_e32 v33, v43, v43
	v_mul_f32_e32 v42, v33, v33
	v_mul_f32_e32 v43, v32, v33
	v_fma_f32 v34, v32, v32, -v42
	v_add_f32_e32 v35, v43, v43
	v_mov_b32_e32 v16, 1.0
	v_mov_b32_e32 v17, 0
	v_mul_f32_e32 v15, v17, v25
	v_fma_f32 v42, v16, v24, -v15
	v_mul_f32_e32 v15, v16, v25
	v_fma_f32 v43, v17, v24, v15
	v_cndmask_b32_e64 v16, v16, v42, s[10:11]
	v_cndmask_b32_e64 v17, v17, v43, s[10:11]
	v_mul_f32_e32 v15, v17, v31
	v_fma_f32 v42, v16, v30, -v15
	v_mul_f32_e32 v15, v16, v31
	v_fma_f32 v43, v17, v30, v15
	v_cndmask_b32_e64 v16, v16, v42, s[12:13]
	v_cndmask_b32_e64 v17, v17, v43, s[12:13]
	v_mul_f32_e32 v15, v17, v33
	v_fma_f32 v42, v16, v32, -v15
	v_mul_f32_e32 v15, v16, v33
	v_fma_f32 v43, v17, v32, v15
	v_cndmask_b32_e64 v16, v16, v42, s[14:15]
	v_cndmask_b32_e64 v17, v17, v43, s[14:15]
	v_mul_f32_e32 v15, v17, v35
	v_fma_f32 v42, v16, v34, -v15
	v_mul_f32_e32 v15, v16, v35
	v_fma_f32 v43, v17, v34, v15
	v_cndmask_b32_e64 v16, v16, v42, s[16:17]
	v_cndmask_b32_e64 v17, v17, v43, s[16:17]
	v_mul_f32_e32 v15, v29, v17
	v_fma_f32 v18, v28, v16, -v15
	v_mul_f32_e32 v15, v28, v17
	v_fma_f32 v19, v29, v16, v15
	v_mul_f32_e32 v15, v29, v41
	v_fma_f32 v20, v28, v40, -v15
	v_mul_f32_e32 v15, v28, v41
	v_fma_f32 v21, v29, v40, v15
	global_store_dwordx2 v13, v[18:19], s[20:21] offset:3072
	global_store_dwordx2 v13, v[38:39], s[20:21] offset:3080
	global_store_dwordx2 v44, v[36:37], s[20:21] offset:3072
	global_store_dwordx2 v44, v[22:23], s[20:21] offset:3080
	global_store_dwordx2 v14, v[20:21], s[22:23] offset:3072
	global_store_dwordx2 v14, v[36:37], s[22:23] offset:3080
	s_nop 1
	s_lshl_b32 s0, s7, 2
	s_add_i32 s0, s0, s6
	s_lshl_b32 s8, s7, 12
	s_lshl_b32 s9, s6, 10
	s_add_i32 s8, s8, s9
	s_add_u32 s8, s8, 0x11fb20
	s_add_u32 s8, s4, s8
	s_addc_u32 s9, s5, 0
	s_add_u32 s10, s8, 0x40000
	s_addc_u32 s11, s9, 0
	s_lshl_b32 s12, s7, 12
	s_lshl_b32 s13, s6, 6
	s_add_i32 s12, s12, s13
	s_add_u32 s12, s12, 0x19fb20
	s_add_u32 s12, s4, s12
	s_addc_u32 s13, s5, 0
	s_add_u32 s14, s12, 0x40000
	s_addc_u32 s15, s13, 0
	s_lshl_b32 s16, s0, 11
	s_add_u32 s16, s16, 0xfd00000
	s_add_u32 s16, s4, s16
	s_addc_u32 s17, s5, 0
	s_lshl_b32 s18, s0, 10
	s_add_u32 s18, s18, 0xfd80000
	s_add_u32 s18, s4, s18
	s_addc_u32 s19, s5, 0
	v_mov_b32_e32 v0, 0
	v_mov_b32_e32 v1, 0
	v_mov_b32_e32 v2, 0
	v_mov_b32_e32 v3, 0
	v_mov_b32_e32 v4, 0
	v_mov_b32_e32 v5, 0
	v_mov_b32_e32 v6, 0
	v_mov_b32_e32 v7, 0
	v_mov_b32_e32 v8, 0
	v_mov_b32_e32 v9, 0
	v_mov_b32_e32 v10, 0
	v_mov_b32_e32 v11, 0
	v_mov_b32_e32 v12, 0
	v_mov_b32_e32 v13, 0
	v_mov_b32_e32 v14, 0
	v_mov_b32_e32 v15, 0
	v_and_b32_e32 v24, 15, v205
	v_lshrrev_b32_e32 v26, 4, v205
	v_lshlrev_b32_e32 v25, 8, v24
	v_lshl_add_u32 v25, v26, 4, v25
	v_lshlrev_b32_e32 v24, 6, v24
	v_and_b32_e32 v26, 16, v205
	v_lshl_add_u32 v24, v26, 1, v24
	s_mov_b32 exec_hi, 0
	global_load_dwordx4 v[0:3], v24, s[8:9]
	global_load_dwordx4 v[4:7], v24, s[8:9] offset:16
	global_load_dwordx4 v[8:11], v24, s[10:11]
	global_load_dwordx4 v[12:15], v24, s[10:11] offset:16
	s_mov_b64 exec, -1
	global_load_dwordx4 v[16:19], v25, s[12:13]
	global_load_dwordx4 v[20:23], v25, s[14:15]
	s_waitcnt vmcnt(2)
	v_cvt_pk_bf16_f32 v0, v0, v1
	v_cvt_pk_bf16_f32 v1, v2, v3
	v_cvt_pk_bf16_f32 v2, v4, v5
	v_cvt_pk_bf16_f32 v3, v6, v7
	v_cvt_pk_bf16_f32 v8, v8, v9
	v_cvt_pk_bf16_f32 v9, v10, v11
	v_cvt_pk_bf16_f32 v10, v12, v13
	v_cvt_pk_bf16_f32 v11, v14, v15
	v_lshlrev_b32_e32 v27, 4, v205
	global_store_dwordx4 v27, v[0:3], s[16:17]
	global_store_dwordx4 v27, v[8:11], s[16:17] offset:1024
	s_waitcnt vmcnt(0)
	v_cvt_pk_bf16_f32 v16, v16, v17
	v_cvt_pk_bf16_f32 v17, v18, v19
	v_cvt_pk_bf16_f32 v18, -v20, -v21
	v_cvt_pk_bf16_f32 v19, -v22, -v23
	global_store_dwordx4 v27, v[16:19], s[18:19]
	s_nop 1

.Lrn_p1_end:
.LBB0_620:
	s_bitcmp0_b32 s94, 14
	s_cbranch_scc1 .LBB0_624
	v_and_b32_e32 v206, 15, v205
	v_lshrrev_b32_e32 v207, 4, v205
	v_lshlrev_b32_e32 v208, 3, v205
	v_lshlrev_b32_e32 v209, 4, v205
	v_lshrrev_b32_e32 v210, 6, v186
	s_nop 0
	v_readfirstlane_b32 s22, v210
	v_lshrrev_b32_e32 v135, 3, v205
	v_and_b32_e32 v132, 7, v205
	v_xor_b32_e32 v132, v132, v135
	v_lshlrev_b32_e32 v132, 4, v132
	v_lshl_add_u32 v132, v135, 9, v132
	s_lshl_b32 s23, s22, 13
	v_and_b32_e32 v135, 7, v206
	v_xor_b32_e32 v133, 0, v207
	v_xor_b32_e32 v133, v133, v135
	v_lshlrev_b32_e32 v133, 4, v133
	v_lshl_add_u32 v133, v206, 7, v133
	v_add_u32_e32 v128, 0x10000, v133
	v_add_u32_e32 v133, s23, v133
	v_xor_b32_e32 v134, 4, v207
	v_or_b32_e32 v134, 4, v207
	v_xor_b32_e32 v134, v134, v135
	v_lshlrev_b32_e32 v134, 4, v134
	v_lshl_add_u32 v134, v206, 7, v134
	v_add_u32_e32 v129, 0x10000, v134
	v_add_u32_e32 v134, s23, v134
	v_mul_u32_u24_e32 v212, 0x90, v206
	v_add_u32_e32 v212, 0x18000, v212
	v_lshl_add_u32 v211, v210, 2, v207
	v_lshl_add_u32 v211, v211, 2, v212
	v_lshlrev_b32_e32 v213, 11, v206
	v_lshl_add_u32 v213, v207, 3, v213
	s_lshl_b32 s0, s22, 6
	s_addk_i32 s0, 0x600
	v_add_u32_e32 v213, s0, v213
	s_mul_i32 s0, s24, 0x1600000
	s_add_u32 s0, s0, 0xfc0000
	s_lshl_b32 s1, s22, 14
	s_add_u32 s0, s0, s1
	s_add_u32 s8, s4, s0
	s_addc_u32 s9, s5, 0
	s_lshl_b32 s16, s69, 6
	s_addk_i32 s16, 0x400
	s_mov_b32 s17, 0
.Lgg_blk:
	s_lshl_b32 s0, s22, 3
	s_add_i32 s0, s0, s16
	s_mul_i32 s1, s0, 0x600
	s_add_u32 s1, s1, 0xdf00000
	s_add_u32 s10, s4, s1
	s_addc_u32 s11, s5, 0
	s_lshl_b32 s1, s0, 11
	s_add_u32 s1, s1, 0x3c00000
	s_add_u32 s12, s4, s1
	s_addc_u32 s13, s5, 0
	s_lshl_b32 s1, s16, 11
	s_add_u32 s1, s1, 0x3c00000
	s_add_u32 s14, s4, s1
	s_addc_u32 s15, s5, 0
	s_lshl_b32 s1, s16, 9
	s_add_u32 s1, s1, 0xc500000
	s_add_u32 s6, s4, s1
	s_addc_u32 s7, s5, 0
	s_lshl_b32 s0, s22, 12
	s_add_u32 s6, s6, s0
	s_addc_u32 s7, s7, 0
	s_lshl_b32 s18, s22, 10
	s_add_i32 s18, s18, 0x10000
	s_add_i32 m0, s18, 0x0
	s_nop 0
	global_load_lds_dwordx4 v132, s[6:7]
	s_add_u32 s6, s6, 0x80
	s_addc_u32 s7, s7, 0
	s_add_i32 m0, s18, 0x2000
	s_nop 0
	global_load_lds_dwordx4 v132, s[6:7]
	s_add_u32 s6, s6, 0x80
	s_addc_u32 s7, s7, 0
	s_add_i32 m0, s18, 0x4000
	s_nop 0
	global_load_lds_dwordx4 v132, s[6:7]
	s_add_u32 s6, s6, 0x80
	s_addc_u32 s7, s7, 0
	s_add_i32 m0, s18, 0x6000
	s_nop 0
	global_load_lds_dwordx4 v132, s[6:7]
	s_add_u32 s0, s8, 0x0
	s_addc_u32 s1, s9, 0
	s_add_i32 m0, s23, 0x0
	s_nop 0
	global_load_lds_dwordx4 v132, s[0:1]
	s_add_u32 s0, s8, 0x1000
	s_addc_u32 s1, s9, 0
	s_add_i32 m0, s23, 0x400
	s_nop 0
	global_load_lds_dwordx4 v132, s[0:1]
	s_add_u32 s0, s8, 0x2000
	s_addc_u32 s1, s9, 0
	s_add_i32 m0, s23, 0x800
	s_nop 0
	global_load_lds_dwordx4 v132, s[0:1]
	s_add_u32 s0, s8, 0x3000
	s_addc_u32 s1, s9, 0
	s_add_i32 m0, s23, 0xc00
	s_nop 0
	global_load_lds_dwordx4 v132, s[0:1]
	s_add_u32 s0, s8, 0x20000
	s_addc_u32 s1, s9, 0
	s_add_i32 m0, s23, 0x1000
	s_nop 0
	global_load_lds_dwordx4 v132, s[0:1]
	s_add_u32 s0, s8, 0x21000
	s_addc_u32 s1, s9, 0
	s_add_i32 m0, s23, 0x1400
	s_nop 0
	global_load_lds_dwordx4 v132, s[0:1]
	s_add_u32 s0, s8, 0x22000
	s_addc_u32 s1, s9, 0
	s_add_i32 m0, s23, 0x1800
	s_nop 0
	global_load_lds_dwordx4 v132, s[0:1]
	s_add_u32 s0, s8, 0x23000
	s_addc_u32 s1, s9, 0
	s_add_i32 m0, s23, 0x1c00
	s_nop 0
	global_load_lds_dwordx4 v132, s[0:1]
	s_waitcnt vmcnt(8)
	s_barrier
	ds_read_b128 v[138:141], v128 offset:0
	ds_read_b128 v[142:145], v128 offset:2048
	ds_read_b128 v[146:149], v128 offset:4096
	ds_read_b128 v[150:153], v128 offset:6144
	ds_read_b128 v[154:157], v129 offset:0
	ds_read_b128 v[158:161], v129 offset:2048
	ds_read_b128 v[162:165], v129 offset:4096
	ds_read_b128 v[166:169], v129 offset:6144
	s_waitcnt vmcnt(0)
	ds_read_b128 v[64:67], v133 offset:0
	ds_read_b128 v[72:75], v133 offset:2048
	ds_read_b128 v[80:83], v133 offset:4096
	ds_read_b128 v[88:91], v133 offset:6144
	ds_read_b128 v[68:71], v134 offset:0
	ds_read_b128 v[76:79], v134 offset:2048
	ds_read_b128 v[84:87], v134 offset:4096
	ds_read_b128 v[92:95], v134 offset:6144
	s_waitcnt lgkmcnt(0)
	s_add_u32 s0, s8, 0x80
	s_addc_u32 s1, s9, 0
	s_add_i32 m0, s23, 0x0
	s_nop 0
	global_load_lds_dwordx4 v132, s[0:1]
	s_add_u32 s0, s8, 0x1080
	s_addc_u32 s1, s9, 0
	s_add_i32 m0, s23, 0x400
	s_nop 0
	global_load_lds_dwordx4 v132, s[0:1]
	s_add_u32 s0, s8, 0x2080
	s_addc_u32 s1, s9, 0
	s_add_i32 m0, s23, 0x800
	s_nop 0
	global_load_lds_dwordx4 v132, s[0:1]
	s_add_u32 s0, s8, 0x3080
	s_addc_u32 s1, s9, 0
	s_add_i32 m0, s23, 0xc00
	s_nop 0
	global_load_lds_dwordx4 v132, s[0:1]
	s_add_u32 s0, s8, 0x20080
	s_addc_u32 s1, s9, 0
	s_add_i32 m0, s23, 0x1000
	s_nop 0
	global_load_lds_dwordx4 v132, s[0:1]
	s_add_u32 s0, s8, 0x21080
	s_addc_u32 s1, s9, 0
	s_add_i32 m0, s23, 0x1400
	s_nop 0
	global_load_lds_dwordx4 v132, s[0:1]
	s_add_u32 s0, s8, 0x22080
	s_addc_u32 s1, s9, 0
	s_add_i32 m0, s23, 0x1800
	s_nop 0
	global_load_lds_dwordx4 v132, s[0:1]
	s_add_u32 s0, s8, 0x23080
	s_addc_u32 s1, s9, 0
	s_add_i32 m0, s23, 0x1c00
	s_nop 0
	global_load_lds_dwordx4 v132, s[0:1]
	v_mfma_f32_16x16x32_bf16 v[0:3], v[64:67], v[138:141], 0
	v_mfma_f32_16x16x32_bf16 v[16:19], v[64:67], v[142:145], 0
	v_mfma_f32_16x16x32_bf16 v[32:35], v[64:67], v[146:149], 0
	v_mfma_f32_16x16x32_bf16 v[48:51], v[64:67], v[150:153], 0
	v_mfma_f32_16x16x32_bf16 v[4:7], v[72:75], v[138:141], 0
	v_mfma_f32_16x16x32_bf16 v[20:23], v[72:75], v[142:145], 0
	v_mfma_f32_16x16x32_bf16 v[36:39], v[72:75], v[146:149], 0
	v_mfma_f32_16x16x32_bf16 v[52:55], v[72:75], v[150:153], 0
	v_mfma_f32_16x16x32_bf16 v[8:11], v[80:83], v[138:141], 0
	v_mfma_f32_16x16x32_bf16 v[24:27], v[80:83], v[142:145], 0
	v_mfma_f32_16x16x32_bf16 v[40:43], v[80:83], v[146:149], 0
	v_mfma_f32_16x16x32_bf16 v[56:59], v[80:83], v[150:153], 0
	v_mfma_f32_16x16x32_bf16 v[12:15], v[88:91], v[138:141], 0
	v_mfma_f32_16x16x32_bf16 v[28:31], v[88:91], v[142:145], 0
	v_mfma_f32_16x16x32_bf16 v[44:47], v[88:91], v[146:149], 0
	v_mfma_f32_16x16x32_bf16 v[60:63], v[88:91], v[150:153], 0
	ds_read_b128 v[170:173], v128 offset:8192
	ds_read_b128 v[174:177], v128 offset:10240
	ds_read_b128 v[178:181], v128 offset:12288
	ds_read_b128 v[182:185], v128 offset:14336
	s_waitcnt vmcnt(0)
	ds_read_b128 v[96:99], v133 offset:0
	ds_read_b128 v[104:107], v133 offset:2048
	ds_read_b128 v[112:115], v133 offset:4096
	ds_read_b128 v[120:123], v133 offset:6144
	ds_read_b128 v[100:103], v134 offset:0
	ds_read_b128 v[108:111], v134 offset:2048
	ds_read_b128 v[116:119], v134 offset:4096
	ds_read_b128 v[124:127], v134 offset:6144
	v_mfma_f32_16x16x32_bf16 v[0:3], v[68:71], v[154:157], v[0:3]
	v_mfma_f32_16x16x32_bf16 v[16:19], v[68:71], v[158:161], v[16:19]
	v_mfma_f32_16x16x32_bf16 v[32:35], v[68:71], v[162:165], v[32:35]
	v_mfma_f32_16x16x32_bf16 v[48:51], v[68:71], v[166:169], v[48:51]
	v_mfma_f32_16x16x32_bf16 v[4:7], v[76:79], v[154:157], v[4:7]
	v_mfma_f32_16x16x32_bf16 v[20:23], v[76:79], v[158:161], v[20:23]
	v_mfma_f32_16x16x32_bf16 v[36:39], v[76:79], v[162:165], v[36:39]
	v_mfma_f32_16x16x32_bf16 v[52:55], v[76:79], v[166:169], v[52:55]
	v_mfma_f32_16x16x32_bf16 v[8:11], v[84:87], v[154:157], v[8:11]
	v_mfma_f32_16x16x32_bf16 v[24:27], v[84:87], v[158:161], v[24:27]
	v_mfma_f32_16x16x32_bf16 v[40:43], v[84:87], v[162:165], v[40:43]
	v_mfma_f32_16x16x32_bf16 v[56:59], v[84:87], v[166:169], v[56:59]
	v_mfma_f32_16x16x32_bf16 v[12:15], v[92:95], v[154:157], v[12:15]
	v_mfma_f32_16x16x32_bf16 v[28:31], v[92:95], v[158:161], v[28:31]
	v_mfma_f32_16x16x32_bf16 v[44:47], v[92:95], v[162:165], v[44:47]
	v_mfma_f32_16x16x32_bf16 v[60:63], v[92:95], v[166:169], v[60:63]
	ds_read_b128 v[138:141], v129 offset:8192
	ds_read_b128 v[142:145], v129 offset:10240
	ds_read_b128 v[146:149], v129 offset:12288
	ds_read_b128 v[150:153], v129 offset:14336
	s_waitcnt lgkmcnt(4)
	s_add_u32 s0, s8, 0x100
	s_addc_u32 s1, s9, 0
	s_add_i32 m0, s23, 0x0
	s_nop 0
	global_load_lds_dwordx4 v132, s[0:1]
	s_add_u32 s0, s8, 0x1100
	s_addc_u32 s1, s9, 0
	s_add_i32 m0, s23, 0x400
	s_nop 0
	global_load_lds_dwordx4 v132, s[0:1]
	s_add_u32 s0, s8, 0x2100
	s_addc_u32 s1, s9, 0
	s_add_i32 m0, s23, 0x800
	s_nop 0
	global_load_lds_dwordx4 v132, s[0:1]
	s_add_u32 s0, s8, 0x3100
	s_addc_u32 s1, s9, 0
	s_add_i32 m0, s23, 0xc00
	s_nop 0
	global_load_lds_dwordx4 v132, s[0:1]
	s_add_u32 s0, s8, 0x20100
	s_addc_u32 s1, s9, 0
	s_add_i32 m0, s23, 0x1000
	s_nop 0
	global_load_lds_dwordx4 v132, s[0:1]
	s_add_u32 s0, s8, 0x21100
	s_addc_u32 s1, s9, 0
	s_add_i32 m0, s23, 0x1400
	s_nop 0
	global_load_lds_dwordx4 v132, s[0:1]
	s_add_u32 s0, s8, 0x22100
	s_addc_u32 s1, s9, 0
	s_add_i32 m0, s23, 0x1800
	s_nop 0
	global_load_lds_dwordx4 v132, s[0:1]
	s_add_u32 s0, s8, 0x23100
	s_addc_u32 s1, s9, 0
	s_add_i32 m0, s23, 0x1c00
	s_nop 0
	global_load_lds_dwordx4 v132, s[0:1]
	v_mfma_f32_16x16x32_bf16 v[0:3], v[96:99], v[170:173], v[0:3]
	v_mfma_f32_16x16x32_bf16 v[16:19], v[96:99], v[174:177], v[16:19]
	v_mfma_f32_16x16x32_bf16 v[32:35], v[96:99], v[178:181], v[32:35]
	v_mfma_f32_16x16x32_bf16 v[48:51], v[96:99], v[182:185], v[48:51]
	v_mfma_f32_16x16x32_bf16 v[4:7], v[104:107], v[170:173], v[4:7]
	v_mfma_f32_16x16x32_bf16 v[20:23], v[104:107], v[174:177], v[20:23]
	v_mfma_f32_16x16x32_bf16 v[36:39], v[104:107], v[178:181], v[36:39]
	v_mfma_f32_16x16x32_bf16 v[52:55], v[104:107], v[182:185], v[52:55]
	v_mfma_f32_16x16x32_bf16 v[8:11], v[112:115], v[170:173], v[8:11]
	v_mfma_f32_16x16x32_bf16 v[24:27], v[112:115], v[174:177], v[24:27]
	v_mfma_f32_16x16x32_bf16 v[40:43], v[112:115], v[178:181], v[40:43]
	v_mfma_f32_16x16x32_bf16 v[56:59], v[112:115], v[182:185], v[56:59]
	v_mfma_f32_16x16x32_bf16 v[12:15], v[120:123], v[170:173], v[12:15]
	v_mfma_f32_16x16x32_bf16 v[28:31], v[120:123], v[174:177], v[28:31]
	v_mfma_f32_16x16x32_bf16 v[44:47], v[120:123], v[178:181], v[44:47]
	v_mfma_f32_16x16x32_bf16 v[60:63], v[120:123], v[182:185], v[60:63]
	ds_read_b128 v[154:157], v128 offset:16384
	ds_read_b128 v[158:161], v128 offset:18432
	ds_read_b128 v[162:165], v128 offset:20480
	ds_read_b128 v[166:169], v128 offset:22528
	s_waitcnt vmcnt(0)
	ds_read_b128 v[64:67], v133 offset:0
	ds_read_b128 v[72:75], v133 offset:2048
	ds_read_b128 v[80:83], v133 offset:4096
	ds_read_b128 v[88:91], v133 offset:6144
	ds_read_b128 v[68:71], v134 offset:0
	ds_read_b128 v[76:79], v134 offset:2048
	ds_read_b128 v[84:87], v134 offset:4096
	ds_read_b128 v[92:95], v134 offset:6144
	s_waitcnt lgkmcnt(12)
	v_mfma_f32_16x16x32_bf16 v[0:3], v[100:103], v[138:141], v[0:3]
	v_mfma_f32_16x16x32_bf16 v[16:19], v[100:103], v[142:145], v[16:19]
	v_mfma_f32_16x16x32_bf16 v[32:35], v[100:103], v[146:149], v[32:35]
	v_mfma_f32_16x16x32_bf16 v[48:51], v[100:103], v[150:153], v[48:51]
	v_mfma_f32_16x16x32_bf16 v[4:7], v[108:111], v[138:141], v[4:7]
	v_mfma_f32_16x16x32_bf16 v[20:23], v[108:111], v[142:145], v[20:23]
	v_mfma_f32_16x16x32_bf16 v[36:39], v[108:111], v[146:149], v[36:39]
	v_mfma_f32_16x16x32_bf16 v[52:55], v[108:111], v[150:153], v[52:55]
	v_mfma_f32_16x16x32_bf16 v[8:11], v[116:119], v[138:141], v[8:11]
	v_mfma_f32_16x16x32_bf16 v[24:27], v[116:119], v[142:145], v[24:27]
	v_mfma_f32_16x16x32_bf16 v[40:43], v[116:119], v[146:149], v[40:43]
	v_mfma_f32_16x16x32_bf16 v[56:59], v[116:119], v[150:153], v[56:59]
	v_mfma_f32_16x16x32_bf16 v[12:15], v[124:127], v[138:141], v[12:15]
	v_mfma_f32_16x16x32_bf16 v[28:31], v[124:127], v[142:145], v[28:31]
	v_mfma_f32_16x16x32_bf16 v[44:47], v[124:127], v[146:149], v[44:47]
	v_mfma_f32_16x16x32_bf16 v[60:63], v[124:127], v[150:153], v[60:63]
	ds_read_b128 v[170:173], v129 offset:16384
	ds_read_b128 v[174:177], v129 offset:18432
	ds_read_b128 v[178:181], v129 offset:20480
	ds_read_b128 v[182:185], v129 offset:22528
	s_waitcnt lgkmcnt(4)
	s_add_u32 s0, s8, 0x180
	s_addc_u32 s1, s9, 0
	s_add_i32 m0, s23, 0x0
	s_nop 0
	global_load_lds_dwordx4 v132, s[0:1]
	s_add_u32 s0, s8, 0x1180
	s_addc_u32 s1, s9, 0
	s_add_i32 m0, s23, 0x400
	s_nop 0
	global_load_lds_dwordx4 v132, s[0:1]
	s_add_u32 s0, s8, 0x2180
	s_addc_u32 s1, s9, 0
	s_add_i32 m0, s23, 0x800
	s_nop 0
	global_load_lds_dwordx4 v132, s[0:1]
	s_add_u32 s0, s8, 0x3180
	s_addc_u32 s1, s9, 0
	s_add_i32 m0, s23, 0xc00
	s_nop 0
	global_load_lds_dwordx4 v132, s[0:1]
	s_add_u32 s0, s8, 0x20180
	s_addc_u32 s1, s9, 0
	s_add_i32 m0, s23, 0x1000
	s_nop 0
	global_load_lds_dwordx4 v132, s[0:1]
	s_add_u32 s0, s8, 0x21180
	s_addc_u32 s1, s9, 0
	s_add_i32 m0, s23, 0x1400
	s_nop 0
	global_load_lds_dwordx4 v132, s[0:1]
	s_add_u32 s0, s8, 0x22180
	s_addc_u32 s1, s9, 0
	s_add_i32 m0, s23, 0x1800
	s_nop 0
	global_load_lds_dwordx4 v132, s[0:1]
	s_add_u32 s0, s8, 0x23180
	s_addc_u32 s1, s9, 0
	s_add_i32 m0, s23, 0x1c00
	s_nop 0
	global_load_lds_dwordx4 v132, s[0:1]
	v_mfma_f32_16x16x32_bf16 v[0:3], v[64:67], v[154:157], v[0:3]
	v_mfma_f32_16x16x32_bf16 v[16:19], v[64:67], v[158:161], v[16:19]
	v_mfma_f32_16x16x32_bf16 v[32:35], v[64:67], v[162:165], v[32:35]
	v_mfma_f32_16x16x32_bf16 v[48:51], v[64:67], v[166:169], v[48:51]
	v_mfma_f32_16x16x32_bf16 v[4:7], v[72:75], v[154:157], v[4:7]
	v_mfma_f32_16x16x32_bf16 v[20:23], v[72:75], v[158:161], v[20:23]
	v_mfma_f32_16x16x32_bf16 v[36:39], v[72:75], v[162:165], v[36:39]
	v_mfma_f32_16x16x32_bf16 v[52:55], v[72:75], v[166:169], v[52:55]
	v_mfma_f32_16x16x32_bf16 v[8:11], v[80:83], v[154:157], v[8:11]
	v_mfma_f32_16x16x32_bf16 v[24:27], v[80:83], v[158:161], v[24:27]
	v_mfma_f32_16x16x32_bf16 v[40:43], v[80:83], v[162:165], v[40:43]
	v_mfma_f32_16x16x32_bf16 v[56:59], v[80:83], v[166:169], v[56:59]
	v_mfma_f32_16x16x32_bf16 v[12:15], v[88:91], v[154:157], v[12:15]
	v_mfma_f32_16x16x32_bf16 v[28:31], v[88:91], v[158:161], v[28:31]
	v_mfma_f32_16x16x32_bf16 v[44:47], v[88:91], v[162:165], v[44:47]
	v_mfma_f32_16x16x32_bf16 v[60:63], v[88:91], v[166:169], v[60:63]
	ds_read_b128 v[138:141], v128 offset:24576
	ds_read_b128 v[142:145], v128 offset:26624
	ds_read_b128 v[146:149], v128 offset:28672
	ds_read_b128 v[150:153], v128 offset:30720
	s_waitcnt vmcnt(0)
	ds_read_b128 v[96:99], v133 offset:0
	ds_read_b128 v[104:107], v133 offset:2048
	ds_read_b128 v[112:115], v133 offset:4096
	ds_read_b128 v[120:123], v133 offset:6144
	ds_read_b128 v[100:103], v134 offset:0
	ds_read_b128 v[108:111], v134 offset:2048
	ds_read_b128 v[116:119], v134 offset:4096
	ds_read_b128 v[124:127], v134 offset:6144
	s_waitcnt lgkmcnt(12)
	v_mfma_f32_16x16x32_bf16 v[0:3], v[68:71], v[170:173], v[0:3]
	v_mfma_f32_16x16x32_bf16 v[16:19], v[68:71], v[174:177], v[16:19]
	v_mfma_f32_16x16x32_bf16 v[32:35], v[68:71], v[178:181], v[32:35]
	v_mfma_f32_16x16x32_bf16 v[48:51], v[68:71], v[182:185], v[48:51]
	v_mfma_f32_16x16x32_bf16 v[4:7], v[76:79], v[170:173], v[4:7]
	v_mfma_f32_16x16x32_bf16 v[20:23], v[76:79], v[174:177], v[20:23]
	v_mfma_f32_16x16x32_bf16 v[36:39], v[76:79], v[178:181], v[36:39]
	v_mfma_f32_16x16x32_bf16 v[52:55], v[76:79], v[182:185], v[52:55]
	v_mfma_f32_16x16x32_bf16 v[8:11], v[84:87], v[170:173], v[8:11]
	v_mfma_f32_16x16x32_bf16 v[24:27], v[84:87], v[174:177], v[24:27]
	v_mfma_f32_16x16x32_bf16 v[40:43], v[84:87], v[178:181], v[40:43]
	v_mfma_f32_16x16x32_bf16 v[56:59], v[84:87], v[182:185], v[56:59]
	v_mfma_f32_16x16x32_bf16 v[12:15], v[92:95], v[170:173], v[12:15]
	v_mfma_f32_16x16x32_bf16 v[28:31], v[92:95], v[174:177], v[28:31]
	v_mfma_f32_16x16x32_bf16 v[44:47], v[92:95], v[178:181], v[44:47]
	v_mfma_f32_16x16x32_bf16 v[60:63], v[92:95], v[182:185], v[60:63]
	ds_read_b128 v[154:157], v129 offset:24576
	ds_read_b128 v[158:161], v129 offset:26624
	ds_read_b128 v[162:165], v129 offset:28672
	ds_read_b128 v[166:169], v129 offset:30720
	s_waitcnt lgkmcnt(4)
	s_lshl_b32 s0, s24, 11
	s_add_u32 s0, s0, 0x220320
	s_lshl_b32 s1, s22, 7
	s_add_u32 s0, s0, s1
	s_add_u32 s20, s4, s0
	s_addc_u32 s21, s5, 0
	s_lshl_b32 s0, s24, 12
	s_add_u32 s0, s0, 0x221f20
	s_add_u32 s0, s0, s1
	s_add_u32 s18, s4, s0
	s_addc_u32 s19, s5, 0
	v_lshlrev_b32_e32 v214, 4, v207
	global_load_dwordx4 v[64:67], v214, s[20:21] offset:0
	global_load_dwordx4 v[72:75], v214, s[20:21] offset:1024
	global_load_dwordx4 v[80:83], v214, s[18:19] offset:0
	global_load_dwordx4 v[68:71], v214, s[20:21] offset:64
	global_load_dwordx4 v[76:79], v214, s[20:21] offset:1088
	global_load_dwordx4 v[84:87], v214, s[18:19] offset:64
	v_mfma_f32_16x16x32_bf16 v[0:3], v[96:99], v[138:141], v[0:3]
	v_mfma_f32_16x16x32_bf16 v[16:19], v[96:99], v[142:145], v[16:19]
	v_mfma_f32_16x16x32_bf16 v[32:35], v[96:99], v[146:149], v[32:35]
	v_mfma_f32_16x16x32_bf16 v[48:51], v[96:99], v[150:153], v[48:51]
	v_mfma_f32_16x16x32_bf16 v[4:7], v[104:107], v[138:141], v[4:7]
	v_mfma_f32_16x16x32_bf16 v[20:23], v[104:107], v[142:145], v[20:23]
	v_mfma_f32_16x16x32_bf16 v[36:39], v[104:107], v[146:149], v[36:39]
	v_mfma_f32_16x16x32_bf16 v[52:55], v[104:107], v[150:153], v[52:55]
	v_mfma_f32_16x16x32_bf16 v[8:11], v[112:115], v[138:141], v[8:11]
	v_mfma_f32_16x16x32_bf16 v[24:27], v[112:115], v[142:145], v[24:27]
	v_mfma_f32_16x16x32_bf16 v[40:43], v[112:115], v[146:149], v[40:43]
	v_mfma_f32_16x16x32_bf16 v[56:59], v[112:115], v[150:153], v[56:59]
	v_mfma_f32_16x16x32_bf16 v[12:15], v[120:123], v[138:141], v[12:15]
	v_mfma_f32_16x16x32_bf16 v[28:31], v[120:123], v[142:145], v[28:31]
	v_mfma_f32_16x16x32_bf16 v[44:47], v[120:123], v[146:149], v[44:47]
	v_mfma_f32_16x16x32_bf16 v[60:63], v[120:123], v[150:153], v[60:63]
	s_waitcnt lgkmcnt(0)
	v_mfma_f32_16x16x32_bf16 v[0:3], v[100:103], v[154:157], v[0:3]
	v_mfma_f32_16x16x32_bf16 v[16:19], v[100:103], v[158:161], v[16:19]
	v_mfma_f32_16x16x32_bf16 v[32:35], v[100:103], v[162:165], v[32:35]
	v_mfma_f32_16x16x32_bf16 v[48:51], v[100:103], v[166:169], v[48:51]
	v_mfma_f32_16x16x32_bf16 v[4:7], v[108:111], v[154:157], v[4:7]
	v_mfma_f32_16x16x32_bf16 v[20:23], v[108:111], v[158:161], v[20:23]
	v_mfma_f32_16x16x32_bf16 v[36:39], v[108:111], v[162:165], v[36:39]
	v_mfma_f32_16x16x32_bf16 v[52:55], v[108:111], v[166:169], v[52:55]
	v_mfma_f32_16x16x32_bf16 v[8:11], v[116:119], v[154:157], v[8:11]
	v_mfma_f32_16x16x32_bf16 v[24:27], v[116:119], v[158:161], v[24:27]
	v_mfma_f32_16x16x32_bf16 v[40:43], v[116:119], v[162:165], v[40:43]
	v_mfma_f32_16x16x32_bf16 v[56:59], v[116:119], v[166:169], v[56:59]
	v_mfma_f32_16x16x32_bf16 v[12:15], v[124:127], v[154:157], v[12:15]
	v_mfma_f32_16x16x32_bf16 v[28:31], v[124:127], v[158:161], v[28:31]
	v_mfma_f32_16x16x32_bf16 v[44:47], v[124:127], v[162:165], v[44:47]
	v_mfma_f32_16x16x32_bf16 v[60:63], v[124:127], v[166:169], v[60:63]
	s_lshl_b32 s1, s24, 12
	s_add_u32 s1, s1, 0x221320
	s_add_u32 s20, s4, s1
	s_addc_u32 s21, s5, 0
	global_load_dwordx4 v[116:119], v209, s[20:21] offset:0
	global_load_dwordx4 v[120:123], v209, s[20:21] offset:1024
	global_load_dwordx4 v[124:127], v209, s[20:21] offset:2048
	global_load_dwordx2 v[142:143], v208, s[10:11] offset:0
	global_load_dwordx2 v[144:145], v208, s[10:11] offset:512
	global_load_dwordx2 v[146:147], v208, s[10:11] offset:1024
	s_add_u32 s10, s10, 0x600
	s_addc_u32 s11, s11, 0
	global_load_dwordx2 v[148:149], v208, s[10:11] offset:0
	global_load_dwordx2 v[150:151], v208, s[10:11] offset:512
	global_load_dwordx2 v[152:153], v208, s[10:11] offset:1024
	s_add_u32 s10, s10, 0x600
	s_addc_u32 s11, s11, 0
	global_load_dwordx2 v[154:155], v208, s[10:11] offset:0
	global_load_dwordx2 v[156:157], v208, s[10:11] offset:512
	global_load_dwordx2 v[158:159], v208, s[10:11] offset:1024
	s_add_u32 s10, s10, 0x600
	s_addc_u32 s11, s11, 0
	global_load_dwordx2 v[160:161], v208, s[10:11] offset:0
	global_load_dwordx2 v[162:163], v208, s[10:11] offset:512
	global_load_dwordx2 v[164:165], v208, s[10:11] offset:1024
	s_add_u32 s10, s10, 0x600
	s_addc_u32 s11, s11, 0
	global_load_dwordx2 v[166:167], v208, s[10:11] offset:0
	global_load_dwordx2 v[168:169], v208, s[10:11] offset:512
	global_load_dwordx2 v[170:171], v208, s[10:11] offset:1024
	s_add_u32 s10, s10, 0x600
	s_addc_u32 s11, s11, 0
	global_load_dwordx2 v[172:173], v208, s[10:11] offset:0
	global_load_dwordx2 v[174:175], v208, s[10:11] offset:512
	global_load_dwordx2 v[176:177], v208, s[10:11] offset:1024
	s_add_u32 s10, s10, 0x600
	s_addc_u32 s11, s11, 0
	global_load_dwordx2 v[178:179], v208, s[10:11] offset:0
	global_load_dwordx2 v[180:181], v208, s[10:11] offset:512
	global_load_dwordx2 v[182:183], v208, s[10:11] offset:1024
	s_add_u32 s10, s10, 0x600
	s_addc_u32 s11, s11, 0
	global_load_dwordx2 v[184:185], v208, s[10:11] offset:0
	global_load_dwordx2 v[112:113], v208, s[10:11] offset:512
	global_load_dwordx2 v[114:115], v208, s[10:11] offset:1024
	s_waitcnt vmcnt(27)
	s_nop 6
	v_mov_b32_e32 v94, 0
	v_mov_b32_e32 v95, 0
	v_mov_b32_e32 v215, 0
	v_mov_b32_e32 v216, 0
	v_add_f32_e32 v0, v0, v64
	v_add_f32_e32 v8, v8, v72
	v_bfe_u32 v88, v0, 16, 1
	v_bfe_u32 v89, v8, 16, 1
	v_add3_u32 v0, v0, v88, s77
	v_add3_u32 v8, v8, v89, s77
	v_and_b32_e32 v0, s35, v0
	v_and_b32_e32 v8, s35, v8
	v_mul_f32_e32 v8, 0xbfb8aa3b, v8
	v_exp_f32_e32 v8, v8
	s_nop 0
	v_add_f32_e32 v8, 1.0, v8
	v_div_scale_f32 v88, s[20:21], v8, v8, 1.0
	v_rcp_f32_e32 v89, v88
	s_nop 0
	v_fma_f32 v90, -v88, v89, 1.0
	v_fmac_f32_e32 v89, v90, v89
	v_div_scale_f32 v90, vcc, 1.0, v8, 1.0
	v_mul_f32_e32 v91, v90, v89
	v_fma_f32 v92, -v88, v91, v90
	v_fmac_f32_e32 v91, v92, v89
	v_fma_f32 v88, -v88, v91, v90
	v_div_fmas_f32 v88, v88, v89, v91
	v_div_fixup_f32 v8, v88, v8, 1.0
	v_mul_f32_e32 v0, v8, v0
	v_fmac_f32_e32 v94, v0, v0
	v_add_f32_e32 v1, v1, v65
	v_add_f32_e32 v9, v9, v73
	v_bfe_u32 v88, v1, 16, 1
	v_bfe_u32 v89, v9, 16, 1
	v_add3_u32 v1, v1, v88, s77
	v_add3_u32 v9, v9, v89, s77
	v_and_b32_e32 v1, s35, v1
	v_and_b32_e32 v9, s35, v9
	v_mul_f32_e32 v9, 0xbfb8aa3b, v9
	v_exp_f32_e32 v9, v9
	s_nop 0
	v_add_f32_e32 v9, 1.0, v9
	v_div_scale_f32 v88, s[20:21], v9, v9, 1.0
	v_rcp_f32_e32 v89, v88
	s_nop 0
	v_fma_f32 v90, -v88, v89, 1.0
	v_fmac_f32_e32 v89, v90, v89
	v_div_scale_f32 v90, vcc, 1.0, v9, 1.0
	v_mul_f32_e32 v91, v90, v89
	v_fma_f32 v92, -v88, v91, v90
	v_fmac_f32_e32 v91, v92, v89
	v_fma_f32 v88, -v88, v91, v90
	v_div_fmas_f32 v88, v88, v89, v91
	v_div_fixup_f32 v9, v88, v9, 1.0
	v_mul_f32_e32 v1, v9, v1
	v_fmac_f32_e32 v94, v1, v1
	v_add_f32_e32 v2, v2, v66
	v_add_f32_e32 v10, v10, v74
	v_bfe_u32 v88, v2, 16, 1
	v_bfe_u32 v89, v10, 16, 1
	v_add3_u32 v2, v2, v88, s77
	v_add3_u32 v10, v10, v89, s77
	v_and_b32_e32 v2, s35, v2
	v_and_b32_e32 v10, s35, v10
	v_mul_f32_e32 v10, 0xbfb8aa3b, v10
	v_exp_f32_e32 v10, v10
	s_nop 0
	v_add_f32_e32 v10, 1.0, v10
	v_div_scale_f32 v88, s[20:21], v10, v10, 1.0
	v_rcp_f32_e32 v89, v88
	s_nop 0
	v_fma_f32 v90, -v88, v89, 1.0
	v_fmac_f32_e32 v89, v90, v89
	v_div_scale_f32 v90, vcc, 1.0, v10, 1.0
	v_mul_f32_e32 v91, v90, v89
	v_fma_f32 v92, -v88, v91, v90
	v_fmac_f32_e32 v91, v92, v89
	v_fma_f32 v88, -v88, v91, v90
	v_div_fmas_f32 v88, v88, v89, v91
	v_div_fixup_f32 v10, v88, v10, 1.0
	v_mul_f32_e32 v2, v10, v2
	v_fmac_f32_e32 v94, v2, v2
	v_add_f32_e32 v3, v3, v67
	v_add_f32_e32 v11, v11, v75
	v_bfe_u32 v88, v3, 16, 1
	v_bfe_u32 v89, v11, 16, 1
	v_add3_u32 v3, v3, v88, s77
	v_add3_u32 v11, v11, v89, s77
	v_and_b32_e32 v3, s35, v3
	v_and_b32_e32 v11, s35, v11
	v_mul_f32_e32 v11, 0xbfb8aa3b, v11
	v_exp_f32_e32 v11, v11
	s_nop 0
	v_add_f32_e32 v11, 1.0, v11
	v_div_scale_f32 v88, s[20:21], v11, v11, 1.0
	v_rcp_f32_e32 v89, v88
	s_nop 0
	v_fma_f32 v90, -v88, v89, 1.0
	v_fmac_f32_e32 v89, v90, v89
	v_div_scale_f32 v90, vcc, 1.0, v11, 1.0
	v_mul_f32_e32 v91, v90, v89
	v_fma_f32 v92, -v88, v91, v90
	v_fmac_f32_e32 v91, v92, v89
	v_fma_f32 v88, -v88, v91, v90
	v_div_fmas_f32 v88, v88, v89, v91
	v_div_fixup_f32 v11, v88, v11, 1.0
	v_mul_f32_e32 v3, v11, v3
	v_fmac_f32_e32 v94, v3, v3
	v_add_f32_e32 v4, v4, v68
	v_add_f32_e32 v12, v12, v76
	v_bfe_u32 v88, v4, 16, 1
	v_bfe_u32 v89, v12, 16, 1
	v_add3_u32 v4, v4, v88, s77
	v_add3_u32 v12, v12, v89, s77
	v_and_b32_e32 v4, s35, v4
	v_and_b32_e32 v12, s35, v12
	v_mul_f32_e32 v12, 0xbfb8aa3b, v12
	v_exp_f32_e32 v12, v12
	s_nop 0
	v_add_f32_e32 v12, 1.0, v12
	v_div_scale_f32 v88, s[20:21], v12, v12, 1.0
	v_rcp_f32_e32 v89, v88
	s_nop 0
	v_fma_f32 v90, -v88, v89, 1.0
	v_fmac_f32_e32 v89, v90, v89
	v_div_scale_f32 v90, vcc, 1.0, v12, 1.0
	v_mul_f32_e32 v91, v90, v89
	v_fma_f32 v92, -v88, v91, v90
	v_fmac_f32_e32 v91, v92, v89
	v_fma_f32 v88, -v88, v91, v90
	v_div_fmas_f32 v88, v88, v89, v91
	v_div_fixup_f32 v12, v88, v12, 1.0
	v_mul_f32_e32 v4, v12, v4
	v_fmac_f32_e32 v94, v4, v4
	v_add_f32_e32 v5, v5, v69
	v_add_f32_e32 v13, v13, v77
	v_bfe_u32 v88, v5, 16, 1
	v_bfe_u32 v89, v13, 16, 1
	v_add3_u32 v5, v5, v88, s77
	v_add3_u32 v13, v13, v89, s77
	v_and_b32_e32 v5, s35, v5
	v_and_b32_e32 v13, s35, v13
	v_mul_f32_e32 v13, 0xbfb8aa3b, v13
	v_exp_f32_e32 v13, v13
	s_nop 0
	v_add_f32_e32 v13, 1.0, v13
	v_div_scale_f32 v88, s[20:21], v13, v13, 1.0
	v_rcp_f32_e32 v89, v88
	s_nop 0
	v_fma_f32 v90, -v88, v89, 1.0
	v_fmac_f32_e32 v89, v90, v89
	v_div_scale_f32 v90, vcc, 1.0, v13, 1.0
	v_mul_f32_e32 v91, v90, v89
	v_fma_f32 v92, -v88, v91, v90
	v_fmac_f32_e32 v91, v92, v89
	v_fma_f32 v88, -v88, v91, v90
	v_div_fmas_f32 v88, v88, v89, v91
	v_div_fixup_f32 v13, v88, v13, 1.0
	v_mul_f32_e32 v5, v13, v5
	v_fmac_f32_e32 v94, v5, v5
	v_add_f32_e32 v6, v6, v70
	v_add_f32_e32 v14, v14, v78
	v_bfe_u32 v88, v6, 16, 1
	v_bfe_u32 v89, v14, 16, 1
	v_add3_u32 v6, v6, v88, s77
	v_add3_u32 v14, v14, v89, s77
	v_and_b32_e32 v6, s35, v6
	v_and_b32_e32 v14, s35, v14
	v_mul_f32_e32 v14, 0xbfb8aa3b, v14
	v_exp_f32_e32 v14, v14
	s_nop 0
	v_add_f32_e32 v14, 1.0, v14
	v_div_scale_f32 v88, s[20:21], v14, v14, 1.0
	v_rcp_f32_e32 v89, v88
	s_nop 0
	v_fma_f32 v90, -v88, v89, 1.0
	v_fmac_f32_e32 v89, v90, v89
	v_div_scale_f32 v90, vcc, 1.0, v14, 1.0
	v_mul_f32_e32 v91, v90, v89
	v_fma_f32 v92, -v88, v91, v90
	v_fmac_f32_e32 v91, v92, v89
	v_fma_f32 v88, -v88, v91, v90
	v_div_fmas_f32 v88, v88, v89, v91
	v_div_fixup_f32 v14, v88, v14, 1.0
	v_mul_f32_e32 v6, v14, v6
	v_fmac_f32_e32 v94, v6, v6
	v_add_f32_e32 v7, v7, v71
	v_add_f32_e32 v15, v15, v79
	v_bfe_u32 v88, v7, 16, 1
	v_bfe_u32 v89, v15, 16, 1
	v_add3_u32 v7, v7, v88, s77
	v_add3_u32 v15, v15, v89, s77
	v_and_b32_e32 v7, s35, v7
	v_and_b32_e32 v15, s35, v15
	v_mul_f32_e32 v15, 0xbfb8aa3b, v15
	v_exp_f32_e32 v15, v15
	s_nop 0
	v_add_f32_e32 v15, 1.0, v15
	v_div_scale_f32 v88, s[20:21], v15, v15, 1.0
	v_rcp_f32_e32 v89, v88
	s_nop 0
	v_fma_f32 v90, -v88, v89, 1.0
	v_fmac_f32_e32 v89, v90, v89
	v_div_scale_f32 v90, vcc, 1.0, v15, 1.0
	v_mul_f32_e32 v91, v90, v89
	v_fma_f32 v92, -v88, v91, v90
	v_fmac_f32_e32 v91, v92, v89
	v_fma_f32 v88, -v88, v91, v90
	v_div_fmas_f32 v88, v88, v89, v91
	v_div_fixup_f32 v15, v88, v15, 1.0
	v_mul_f32_e32 v7, v15, v7
	v_fmac_f32_e32 v94, v7, v7
	v_add_f32_e32 v16, v16, v64
	v_add_f32_e32 v24, v24, v72
	v_bfe_u32 v88, v16, 16, 1
	v_bfe_u32 v89, v24, 16, 1
	v_add3_u32 v16, v16, v88, s77
	v_add3_u32 v24, v24, v89, s77
	v_and_b32_e32 v16, s35, v16
	v_and_b32_e32 v24, s35, v24
	v_mul_f32_e32 v24, 0xbfb8aa3b, v24
	v_exp_f32_e32 v24, v24
	s_nop 0
	v_add_f32_e32 v24, 1.0, v24
	v_div_scale_f32 v88, s[20:21], v24, v24, 1.0
	v_rcp_f32_e32 v89, v88
	s_nop 0
	v_fma_f32 v90, -v88, v89, 1.0
	v_fmac_f32_e32 v89, v90, v89
	v_div_scale_f32 v90, vcc, 1.0, v24, 1.0
	v_mul_f32_e32 v91, v90, v89
	v_fma_f32 v92, -v88, v91, v90
	v_fmac_f32_e32 v91, v92, v89
	v_fma_f32 v88, -v88, v91, v90
	v_div_fmas_f32 v88, v88, v89, v91
	v_div_fixup_f32 v24, v88, v24, 1.0
	v_mul_f32_e32 v16, v24, v16
	v_fmac_f32_e32 v95, v16, v16
	v_add_f32_e32 v17, v17, v65
	v_add_f32_e32 v25, v25, v73
	v_bfe_u32 v88, v17, 16, 1
	v_bfe_u32 v89, v25, 16, 1
	v_add3_u32 v17, v17, v88, s77
	v_add3_u32 v25, v25, v89, s77
	v_and_b32_e32 v17, s35, v17
	v_and_b32_e32 v25, s35, v25
	v_mul_f32_e32 v25, 0xbfb8aa3b, v25
	v_exp_f32_e32 v25, v25
	s_nop 0
	v_add_f32_e32 v25, 1.0, v25
	v_div_scale_f32 v88, s[20:21], v25, v25, 1.0
	v_rcp_f32_e32 v89, v88
	s_nop 0
	v_fma_f32 v90, -v88, v89, 1.0
	v_fmac_f32_e32 v89, v90, v89
	v_div_scale_f32 v90, vcc, 1.0, v25, 1.0
	v_mul_f32_e32 v91, v90, v89
	v_fma_f32 v92, -v88, v91, v90
	v_fmac_f32_e32 v91, v92, v89
	v_fma_f32 v88, -v88, v91, v90
	v_div_fmas_f32 v88, v88, v89, v91
	v_div_fixup_f32 v25, v88, v25, 1.0
	v_mul_f32_e32 v17, v25, v17
	v_fmac_f32_e32 v95, v17, v17
	v_add_f32_e32 v18, v18, v66
	v_add_f32_e32 v26, v26, v74
	v_bfe_u32 v88, v18, 16, 1
	v_bfe_u32 v89, v26, 16, 1
	v_add3_u32 v18, v18, v88, s77
	v_add3_u32 v26, v26, v89, s77
	v_and_b32_e32 v18, s35, v18
	v_and_b32_e32 v26, s35, v26
	v_mul_f32_e32 v26, 0xbfb8aa3b, v26
	v_exp_f32_e32 v26, v26
	s_nop 0
	v_add_f32_e32 v26, 1.0, v26
	v_div_scale_f32 v88, s[20:21], v26, v26, 1.0
	v_rcp_f32_e32 v89, v88
	s_nop 0
	v_fma_f32 v90, -v88, v89, 1.0
	v_fmac_f32_e32 v89, v90, v89
	v_div_scale_f32 v90, vcc, 1.0, v26, 1.0
	v_mul_f32_e32 v91, v90, v89
	v_fma_f32 v92, -v88, v91, v90
	v_fmac_f32_e32 v91, v92, v89
	v_fma_f32 v88, -v88, v91, v90
	v_div_fmas_f32 v88, v88, v89, v91
	v_div_fixup_f32 v26, v88, v26, 1.0
	v_mul_f32_e32 v18, v26, v18
	v_fmac_f32_e32 v95, v18, v18
	v_add_f32_e32 v19, v19, v67
	v_add_f32_e32 v27, v27, v75
	v_bfe_u32 v88, v19, 16, 1
	v_bfe_u32 v89, v27, 16, 1
	v_add3_u32 v19, v19, v88, s77
	v_add3_u32 v27, v27, v89, s77
	v_and_b32_e32 v19, s35, v19
	v_and_b32_e32 v27, s35, v27
	v_mul_f32_e32 v27, 0xbfb8aa3b, v27
	v_exp_f32_e32 v27, v27
	s_nop 0
	v_add_f32_e32 v27, 1.0, v27
	v_div_scale_f32 v88, s[20:21], v27, v27, 1.0
	v_rcp_f32_e32 v89, v88
	s_nop 0
	v_fma_f32 v90, -v88, v89, 1.0
	v_fmac_f32_e32 v89, v90, v89
	v_div_scale_f32 v90, vcc, 1.0, v27, 1.0
	v_mul_f32_e32 v91, v90, v89
	v_fma_f32 v92, -v88, v91, v90
	v_fmac_f32_e32 v91, v92, v89
	v_fma_f32 v88, -v88, v91, v90
	v_div_fmas_f32 v88, v88, v89, v91
	v_div_fixup_f32 v27, v88, v27, 1.0
	v_mul_f32_e32 v19, v27, v19
	v_fmac_f32_e32 v95, v19, v19
	v_add_f32_e32 v20, v20, v68
	v_add_f32_e32 v28, v28, v76
	v_bfe_u32 v88, v20, 16, 1
	v_bfe_u32 v89, v28, 16, 1
	v_add3_u32 v20, v20, v88, s77
	v_add3_u32 v28, v28, v89, s77
	v_and_b32_e32 v20, s35, v20
	v_and_b32_e32 v28, s35, v28
	v_mul_f32_e32 v28, 0xbfb8aa3b, v28
	v_exp_f32_e32 v28, v28
	s_nop 0
	v_add_f32_e32 v28, 1.0, v28
	v_div_scale_f32 v88, s[20:21], v28, v28, 1.0
	v_rcp_f32_e32 v89, v88
	s_nop 0
	v_fma_f32 v90, -v88, v89, 1.0
	v_fmac_f32_e32 v89, v90, v89
	v_div_scale_f32 v90, vcc, 1.0, v28, 1.0
	v_mul_f32_e32 v91, v90, v89
	v_fma_f32 v92, -v88, v91, v90
	v_fmac_f32_e32 v91, v92, v89
	v_fma_f32 v88, -v88, v91, v90
	v_div_fmas_f32 v88, v88, v89, v91
	v_div_fixup_f32 v28, v88, v28, 1.0
	v_mul_f32_e32 v20, v28, v20
	v_fmac_f32_e32 v95, v20, v20
	v_add_f32_e32 v21, v21, v69
	v_add_f32_e32 v29, v29, v77
	v_bfe_u32 v88, v21, 16, 1
	v_bfe_u32 v89, v29, 16, 1
	v_add3_u32 v21, v21, v88, s77
	v_add3_u32 v29, v29, v89, s77
	v_and_b32_e32 v21, s35, v21
	v_and_b32_e32 v29, s35, v29
	v_mul_f32_e32 v29, 0xbfb8aa3b, v29
	v_exp_f32_e32 v29, v29
	s_nop 0
	v_add_f32_e32 v29, 1.0, v29
	v_div_scale_f32 v88, s[20:21], v29, v29, 1.0
	v_rcp_f32_e32 v89, v88
	s_nop 0
	v_fma_f32 v90, -v88, v89, 1.0
	v_fmac_f32_e32 v89, v90, v89
	v_div_scale_f32 v90, vcc, 1.0, v29, 1.0
	v_mul_f32_e32 v91, v90, v89
	v_fma_f32 v92, -v88, v91, v90
	v_fmac_f32_e32 v91, v92, v89
	v_fma_f32 v88, -v88, v91, v90
	v_div_fmas_f32 v88, v88, v89, v91
	v_div_fixup_f32 v29, v88, v29, 1.0
	v_mul_f32_e32 v21, v29, v21
	v_fmac_f32_e32 v95, v21, v21
	v_add_f32_e32 v22, v22, v70
	v_add_f32_e32 v30, v30, v78
	v_bfe_u32 v88, v22, 16, 1
	v_bfe_u32 v89, v30, 16, 1
	v_add3_u32 v22, v22, v88, s77
	v_add3_u32 v30, v30, v89, s77
	v_and_b32_e32 v22, s35, v22
	v_and_b32_e32 v30, s35, v30
	v_mul_f32_e32 v30, 0xbfb8aa3b, v30
	v_exp_f32_e32 v30, v30
	s_nop 0
	v_add_f32_e32 v30, 1.0, v30
	v_div_scale_f32 v88, s[20:21], v30, v30, 1.0
	v_rcp_f32_e32 v89, v88
	s_nop 0
	v_fma_f32 v90, -v88, v89, 1.0
	v_fmac_f32_e32 v89, v90, v89
	v_div_scale_f32 v90, vcc, 1.0, v30, 1.0
	v_mul_f32_e32 v91, v90, v89
	v_fma_f32 v92, -v88, v91, v90
	v_fmac_f32_e32 v91, v92, v89
	v_fma_f32 v88, -v88, v91, v90
	v_div_fmas_f32 v88, v88, v89, v91
	v_div_fixup_f32 v30, v88, v30, 1.0
	v_mul_f32_e32 v22, v30, v22
	v_fmac_f32_e32 v95, v22, v22
	v_add_f32_e32 v23, v23, v71
	v_add_f32_e32 v31, v31, v79
	v_bfe_u32 v88, v23, 16, 1
	v_bfe_u32 v89, v31, 16, 1
	v_add3_u32 v23, v23, v88, s77
	v_add3_u32 v31, v31, v89, s77
	v_and_b32_e32 v23, s35, v23
	v_and_b32_e32 v31, s35, v31
	v_mul_f32_e32 v31, 0xbfb8aa3b, v31
	v_exp_f32_e32 v31, v31
	s_nop 0
	v_add_f32_e32 v31, 1.0, v31
	v_div_scale_f32 v88, s[20:21], v31, v31, 1.0
	v_rcp_f32_e32 v89, v88
	s_nop 0
	v_fma_f32 v90, -v88, v89, 1.0
	v_fmac_f32_e32 v89, v90, v89
	v_div_scale_f32 v90, vcc, 1.0, v31, 1.0
	v_mul_f32_e32 v91, v90, v89
	v_fma_f32 v92, -v88, v91, v90
	v_fmac_f32_e32 v91, v92, v89
	v_fma_f32 v88, -v88, v91, v90
	v_div_fmas_f32 v88, v88, v89, v91
	v_div_fixup_f32 v31, v88, v31, 1.0
	v_mul_f32_e32 v23, v31, v23
	v_fmac_f32_e32 v95, v23, v23
	v_add_f32_e32 v32, v32, v64
	v_add_f32_e32 v40, v40, v72
	v_bfe_u32 v88, v32, 16, 1
	v_bfe_u32 v89, v40, 16, 1
	v_add3_u32 v32, v32, v88, s77
	v_add3_u32 v40, v40, v89, s77
	v_and_b32_e32 v32, s35, v32
	v_and_b32_e32 v40, s35, v40
	v_mul_f32_e32 v40, 0xbfb8aa3b, v40
	v_exp_f32_e32 v40, v40
	s_nop 0
	v_add_f32_e32 v40, 1.0, v40
	v_div_scale_f32 v88, s[20:21], v40, v40, 1.0
	v_rcp_f32_e32 v89, v88
	s_nop 0
	v_fma_f32 v90, -v88, v89, 1.0
	v_fmac_f32_e32 v89, v90, v89
	v_div_scale_f32 v90, vcc, 1.0, v40, 1.0
	v_mul_f32_e32 v91, v90, v89
	v_fma_f32 v92, -v88, v91, v90
	v_fmac_f32_e32 v91, v92, v89
	v_fma_f32 v88, -v88, v91, v90
	v_div_fmas_f32 v88, v88, v89, v91
	v_div_fixup_f32 v40, v88, v40, 1.0
	v_mul_f32_e32 v32, v40, v32
	v_fmac_f32_e32 v215, v32, v32
	v_add_f32_e32 v33, v33, v65
	v_add_f32_e32 v41, v41, v73
	v_bfe_u32 v88, v33, 16, 1
	v_bfe_u32 v89, v41, 16, 1
	v_add3_u32 v33, v33, v88, s77
	v_add3_u32 v41, v41, v89, s77
	v_and_b32_e32 v33, s35, v33
	v_and_b32_e32 v41, s35, v41
	v_mul_f32_e32 v41, 0xbfb8aa3b, v41
	v_exp_f32_e32 v41, v41
	s_nop 0
	v_add_f32_e32 v41, 1.0, v41
	v_div_scale_f32 v88, s[20:21], v41, v41, 1.0
	v_rcp_f32_e32 v89, v88
	s_nop 0
	v_fma_f32 v90, -v88, v89, 1.0
	v_fmac_f32_e32 v89, v90, v89
	v_div_scale_f32 v90, vcc, 1.0, v41, 1.0
	v_mul_f32_e32 v91, v90, v89
	v_fma_f32 v92, -v88, v91, v90
	v_fmac_f32_e32 v91, v92, v89
	v_fma_f32 v88, -v88, v91, v90
	v_div_fmas_f32 v88, v88, v89, v91
	v_div_fixup_f32 v41, v88, v41, 1.0
	v_mul_f32_e32 v33, v41, v33
	v_fmac_f32_e32 v215, v33, v33
	v_add_f32_e32 v34, v34, v66
	v_add_f32_e32 v42, v42, v74
	v_bfe_u32 v88, v34, 16, 1
	v_bfe_u32 v89, v42, 16, 1
	v_add3_u32 v34, v34, v88, s77
	v_add3_u32 v42, v42, v89, s77
	v_and_b32_e32 v34, s35, v34
	v_and_b32_e32 v42, s35, v42
	v_mul_f32_e32 v42, 0xbfb8aa3b, v42
	v_exp_f32_e32 v42, v42
	s_nop 0
	v_add_f32_e32 v42, 1.0, v42
	v_div_scale_f32 v88, s[20:21], v42, v42, 1.0
	v_rcp_f32_e32 v89, v88
	s_nop 0
	v_fma_f32 v90, -v88, v89, 1.0
	v_fmac_f32_e32 v89, v90, v89
	v_div_scale_f32 v90, vcc, 1.0, v42, 1.0
	v_mul_f32_e32 v91, v90, v89
	v_fma_f32 v92, -v88, v91, v90
	v_fmac_f32_e32 v91, v92, v89
	v_fma_f32 v88, -v88, v91, v90
	v_div_fmas_f32 v88, v88, v89, v91
	v_div_fixup_f32 v42, v88, v42, 1.0
	v_mul_f32_e32 v34, v42, v34
	v_fmac_f32_e32 v215, v34, v34
	v_add_f32_e32 v35, v35, v67
	v_add_f32_e32 v43, v43, v75
	v_bfe_u32 v88, v35, 16, 1
	v_bfe_u32 v89, v43, 16, 1
	v_add3_u32 v35, v35, v88, s77
	v_add3_u32 v43, v43, v89, s77
	v_and_b32_e32 v35, s35, v35
	v_and_b32_e32 v43, s35, v43
	v_mul_f32_e32 v43, 0xbfb8aa3b, v43
	v_exp_f32_e32 v43, v43
	s_nop 0
	v_add_f32_e32 v43, 1.0, v43
	v_div_scale_f32 v88, s[20:21], v43, v43, 1.0
	v_rcp_f32_e32 v89, v88
	s_nop 0
	v_fma_f32 v90, -v88, v89, 1.0
	v_fmac_f32_e32 v89, v90, v89
	v_div_scale_f32 v90, vcc, 1.0, v43, 1.0
	v_mul_f32_e32 v91, v90, v89
	v_fma_f32 v92, -v88, v91, v90
	v_fmac_f32_e32 v91, v92, v89
	v_fma_f32 v88, -v88, v91, v90
	v_div_fmas_f32 v88, v88, v89, v91
	v_div_fixup_f32 v43, v88, v43, 1.0
	v_mul_f32_e32 v35, v43, v35
	v_fmac_f32_e32 v215, v35, v35
	v_add_f32_e32 v36, v36, v68
	v_add_f32_e32 v44, v44, v76
	v_bfe_u32 v88, v36, 16, 1
	v_bfe_u32 v89, v44, 16, 1
	v_add3_u32 v36, v36, v88, s77
	v_add3_u32 v44, v44, v89, s77
	v_and_b32_e32 v36, s35, v36
	v_and_b32_e32 v44, s35, v44
	v_mul_f32_e32 v44, 0xbfb8aa3b, v44
	v_exp_f32_e32 v44, v44
	s_nop 0
	v_add_f32_e32 v44, 1.0, v44
	v_div_scale_f32 v88, s[20:21], v44, v44, 1.0
	v_rcp_f32_e32 v89, v88
	s_nop 0
	v_fma_f32 v90, -v88, v89, 1.0
	v_fmac_f32_e32 v89, v90, v89
	v_div_scale_f32 v90, vcc, 1.0, v44, 1.0
	v_mul_f32_e32 v91, v90, v89
	v_fma_f32 v92, -v88, v91, v90
	v_fmac_f32_e32 v91, v92, v89
	v_fma_f32 v88, -v88, v91, v90
	v_div_fmas_f32 v88, v88, v89, v91
	v_div_fixup_f32 v44, v88, v44, 1.0
	v_mul_f32_e32 v36, v44, v36
	v_fmac_f32_e32 v215, v36, v36
	v_add_f32_e32 v37, v37, v69
	v_add_f32_e32 v45, v45, v77
	v_bfe_u32 v88, v37, 16, 1
	v_bfe_u32 v89, v45, 16, 1
	v_add3_u32 v37, v37, v88, s77
	v_add3_u32 v45, v45, v89, s77
	v_and_b32_e32 v37, s35, v37
	v_and_b32_e32 v45, s35, v45
	v_mul_f32_e32 v45, 0xbfb8aa3b, v45
	v_exp_f32_e32 v45, v45
	s_nop 0
	v_add_f32_e32 v45, 1.0, v45
	v_div_scale_f32 v88, s[20:21], v45, v45, 1.0
	v_rcp_f32_e32 v89, v88
	s_nop 0
	v_fma_f32 v90, -v88, v89, 1.0
	v_fmac_f32_e32 v89, v90, v89
	v_div_scale_f32 v90, vcc, 1.0, v45, 1.0
	v_mul_f32_e32 v91, v90, v89
	v_fma_f32 v92, -v88, v91, v90
	v_fmac_f32_e32 v91, v92, v89
	v_fma_f32 v88, -v88, v91, v90
	v_div_fmas_f32 v88, v88, v89, v91
	v_div_fixup_f32 v45, v88, v45, 1.0
	v_mul_f32_e32 v37, v45, v37
	v_fmac_f32_e32 v215, v37, v37
	v_add_f32_e32 v38, v38, v70
	v_add_f32_e32 v46, v46, v78
	v_bfe_u32 v88, v38, 16, 1
	v_bfe_u32 v89, v46, 16, 1
	v_add3_u32 v38, v38, v88, s77
	v_add3_u32 v46, v46, v89, s77
	v_and_b32_e32 v38, s35, v38
	v_and_b32_e32 v46, s35, v46
	v_mul_f32_e32 v46, 0xbfb8aa3b, v46
	v_exp_f32_e32 v46, v46
	s_nop 0
	v_add_f32_e32 v46, 1.0, v46
	v_div_scale_f32 v88, s[20:21], v46, v46, 1.0
	v_rcp_f32_e32 v89, v88
	s_nop 0
	v_fma_f32 v90, -v88, v89, 1.0
	v_fmac_f32_e32 v89, v90, v89
	v_div_scale_f32 v90, vcc, 1.0, v46, 1.0
	v_mul_f32_e32 v91, v90, v89
	v_fma_f32 v92, -v88, v91, v90
	v_fmac_f32_e32 v91, v92, v89
	v_fma_f32 v88, -v88, v91, v90
	v_div_fmas_f32 v88, v88, v89, v91
	v_div_fixup_f32 v46, v88, v46, 1.0
	v_mul_f32_e32 v38, v46, v38
	v_fmac_f32_e32 v215, v38, v38
	v_add_f32_e32 v39, v39, v71
	v_add_f32_e32 v47, v47, v79
	v_bfe_u32 v88, v39, 16, 1
	v_bfe_u32 v89, v47, 16, 1
	v_add3_u32 v39, v39, v88, s77
	v_add3_u32 v47, v47, v89, s77
	v_and_b32_e32 v39, s35, v39
	v_and_b32_e32 v47, s35, v47
	v_mul_f32_e32 v47, 0xbfb8aa3b, v47
	v_exp_f32_e32 v47, v47
	s_nop 0
	v_add_f32_e32 v47, 1.0, v47
	v_div_scale_f32 v88, s[20:21], v47, v47, 1.0
	v_rcp_f32_e32 v89, v88
	s_nop 0
	v_fma_f32 v90, -v88, v89, 1.0
	v_fmac_f32_e32 v89, v90, v89
	v_div_scale_f32 v90, vcc, 1.0, v47, 1.0
	v_mul_f32_e32 v91, v90, v89
	v_fma_f32 v92, -v88, v91, v90
	v_fmac_f32_e32 v91, v92, v89
	v_fma_f32 v88, -v88, v91, v90
	v_div_fmas_f32 v88, v88, v89, v91
	v_div_fixup_f32 v47, v88, v47, 1.0
	v_mul_f32_e32 v39, v47, v39
	v_fmac_f32_e32 v215, v39, v39
	v_add_f32_e32 v48, v48, v64
	v_add_f32_e32 v56, v56, v72
	v_bfe_u32 v88, v48, 16, 1
	v_bfe_u32 v89, v56, 16, 1
	v_add3_u32 v48, v48, v88, s77
	v_add3_u32 v56, v56, v89, s77
	v_and_b32_e32 v48, s35, v48
	v_and_b32_e32 v56, s35, v56
	v_mul_f32_e32 v56, 0xbfb8aa3b, v56
	v_exp_f32_e32 v56, v56
	s_nop 0
	v_add_f32_e32 v56, 1.0, v56
	v_div_scale_f32 v88, s[20:21], v56, v56, 1.0
	v_rcp_f32_e32 v89, v88
	s_nop 0
	v_fma_f32 v90, -v88, v89, 1.0
	v_fmac_f32_e32 v89, v90, v89
	v_div_scale_f32 v90, vcc, 1.0, v56, 1.0
	v_mul_f32_e32 v91, v90, v89
	v_fma_f32 v92, -v88, v91, v90
	v_fmac_f32_e32 v91, v92, v89
	v_fma_f32 v88, -v88, v91, v90
	v_div_fmas_f32 v88, v88, v89, v91
	v_div_fixup_f32 v56, v88, v56, 1.0
	v_mul_f32_e32 v48, v56, v48
	v_fmac_f32_e32 v216, v48, v48
	v_add_f32_e32 v49, v49, v65
	v_add_f32_e32 v57, v57, v73
	v_bfe_u32 v88, v49, 16, 1
	v_bfe_u32 v89, v57, 16, 1
	v_add3_u32 v49, v49, v88, s77
	v_add3_u32 v57, v57, v89, s77
	v_and_b32_e32 v49, s35, v49
	v_and_b32_e32 v57, s35, v57
	v_mul_f32_e32 v57, 0xbfb8aa3b, v57
	v_exp_f32_e32 v57, v57
	s_nop 0
	v_add_f32_e32 v57, 1.0, v57
	v_div_scale_f32 v88, s[20:21], v57, v57, 1.0
	v_rcp_f32_e32 v89, v88
	s_nop 0
	v_fma_f32 v90, -v88, v89, 1.0
	v_fmac_f32_e32 v89, v90, v89
	v_div_scale_f32 v90, vcc, 1.0, v57, 1.0
	v_mul_f32_e32 v91, v90, v89
	v_fma_f32 v92, -v88, v91, v90
	v_fmac_f32_e32 v91, v92, v89
	v_fma_f32 v88, -v88, v91, v90
	v_div_fmas_f32 v88, v88, v89, v91
	v_div_fixup_f32 v57, v88, v57, 1.0
	v_mul_f32_e32 v49, v57, v49
	v_fmac_f32_e32 v216, v49, v49
	v_add_f32_e32 v50, v50, v66
	v_add_f32_e32 v58, v58, v74
	v_bfe_u32 v88, v50, 16, 1
	v_bfe_u32 v89, v58, 16, 1
	v_add3_u32 v50, v50, v88, s77
	v_add3_u32 v58, v58, v89, s77
	v_and_b32_e32 v50, s35, v50
	v_and_b32_e32 v58, s35, v58
	v_mul_f32_e32 v58, 0xbfb8aa3b, v58
	v_exp_f32_e32 v58, v58
	s_nop 0
	v_add_f32_e32 v58, 1.0, v58
	v_div_scale_f32 v88, s[20:21], v58, v58, 1.0
	v_rcp_f32_e32 v89, v88
	s_nop 0
	v_fma_f32 v90, -v88, v89, 1.0
	v_fmac_f32_e32 v89, v90, v89
	v_div_scale_f32 v90, vcc, 1.0, v58, 1.0
	v_mul_f32_e32 v91, v90, v89
	v_fma_f32 v92, -v88, v91, v90
	v_fmac_f32_e32 v91, v92, v89
	v_fma_f32 v88, -v88, v91, v90
	v_div_fmas_f32 v88, v88, v89, v91
	v_div_fixup_f32 v58, v88, v58, 1.0
	v_mul_f32_e32 v50, v58, v50
	v_fmac_f32_e32 v216, v50, v50
	v_add_f32_e32 v51, v51, v67
	v_add_f32_e32 v59, v59, v75
	v_bfe_u32 v88, v51, 16, 1
	v_bfe_u32 v89, v59, 16, 1
	v_add3_u32 v51, v51, v88, s77
	v_add3_u32 v59, v59, v89, s77
	v_and_b32_e32 v51, s35, v51
	v_and_b32_e32 v59, s35, v59
	v_mul_f32_e32 v59, 0xbfb8aa3b, v59
	v_exp_f32_e32 v59, v59
	s_nop 0
	v_add_f32_e32 v59, 1.0, v59
	v_div_scale_f32 v88, s[20:21], v59, v59, 1.0
	v_rcp_f32_e32 v89, v88
	s_nop 0
	v_fma_f32 v90, -v88, v89, 1.0
	v_fmac_f32_e32 v89, v90, v89
	v_div_scale_f32 v90, vcc, 1.0, v59, 1.0
	v_mul_f32_e32 v91, v90, v89
	v_fma_f32 v92, -v88, v91, v90
	v_fmac_f32_e32 v91, v92, v89
	v_fma_f32 v88, -v88, v91, v90
	v_div_fmas_f32 v88, v88, v89, v91
	v_div_fixup_f32 v59, v88, v59, 1.0
	v_mul_f32_e32 v51, v59, v51
	v_fmac_f32_e32 v216, v51, v51
	v_add_f32_e32 v52, v52, v68
	v_add_f32_e32 v60, v60, v76
	v_bfe_u32 v88, v52, 16, 1
	v_bfe_u32 v89, v60, 16, 1
	v_add3_u32 v52, v52, v88, s77
	v_add3_u32 v60, v60, v89, s77
	v_and_b32_e32 v52, s35, v52
	v_and_b32_e32 v60, s35, v60
	v_mul_f32_e32 v60, 0xbfb8aa3b, v60
	v_exp_f32_e32 v60, v60
	s_nop 0
	v_add_f32_e32 v60, 1.0, v60
	v_div_scale_f32 v88, s[20:21], v60, v60, 1.0
	v_rcp_f32_e32 v89, v88
	s_nop 0
	v_fma_f32 v90, -v88, v89, 1.0
	v_fmac_f32_e32 v89, v90, v89
	v_div_scale_f32 v90, vcc, 1.0, v60, 1.0
	v_mul_f32_e32 v91, v90, v89
	v_fma_f32 v92, -v88, v91, v90
	v_fmac_f32_e32 v91, v92, v89
	v_fma_f32 v88, -v88, v91, v90
	v_div_fmas_f32 v88, v88, v89, v91
	v_div_fixup_f32 v60, v88, v60, 1.0
	v_mul_f32_e32 v52, v60, v52
	v_fmac_f32_e32 v216, v52, v52
	v_add_f32_e32 v53, v53, v69
	v_add_f32_e32 v61, v61, v77
	v_bfe_u32 v88, v53, 16, 1
	v_bfe_u32 v89, v61, 16, 1
	v_add3_u32 v53, v53, v88, s77
	v_add3_u32 v61, v61, v89, s77
	v_and_b32_e32 v53, s35, v53
	v_and_b32_e32 v61, s35, v61
	v_mul_f32_e32 v61, 0xbfb8aa3b, v61
	v_exp_f32_e32 v61, v61
	s_nop 0
	v_add_f32_e32 v61, 1.0, v61
	v_div_scale_f32 v88, s[20:21], v61, v61, 1.0
	v_rcp_f32_e32 v89, v88
	s_nop 0
	v_fma_f32 v90, -v88, v89, 1.0
	v_fmac_f32_e32 v89, v90, v89
	v_div_scale_f32 v90, vcc, 1.0, v61, 1.0
	v_mul_f32_e32 v91, v90, v89
	v_fma_f32 v92, -v88, v91, v90
	v_fmac_f32_e32 v91, v92, v89
	v_fma_f32 v88, -v88, v91, v90
	v_div_fmas_f32 v88, v88, v89, v91
	v_div_fixup_f32 v61, v88, v61, 1.0
	v_mul_f32_e32 v53, v61, v53
	v_fmac_f32_e32 v216, v53, v53
	v_add_f32_e32 v54, v54, v70
	v_add_f32_e32 v62, v62, v78
	v_bfe_u32 v88, v54, 16, 1
	v_bfe_u32 v89, v62, 16, 1
	v_add3_u32 v54, v54, v88, s77
	v_add3_u32 v62, v62, v89, s77
	v_and_b32_e32 v54, s35, v54
	v_and_b32_e32 v62, s35, v62
	v_mul_f32_e32 v62, 0xbfb8aa3b, v62
	v_exp_f32_e32 v62, v62
	s_nop 0
	v_add_f32_e32 v62, 1.0, v62
	v_div_scale_f32 v88, s[20:21], v62, v62, 1.0
	v_rcp_f32_e32 v89, v88
	s_nop 0
	v_fma_f32 v90, -v88, v89, 1.0
	v_fmac_f32_e32 v89, v90, v89
	v_div_scale_f32 v90, vcc, 1.0, v62, 1.0
	v_mul_f32_e32 v91, v90, v89
	v_fma_f32 v92, -v88, v91, v90
	v_fmac_f32_e32 v91, v92, v89
	v_fma_f32 v88, -v88, v91, v90
	v_div_fmas_f32 v88, v88, v89, v91
	v_div_fixup_f32 v62, v88, v62, 1.0
	v_mul_f32_e32 v54, v62, v54
	v_fmac_f32_e32 v216, v54, v54
	v_add_f32_e32 v55, v55, v71
	v_add_f32_e32 v63, v63, v79
	v_bfe_u32 v88, v55, 16, 1
	v_bfe_u32 v89, v63, 16, 1
	v_add3_u32 v55, v55, v88, s77
	v_add3_u32 v63, v63, v89, s77
	v_and_b32_e32 v55, s35, v55
	v_and_b32_e32 v63, s35, v63
	v_mul_f32_e32 v63, 0xbfb8aa3b, v63
	v_exp_f32_e32 v63, v63
	s_nop 0
	v_add_f32_e32 v63, 1.0, v63
	v_div_scale_f32 v88, s[20:21], v63, v63, 1.0
	v_rcp_f32_e32 v89, v88
	s_nop 0
	v_fma_f32 v90, -v88, v89, 1.0
	v_fmac_f32_e32 v89, v90, v89
	v_div_scale_f32 v90, vcc, 1.0, v63, 1.0
	v_mul_f32_e32 v91, v90, v89
	v_fma_f32 v92, -v88, v91, v90
	v_fmac_f32_e32 v91, v92, v89
	v_fma_f32 v88, -v88, v91, v90
	v_div_fmas_f32 v88, v88, v89, v91
	v_div_fixup_f32 v63, v88, v63, 1.0
	v_mul_f32_e32 v55, v63, v55
	v_fmac_f32_e32 v216, v55, v55
	ds_write_b32 v211, v94 offset:0
	ds_write_b32 v211, v95 offset:2304
	ds_write_b32 v211, v215 offset:4608
	ds_write_b32 v211, v216 offset:6912
	s_waitcnt lgkmcnt(0)
	s_barrier
	ds_read_b128 v[96:99], v212 offset:0
	ds_read_b128 v[100:103], v212 offset:16
	ds_read_b128 v[104:107], v212 offset:32
	ds_read_b128 v[108:111], v212 offset:48
	s_waitcnt lgkmcnt(0)
	v_add_f32_e32 v96, v96, v100
	v_add_f32_e32 v97, v97, v101
	v_add_f32_e32 v98, v98, v102
	v_add_f32_e32 v99, v99, v103
	v_add_f32_e32 v96, v96, v104
	v_add_f32_e32 v97, v97, v105
	v_add_f32_e32 v98, v98, v106
	v_add_f32_e32 v99, v99, v107
	v_add_f32_e32 v96, v96, v108
	v_add_f32_e32 v97, v97, v109
	v_add_f32_e32 v98, v98, v110
	v_add_f32_e32 v99, v99, v111
	v_add_f32_e32 v96, v96, v97
	v_add_f32_e32 v98, v98, v99
	v_add_f32_e32 v94, v96, v98
	ds_read_b128 v[96:99], v212 offset:64
	ds_read_b128 v[100:103], v212 offset:80
	ds_read_b128 v[104:107], v212 offset:96
	ds_read_b128 v[108:111], v212 offset:112
	s_waitcnt lgkmcnt(0)
	v_add_f32_e32 v96, v96, v100
	v_add_f32_e32 v97, v97, v101
	v_add_f32_e32 v98, v98, v102
	v_add_f32_e32 v99, v99, v103
	v_add_f32_e32 v96, v96, v104
	v_add_f32_e32 v97, v97, v105
	v_add_f32_e32 v98, v98, v106
	v_add_f32_e32 v99, v99, v107
	v_add_f32_e32 v96, v96, v108
	v_add_f32_e32 v97, v97, v109
	v_add_f32_e32 v98, v98, v110
	v_add_f32_e32 v99, v99, v111
	v_add_f32_e32 v96, v96, v97
	v_add_f32_e32 v98, v98, v99
	v_add_f32_e32 v96, v96, v98
	v_add_f32_e32 v94, v94, v96
	ds_read_b128 v[96:99], v212 offset:2304
	ds_read_b128 v[100:103], v212 offset:2320
	ds_read_b128 v[104:107], v212 offset:2336
	ds_read_b128 v[108:111], v212 offset:2352
	s_waitcnt lgkmcnt(0)
	v_add_f32_e32 v96, v96, v100
	v_add_f32_e32 v97, v97, v101
	v_add_f32_e32 v98, v98, v102
	v_add_f32_e32 v99, v99, v103
	v_add_f32_e32 v96, v96, v104
	v_add_f32_e32 v97, v97, v105
	v_add_f32_e32 v98, v98, v106
	v_add_f32_e32 v99, v99, v107
	v_add_f32_e32 v96, v96, v108
	v_add_f32_e32 v97, v97, v109
	v_add_f32_e32 v98, v98, v110
	v_add_f32_e32 v99, v99, v111
	v_add_f32_e32 v96, v96, v97
	v_add_f32_e32 v98, v98, v99
	v_add_f32_e32 v95, v96, v98
	ds_read_b128 v[96:99], v212 offset:2368
	ds_read_b128 v[100:103], v212 offset:2384
	ds_read_b128 v[104:107], v212 offset:2400
	ds_read_b128 v[108:111], v212 offset:2416
	s_waitcnt lgkmcnt(0)
	v_add_f32_e32 v96, v96, v100
	v_add_f32_e32 v97, v97, v101
	v_add_f32_e32 v98, v98, v102
	v_add_f32_e32 v99, v99, v103
	v_add_f32_e32 v96, v96, v104
	v_add_f32_e32 v97, v97, v105
	v_add_f32_e32 v98, v98, v106
	v_add_f32_e32 v99, v99, v107
	v_add_f32_e32 v96, v96, v108
	v_add_f32_e32 v97, v97, v109
	v_add_f32_e32 v98, v98, v110
	v_add_f32_e32 v99, v99, v111
	v_add_f32_e32 v96, v96, v97
	v_add_f32_e32 v98, v98, v99
	v_add_f32_e32 v96, v96, v98
	v_add_f32_e32 v95, v95, v96
	ds_read_b128 v[96:99], v212 offset:4608
	ds_read_b128 v[100:103], v212 offset:4624
	ds_read_b128 v[104:107], v212 offset:4640
	ds_read_b128 v[108:111], v212 offset:4656
	s_waitcnt lgkmcnt(0)
	v_add_f32_e32 v96, v96, v100
	v_add_f32_e32 v97, v97, v101
	v_add_f32_e32 v98, v98, v102
	v_add_f32_e32 v99, v99, v103
	v_add_f32_e32 v96, v96, v104
	v_add_f32_e32 v97, v97, v105
	v_add_f32_e32 v98, v98, v106
	v_add_f32_e32 v99, v99, v107
	v_add_f32_e32 v96, v96, v108
	v_add_f32_e32 v97, v97, v109
	v_add_f32_e32 v98, v98, v110
	v_add_f32_e32 v99, v99, v111
	v_add_f32_e32 v96, v96, v97
	v_add_f32_e32 v98, v98, v99
	v_add_f32_e32 v215, v96, v98
	ds_read_b128 v[96:99], v212 offset:4672
	ds_read_b128 v[100:103], v212 offset:4688
	ds_read_b128 v[104:107], v212 offset:4704
	ds_read_b128 v[108:111], v212 offset:4720
	s_waitcnt lgkmcnt(0)
	v_add_f32_e32 v96, v96, v100
	v_add_f32_e32 v97, v97, v101
	v_add_f32_e32 v98, v98, v102
	v_add_f32_e32 v99, v99, v103
	v_add_f32_e32 v96, v96, v104
	v_add_f32_e32 v97, v97, v105
	v_add_f32_e32 v98, v98, v106
	v_add_f32_e32 v99, v99, v107
	v_add_f32_e32 v96, v96, v108
	v_add_f32_e32 v97, v97, v109
	v_add_f32_e32 v98, v98, v110
	v_add_f32_e32 v99, v99, v111
	v_add_f32_e32 v96, v96, v97
	v_add_f32_e32 v98, v98, v99
	v_add_f32_e32 v96, v96, v98
	v_add_f32_e32 v215, v215, v96
	ds_read_b128 v[96:99], v212 offset:6912
	ds_read_b128 v[100:103], v212 offset:6928
	ds_read_b128 v[104:107], v212 offset:6944
	ds_read_b128 v[108:111], v212 offset:6960
	s_waitcnt lgkmcnt(0)
	v_add_f32_e32 v96, v96, v100
	v_add_f32_e32 v97, v97, v101
	v_add_f32_e32 v98, v98, v102
	v_add_f32_e32 v99, v99, v103
	v_add_f32_e32 v96, v96, v104
	v_add_f32_e32 v97, v97, v105
	v_add_f32_e32 v98, v98, v106
	v_add_f32_e32 v99, v99, v107
	v_add_f32_e32 v96, v96, v108
	v_add_f32_e32 v97, v97, v109
	v_add_f32_e32 v98, v98, v110
	v_add_f32_e32 v99, v99, v111
	v_add_f32_e32 v96, v96, v97
	v_add_f32_e32 v98, v98, v99
	v_add_f32_e32 v216, v96, v98
	ds_read_b128 v[96:99], v212 offset:6976
	ds_read_b128 v[100:103], v212 offset:6992
	ds_read_b128 v[104:107], v212 offset:7008
	ds_read_b128 v[108:111], v212 offset:7024
	s_waitcnt lgkmcnt(0)
	v_add_f32_e32 v96, v96, v100
	v_add_f32_e32 v97, v97, v101
	v_add_f32_e32 v98, v98, v102
	v_add_f32_e32 v99, v99, v103
	v_add_f32_e32 v96, v96, v104
	v_add_f32_e32 v97, v97, v105
	v_add_f32_e32 v98, v98, v106
	v_add_f32_e32 v99, v99, v107
	v_add_f32_e32 v96, v96, v108
	v_add_f32_e32 v97, v97, v109
	v_add_f32_e32 v98, v98, v110
	v_add_f32_e32 v99, v99, v111
	v_add_f32_e32 v96, v96, v97
	v_add_f32_e32 v98, v98, v99
	v_add_f32_e32 v96, v96, v98
	v_add_f32_e32 v216, v216, v96
	v_fmamk_f32 v94, v94, 0x3b800000, v197
	v_fmamk_f32 v95, v95, 0x3b800000, v197
	v_fmamk_f32 v215, v215, 0x3b800000, v197
	v_fmamk_f32 v216, v216, 0x3b800000, v197
	v_rsq_f32_e32 v94, v94
	v_rsq_f32_e32 v95, v95
	v_rsq_f32_e32 v215, v215
	v_rsq_f32_e32 v216, v216
	s_nop 0
	v_mul_f32_e32 v0, v94, v0
	v_mul_f32_e32 v1, v94, v1
	v_mul_f32_e32 v2, v94, v2
	v_mul_f32_e32 v3, v94, v3
	v_mul_f32_e32 v0, v80, v0
	v_mul_f32_e32 v1, v81, v1
	v_mul_f32_e32 v2, v82, v2
	v_mul_f32_e32 v3, v83, v3
	v_cvt_pk_bf16_f32 v0, v0, v1
	v_cvt_pk_bf16_f32 v1, v2, v3
	global_store_dwordx2 v213, v[0:1], s[14:15] offset:0
	v_mul_f32_e32 v4, v94, v4
	v_mul_f32_e32 v5, v94, v5
	v_mul_f32_e32 v6, v94, v6
	v_mul_f32_e32 v7, v94, v7
	v_mul_f32_e32 v4, v84, v4
	v_mul_f32_e32 v5, v85, v5
	v_mul_f32_e32 v6, v86, v6
	v_mul_f32_e32 v7, v87, v7
	v_cvt_pk_bf16_f32 v4, v4, v5
	v_cvt_pk_bf16_f32 v5, v6, v7
	global_store_dwordx2 v213, v[4:5], s[14:15] offset:32
	s_add_u32 s14, s14, 0x8000
	s_addc_u32 s15, s15, 0
	v_mul_f32_e32 v16, v95, v16
	v_mul_f32_e32 v17, v95, v17
	v_mul_f32_e32 v18, v95, v18
	v_mul_f32_e32 v19, v95, v19
	v_mul_f32_e32 v16, v80, v16
	v_mul_f32_e32 v17, v81, v17
	v_mul_f32_e32 v18, v82, v18
	v_mul_f32_e32 v19, v83, v19
	v_cvt_pk_bf16_f32 v16, v16, v17
	v_cvt_pk_bf16_f32 v17, v18, v19
	global_store_dwordx2 v213, v[16:17], s[14:15] offset:0
	v_mul_f32_e32 v20, v95, v20
	v_mul_f32_e32 v21, v95, v21
	v_mul_f32_e32 v22, v95, v22
	v_mul_f32_e32 v23, v95, v23
	v_mul_f32_e32 v20, v84, v20
	v_mul_f32_e32 v21, v85, v21
	v_mul_f32_e32 v22, v86, v22
	v_mul_f32_e32 v23, v87, v23
	v_cvt_pk_bf16_f32 v20, v20, v21
	v_cvt_pk_bf16_f32 v21, v22, v23
	global_store_dwordx2 v213, v[20:21], s[14:15] offset:32
	s_add_u32 s14, s14, 0x8000
	s_addc_u32 s15, s15, 0
	v_mul_f32_e32 v32, v215, v32
	v_mul_f32_e32 v33, v215, v33
	v_mul_f32_e32 v34, v215, v34
	v_mul_f32_e32 v35, v215, v35
	v_mul_f32_e32 v32, v80, v32
	v_mul_f32_e32 v33, v81, v33
	v_mul_f32_e32 v34, v82, v34
	v_mul_f32_e32 v35, v83, v35
	v_cvt_pk_bf16_f32 v32, v32, v33
	v_cvt_pk_bf16_f32 v33, v34, v35
	global_store_dwordx2 v213, v[32:33], s[14:15] offset:0
	v_mul_f32_e32 v36, v215, v36
	v_mul_f32_e32 v37, v215, v37
	v_mul_f32_e32 v38, v215, v38
	v_mul_f32_e32 v39, v215, v39
	v_mul_f32_e32 v36, v84, v36
	v_mul_f32_e32 v37, v85, v37
	v_mul_f32_e32 v38, v86, v38
	v_mul_f32_e32 v39, v87, v39
	v_cvt_pk_bf16_f32 v36, v36, v37
	v_cvt_pk_bf16_f32 v37, v38, v39
	global_store_dwordx2 v213, v[36:37], s[14:15] offset:32
	s_add_u32 s14, s14, 0x8000
	s_addc_u32 s15, s15, 0
	v_mul_f32_e32 v48, v216, v48
	v_mul_f32_e32 v49, v216, v49
	v_mul_f32_e32 v50, v216, v50
	v_mul_f32_e32 v51, v216, v51
	v_mul_f32_e32 v48, v80, v48
	v_mul_f32_e32 v49, v81, v49
	v_mul_f32_e32 v50, v82, v50
	v_mul_f32_e32 v51, v83, v51
	v_cvt_pk_bf16_f32 v48, v48, v49
	v_cvt_pk_bf16_f32 v49, v50, v51
	global_store_dwordx2 v213, v[48:49], s[14:15] offset:0
	v_mul_f32_e32 v52, v216, v52
	v_mul_f32_e32 v53, v216, v53
	v_mul_f32_e32 v54, v216, v54
	v_mul_f32_e32 v55, v216, v55
	v_mul_f32_e32 v52, v84, v52
	v_mul_f32_e32 v53, v85, v53
	v_mul_f32_e32 v54, v86, v54
	v_mul_f32_e32 v55, v87, v55
	v_cvt_pk_bf16_f32 v52, v52, v53
	v_cvt_pk_bf16_f32 v53, v54, v55
	global_store_dwordx2 v213, v[52:53], s[14:15] offset:32
	s_waitcnt vmcnt(29)
	v_lshlrev_b32_e32 v64, 16, v142
	v_and_b32_e32 v65, 0xffff0000, v142
	v_lshlrev_b32_e32 v66, 16, v143
	v_and_b32_e32 v67, 0xffff0000, v143
	v_lshlrev_b32_e32 v68, 16, v144
	v_and_b32_e32 v69, 0xffff0000, v144
	v_lshlrev_b32_e32 v70, 16, v145
	v_and_b32_e32 v71, 0xffff0000, v145
	v_lshlrev_b32_e32 v72, 16, v146
	v_and_b32_e32 v73, 0xffff0000, v146
	v_lshlrev_b32_e32 v74, 16, v147
	v_and_b32_e32 v75, 0xffff0000, v147
	v_pk_mul_f32 v[86:87], v[64:65], v[64:65]
	v_pk_fma_f32 v[86:87], v[66:67], v[66:67], v[86:87]
	v_add_f32_e32 v76, v86, v87
	v_pk_mul_f32 v[88:89], v[68:69], v[68:69]
	v_pk_fma_f32 v[88:89], v[70:71], v[70:71], v[88:89]
	v_add_f32_e32 v77, v88, v89
	v_pk_mul_f32 v[86:87], v[72:73], v[72:73]
	v_pk_fma_f32 v[86:87], v[74:75], v[74:75], v[86:87]
	v_add_f32_e32 v78, v86, v87
	s_nop 0
	v_add_f32_dpp v76, v76, v76 row_ror:8 row_mask:0xf bank_mask:0xf
	s_nop 0
	v_add_f32_dpp v77, v77, v77 row_ror:8 row_mask:0xf bank_mask:0xf
	s_nop 0
	v_add_f32_dpp v76, v76, v76 row_ror:4 row_mask:0xf bank_mask:0xf
	s_nop 0
	v_add_f32_dpp v77, v77, v77 row_ror:4 row_mask:0xf bank_mask:0xf
	s_nop 0
	v_add_f32_dpp v76, v76, v76 row_ror:2 row_mask:0xf bank_mask:0xf
	s_nop 0
	v_add_f32_dpp v77, v77, v77 row_ror:2 row_mask:0xf bank_mask:0xf
	s_nop 0
	v_add_f32_dpp v76, v76, v76 row_ror:1 row_mask:0xf bank_mask:0xf
	s_nop 0
	v_add_f32_dpp v77, v77, v77 row_ror:1 row_mask:0xf bank_mask:0xf
	s_nop 0
	v_readlane_b32 s0, v76, 0
	v_readlane_b32 s1, v76, 16
	v_readlane_b32 s14, v76, 32
	v_readlane_b32 s15, v76, 48
	v_readlane_b32 s18, v77, 0
	v_readlane_b32 s19, v77, 16
	v_readlane_b32 s20, v77, 32
	v_readlane_b32 s21, v77, 48
	s_nop 1
	v_mov_b32_e32 v80, s0
	v_mov_b32_e32 v82, s18
	v_add_f32_e32 v80, s1, v80
	v_add_f32_e32 v82, s19, v82
	v_add_f32_e32 v80, s14, v80
	v_add_f32_e32 v82, s20, v82
	v_add_f32_e32 v80, s15, v80
	v_add_f32_e32 v82, s21, v82
	v_add_f32_dpp v78, v78, v78 row_ror:8 row_mask:0xf bank_mask:0xf
	s_nop 1
	v_add_f32_dpp v78, v78, v78 row_ror:4 row_mask:0xf bank_mask:0xf
	s_nop 1
	v_add_f32_dpp v78, v78, v78 row_ror:2 row_mask:0xf bank_mask:0xf
	s_nop 1
	v_add_f32_dpp v78, v78, v78 row_ror:1 row_mask:0xf bank_mask:0xf
	s_nop 1
	s_nop 0
	v_readlane_b32 s0, v78, 0
	v_readlane_b32 s1, v78, 16
	v_readlane_b32 s14, v78, 32
	v_readlane_b32 s15, v78, 48
	s_nop 1
	v_mov_b32_e32 v84, s0
	v_add_f32_e32 v84, s1, v84
	v_add_f32_e32 v84, s14, v84
	v_add_f32_e32 v84, s15, v84
	v_fmamk_f32 v80, v80, 0x3b800000, v197
	v_fmamk_f32 v82, v82, 0x3b800000, v197
	v_fmamk_f32 v84, v84, 0x3b800000, v197
	v_rsq_f32_e32 v80, v80
	v_rsq_f32_e32 v82, v82
	v_rsq_f32_e32 v84, v84
	s_nop 0
	v_pk_mul_f32 v[64:65], v[80:81], v[64:65] op_sel_hi:[0,1]
	v_pk_mul_f32 v[66:67], v[80:81], v[66:67] op_sel_hi:[0,1]
	v_pk_mul_f32 v[68:69], v[82:83], v[68:69] op_sel_hi:[0,1]
	v_pk_mul_f32 v[70:71], v[82:83], v[70:71] op_sel_hi:[0,1]
	v_pk_mul_f32 v[72:73], v[84:85], v[72:73] op_sel_hi:[0,1]
	v_pk_mul_f32 v[74:75], v[84:85], v[74:75] op_sel_hi:[0,1]
	v_pk_mul_f32 v[64:65], v[116:117], v[64:65]
	v_pk_mul_f32 v[66:67], v[118:119], v[66:67]
	v_pk_mul_f32 v[68:69], v[120:121], v[68:69]
	v_pk_mul_f32 v[70:71], v[122:123], v[70:71]
	v_pk_mul_f32 v[72:73], v[124:125], v[72:73]
	v_pk_mul_f32 v[74:75], v[126:127], v[74:75]
	v_cvt_pk_bf16_f32 v142, v64, v65
	v_cvt_pk_bf16_f32 v143, v66, v67
	v_cvt_pk_bf16_f32 v144, v68, v69
	v_cvt_pk_bf16_f32 v145, v70, v71
	v_cvt_pk_bf16_f32 v146, v72, v73
	v_cvt_pk_bf16_f32 v147, v74, v75
	global_store_dwordx2 v208, v[142:143], s[12:13] offset:0
	global_store_dwordx2 v208, v[144:145], s[12:13] offset:512
	global_store_dwordx2 v208, v[146:147], s[12:13] offset:1024
	s_add_u32 s12, s12, 0x800
	s_addc_u32 s13, s13, 0
	s_waitcnt vmcnt(29)
	v_lshlrev_b32_e32 v64, 16, v148
	v_and_b32_e32 v65, 0xffff0000, v148
	v_lshlrev_b32_e32 v66, 16, v149
	v_and_b32_e32 v67, 0xffff0000, v149
	v_lshlrev_b32_e32 v68, 16, v150
	v_and_b32_e32 v69, 0xffff0000, v150
	v_lshlrev_b32_e32 v70, 16, v151
	v_and_b32_e32 v71, 0xffff0000, v151
	v_lshlrev_b32_e32 v72, 16, v152
	v_and_b32_e32 v73, 0xffff0000, v152
	v_lshlrev_b32_e32 v74, 16, v153
	v_and_b32_e32 v75, 0xffff0000, v153
	v_pk_mul_f32 v[86:87], v[64:65], v[64:65]
	v_pk_fma_f32 v[86:87], v[66:67], v[66:67], v[86:87]
	v_add_f32_e32 v76, v86, v87
	v_pk_mul_f32 v[88:89], v[68:69], v[68:69]
	v_pk_fma_f32 v[88:89], v[70:71], v[70:71], v[88:89]
	v_add_f32_e32 v77, v88, v89
	v_pk_mul_f32 v[86:87], v[72:73], v[72:73]
	v_pk_fma_f32 v[86:87], v[74:75], v[74:75], v[86:87]
	v_add_f32_e32 v78, v86, v87
	s_nop 0
	v_add_f32_dpp v76, v76, v76 row_ror:8 row_mask:0xf bank_mask:0xf
	s_nop 0
	v_add_f32_dpp v77, v77, v77 row_ror:8 row_mask:0xf bank_mask:0xf
	s_nop 0
	v_add_f32_dpp v76, v76, v76 row_ror:4 row_mask:0xf bank_mask:0xf
	s_nop 0
	v_add_f32_dpp v77, v77, v77 row_ror:4 row_mask:0xf bank_mask:0xf
	s_nop 0
	v_add_f32_dpp v76, v76, v76 row_ror:2 row_mask:0xf bank_mask:0xf
	s_nop 0
	v_add_f32_dpp v77, v77, v77 row_ror:2 row_mask:0xf bank_mask:0xf
	s_nop 0
	v_add_f32_dpp v76, v76, v76 row_ror:1 row_mask:0xf bank_mask:0xf
	s_nop 0
	v_add_f32_dpp v77, v77, v77 row_ror:1 row_mask:0xf bank_mask:0xf
	s_nop 0
	v_readlane_b32 s0, v76, 0
	v_readlane_b32 s1, v76, 16
	v_readlane_b32 s14, v76, 32
	v_readlane_b32 s15, v76, 48
	v_readlane_b32 s18, v77, 0
	v_readlane_b32 s19, v77, 16
	v_readlane_b32 s20, v77, 32
	v_readlane_b32 s21, v77, 48
	s_nop 1
	v_mov_b32_e32 v80, s0
	v_mov_b32_e32 v82, s18
	v_add_f32_e32 v80, s1, v80
	v_add_f32_e32 v82, s19, v82
	v_add_f32_e32 v80, s14, v80
	v_add_f32_e32 v82, s20, v82
	v_add_f32_e32 v80, s15, v80
	v_add_f32_e32 v82, s21, v82
	v_add_f32_dpp v78, v78, v78 row_ror:8 row_mask:0xf bank_mask:0xf
	s_nop 1
	v_add_f32_dpp v78, v78, v78 row_ror:4 row_mask:0xf bank_mask:0xf
	s_nop 1
	v_add_f32_dpp v78, v78, v78 row_ror:2 row_mask:0xf bank_mask:0xf
	s_nop 1
	v_add_f32_dpp v78, v78, v78 row_ror:1 row_mask:0xf bank_mask:0xf
	s_nop 1
	s_nop 0
	v_readlane_b32 s0, v78, 0
	v_readlane_b32 s1, v78, 16
	v_readlane_b32 s14, v78, 32
	v_readlane_b32 s15, v78, 48
	s_nop 1
	v_mov_b32_e32 v84, s0
	v_add_f32_e32 v84, s1, v84
	v_add_f32_e32 v84, s14, v84
	v_add_f32_e32 v84, s15, v84
	v_fmamk_f32 v80, v80, 0x3b800000, v197
	v_fmamk_f32 v82, v82, 0x3b800000, v197
	v_fmamk_f32 v84, v84, 0x3b800000, v197
	v_rsq_f32_e32 v80, v80
	v_rsq_f32_e32 v82, v82
	v_rsq_f32_e32 v84, v84
	s_nop 0
	v_pk_mul_f32 v[64:65], v[80:81], v[64:65] op_sel_hi:[0,1]
	v_pk_mul_f32 v[66:67], v[80:81], v[66:67] op_sel_hi:[0,1]
	v_pk_mul_f32 v[68:69], v[82:83], v[68:69] op_sel_hi:[0,1]
	v_pk_mul_f32 v[70:71], v[82:83], v[70:71] op_sel_hi:[0,1]
	v_pk_mul_f32 v[72:73], v[84:85], v[72:73] op_sel_hi:[0,1]
	v_pk_mul_f32 v[74:75], v[84:85], v[74:75] op_sel_hi:[0,1]
	v_pk_mul_f32 v[64:65], v[116:117], v[64:65]
	v_pk_mul_f32 v[66:67], v[118:119], v[66:67]
	v_pk_mul_f32 v[68:69], v[120:121], v[68:69]
	v_pk_mul_f32 v[70:71], v[122:123], v[70:71]
	v_pk_mul_f32 v[72:73], v[124:125], v[72:73]
	v_pk_mul_f32 v[74:75], v[126:127], v[74:75]
	v_cvt_pk_bf16_f32 v148, v64, v65
	v_cvt_pk_bf16_f32 v149, v66, v67
	v_cvt_pk_bf16_f32 v150, v68, v69
	v_cvt_pk_bf16_f32 v151, v70, v71
	v_cvt_pk_bf16_f32 v152, v72, v73
	v_cvt_pk_bf16_f32 v153, v74, v75
	global_store_dwordx2 v208, v[148:149], s[12:13] offset:0
	global_store_dwordx2 v208, v[150:151], s[12:13] offset:512
	global_store_dwordx2 v208, v[152:153], s[12:13] offset:1024
	s_add_u32 s12, s12, 0x800
	s_addc_u32 s13, s13, 0
	s_waitcnt vmcnt(29)
	v_lshlrev_b32_e32 v64, 16, v154
	v_and_b32_e32 v65, 0xffff0000, v154
	v_lshlrev_b32_e32 v66, 16, v155
	v_and_b32_e32 v67, 0xffff0000, v155
	v_lshlrev_b32_e32 v68, 16, v156
	v_and_b32_e32 v69, 0xffff0000, v156
	v_lshlrev_b32_e32 v70, 16, v157
	v_and_b32_e32 v71, 0xffff0000, v157
	v_lshlrev_b32_e32 v72, 16, v158
	v_and_b32_e32 v73, 0xffff0000, v158
	v_lshlrev_b32_e32 v74, 16, v159
	v_and_b32_e32 v75, 0xffff0000, v159
	v_pk_mul_f32 v[86:87], v[64:65], v[64:65]
	v_pk_fma_f32 v[86:87], v[66:67], v[66:67], v[86:87]
	v_add_f32_e32 v76, v86, v87
	v_pk_mul_f32 v[88:89], v[68:69], v[68:69]
	v_pk_fma_f32 v[88:89], v[70:71], v[70:71], v[88:89]
	v_add_f32_e32 v77, v88, v89
	v_pk_mul_f32 v[86:87], v[72:73], v[72:73]
	v_pk_fma_f32 v[86:87], v[74:75], v[74:75], v[86:87]
	v_add_f32_e32 v78, v86, v87
	s_nop 0
	v_add_f32_dpp v76, v76, v76 row_ror:8 row_mask:0xf bank_mask:0xf
	s_nop 0
	v_add_f32_dpp v77, v77, v77 row_ror:8 row_mask:0xf bank_mask:0xf
	s_nop 0
	v_add_f32_dpp v76, v76, v76 row_ror:4 row_mask:0xf bank_mask:0xf
	s_nop 0
	v_add_f32_dpp v77, v77, v77 row_ror:4 row_mask:0xf bank_mask:0xf
	s_nop 0
	v_add_f32_dpp v76, v76, v76 row_ror:2 row_mask:0xf bank_mask:0xf
	s_nop 0
	v_add_f32_dpp v77, v77, v77 row_ror:2 row_mask:0xf bank_mask:0xf
	s_nop 0
	v_add_f32_dpp v76, v76, v76 row_ror:1 row_mask:0xf bank_mask:0xf
	s_nop 0
	v_add_f32_dpp v77, v77, v77 row_ror:1 row_mask:0xf bank_mask:0xf
	s_nop 0
	v_readlane_b32 s0, v76, 0
	v_readlane_b32 s1, v76, 16
	v_readlane_b32 s14, v76, 32
	v_readlane_b32 s15, v76, 48
	v_readlane_b32 s18, v77, 0
	v_readlane_b32 s19, v77, 16
	v_readlane_b32 s20, v77, 32
	v_readlane_b32 s21, v77, 48
	s_nop 1
	v_mov_b32_e32 v80, s0
	v_mov_b32_e32 v82, s18
	v_add_f32_e32 v80, s1, v80
	v_add_f32_e32 v82, s19, v82
	v_add_f32_e32 v80, s14, v80
	v_add_f32_e32 v82, s20, v82
	v_add_f32_e32 v80, s15, v80
	v_add_f32_e32 v82, s21, v82
	v_add_f32_dpp v78, v78, v78 row_ror:8 row_mask:0xf bank_mask:0xf
	s_nop 1
	v_add_f32_dpp v78, v78, v78 row_ror:4 row_mask:0xf bank_mask:0xf
	s_nop 1
	v_add_f32_dpp v78, v78, v78 row_ror:2 row_mask:0xf bank_mask:0xf
	s_nop 1
	v_add_f32_dpp v78, v78, v78 row_ror:1 row_mask:0xf bank_mask:0xf
	s_nop 1
	s_nop 0
	v_readlane_b32 s0, v78, 0
	v_readlane_b32 s1, v78, 16
	v_readlane_b32 s14, v78, 32
	v_readlane_b32 s15, v78, 48
	s_nop 1
	v_mov_b32_e32 v84, s0
	v_add_f32_e32 v84, s1, v84
	v_add_f32_e32 v84, s14, v84
	v_add_f32_e32 v84, s15, v84
	v_fmamk_f32 v80, v80, 0x3b800000, v197
	v_fmamk_f32 v82, v82, 0x3b800000, v197
	v_fmamk_f32 v84, v84, 0x3b800000, v197
	v_rsq_f32_e32 v80, v80
	v_rsq_f32_e32 v82, v82
	v_rsq_f32_e32 v84, v84
	s_nop 0
	v_pk_mul_f32 v[64:65], v[80:81], v[64:65] op_sel_hi:[0,1]
	v_pk_mul_f32 v[66:67], v[80:81], v[66:67] op_sel_hi:[0,1]
	v_pk_mul_f32 v[68:69], v[82:83], v[68:69] op_sel_hi:[0,1]
	v_pk_mul_f32 v[70:71], v[82:83], v[70:71] op_sel_hi:[0,1]
	v_pk_mul_f32 v[72:73], v[84:85], v[72:73] op_sel_hi:[0,1]
	v_pk_mul_f32 v[74:75], v[84:85], v[74:75] op_sel_hi:[0,1]
	v_pk_mul_f32 v[64:65], v[116:117], v[64:65]
	v_pk_mul_f32 v[66:67], v[118:119], v[66:67]
	v_pk_mul_f32 v[68:69], v[120:121], v[68:69]
	v_pk_mul_f32 v[70:71], v[122:123], v[70:71]
	v_pk_mul_f32 v[72:73], v[124:125], v[72:73]
	v_pk_mul_f32 v[74:75], v[126:127], v[74:75]
	v_cvt_pk_bf16_f32 v154, v64, v65
	v_cvt_pk_bf16_f32 v155, v66, v67
	v_cvt_pk_bf16_f32 v156, v68, v69
	v_cvt_pk_bf16_f32 v157, v70, v71
	v_cvt_pk_bf16_f32 v158, v72, v73
	v_cvt_pk_bf16_f32 v159, v74, v75
	global_store_dwordx2 v208, v[154:155], s[12:13] offset:0
	global_store_dwordx2 v208, v[156:157], s[12:13] offset:512
	global_store_dwordx2 v208, v[158:159], s[12:13] offset:1024
	s_add_u32 s12, s12, 0x800
	s_addc_u32 s13, s13, 0
	s_waitcnt vmcnt(29)
	v_lshlrev_b32_e32 v64, 16, v160
	v_and_b32_e32 v65, 0xffff0000, v160
	v_lshlrev_b32_e32 v66, 16, v161
	v_and_b32_e32 v67, 0xffff0000, v161
	v_lshlrev_b32_e32 v68, 16, v162
	v_and_b32_e32 v69, 0xffff0000, v162
	v_lshlrev_b32_e32 v70, 16, v163
	v_and_b32_e32 v71, 0xffff0000, v163
	v_lshlrev_b32_e32 v72, 16, v164
	v_and_b32_e32 v73, 0xffff0000, v164
	v_lshlrev_b32_e32 v74, 16, v165
	v_and_b32_e32 v75, 0xffff0000, v165
	v_pk_mul_f32 v[86:87], v[64:65], v[64:65]
	v_pk_fma_f32 v[86:87], v[66:67], v[66:67], v[86:87]
	v_add_f32_e32 v76, v86, v87
	v_pk_mul_f32 v[88:89], v[68:69], v[68:69]
	v_pk_fma_f32 v[88:89], v[70:71], v[70:71], v[88:89]
	v_add_f32_e32 v77, v88, v89
	v_pk_mul_f32 v[86:87], v[72:73], v[72:73]
	v_pk_fma_f32 v[86:87], v[74:75], v[74:75], v[86:87]
	v_add_f32_e32 v78, v86, v87
	s_nop 0
	v_add_f32_dpp v76, v76, v76 row_ror:8 row_mask:0xf bank_mask:0xf
	s_nop 0
	v_add_f32_dpp v77, v77, v77 row_ror:8 row_mask:0xf bank_mask:0xf
	s_nop 0
	v_add_f32_dpp v76, v76, v76 row_ror:4 row_mask:0xf bank_mask:0xf
	s_nop 0
	v_add_f32_dpp v77, v77, v77 row_ror:4 row_mask:0xf bank_mask:0xf
	s_nop 0
	v_add_f32_dpp v76, v76, v76 row_ror:2 row_mask:0xf bank_mask:0xf
	s_nop 0
	v_add_f32_dpp v77, v77, v77 row_ror:2 row_mask:0xf bank_mask:0xf
	s_nop 0
	v_add_f32_dpp v76, v76, v76 row_ror:1 row_mask:0xf bank_mask:0xf
	s_nop 0
	v_add_f32_dpp v77, v77, v77 row_ror:1 row_mask:0xf bank_mask:0xf
	s_nop 0
	v_readlane_b32 s0, v76, 0
	v_readlane_b32 s1, v76, 16
	v_readlane_b32 s14, v76, 32
	v_readlane_b32 s15, v76, 48
	v_readlane_b32 s18, v77, 0
	v_readlane_b32 s19, v77, 16
	v_readlane_b32 s20, v77, 32
	v_readlane_b32 s21, v77, 48
	s_nop 1
	v_mov_b32_e32 v80, s0
	v_mov_b32_e32 v82, s18
	v_add_f32_e32 v80, s1, v80
	v_add_f32_e32 v82, s19, v82
	v_add_f32_e32 v80, s14, v80
	v_add_f32_e32 v82, s20, v82
	v_add_f32_e32 v80, s15, v80
	v_add_f32_e32 v82, s21, v82
	v_add_f32_dpp v78, v78, v78 row_ror:8 row_mask:0xf bank_mask:0xf
	s_nop 1
	v_add_f32_dpp v78, v78, v78 row_ror:4 row_mask:0xf bank_mask:0xf
	s_nop 1
	v_add_f32_dpp v78, v78, v78 row_ror:2 row_mask:0xf bank_mask:0xf
	s_nop 1
	v_add_f32_dpp v78, v78, v78 row_ror:1 row_mask:0xf bank_mask:0xf
	s_nop 1
	s_nop 0
	v_readlane_b32 s0, v78, 0
	v_readlane_b32 s1, v78, 16
	v_readlane_b32 s14, v78, 32
	v_readlane_b32 s15, v78, 48
	s_nop 1
	v_mov_b32_e32 v84, s0
	v_add_f32_e32 v84, s1, v84
	v_add_f32_e32 v84, s14, v84
	v_add_f32_e32 v84, s15, v84
	v_fmamk_f32 v80, v80, 0x3b800000, v197
	v_fmamk_f32 v82, v82, 0x3b800000, v197
	v_fmamk_f32 v84, v84, 0x3b800000, v197
	v_rsq_f32_e32 v80, v80
	v_rsq_f32_e32 v82, v82
	v_rsq_f32_e32 v84, v84
	s_nop 0
	v_pk_mul_f32 v[64:65], v[80:81], v[64:65] op_sel_hi:[0,1]
	v_pk_mul_f32 v[66:67], v[80:81], v[66:67] op_sel_hi:[0,1]
	v_pk_mul_f32 v[68:69], v[82:83], v[68:69] op_sel_hi:[0,1]
	v_pk_mul_f32 v[70:71], v[82:83], v[70:71] op_sel_hi:[0,1]
	v_pk_mul_f32 v[72:73], v[84:85], v[72:73] op_sel_hi:[0,1]
	v_pk_mul_f32 v[74:75], v[84:85], v[74:75] op_sel_hi:[0,1]
	v_pk_mul_f32 v[64:65], v[116:117], v[64:65]
	v_pk_mul_f32 v[66:67], v[118:119], v[66:67]
	v_pk_mul_f32 v[68:69], v[120:121], v[68:69]
	v_pk_mul_f32 v[70:71], v[122:123], v[70:71]
	v_pk_mul_f32 v[72:73], v[124:125], v[72:73]
	v_pk_mul_f32 v[74:75], v[126:127], v[74:75]
	v_cvt_pk_bf16_f32 v160, v64, v65
	v_cvt_pk_bf16_f32 v161, v66, v67
	v_cvt_pk_bf16_f32 v162, v68, v69
	v_cvt_pk_bf16_f32 v163, v70, v71
	v_cvt_pk_bf16_f32 v164, v72, v73
	v_cvt_pk_bf16_f32 v165, v74, v75
	global_store_dwordx2 v208, v[160:161], s[12:13] offset:0
	global_store_dwordx2 v208, v[162:163], s[12:13] offset:512
	global_store_dwordx2 v208, v[164:165], s[12:13] offset:1024
	s_add_u32 s12, s12, 0x800
	s_addc_u32 s13, s13, 0
	s_waitcnt vmcnt(29)
	v_lshlrev_b32_e32 v64, 16, v166
	v_and_b32_e32 v65, 0xffff0000, v166
	v_lshlrev_b32_e32 v66, 16, v167
	v_and_b32_e32 v67, 0xffff0000, v167
	v_lshlrev_b32_e32 v68, 16, v168
	v_and_b32_e32 v69, 0xffff0000, v168
	v_lshlrev_b32_e32 v70, 16, v169
	v_and_b32_e32 v71, 0xffff0000, v169
	v_lshlrev_b32_e32 v72, 16, v170
	v_and_b32_e32 v73, 0xffff0000, v170
	v_lshlrev_b32_e32 v74, 16, v171
	v_and_b32_e32 v75, 0xffff0000, v171
	v_pk_mul_f32 v[86:87], v[64:65], v[64:65]
	v_pk_fma_f32 v[86:87], v[66:67], v[66:67], v[86:87]
	v_add_f32_e32 v76, v86, v87
	v_pk_mul_f32 v[88:89], v[68:69], v[68:69]
	v_pk_fma_f32 v[88:89], v[70:71], v[70:71], v[88:89]
	v_add_f32_e32 v77, v88, v89
	v_pk_mul_f32 v[86:87], v[72:73], v[72:73]
	v_pk_fma_f32 v[86:87], v[74:75], v[74:75], v[86:87]
	v_add_f32_e32 v78, v86, v87
	s_nop 0
	v_add_f32_dpp v76, v76, v76 row_ror:8 row_mask:0xf bank_mask:0xf
	s_nop 0
	v_add_f32_dpp v77, v77, v77 row_ror:8 row_mask:0xf bank_mask:0xf
	s_nop 0
	v_add_f32_dpp v76, v76, v76 row_ror:4 row_mask:0xf bank_mask:0xf
	s_nop 0
	v_add_f32_dpp v77, v77, v77 row_ror:4 row_mask:0xf bank_mask:0xf
	s_nop 0
	v_add_f32_dpp v76, v76, v76 row_ror:2 row_mask:0xf bank_mask:0xf
	s_nop 0
	v_add_f32_dpp v77, v77, v77 row_ror:2 row_mask:0xf bank_mask:0xf
	s_nop 0
	v_add_f32_dpp v76, v76, v76 row_ror:1 row_mask:0xf bank_mask:0xf
	s_nop 0
	v_add_f32_dpp v77, v77, v77 row_ror:1 row_mask:0xf bank_mask:0xf
	s_nop 0
	v_readlane_b32 s0, v76, 0
	v_readlane_b32 s1, v76, 16
	v_readlane_b32 s14, v76, 32
	v_readlane_b32 s15, v76, 48
	v_readlane_b32 s18, v77, 0
	v_readlane_b32 s19, v77, 16
	v_readlane_b32 s20, v77, 32
	v_readlane_b32 s21, v77, 48
	s_nop 1
	v_mov_b32_e32 v80, s0
	v_mov_b32_e32 v82, s18
	v_add_f32_e32 v80, s1, v80
	v_add_f32_e32 v82, s19, v82
	v_add_f32_e32 v80, s14, v80
	v_add_f32_e32 v82, s20, v82
	v_add_f32_e32 v80, s15, v80
	v_add_f32_e32 v82, s21, v82
	v_add_f32_dpp v78, v78, v78 row_ror:8 row_mask:0xf bank_mask:0xf
	s_nop 1
	v_add_f32_dpp v78, v78, v78 row_ror:4 row_mask:0xf bank_mask:0xf
	s_nop 1
	v_add_f32_dpp v78, v78, v78 row_ror:2 row_mask:0xf bank_mask:0xf
	s_nop 1
	v_add_f32_dpp v78, v78, v78 row_ror:1 row_mask:0xf bank_mask:0xf
	s_nop 1
	s_nop 0
	v_readlane_b32 s0, v78, 0
	v_readlane_b32 s1, v78, 16
	v_readlane_b32 s14, v78, 32
	v_readlane_b32 s15, v78, 48
	s_nop 1
	v_mov_b32_e32 v84, s0
	v_add_f32_e32 v84, s1, v84
	v_add_f32_e32 v84, s14, v84
	v_add_f32_e32 v84, s15, v84
	v_fmamk_f32 v80, v80, 0x3b800000, v197
	v_fmamk_f32 v82, v82, 0x3b800000, v197
	v_fmamk_f32 v84, v84, 0x3b800000, v197
	v_rsq_f32_e32 v80, v80
	v_rsq_f32_e32 v82, v82
	v_rsq_f32_e32 v84, v84
	s_nop 0
	v_pk_mul_f32 v[64:65], v[80:81], v[64:65] op_sel_hi:[0,1]
	v_pk_mul_f32 v[66:67], v[80:81], v[66:67] op_sel_hi:[0,1]
	v_pk_mul_f32 v[68:69], v[82:83], v[68:69] op_sel_hi:[0,1]
	v_pk_mul_f32 v[70:71], v[82:83], v[70:71] op_sel_hi:[0,1]
	v_pk_mul_f32 v[72:73], v[84:85], v[72:73] op_sel_hi:[0,1]
	v_pk_mul_f32 v[74:75], v[84:85], v[74:75] op_sel_hi:[0,1]
	v_pk_mul_f32 v[64:65], v[116:117], v[64:65]
	v_pk_mul_f32 v[66:67], v[118:119], v[66:67]
	v_pk_mul_f32 v[68:69], v[120:121], v[68:69]
	v_pk_mul_f32 v[70:71], v[122:123], v[70:71]
	v_pk_mul_f32 v[72:73], v[124:125], v[72:73]
	v_pk_mul_f32 v[74:75], v[126:127], v[74:75]
	v_cvt_pk_bf16_f32 v166, v64, v65
	v_cvt_pk_bf16_f32 v167, v66, v67
	v_cvt_pk_bf16_f32 v168, v68, v69
	v_cvt_pk_bf16_f32 v169, v70, v71
	v_cvt_pk_bf16_f32 v170, v72, v73
	v_cvt_pk_bf16_f32 v171, v74, v75
	global_store_dwordx2 v208, v[166:167], s[12:13] offset:0
	global_store_dwordx2 v208, v[168:169], s[12:13] offset:512
	global_store_dwordx2 v208, v[170:171], s[12:13] offset:1024
	s_add_u32 s12, s12, 0x800
	s_addc_u32 s13, s13, 0
	s_waitcnt vmcnt(29)
	v_lshlrev_b32_e32 v64, 16, v172
	v_and_b32_e32 v65, 0xffff0000, v172
	v_lshlrev_b32_e32 v66, 16, v173
	v_and_b32_e32 v67, 0xffff0000, v173
	v_lshlrev_b32_e32 v68, 16, v174
	v_and_b32_e32 v69, 0xffff0000, v174
	v_lshlrev_b32_e32 v70, 16, v175
	v_and_b32_e32 v71, 0xffff0000, v175
	v_lshlrev_b32_e32 v72, 16, v176
	v_and_b32_e32 v73, 0xffff0000, v176
	v_lshlrev_b32_e32 v74, 16, v177
	v_and_b32_e32 v75, 0xffff0000, v177
	v_pk_mul_f32 v[86:87], v[64:65], v[64:65]
	v_pk_fma_f32 v[86:87], v[66:67], v[66:67], v[86:87]
	v_add_f32_e32 v76, v86, v87
	v_pk_mul_f32 v[88:89], v[68:69], v[68:69]
	v_pk_fma_f32 v[88:89], v[70:71], v[70:71], v[88:89]
	v_add_f32_e32 v77, v88, v89
	v_pk_mul_f32 v[86:87], v[72:73], v[72:73]
	v_pk_fma_f32 v[86:87], v[74:75], v[74:75], v[86:87]
	v_add_f32_e32 v78, v86, v87
	s_nop 0
	v_add_f32_dpp v76, v76, v76 row_ror:8 row_mask:0xf bank_mask:0xf
	s_nop 0
	v_add_f32_dpp v77, v77, v77 row_ror:8 row_mask:0xf bank_mask:0xf
	s_nop 0
	v_add_f32_dpp v76, v76, v76 row_ror:4 row_mask:0xf bank_mask:0xf
	s_nop 0
	v_add_f32_dpp v77, v77, v77 row_ror:4 row_mask:0xf bank_mask:0xf
	s_nop 0
	v_add_f32_dpp v76, v76, v76 row_ror:2 row_mask:0xf bank_mask:0xf
	s_nop 0
	v_add_f32_dpp v77, v77, v77 row_ror:2 row_mask:0xf bank_mask:0xf
	s_nop 0
	v_add_f32_dpp v76, v76, v76 row_ror:1 row_mask:0xf bank_mask:0xf
	s_nop 0
	v_add_f32_dpp v77, v77, v77 row_ror:1 row_mask:0xf bank_mask:0xf
	s_nop 0
	v_readlane_b32 s0, v76, 0
	v_readlane_b32 s1, v76, 16
	v_readlane_b32 s14, v76, 32
	v_readlane_b32 s15, v76, 48
	v_readlane_b32 s18, v77, 0
	v_readlane_b32 s19, v77, 16
	v_readlane_b32 s20, v77, 32
	v_readlane_b32 s21, v77, 48
	s_nop 1
	v_mov_b32_e32 v80, s0
	v_mov_b32_e32 v82, s18
	v_add_f32_e32 v80, s1, v80
	v_add_f32_e32 v82, s19, v82
	v_add_f32_e32 v80, s14, v80
	v_add_f32_e32 v82, s20, v82
	v_add_f32_e32 v80, s15, v80
	v_add_f32_e32 v82, s21, v82
	v_add_f32_dpp v78, v78, v78 row_ror:8 row_mask:0xf bank_mask:0xf
	s_nop 1
	v_add_f32_dpp v78, v78, v78 row_ror:4 row_mask:0xf bank_mask:0xf
	s_nop 1
	v_add_f32_dpp v78, v78, v78 row_ror:2 row_mask:0xf bank_mask:0xf
	s_nop 1
	v_add_f32_dpp v78, v78, v78 row_ror:1 row_mask:0xf bank_mask:0xf
	s_nop 1
	s_nop 0
	v_readlane_b32 s0, v78, 0
	v_readlane_b32 s1, v78, 16
	v_readlane_b32 s14, v78, 32
	v_readlane_b32 s15, v78, 48
	s_nop 1
	v_mov_b32_e32 v84, s0
	v_add_f32_e32 v84, s1, v84
	v_add_f32_e32 v84, s14, v84
	v_add_f32_e32 v84, s15, v84
	v_fmamk_f32 v80, v80, 0x3b800000, v197
	v_fmamk_f32 v82, v82, 0x3b800000, v197
	v_fmamk_f32 v84, v84, 0x3b800000, v197
	v_rsq_f32_e32 v80, v80
	v_rsq_f32_e32 v82, v82
	v_rsq_f32_e32 v84, v84
	s_nop 0
	v_pk_mul_f32 v[64:65], v[80:81], v[64:65] op_sel_hi:[0,1]
	v_pk_mul_f32 v[66:67], v[80:81], v[66:67] op_sel_hi:[0,1]
	v_pk_mul_f32 v[68:69], v[82:83], v[68:69] op_sel_hi:[0,1]
	v_pk_mul_f32 v[70:71], v[82:83], v[70:71] op_sel_hi:[0,1]
	v_pk_mul_f32 v[72:73], v[84:85], v[72:73] op_sel_hi:[0,1]
	v_pk_mul_f32 v[74:75], v[84:85], v[74:75] op_sel_hi:[0,1]
	v_pk_mul_f32 v[64:65], v[116:117], v[64:65]
	v_pk_mul_f32 v[66:67], v[118:119], v[66:67]
	v_pk_mul_f32 v[68:69], v[120:121], v[68:69]
	v_pk_mul_f32 v[70:71], v[122:123], v[70:71]
	v_pk_mul_f32 v[72:73], v[124:125], v[72:73]
	v_pk_mul_f32 v[74:75], v[126:127], v[74:75]
	v_cvt_pk_bf16_f32 v172, v64, v65
	v_cvt_pk_bf16_f32 v173, v66, v67
	v_cvt_pk_bf16_f32 v174, v68, v69
	v_cvt_pk_bf16_f32 v175, v70, v71
	v_cvt_pk_bf16_f32 v176, v72, v73
	v_cvt_pk_bf16_f32 v177, v74, v75
	global_store_dwordx2 v208, v[172:173], s[12:13] offset:0
	global_store_dwordx2 v208, v[174:175], s[12:13] offset:512
	global_store_dwordx2 v208, v[176:177], s[12:13] offset:1024
	s_add_u32 s12, s12, 0x800
	s_addc_u32 s13, s13, 0
	s_waitcnt vmcnt(29)
	v_lshlrev_b32_e32 v64, 16, v178
	v_and_b32_e32 v65, 0xffff0000, v178
	v_lshlrev_b32_e32 v66, 16, v179
	v_and_b32_e32 v67, 0xffff0000, v179
	v_lshlrev_b32_e32 v68, 16, v180
	v_and_b32_e32 v69, 0xffff0000, v180
	v_lshlrev_b32_e32 v70, 16, v181
	v_and_b32_e32 v71, 0xffff0000, v181
	v_lshlrev_b32_e32 v72, 16, v182
	v_and_b32_e32 v73, 0xffff0000, v182
	v_lshlrev_b32_e32 v74, 16, v183
	v_and_b32_e32 v75, 0xffff0000, v183
	v_pk_mul_f32 v[86:87], v[64:65], v[64:65]
	v_pk_fma_f32 v[86:87], v[66:67], v[66:67], v[86:87]
	v_add_f32_e32 v76, v86, v87
	v_pk_mul_f32 v[88:89], v[68:69], v[68:69]
	v_pk_fma_f32 v[88:89], v[70:71], v[70:71], v[88:89]
	v_add_f32_e32 v77, v88, v89
	v_pk_mul_f32 v[86:87], v[72:73], v[72:73]
	v_pk_fma_f32 v[86:87], v[74:75], v[74:75], v[86:87]
	v_add_f32_e32 v78, v86, v87
	s_nop 0
	v_add_f32_dpp v76, v76, v76 row_ror:8 row_mask:0xf bank_mask:0xf
	s_nop 0
	v_add_f32_dpp v77, v77, v77 row_ror:8 row_mask:0xf bank_mask:0xf
	s_nop 0
	v_add_f32_dpp v76, v76, v76 row_ror:4 row_mask:0xf bank_mask:0xf
	s_nop 0
	v_add_f32_dpp v77, v77, v77 row_ror:4 row_mask:0xf bank_mask:0xf
	s_nop 0
	v_add_f32_dpp v76, v76, v76 row_ror:2 row_mask:0xf bank_mask:0xf
	s_nop 0
	v_add_f32_dpp v77, v77, v77 row_ror:2 row_mask:0xf bank_mask:0xf
	s_nop 0
	v_add_f32_dpp v76, v76, v76 row_ror:1 row_mask:0xf bank_mask:0xf
	s_nop 0
	v_add_f32_dpp v77, v77, v77 row_ror:1 row_mask:0xf bank_mask:0xf
	s_nop 0
	v_readlane_b32 s0, v76, 0
	v_readlane_b32 s1, v76, 16
	v_readlane_b32 s14, v76, 32
	v_readlane_b32 s15, v76, 48
	v_readlane_b32 s18, v77, 0
	v_readlane_b32 s19, v77, 16
	v_readlane_b32 s20, v77, 32
	v_readlane_b32 s21, v77, 48
	s_nop 1
	v_mov_b32_e32 v80, s0
	v_mov_b32_e32 v82, s18
	v_add_f32_e32 v80, s1, v80
	v_add_f32_e32 v82, s19, v82
	v_add_f32_e32 v80, s14, v80
	v_add_f32_e32 v82, s20, v82
	v_add_f32_e32 v80, s15, v80
	v_add_f32_e32 v82, s21, v82
	v_add_f32_dpp v78, v78, v78 row_ror:8 row_mask:0xf bank_mask:0xf
	s_nop 1
	v_add_f32_dpp v78, v78, v78 row_ror:4 row_mask:0xf bank_mask:0xf
	s_nop 1
	v_add_f32_dpp v78, v78, v78 row_ror:2 row_mask:0xf bank_mask:0xf
	s_nop 1
	v_add_f32_dpp v78, v78, v78 row_ror:1 row_mask:0xf bank_mask:0xf
	s_nop 1
	s_nop 0
	v_readlane_b32 s0, v78, 0
	v_readlane_b32 s1, v78, 16
	v_readlane_b32 s14, v78, 32
	v_readlane_b32 s15, v78, 48
	s_nop 1
	v_mov_b32_e32 v84, s0
	v_add_f32_e32 v84, s1, v84
	v_add_f32_e32 v84, s14, v84
	v_add_f32_e32 v84, s15, v84
	v_fmamk_f32 v80, v80, 0x3b800000, v197
	v_fmamk_f32 v82, v82, 0x3b800000, v197
	v_fmamk_f32 v84, v84, 0x3b800000, v197
	v_rsq_f32_e32 v80, v80
	v_rsq_f32_e32 v82, v82
	v_rsq_f32_e32 v84, v84
	s_nop 0
	v_pk_mul_f32 v[64:65], v[80:81], v[64:65] op_sel_hi:[0,1]
	v_pk_mul_f32 v[66:67], v[80:81], v[66:67] op_sel_hi:[0,1]
	v_pk_mul_f32 v[68:69], v[82:83], v[68:69] op_sel_hi:[0,1]
	v_pk_mul_f32 v[70:71], v[82:83], v[70:71] op_sel_hi:[0,1]
	v_pk_mul_f32 v[72:73], v[84:85], v[72:73] op_sel_hi:[0,1]
	v_pk_mul_f32 v[74:75], v[84:85], v[74:75] op_sel_hi:[0,1]
	v_pk_mul_f32 v[64:65], v[116:117], v[64:65]
	v_pk_mul_f32 v[66:67], v[118:119], v[66:67]
	v_pk_mul_f32 v[68:69], v[120:121], v[68:69]
	v_pk_mul_f32 v[70:71], v[122:123], v[70:71]
	v_pk_mul_f32 v[72:73], v[124:125], v[72:73]
	v_pk_mul_f32 v[74:75], v[126:127], v[74:75]
	v_cvt_pk_bf16_f32 v178, v64, v65
	v_cvt_pk_bf16_f32 v179, v66, v67
	v_cvt_pk_bf16_f32 v180, v68, v69
	v_cvt_pk_bf16_f32 v181, v70, v71
	v_cvt_pk_bf16_f32 v182, v72, v73
	v_cvt_pk_bf16_f32 v183, v74, v75
	global_store_dwordx2 v208, v[178:179], s[12:13] offset:0
	global_store_dwordx2 v208, v[180:181], s[12:13] offset:512
	global_store_dwordx2 v208, v[182:183], s[12:13] offset:1024
	s_add_u32 s12, s12, 0x800
	s_addc_u32 s13, s13, 0
	s_waitcnt vmcnt(29)
	v_lshlrev_b32_e32 v64, 16, v184
	v_and_b32_e32 v65, 0xffff0000, v184
	v_lshlrev_b32_e32 v66, 16, v185
	v_and_b32_e32 v67, 0xffff0000, v185
	v_lshlrev_b32_e32 v68, 16, v112
	v_and_b32_e32 v69, 0xffff0000, v112
	v_lshlrev_b32_e32 v70, 16, v113
	v_and_b32_e32 v71, 0xffff0000, v113
	v_lshlrev_b32_e32 v72, 16, v114
	v_and_b32_e32 v73, 0xffff0000, v114
	v_lshlrev_b32_e32 v74, 16, v115
	v_and_b32_e32 v75, 0xffff0000, v115
	v_pk_mul_f32 v[86:87], v[64:65], v[64:65]
	v_pk_fma_f32 v[86:87], v[66:67], v[66:67], v[86:87]
	v_add_f32_e32 v76, v86, v87
	v_pk_mul_f32 v[88:89], v[68:69], v[68:69]
	v_pk_fma_f32 v[88:89], v[70:71], v[70:71], v[88:89]
	v_add_f32_e32 v77, v88, v89
	v_pk_mul_f32 v[86:87], v[72:73], v[72:73]
	v_pk_fma_f32 v[86:87], v[74:75], v[74:75], v[86:87]
	v_add_f32_e32 v78, v86, v87
	s_nop 0
	v_add_f32_dpp v76, v76, v76 row_ror:8 row_mask:0xf bank_mask:0xf
	s_nop 0
	v_add_f32_dpp v77, v77, v77 row_ror:8 row_mask:0xf bank_mask:0xf
	s_nop 0
	v_add_f32_dpp v76, v76, v76 row_ror:4 row_mask:0xf bank_mask:0xf
	s_nop 0
	v_add_f32_dpp v77, v77, v77 row_ror:4 row_mask:0xf bank_mask:0xf
	s_nop 0
	v_add_f32_dpp v76, v76, v76 row_ror:2 row_mask:0xf bank_mask:0xf
	s_nop 0
	v_add_f32_dpp v77, v77, v77 row_ror:2 row_mask:0xf bank_mask:0xf
	s_nop 0
	v_add_f32_dpp v76, v76, v76 row_ror:1 row_mask:0xf bank_mask:0xf
	s_nop 0
	v_add_f32_dpp v77, v77, v77 row_ror:1 row_mask:0xf bank_mask:0xf
	s_nop 0
	v_readlane_b32 s0, v76, 0
	v_readlane_b32 s1, v76, 16
	v_readlane_b32 s14, v76, 32
	v_readlane_b32 s15, v76, 48
	v_readlane_b32 s18, v77, 0
	v_readlane_b32 s19, v77, 16
	v_readlane_b32 s20, v77, 32
	v_readlane_b32 s21, v77, 48
	s_nop 1
	v_mov_b32_e32 v80, s0
	v_mov_b32_e32 v82, s18
	v_add_f32_e32 v80, s1, v80
	v_add_f32_e32 v82, s19, v82
	v_add_f32_e32 v80, s14, v80
	v_add_f32_e32 v82, s20, v82
	v_add_f32_e32 v80, s15, v80
	v_add_f32_e32 v82, s21, v82
	v_add_f32_dpp v78, v78, v78 row_ror:8 row_mask:0xf bank_mask:0xf
	s_nop 1
	v_add_f32_dpp v78, v78, v78 row_ror:4 row_mask:0xf bank_mask:0xf
	s_nop 1
	v_add_f32_dpp v78, v78, v78 row_ror:2 row_mask:0xf bank_mask:0xf
	s_nop 1
	v_add_f32_dpp v78, v78, v78 row_ror:1 row_mask:0xf bank_mask:0xf
	s_nop 1
	s_nop 0
	v_readlane_b32 s0, v78, 0
	v_readlane_b32 s1, v78, 16
	v_readlane_b32 s14, v78, 32
	v_readlane_b32 s15, v78, 48
	s_nop 1
	v_mov_b32_e32 v84, s0
	v_add_f32_e32 v84, s1, v84
	v_add_f32_e32 v84, s14, v84
	v_add_f32_e32 v84, s15, v84
	v_fmamk_f32 v80, v80, 0x3b800000, v197
	v_fmamk_f32 v82, v82, 0x3b800000, v197
	v_fmamk_f32 v84, v84, 0x3b800000, v197
	v_rsq_f32_e32 v80, v80
	v_rsq_f32_e32 v82, v82
	v_rsq_f32_e32 v84, v84
	s_nop 0
	v_pk_mul_f32 v[64:65], v[80:81], v[64:65] op_sel_hi:[0,1]
	v_pk_mul_f32 v[66:67], v[80:81], v[66:67] op_sel_hi:[0,1]
	v_pk_mul_f32 v[68:69], v[82:83], v[68:69] op_sel_hi:[0,1]
	v_pk_mul_f32 v[70:71], v[82:83], v[70:71] op_sel_hi:[0,1]
	v_pk_mul_f32 v[72:73], v[84:85], v[72:73] op_sel_hi:[0,1]
	v_pk_mul_f32 v[74:75], v[84:85], v[74:75] op_sel_hi:[0,1]
	v_pk_mul_f32 v[64:65], v[116:117], v[64:65]
	v_pk_mul_f32 v[66:67], v[118:119], v[66:67]
	v_pk_mul_f32 v[68:69], v[120:121], v[68:69]
	v_pk_mul_f32 v[70:71], v[122:123], v[70:71]
	v_pk_mul_f32 v[72:73], v[124:125], v[72:73]
	v_pk_mul_f32 v[74:75], v[126:127], v[74:75]
	v_cvt_pk_bf16_f32 v184, v64, v65
	v_cvt_pk_bf16_f32 v185, v66, v67
	v_cvt_pk_bf16_f32 v112, v68, v69
	v_cvt_pk_bf16_f32 v113, v70, v71
	v_cvt_pk_bf16_f32 v114, v72, v73
	v_cvt_pk_bf16_f32 v115, v74, v75
	global_store_dwordx2 v208, v[184:185], s[12:13] offset:0
	global_store_dwordx2 v208, v[112:113], s[12:13] offset:512
	global_store_dwordx2 v208, v[114:115], s[12:13] offset:1024
	s_cmp_eq_u32 s17, 0
	s_cselect_b32 s0, 1, 0
	s_cmp_eq_u32 s27, 0
	s_cselect_b32 s0, s0, 0
	s_cmp_lt_u32 s69, 16
	s_cselect_b32 s0, s0, 0
	s_cmp_eq_u32 s0, 1
	s_cbranch_scc0 .Lgg_end
	s_mov_b32 s17, 1
	s_lshl_b32 s16, s69, 6
	s_barrier
	s_branch .Lgg_blk
